# hyena region: packed f32 VOP3P ops split into scalar pairs (instruction-selection test)
# baseline (speedup 1.0000x reference)
; __device__ __forceinline__ cf cmul(cf a, cf b) { return mk2(a.x * b.x - a.y * b.y, a.x * b.y + a.y * b.x); }
; __device__ __forceinline__ cf twid(float frac) { return mk2(__builtin_amdgcn_cosf(frac), -__builtin_amdgcn_sinf(frac)); }
; template <int LG, bool INV> __device__ __forceinline__ void fft_pass2(LAS cf* X, int tid) {
;     ...
;         const int it = tid + 512 * i; int g, j;
;         if (LG == 14) { g = 0; j = it; } else if (LG == 10) { j = it & 63; g = it >> 6; } else { g = it & 255; j = it >> 8; }
;         const int base = g * L + j;
;         const int pb = PX(base);
;     ...
;         cf e[4][4];
; #pragma unroll
;         for (int r = 0; r < 4; ++r)
; #pragma unroll
;             for (int m = 0; m < 4; ++m) e[r][m] = X[pb + POFF(r, m)];
;         const cf v1 = twid((float)(4 * j) * fL), v2 = cmul(v1, v1), v3 = cmul(v2, v1);
;         if (!INV) {
; #pragma unroll
;             for (int r = 0; r < 4; ++r) { bfly4_fwd(e[r][0], e[r][1], e[r][2], e[r][3]);
;                 const cf w1 = twid((float)(j + r * L16) * fL), w2 = cmul(w1, w1), w3 = cmul(w2, w1);
;                 e[r][1] = cmul(e[r][1], w1); e[r][2] = cmul(e[r][2], w2); e[r][3] = cmul(e[r][3], w3); }
; #pragma unroll
;             for (int p = 0; p < 4; ++p) { bfly4_fwd(e[0][p], e[1][p], e[2][p], e[3][p]); e[1][p] = cmul(e[1][p], v1); e[2][p] = cmul(e[2][p], v2); e[3][p] = cmul(e[3][p], v3); }
.LBB0_521:
	v_add_u32_e32 v1, s6, v16
	v_ashrrev_i32_e32 v2, 6, v1
	v_lshlrev_b32_e32 v2, 3, v2
	v_lshlrev_b32_e32 v3, 3, v1
	v_add3_u32 v127, 0, v2, v3
	v_add_u32_e32 v131, 0x10400, v127
	ds_read_b64 v[4:5], v127
	ds_read_b64 v[6:7], v127 offset:33280
	ds_read_b64 v[8:9], v131
	v_cvt_f32_i32_e32 v132, v1
	v_add_u32_e32 v169, 0x18600, v127
	ds_read_b64 v[10:11], v169
	ds_read_b64 v[12:13], v127 offset:8320
	ds_read_b64 v[14:15], v127 offset:41600
	v_add_u32_e32 v192, 0x12480, v127
	v_mul_f32_e32 v132, 0x38800000, v132
	s_waitcnt lgkmcnt(0)
	v_add_f32_e32 v176, v4, v8
	v_add_f32_e32 v177, v5, v9
	v_sub_f32_e32 v4, v4, v8
	v_sub_f32_e32 v5, v5, v9
	s_waitcnt lgkmcnt(2)
	v_add_f32_e32 v8, v6, v10
	v_add_f32_e32 v9, v7, v11
	v_sin_f32_e32 v178, v132
	v_sub_f32_e32 v6, v6, v10
	v_sub_f32_e32 v7, v7, v11
	v_add_f32_e32 v10, v176, v8
	v_add_f32_e32 v11, v177, v9
	v_sub_f32_e32 v8, v176, v8
	v_sub_f32_e32 v9, v177, v9
	v_cos_f32_e32 v176, v132
	v_add_f32_e32 v180, v4, v7
	v_add_f32_e32 v181, v5, v6
	v_sub_f32_e32 v182, v4, v7
	v_sub_f32_e32 v183, v5, v6
	v_xor_b32_e32 v177, 0x80000000, v178
	v_mov_b32_e32 v185, v183
	v_pk_mov_b32 v[182:183], v[182:183], v[180:181] op_sel:[1,0]
	v_mov_b32_e32 v184, v180
	v_mul_f32_e32 v182, v178, v182
	v_mul_f32_e32 v183, v178, v183
	v_fma_f32 v180, v176, v180, v182
	v_fma_f32 v181, v177, v181, v183
	v_fma_f32 v182, v176, v184, -v182
	v_fma_f32 v183, v176, v185, -v183
	v_mov_b32_e32 v181, v183
	v_mov_b32_e32 v179, v176
	v_mov_b32_e32 v182, v178
	v_mov_b32_e32 v183, v177
	v_mul_f32_e32 v182, v178, v182
	v_mul_f32_e32 v183, v179, v183
	ds_read_b64 v[138:139], v192
	v_fma_f32 v184, v176, v176, -v182
	v_fma_f32 v185, v176, v177, -v183
	v_fma_f32 v182, v176, v176, v182
	v_fma_f32 v183, v176, v177, v183
	v_mov_b32_e32 v187, v183
	v_pk_mov_b32 v[182:183], v[182:183], v[184:185] op_sel:[1,0]
	v_mov_b32_e32 v186, v184
	v_mul_f32_e32 v179, v178, v183
	v_mul_f32_e32 v178, v178, v182
	v_mul_f32_e32 v182, v182, v9
	v_mul_f32_e32 v183, v183, v9
	v_add_u32_e32 v193, 0x1a680, v127
	v_fma_f32 v188, v176, v186, v178
	v_fma_f32 v189, v176, v187, v179
	v_fma_f32 v177, v176, v187, -v179
	v_fma_f32 v176, v176, v186, -v178
	v_fma_f32 v184, v184, v8, -v182
	v_fma_f32 v185, v185, v9, -v183
	v_fma_f32 v9, v187, v8, v183
	v_fma_f32 v8, v186, v8, v182
	ds_read_b64 v[140:141], v193
	ds_read_b64 v[142:143], v127 offset:16640
	ds_read_b64 v[144:145], v127 offset:49920
	v_mov_b32_e32 v185, v9
	v_sub_f32_e32 v8, v4, v7
	v_sub_f32_e32 v9, v4, v7
	v_add_f32_e32 v4, v5, v6
	v_add_f32_e32 v5, v5, v6
	v_pk_mov_b32 v[6:7], v[176:177], v[188:189] op_sel:[1,0]
	v_mov_b32_e32 v178, v188
	v_mov_b32_e32 v179, v177
	v_mul_f32_e32 v4, v4, v6
	v_mul_f32_e32 v5, v5, v7
	v_add_u32_e32 v194, 0x14500, v127
	v_fma_f32 v6, v8, v188, -v4
	v_fma_f32 v7, v9, v189, -v5
	v_fma_f32 v4, v8, v178, v4
	v_fma_f32 v5, v9, v179, v5
	s_waitcnt lgkmcnt(0)
	v_sub_f32_e32 v8, v12, v138
	v_sub_f32_e32 v9, v13, v139
	v_mov_b32_e32 v7, v5
	v_add_f32_e32 v4, v12, v138
	v_add_f32_e32 v5, v13, v139
	s_waitcnt lgkmcnt(2)
	v_add_f32_e32 v12, v14, v140
	v_add_f32_e32 v13, v15, v141
	v_sub_f32_e32 v14, v14, v140
	v_sub_f32_e32 v15, v15, v141
	v_add_f32_e32 v138, v4, v12
	v_add_f32_e32 v139, v5, v13
	v_sub_f32_e32 v4, v4, v12
	v_sub_f32_e32 v5, v5, v13
	v_add_u32_e32 v12, 0x400, v1
	v_cvt_f32_i32_e32 v12, v12
	v_add_f32_e32 v186, v8, v15
	v_add_f32_e32 v187, v9, v14
	v_sub_f32_e32 v8, v8, v15
	v_sub_f32_e32 v9, v9, v14
	v_mov_b32_e32 v14, v186
	v_mul_f32_e32 v13, 0x38800000, v12
	v_cos_f32_e32 v12, v13
	v_sin_f32_e32 v13, v13
	v_pk_mov_b32 v[188:189], v[8:9], v[186:187] op_sel:[1,0]
	v_mov_b32_e32 v15, v9
	v_mov_b32_e32 v141, v12
	v_xor_b32_e32 v140, 0x80000000, v13
	v_mov_b32_e32 v176, v140
	v_mov_b32_e32 v177, v13
	v_mul_f32_e32 v176, v12, v176
	v_mul_f32_e32 v177, v13, v177
	v_mov_b32_e32 v132, v13
	v_fma_f32 v178, v12, v140, v176
	v_fma_f32 v179, v12, v141, v177
	v_fma_f32 v140, v12, v140, -v176
	v_fma_f32 v141, v12, v141, -v177
	v_mov_b32_e32 v176, v178
	v_mov_b32_e32 v177, v141
	v_mov_b32_e32 v182, v13
	v_mov_b32_e32 v183, v12
	s_waitcnt vmcnt(0)
	v_mul_f32_e32 v188, v132, v188
	v_mul_f32_e32 v189, v132, v189
	ds_read_b64 v[146:147], v194
	v_mul_f32_e32 v182, v182, v176
	v_mul_f32_e32 v183, v183, v177
	v_mul_f32_e32 v176, v12, v176
	v_mul_f32_e32 v177, v13, v177
	v_fma_f32 v190, v12, v186, v188
	v_fma_f32 v191, v13, v187, v189
	v_fma_f32 v13, v12, v15, -v189
	v_fma_f32 v12, v12, v14, -v188
	v_add_u32_e32 v132, 0x800, v1
	v_add_u32_e32 v195, 0x1c700, v127
	v_mov_b32_e32 v191, v13
	v_mul_f32_e32 v12, v178, v5
	v_mul_f32_e32 v13, v178, v4
	v_cvt_f32_i32_e32 v132, v132
	ds_read_b64 v[148:149], v195
	ds_read_b64 v[150:151], v127 offset:24960
	ds_read_b64 v[152:153], v127 offset:58240
	v_fma_f32 v14, v141, v4, -v12
	v_fma_f32 v15, v141, v5, -v13
	v_fma_f32 v4, v141, v4, v12
	v_fma_f32 v5, v141, v5, v13
	v_sub_f32_e32 v12, v176, v177
	v_sub_f32_e32 v13, v176, v177
	v_pk_mov_b32 v[140:141], v[186:187], v[8:9] op_sel:[1,0]
	v_mov_b32_e32 v15, v5
	v_mov_b32_e32 v4, v8
	v_mov_b32_e32 v5, v187
	v_mul_f32_e32 v12, v12, v140
	v_mul_f32_e32 v13, v13, v141
	v_add_f32_e32 v140, v183, v182
	v_add_f32_e32 v141, v183, v182
	v_mul_f32_e32 v132, 0x38800000, v132
	v_fma_f32 v8, v140, v8, -v12
	v_fma_f32 v9, v141, v9, -v13
	v_fma_f32 v4, v140, v4, v12
	v_fma_f32 v5, v141, v5, v13
	s_waitcnt lgkmcnt(2)
; __device__ __forceinline__ cf cmul(cf a, cf b) { return mk2(a.x * b.x - a.y * b.y, a.x * b.y + a.y * b.x); }
; __device__ __forceinline__ cf twid(float frac) { return mk2(__builtin_amdgcn_cosf(frac), -__builtin_amdgcn_sinf(frac)); }
; template <int LG, bool INV> __device__ __forceinline__ void fft_pass2(LAS cf* X, int tid) {
;     ...
;         const cf v1 = twid((float)(4 * j) * fL), v2 = cmul(v1, v1), v3 = cmul(v2, v1);
;         if (!INV) {
; #pragma unroll
;             for (int r = 0; r < 4; ++r) { bfly4_fwd(e[r][0], e[r][1], e[r][2], e[r][3]);
;                 const cf w1 = twid((float)(j + r * L16) * fL), w2 = cmul(w1, w1), w3 = cmul(w2, w1);
;                 e[r][1] = cmul(e[r][1], w1); e[r][2] = cmul(e[r][2], w2); e[r][3] = cmul(e[r][3], w3); }
; #pragma unroll
;             for (int p = 0; p < 4; ++p) { bfly4_fwd(e[0][p], e[1][p], e[2][p], e[3][p]); e[1][p] = cmul(e[1][p], v1); e[2][p] = cmul(e[2][p], v2); e[3][p] = cmul(e[3][p], v3); }
	v_add_f32_e32 v140, v144, v148
	v_add_f32_e32 v141, v145, v149
	v_mov_b32_e32 v9, v5
	v_add_f32_e32 v4, v142, v146
	v_add_f32_e32 v5, v143, v147
	v_sub_f32_e32 v12, v142, v146
	v_sub_f32_e32 v13, v143, v147
	v_sub_f32_e32 v142, v144, v148
	v_sub_f32_e32 v143, v145, v149
	v_add_f32_e32 v144, v4, v140
	v_add_f32_e32 v145, v5, v141
	v_sub_f32_e32 v4, v4, v140
	v_sub_f32_e32 v5, v5, v141
	v_sin_f32_e32 v141, v132
	v_cos_f32_e32 v140, v132
	v_add_f32_e32 v182, v12, v143
	v_add_f32_e32 v183, v13, v142
	v_sub_f32_e32 v12, v12, v143
	v_sub_f32_e32 v13, v13, v142
	v_xor_b32_e32 v146, 0x80000000, v141
	v_mov_b32_e32 v148, v146
	v_mov_b32_e32 v149, v141
	v_mov_b32_e32 v147, v140
	v_mul_f32_e32 v148, v140, v148
	v_mul_f32_e32 v149, v141, v149
	v_mov_b32_e32 v132, v141
	v_fma_f32 v176, v140, v146, v148
	v_fma_f32 v177, v140, v147, v149
	v_fma_f32 v146, v140, v146, -v148
	v_fma_f32 v147, v140, v147, -v149
	v_pk_mov_b32 v[186:187], v[12:13], v[182:183] op_sel:[1,0]
	v_add_u32_e32 v196, 0x16580, v127
	v_add_u32_e32 v197, 0x1e780, v127
	v_mov_b32_e32 v148, v176
	v_mov_b32_e32 v149, v147
	v_mov_b32_e32 v178, v141
	v_mov_b32_e32 v179, v140
	v_mov_b32_e32 v142, v182
	v_mov_b32_e32 v143, v13
	v_mul_f32_e32 v186, v132, v186
	v_mul_f32_e32 v187, v132, v187
	ds_read_b64 v[170:171], v196
	ds_read_b64 v[172:173], v197
	v_lshlrev_b32_e32 v2, 2, v1
	v_mul_f32_e32 v178, v178, v148
	v_mul_f32_e32 v179, v179, v149
	v_mul_f32_e32 v148, v140, v148
	v_mul_f32_e32 v149, v141, v149
	v_fma_f32 v188, v140, v182, v186
	v_fma_f32 v189, v141, v183, v187
	v_fma_f32 v141, v140, v143, -v187
	v_fma_f32 v140, v140, v142, -v186
	v_add_u32_e32 v1, 0xc00, v1
	v_mov_b32_e32 v189, v141
	v_mul_f32_e32 v140, v176, v5
	v_mul_f32_e32 v141, v176, v4
	v_cvt_f32_i32_e32 v1, v1
	v_fma_f32 v142, v147, v4, -v140
	v_fma_f32 v143, v147, v5, -v141
	v_fma_f32 v4, v147, v4, v140
	v_fma_f32 v5, v147, v5, v141
	v_sub_f32_e32 v140, v148, v149
	v_sub_f32_e32 v141, v148, v149
	v_pk_mov_b32 v[146:147], v[182:183], v[12:13] op_sel:[1,0]
	v_mov_b32_e32 v143, v5
	v_mov_b32_e32 v4, v12
	v_mov_b32_e32 v5, v183
	v_mul_f32_e32 v140, v140, v146
	v_mul_f32_e32 v141, v141, v147
	v_add_f32_e32 v146, v179, v178
	v_add_f32_e32 v147, v179, v178
	v_mul_f32_e32 v1, 0x38800000, v1
	v_fma_f32 v12, v146, v12, -v140
	v_fma_f32 v13, v147, v13, -v141
	v_fma_f32 v4, v146, v4, v140
	v_fma_f32 v5, v147, v5, v141
	s_waitcnt lgkmcnt(0)
	v_add_f32_e32 v146, v152, v172
	v_add_f32_e32 v147, v153, v173
	v_mov_b32_e32 v13, v5
	v_add_f32_e32 v4, v150, v170
	v_add_f32_e32 v5, v151, v171
	v_sub_f32_e32 v140, v150, v170
	v_sub_f32_e32 v141, v151, v171
	v_add_f32_e32 v150, v4, v146
	v_add_f32_e32 v151, v5, v147
	v_sub_f32_e32 v4, v4, v146
	v_sub_f32_e32 v5, v5, v147
	v_sin_f32_e32 v147, v1
	v_cos_f32_e32 v146, v1
	v_cvt_f32_i32_e32 v2, v2
	v_sub_f32_e32 v148, v152, v172
	v_sub_f32_e32 v149, v153, v173
	v_xor_b32_e32 v152, 0x80000000, v147
	v_mov_b32_e32 v170, v152
	v_mov_b32_e32 v171, v147
	v_mov_b32_e32 v153, v146
	v_mul_f32_e32 v170, v146, v170
	v_mul_f32_e32 v171, v147, v171
	v_add_f32_e32 v178, v140, v149
	v_add_f32_e32 v179, v141, v148
	v_sub_f32_e32 v140, v140, v149
	v_sub_f32_e32 v141, v141, v148
	v_fma_f32 v172, v146, v152, v170
	v_fma_f32 v173, v146, v153, v171
	v_fma_f32 v152, v146, v152, -v170
	v_fma_f32 v153, v146, v153, -v171
	v_mov_b32_e32 v132, v147
	v_pk_mov_b32 v[182:183], v[140:141], v[178:179] op_sel:[1,0]
	v_mul_f32_e32 v3, 0x38800000, v2
	v_mov_b32_e32 v170, v172
	v_mov_b32_e32 v171, v153
	v_mov_b32_e32 v176, v147
	v_mov_b32_e32 v177, v146
	v_mov_b32_e32 v148, v178
	v_mov_b32_e32 v149, v141
	v_mul_f32_e32 v182, v132, v182
	v_mul_f32_e32 v183, v132, v183
	v_cos_f32_e32 v2, v3
	v_sin_f32_e32 v3, v3
	v_mul_f32_e32 v176, v176, v170
	v_mul_f32_e32 v177, v177, v171
	v_mul_f32_e32 v170, v146, v170
	v_mul_f32_e32 v171, v147, v171
	v_fma_f32 v186, v146, v178, v182
	v_fma_f32 v187, v147, v179, v183
	v_fma_f32 v147, v146, v149, -v183
	v_fma_f32 v146, v146, v148, -v182
	v_mov_b32_e32 v187, v147
	v_mul_f32_e32 v146, v172, v5
	v_mul_f32_e32 v147, v172, v4
	v_fma_f32 v148, v153, v4, -v146
	v_fma_f32 v149, v153, v5, -v147
	v_fma_f32 v4, v153, v4, v146
	v_fma_f32 v5, v153, v5, v147
	v_sub_f32_e32 v146, v170, v171
	v_sub_f32_e32 v147, v170, v171
	v_pk_mov_b32 v[152:153], v[178:179], v[140:141] op_sel:[1,0]
	v_mov_b32_e32 v149, v5
	v_mov_b32_e32 v4, v140
	v_mov_b32_e32 v5, v179
	v_mul_f32_e32 v146, v146, v152
	v_mul_f32_e32 v147, v147, v153
	v_add_f32_e32 v152, v177, v176
	v_add_f32_e32 v153, v177, v176
	v_xor_b32_e32 v174, 0x80000000, v3
	v_fma_f32 v140, v152, v140, -v146
	v_fma_f32 v141, v153, v141, -v147
	v_fma_f32 v4, v152, v4, v146
	v_fma_f32 v5, v153, v5, v147
	v_add_f32_e32 v172, v10, v144
	v_add_f32_e32 v173, v11, v145
	v_mov_b32_e32 v141, v5
	v_mov_b32_e32 v4, v174
	v_mov_b32_e32 v5, v3
	v_sub_f32_e32 v10, v10, v144
	v_sub_f32_e32 v11, v11, v145
	v_add_f32_e32 v144, v138, v150
	v_add_f32_e32 v145, v139, v151
	v_sub_f32_e32 v138, v138, v150
	v_sub_f32_e32 v139, v139, v151
	v_mov_b32_e32 v175, v2
	v_mul_f32_e32 v4, v2, v4
	v_mul_f32_e32 v5, v3, v5
	v_add_f32_e32 v150, v172, v144
	v_add_f32_e32 v151, v173, v145
	v_sub_f32_e32 v144, v172, v144
	v_sub_f32_e32 v145, v173, v145
	v_add_f32_e32 v172, v10, v139
	v_add_f32_e32 v173, v11, v138
	v_sub_f32_e32 v10, v10, v139
	v_sub_f32_e32 v11, v11, v138
	v_fma_f32 v146, v2, v174, v4
	v_fma_f32 v147, v2, v175, v5
	v_fma_f32 v4, v2, v174, -v4
	v_fma_f32 v5, v2, v175, -v5
	v_mov_b32_e32 v132, v3
	v_pk_mov_b32 v[174:175], v[10:11], v[172:173] op_sel:[1,0]
	v_mov_b32_e32 v138, v172
	v_mov_b32_e32 v139, v11
	v_mul_f32_e32 v174, v132, v174
	v_mul_f32_e32 v175, v132, v175
	v_mov_b32_e32 v152, v146
; __device__ __forceinline__ cf cmul(cf a, cf b) { return mk2(a.x * b.x - a.y * b.y, a.x * b.y + a.y * b.x); }
; __device__ __forceinline__ cf cmulc(cf a, cf b) { return mk2(a.x * b.x + a.y * b.y, a.y * b.x - a.x * b.y); }
; __device__ __forceinline__ cf twid(float frac) { return mk2(__builtin_amdgcn_cosf(frac), -__builtin_amdgcn_sinf(frac)); }
; template <int LG, bool INV> __device__ __forceinline__ void fft_pass2(LAS cf* X, int tid) {
;     ...
; #pragma unroll
;             for (int p = 0; p < 4; ++p) { bfly4_fwd(e[0][p], e[1][p], e[2][p], e[3][p]); e[1][p] = cmul(e[1][p], v1); e[2][p] = cmul(e[2][p], v2); e[3][p] = cmul(e[3][p], v3); }
;         } else {
; #pragma unroll
;             for (int p = 0; p < 4; ++p) { e[1][p] = cmulc(e[1][p], v1); e[2][p] = cmulc(e[2][p], v2); e[3][p] = cmulc(e[3][p], v3); bfly4_inv(e[0][p], e[1][p], e[2][p], e[3][p]); }
; #pragma unroll
;             for (int r = 0; r < 4; ++r) { const cf w1 = twid((float)(j + r * L16) * fL), w2 = cmul(w1, w1), w3 = cmul(w2, w1);
;                 e[r][1] = cmulc(e[r][1], w1); e[r][2] = cmulc(e[r][2], w2); e[r][3] = cmulc(e[r][3], w3); bfly4_inv(e[r][0], e[r][1], e[r][2], e[r][3]); }
;         }
; #pragma unroll
;         for (int r = 0; r < 4; ++r)
; #pragma unroll
;             for (int m = 0; m < 4; ++m) X[pb + POFF(r, m)] = e[r][m];
;     }
;     ...
;     __syncthreads();
	v_mov_b32_e32 v153, v5
	v_mov_b32_e32 v170, v3
	v_mov_b32_e32 v171, v2
	v_fma_f32 v176, v2, v172, v174
	v_fma_f32 v177, v3, v173, v175
	v_fma_f32 v138, v2, v138, -v174
	v_fma_f32 v139, v2, v139, -v175
	v_mul_f32_e32 v170, v170, v152
	v_mul_f32_e32 v171, v171, v153
	v_mul_f32_e32 v152, v2, v152
	v_mul_f32_e32 v153, v3, v153
	v_mov_b32_e32 v177, v139
	v_mul_f32_e32 v138, v146, v144
	v_mul_f32_e32 v139, v146, v145
	v_fma_f32 v174, v5, v144, -v139
	v_fma_f32 v175, v5, v145, -v138
	v_pk_fma_f32 v[138:139], v[4:5], v[144:145], v[138:139] op_sel:[1,0,1] op_sel_hi:[1,1,0]
	v_sub_f32_e32 v144, v152, v153
	v_sub_f32_e32 v145, v152, v153
	v_pk_mov_b32 v[152:153], v[172:173], v[10:11] op_sel:[1,0]
	v_mov_b32_e32 v175, v139
	v_mov_b32_e32 v138, v10
	v_mov_b32_e32 v139, v173
	v_mul_f32_e32 v152, v144, v152
	v_mul_f32_e32 v153, v145, v153
	v_pk_add_f32 v[170:171], v[170:171], v[170:171] op_sel:[1,0] op_sel_hi:[1,0]
	v_add_f32_e32 v172, v190, v186
	v_add_f32_e32 v173, v191, v187
	v_fma_f32 v10, v170, v10, -v152
	v_fma_f32 v11, v171, v11, -v153
	v_fma_f32 v138, v170, v138, v152
	v_fma_f32 v139, v171, v139, v153
	v_sub_f32_e32 v152, v180, v188
	v_sub_f32_e32 v153, v181, v189
	v_mov_b32_e32 v11, v139
	v_add_f32_e32 v138, v180, v188
	v_add_f32_e32 v139, v181, v189
	v_sub_f32_e32 v178, v190, v186
	v_sub_f32_e32 v179, v191, v187
	v_add_f32_e32 v180, v138, v172
	v_add_f32_e32 v181, v139, v173
	v_sub_f32_e32 v138, v138, v172
	v_sub_f32_e32 v139, v139, v173
	v_add_f32_e32 v172, v152, v179
	v_add_f32_e32 v173, v153, v178
	v_sub_f32_e32 v152, v152, v179
	v_sub_f32_e32 v153, v153, v178
	v_mov_b32_e32 v178, v172
	v_pk_mov_b32 v[182:183], v[152:153], v[172:173] op_sel:[1,0]
	v_mov_b32_e32 v179, v153
	v_mul_f32_e32 v182, v132, v182
	v_mul_f32_e32 v183, v132, v183
	v_fma_f32 v186, v2, v172, v182
	v_fma_f32 v187, v3, v173, v183
	v_fma_f32 v178, v2, v178, -v182
	v_fma_f32 v179, v2, v179, -v183
	v_mov_b32_e32 v187, v179
	v_mul_f32_e32 v178, v146, v138
	v_mul_f32_e32 v179, v146, v139
	v_fma_f32 v182, v5, v138, -v179
	v_fma_f32 v183, v5, v139, -v178
	v_fma_f32 v138, v5, v138, v179
	v_fma_f32 v139, v5, v139, v178
	s_movk_i32 s6, 0x200
	v_mov_b32_e32 v183, v139
	v_mov_b32_e32 v139, v173
	v_pk_mov_b32 v[172:173], v[172:173], v[152:153] op_sel:[1,0]
	v_mov_b32_e32 v138, v152
	v_mul_f32_e32 v172, v144, v172
	v_mul_f32_e32 v173, v145, v173
	s_and_b64 vcc, exec, s[4:5]
	v_fma_f32 v152, v170, v152, -v172
	v_fma_f32 v153, v171, v153, -v173
	v_fma_f32 v138, v170, v138, v172
	v_fma_f32 v139, v171, v139, v173
	v_add_f32_e32 v172, v14, v148
	v_add_f32_e32 v173, v15, v149
	v_mov_b32_e32 v153, v139
	v_add_f32_e32 v138, v184, v142
	v_add_f32_e32 v139, v185, v143
	v_sub_f32_e32 v142, v184, v142
	v_sub_f32_e32 v143, v185, v143
	v_sub_f32_e32 v14, v14, v148
	v_sub_f32_e32 v15, v15, v149
	v_add_f32_e32 v148, v138, v172
	v_add_f32_e32 v149, v139, v173
	v_sub_f32_e32 v138, v138, v172
	v_sub_f32_e32 v139, v139, v173
	v_add_f32_e32 v172, v142, v15
	v_add_f32_e32 v173, v143, v14
	v_pk_add_f32 v[14:15], v[142:143], v[14:15] op_sel:[0,1] op_sel_hi:[1,0] neg_lo:[0,1] neg_hi:[0,1]
	v_mov_b32_e32 v142, v172
	v_pk_mov_b32 v[178:179], v[14:15], v[172:173] op_sel:[1,0]
	v_mov_b32_e32 v143, v15
	v_mul_f32_e32 v178, v132, v178
	v_mul_f32_e32 v179, v132, v179
	v_fma_f32 v184, v2, v172, v178
	v_fma_f32 v185, v3, v173, v179
	v_fma_f32 v142, v2, v142, -v178
	v_fma_f32 v143, v2, v143, -v179
	v_mov_b32_e32 v185, v143
	v_mul_f32_e32 v142, v146, v138
	v_mul_f32_e32 v143, v146, v139
	v_fma_f32 v178, v5, v138, -v143
	v_fma_f32 v179, v5, v139, -v142
	v_fma_f32 v138, v5, v138, v143
	v_fma_f32 v139, v5, v139, v142
	v_pk_mov_b32 v[142:143], v[172:173], v[14:15] op_sel:[1,0]
	v_mov_b32_e32 v179, v139
	v_mov_b32_e32 v138, v14
	v_mov_b32_e32 v139, v173
	v_mul_f32_e32 v142, v144, v142
	v_mul_f32_e32 v143, v145, v143
	s_mov_b64 s[4:5], 0
	v_fma_f32 v14, v170, v14, -v142
	v_fma_f32 v15, v171, v15, -v143
	v_fma_f32 v138, v170, v138, v142
	v_fma_f32 v139, v171, v139, v143
	s_nop 0
	v_mov_b32_e32 v15, v139
	v_add_f32_e32 v138, v6, v12
	v_add_f32_e32 v139, v7, v13
	v_sub_f32_e32 v6, v6, v12
	v_sub_f32_e32 v7, v7, v13
	v_add_f32_e32 v12, v8, v140
	v_add_f32_e32 v13, v9, v141
	v_sub_f32_e32 v8, v8, v140
	v_sub_f32_e32 v9, v9, v141
	v_add_f32_e32 v140, v138, v12
	v_add_f32_e32 v141, v139, v13
	v_sub_f32_e32 v12, v138, v12
	v_sub_f32_e32 v13, v139, v13
	v_add_f32_e32 v138, v6, v9
	v_add_f32_e32 v139, v7, v8
	v_sub_f32_e32 v6, v6, v9
	v_sub_f32_e32 v7, v7, v8
	v_mov_b32_e32 v8, v138
	v_pk_mov_b32 v[142:143], v[6:7], v[138:139] op_sel:[1,0]
	v_mov_b32_e32 v9, v7
	v_mul_f32_e32 v142, v132, v142
	v_mul_f32_e32 v143, v132, v143
	v_fma_f32 v172, v2, v138, v142
	v_fma_f32 v173, v3, v139, v143
	v_fma_f32 v3, v2, v9, -v143
	v_fma_f32 v2, v2, v8, -v142
	v_mov_b32_e32 v173, v3
	v_mul_f32_e32 v2, v146, v12
	v_mul_f32_e32 v3, v146, v13
	v_fma_f32 v8, v5, v12, -v3
	v_fma_f32 v9, v5, v13, -v2
	v_pk_fma_f32 v[2:3], v[4:5], v[12:13], v[2:3] op_sel:[1,0,1] op_sel_hi:[1,1,0]
	v_pk_mov_b32 v[4:5], v[138:139], v[6:7] op_sel:[1,0]
	v_mov_b32_e32 v9, v3
	v_mov_b32_e32 v2, v6
	v_mov_b32_e32 v3, v139
	v_mul_f32_e32 v4, v144, v4
	v_mul_f32_e32 v5, v145, v5
	s_nop 0
	v_fma_f32 v6, v170, v6, -v4
	v_fma_f32 v7, v171, v7, -v5
	v_fma_f32 v2, v170, v2, v4
	v_fma_f32 v3, v171, v3, v5
	s_nop 0
	v_mov_b32_e32 v7, v3
	ds_write_b64 v127, v[150:151]
	ds_write_b64 v127, v[180:181] offset:33280
	ds_write_b64 v131, v[148:149]
	ds_write_b64 v169, v[140:141]
	ds_write_b64 v127, v[176:177] offset:8320
	ds_write_b64 v127, v[186:187] offset:41600
	ds_write_b64 v192, v[184:185]
	ds_write_b64 v193, v[172:173]
	ds_write_b64 v127, v[174:175] offset:16640
	ds_write_b64 v127, v[182:183] offset:49920
	ds_write_b64 v194, v[178:179]
	ds_write_b64 v195, v[8:9]
	ds_write_b64 v127, v[10:11] offset:24960
	ds_write_b64 v127, v[152:153] offset:58240
	ds_write_b64 v196, v[14:15]
	ds_write_b64 v197, v[6:7]
	s_cbranch_vccnz .LBB0_521
	s_mov_b32 s6, 0
	s_mov_b64 s[4:5], -1
	s_waitcnt lgkmcnt(0)
	s_barrier
; __device__ __forceinline__ cf cmul(cf a, cf b) { return mk2(a.x * b.x - a.y * b.y, a.x * b.y + a.y * b.x); }
; __device__ __forceinline__ cf twid(float frac) { return mk2(__builtin_amdgcn_cosf(frac), -__builtin_amdgcn_sinf(frac)); }
; template <int LG, bool INV> __device__ __forceinline__ void fft_pass2(LAS cf* X, int tid) {
;     ...
;         const int it = tid + 512 * i; int g, j;
;         if (LG == 14) { g = 0; j = it; } else if (LG == 10) { j = it & 63; g = it >> 6; } else { g = it & 255; j = it >> 8; }
;         const int base = g * L + j;
;         const int pb = PX(base);
;     ...
;         cf e[4][4];
; #pragma unroll
;         for (int r = 0; r < 4; ++r)
; #pragma unroll
;             for (int m = 0; m < 4; ++m) e[r][m] = X[pb + POFF(r, m)];
;         const cf v1 = twid((float)(4 * j) * fL), v2 = cmul(v1, v1), v3 = cmul(v2, v1);
;         if (!INV) {
; #pragma unroll
;             for (int r = 0; r < 4; ++r) { bfly4_fwd(e[r][0], e[r][1], e[r][2], e[r][3]);
;                 const cf w1 = twid((float)(j + r * L16) * fL), w2 = cmul(w1, w1), w3 = cmul(w2, w1);
;                 e[r][1] = cmul(e[r][1], w1); e[r][2] = cmul(e[r][2], w2); e[r][3] = cmul(e[r][3], w3); }
; #pragma unroll
;             for (int p = 0; p < 4; ++p) { bfly4_fwd(e[0][p], e[1][p], e[2][p], e[3][p]); e[1][p] = cmul(e[1][p], v1); e[2][p] = cmul(e[2][p], v2); e[3][p] = cmul(e[3][p], v3); }
.LBB0_523:
	v_add_u32_e32 v1, s6, v155
	v_and_b32_e32 v1, 0xfffffc00, v1
	v_ashrrev_i32_e32 v2, 3, v1
	v_add_u32_e32 v2, 0, v2
	v_lshlrev_b32_e32 v1, 3, v1
	v_lshlrev_b32_e32 v169, 3, v109
	v_add3_u32 v1, v2, v1, v169
	v_add_u32_e32 v127, 0x800, v1
	v_add_u32_e32 v131, 0x1000, v1
	ds_read2_b64 v[2:5], v1 offset1:65
	ds_read2_b64 v[6:9], v127 offset0:4 offset1:69
	ds_read2_b64 v[10:13], v131 offset0:8 offset1:73
	v_add_u32_e32 v132, 0x1800, v1
	ds_read2_b64 v[138:141], v132 offset0:12 offset1:77
	ds_read2_b64 v[142:145], v1 offset0:130 offset1:195
	ds_read2_b64 v[146:149], v127 offset0:134 offset1:199
	ds_read2_b64 v[150:153], v131 offset0:138 offset1:203
	ds_read2_b64 v[170:173], v132 offset0:142 offset1:207
	s_movk_i32 s6, 0x2000
	s_and_b64 vcc, exec, s[4:5]
	s_waitcnt lgkmcnt(5)
	v_add_f32_e32 v14, v2, v10
	v_add_f32_e32 v15, v3, v11
	v_sub_f32_e32 v2, v2, v10
	v_sub_f32_e32 v3, v3, v11
	s_waitcnt lgkmcnt(4)
	v_add_f32_e32 v10, v6, v138
	v_add_f32_e32 v11, v7, v139
	v_sub_f32_e32 v6, v6, v138
	v_sub_f32_e32 v7, v7, v139
	v_add_f32_e32 v138, v14, v10
	v_add_f32_e32 v139, v15, v11
	v_sub_f32_e32 v10, v14, v10
	v_sub_f32_e32 v11, v15, v11
	v_add_f32_e32 v14, v2, v7
	v_add_f32_e32 v15, v3, v6
	v_sub_f32_e32 v174, v2, v7
	v_sub_f32_e32 v175, v3, v6
	v_mov_b32_e32 v176, v14
	v_mov_b32_e32 v177, v175
	v_pk_mov_b32 v[174:175], v[174:175], v[14:15] op_sel:[1,0]
	s_mov_b64 s[4:5], 0
	v_mul_f32_e32 v174, v34, v174
	v_mul_f32_e32 v175, v35, v175
	s_nop 0
	v_fma_f32 v14, v36, v14, v174
	v_fma_f32 v15, v37, v15, v175
	v_fma_f32 v174, v36, v176, -v174
	v_fma_f32 v175, v37, v177, -v175
	s_nop 0
	v_mov_b32_e32 v15, v175
	v_mul_f32_e32 v174, v46, v11
	v_mul_f32_e32 v175, v47, v11
	s_nop 0
	v_fma_f32 v176, v44, v10, -v174
	v_fma_f32 v177, v45, v11, -v175
	v_fma_f32 v11, v45, v10, v175
	v_fma_f32 v10, v44, v10, v174
	s_nop 0
	v_mov_b32_e32 v177, v11
	v_sub_f32_e32 v10, v2, v7
	v_sub_f32_e32 v11, v2, v7
	v_add_f32_e32 v2, v3, v6
	v_add_f32_e32 v3, v3, v6
	s_nop 0
	v_mul_f32_e32 v2, v110, v2
	v_mul_f32_e32 v3, v111, v3
	s_nop 0
	v_fma_f32 v6, v56, v10, -v2
	v_fma_f32 v7, v57, v11, -v3
	v_fma_f32 v2, v56, v10, v2
	v_fma_f32 v3, v57, v11, v3
	v_add_f32_e32 v10, v8, v140
	v_add_f32_e32 v11, v9, v141
	v_mov_b32_e32 v7, v3
	v_add_f32_e32 v2, v4, v12
	v_add_f32_e32 v3, v5, v13
	v_sub_f32_e32 v4, v4, v12
	v_sub_f32_e32 v5, v5, v13
	v_sub_f32_e32 v8, v8, v140
	v_sub_f32_e32 v9, v9, v141
	v_add_f32_e32 v12, v2, v10
	v_add_f32_e32 v13, v3, v11
	v_sub_f32_e32 v2, v2, v10
	v_sub_f32_e32 v3, v3, v11
	v_add_f32_e32 v10, v4, v9
	v_add_f32_e32 v11, v5, v8
	v_sub_f32_e32 v140, v4, v9
	v_sub_f32_e32 v141, v5, v8
	v_mov_b32_e32 v174, v10
	v_mov_b32_e32 v175, v141
	v_pk_mov_b32 v[140:141], v[140:141], v[10:11] op_sel:[1,0]
	s_nop 0
	v_mul_f32_e32 v140, v52, v140
	v_mul_f32_e32 v141, v53, v141
	s_nop 0
	v_fma_f32 v10, v54, v10, v140
	v_fma_f32 v11, v55, v11, v141
	v_fma_f32 v140, v54, v174, -v140
	v_fma_f32 v141, v55, v175, -v141
	s_nop 0
	v_mov_b32_e32 v11, v141
	v_mul_f32_e32 v140, v64, v3
	v_mul_f32_e32 v141, v65, v3
	s_nop 0
	v_fma_f32 v174, v62, v2, -v140
	v_fma_f32 v175, v63, v3, -v141
	v_fma_f32 v3, v63, v2, v141
	v_fma_f32 v2, v62, v2, v140
	s_waitcnt lgkmcnt(0)
	v_add_f32_e32 v140, v146, v170
	v_add_f32_e32 v141, v147, v171
	v_mov_b32_e32 v175, v3
	v_sub_f32_e32 v2, v4, v9
	v_sub_f32_e32 v3, v4, v9
	v_add_f32_e32 v4, v5, v8
	v_add_f32_e32 v5, v5, v8
	s_nop 0
	v_mul_f32_e32 v4, v112, v4
	v_mul_f32_e32 v5, v113, v5
	s_nop 0
	v_fma_f32 v8, v74, v2, -v4
	v_fma_f32 v9, v75, v3, -v5
	v_fma_f32 v2, v74, v2, v4
	v_fma_f32 v3, v75, v3, v5
	v_sub_f32_e32 v4, v142, v150
	v_sub_f32_e32 v5, v143, v151
	v_mov_b32_e32 v9, v3
	v_add_f32_e32 v2, v142, v150
	v_add_f32_e32 v3, v143, v151
	v_sub_f32_e32 v142, v146, v170
	v_sub_f32_e32 v143, v147, v171
	v_add_f32_e32 v146, v2, v140
	v_add_f32_e32 v147, v3, v141
	v_sub_f32_e32 v2, v2, v140
	v_sub_f32_e32 v3, v3, v141
	v_add_f32_e32 v140, v4, v143
	v_add_f32_e32 v141, v5, v142
	v_sub_f32_e32 v150, v4, v143
	v_sub_f32_e32 v151, v5, v142
	v_mov_b32_e32 v170, v140
	v_mov_b32_e32 v171, v151
	v_pk_mov_b32 v[150:151], v[150:151], v[140:141] op_sel:[1,0]
	s_nop 0
	v_mul_f32_e32 v150, v70, v150
	v_mul_f32_e32 v151, v71, v151
	s_nop 0
	v_fma_f32 v140, v72, v140, v150
	v_fma_f32 v141, v73, v141, v151
	v_fma_f32 v150, v72, v170, -v150
	v_fma_f32 v151, v73, v171, -v151
	s_nop 0
	v_mov_b32_e32 v141, v151
	v_mul_f32_e32 v150, v82, v3
	v_mul_f32_e32 v151, v83, v3
	s_nop 0
	v_fma_f32 v170, v80, v2, -v150
	v_fma_f32 v171, v81, v3, -v151
	v_fma_f32 v3, v81, v2, v151
	v_fma_f32 v2, v80, v2, v150
	s_nop 0
	v_mov_b32_e32 v171, v3
	v_sub_f32_e32 v2, v4, v143
	v_sub_f32_e32 v3, v4, v143
	v_add_f32_e32 v4, v5, v142
	v_add_f32_e32 v5, v5, v142
	s_nop 0
	v_mul_f32_e32 v4, v114, v4
	v_mul_f32_e32 v5, v115, v5
	s_nop 0
	v_fma_f32 v142, v92, v2, -v4
	v_fma_f32 v143, v93, v3, -v5
	v_fma_f32 v2, v92, v2, v4
	v_fma_f32 v3, v93, v3, v5
	v_sub_f32_e32 v4, v144, v152
	v_sub_f32_e32 v5, v145, v153
	v_mov_b32_e32 v143, v3
	v_add_f32_e32 v2, v144, v152
	v_add_f32_e32 v3, v145, v153
	v_add_f32_e32 v144, v148, v172
	v_add_f32_e32 v145, v149, v173
	v_sub_f32_e32 v148, v148, v172
	v_sub_f32_e32 v149, v149, v173
	v_add_f32_e32 v150, v2, v144
	v_add_f32_e32 v151, v3, v145
	v_sub_f32_e32 v2, v2, v144
	v_sub_f32_e32 v3, v3, v145
	v_add_f32_e32 v144, v4, v149
	v_add_f32_e32 v145, v5, v148
	v_sub_f32_e32 v152, v4, v149
	v_sub_f32_e32 v153, v5, v148
	v_mov_b32_e32 v172, v144
	v_mov_b32_e32 v173, v153
	v_pk_mov_b32 v[152:153], v[152:153], v[144:145] op_sel:[1,0]
	s_nop 0
	v_mul_f32_e32 v152, v88, v152
	v_mul_f32_e32 v153, v89, v153
	s_nop 0
	v_fma_f32 v144, v90, v144, v152
; __device__ __forceinline__ cf cmul(cf a, cf b) { return mk2(a.x * b.x - a.y * b.y, a.x * b.y + a.y * b.x); }
; __device__ __forceinline__ cf cmulc(cf a, cf b) { return mk2(a.x * b.x + a.y * b.y, a.y * b.x - a.x * b.y); }
; __device__ __forceinline__ cf twid(float frac) { return mk2(__builtin_amdgcn_cosf(frac), -__builtin_amdgcn_sinf(frac)); }
; template <int LG, bool INV> __device__ __forceinline__ void fft_pass2(LAS cf* X, int tid) {
;     ...
;             for (int r = 0; r < 4; ++r) { bfly4_fwd(e[r][0], e[r][1], e[r][2], e[r][3]);
;                 const cf w1 = twid((float)(j + r * L16) * fL), w2 = cmul(w1, w1), w3 = cmul(w2, w1);
;                 e[r][1] = cmul(e[r][1], w1); e[r][2] = cmul(e[r][2], w2); e[r][3] = cmul(e[r][3], w3); }
; #pragma unroll
;             for (int p = 0; p < 4; ++p) { bfly4_fwd(e[0][p], e[1][p], e[2][p], e[3][p]); e[1][p] = cmul(e[1][p], v1); e[2][p] = cmul(e[2][p], v2); e[3][p] = cmul(e[3][p], v3); }
;         } else {
; #pragma unroll
;             for (int p = 0; p < 4; ++p) { e[1][p] = cmulc(e[1][p], v1); e[2][p] = cmulc(e[2][p], v2); e[3][p] = cmulc(e[3][p], v3); bfly4_inv(e[0][p], e[1][p], e[2][p], e[3][p]); }
; #pragma unroll
;             for (int r = 0; r < 4; ++r) { const cf w1 = twid((float)(j + r * L16) * fL), w2 = cmul(w1, w1), w3 = cmul(w2, w1);
;                 e[r][1] = cmulc(e[r][1], w1); e[r][2] = cmulc(e[r][2], w2); e[r][3] = cmulc(e[r][3], w3); bfly4_inv(e[r][0], e[r][1], e[r][2], e[r][3]); }
;         }
; #pragma unroll
;         for (int r = 0; r < 4; ++r)
; #pragma unroll
;             for (int m = 0; m < 4; ++m) X[pb + POFF(r, m)] = e[r][m];
;     }
;     ...
;     __syncthreads();
	v_fma_f32 v145, v91, v145, v153
	v_fma_f32 v152, v90, v172, -v152
	v_fma_f32 v153, v91, v173, -v153
	s_nop 0
	v_mov_b32_e32 v145, v153
	v_mul_f32_e32 v152, v100, v3
	v_mul_f32_e32 v153, v101, v3
	s_nop 0
	v_fma_f32 v172, v98, v2, -v152
	v_fma_f32 v173, v99, v3, -v153
	v_fma_f32 v3, v99, v2, v153
	v_fma_f32 v2, v98, v2, v152
	s_nop 0
	v_mov_b32_e32 v173, v3
	v_sub_f32_e32 v2, v4, v149
	v_sub_f32_e32 v3, v4, v149
	v_add_f32_e32 v4, v5, v148
	v_add_f32_e32 v5, v5, v148
	s_nop 0
	v_mul_f32_e32 v4, v116, v4
	v_mul_f32_e32 v5, v117, v5
	s_nop 0
	v_fma_f32 v148, v106, v2, -v4
	v_fma_f32 v149, v107, v3, -v5
	v_fma_f32 v2, v106, v2, v4
	v_fma_f32 v3, v107, v3, v5
	v_sub_f32_e32 v4, v138, v146
	v_sub_f32_e32 v5, v139, v147
	v_mov_b32_e32 v149, v3
	v_add_f32_e32 v2, v138, v146
	v_add_f32_e32 v3, v139, v147
	v_add_f32_e32 v138, v12, v150
	v_add_f32_e32 v139, v13, v151
	v_sub_f32_e32 v12, v12, v150
	v_sub_f32_e32 v13, v13, v151
	v_add_f32_e32 v146, v2, v138
	v_add_f32_e32 v147, v3, v139
	v_sub_f32_e32 v2, v2, v138
	v_sub_f32_e32 v3, v3, v139
	v_add_f32_e32 v138, v4, v13
	v_add_f32_e32 v139, v5, v12
	v_sub_f32_e32 v150, v4, v13
	v_sub_f32_e32 v151, v5, v12
	v_mov_b32_e32 v152, v138
	v_mov_b32_e32 v153, v151
	v_pk_mov_b32 v[150:151], v[150:151], v[138:139] op_sel:[1,0]
	s_nop 0
	v_mul_f32_e32 v150, v18, v150
	v_mul_f32_e32 v151, v19, v151
	s_nop 0
	v_fma_f32 v138, v20, v138, v150
	v_fma_f32 v139, v21, v139, v151
	v_fma_f32 v150, v20, v152, -v150
	v_fma_f32 v151, v21, v153, -v151
	s_nop 0
	v_mov_b32_e32 v139, v151
	v_mul_f32_e32 v150, v28, v3
	v_mul_f32_e32 v151, v29, v3
	s_nop 0
	v_fma_f32 v152, v26, v2, -v150
	v_fma_f32 v153, v27, v3, -v151
	v_fma_f32 v3, v27, v2, v151
	v_fma_f32 v2, v26, v2, v150
	s_nop 0
	v_mov_b32_e32 v153, v3
	v_sub_f32_e32 v2, v4, v13
	v_sub_f32_e32 v3, v4, v13
	v_add_f32_e32 v4, v5, v12
	v_add_f32_e32 v5, v5, v12
	s_nop 0
	v_mul_f32_e32 v4, v118, v4
	v_mul_f32_e32 v5, v119, v5
	s_nop 0
	v_fma_f32 v12, v38, v2, -v4
	v_fma_f32 v13, v39, v3, -v5
	v_fma_f32 v2, v38, v2, v4
	v_fma_f32 v3, v39, v3, v5
	v_sub_f32_e32 v4, v14, v140
	v_sub_f32_e32 v5, v15, v141
	v_mov_b32_e32 v13, v3
	v_add_f32_e32 v2, v14, v140
	v_add_f32_e32 v3, v15, v141
	v_add_f32_e32 v14, v10, v144
	v_add_f32_e32 v15, v11, v145
	v_sub_f32_e32 v10, v10, v144
	v_sub_f32_e32 v11, v11, v145
	v_add_f32_e32 v140, v2, v14
	v_add_f32_e32 v141, v3, v15
	v_sub_f32_e32 v2, v2, v14
	v_sub_f32_e32 v3, v3, v15
	v_add_f32_e32 v14, v4, v11
	v_add_f32_e32 v15, v5, v10
	v_sub_f32_e32 v144, v4, v11
	v_sub_f32_e32 v145, v5, v10
	v_mov_b32_e32 v150, v14
	v_mov_b32_e32 v151, v145
	v_pk_mov_b32 v[144:145], v[144:145], v[14:15] op_sel:[1,0]
	s_nop 0
	v_mul_f32_e32 v144, v18, v144
	v_mul_f32_e32 v145, v19, v145
	s_nop 0
	v_fma_f32 v14, v20, v14, v144
	v_fma_f32 v15, v21, v15, v145
	v_fma_f32 v144, v20, v150, -v144
	v_fma_f32 v145, v21, v151, -v145
	s_nop 0
	v_mov_b32_e32 v15, v145
	v_mul_f32_e32 v144, v28, v3
	v_mul_f32_e32 v145, v29, v3
	s_nop 0
	v_fma_f32 v150, v26, v2, -v144
	v_fma_f32 v151, v27, v3, -v145
	v_fma_f32 v3, v27, v2, v145
	v_fma_f32 v2, v26, v2, v144
	v_add_f32_e32 v144, v174, v172
	v_add_f32_e32 v145, v175, v173
	v_mov_b32_e32 v151, v3
	v_sub_f32_e32 v2, v4, v11
	v_sub_f32_e32 v3, v4, v11
	v_add_f32_e32 v4, v5, v10
	v_add_f32_e32 v5, v5, v10
	s_nop 0
	v_mul_f32_e32 v4, v118, v4
	v_mul_f32_e32 v5, v119, v5
	s_nop 0
	v_fma_f32 v10, v38, v2, -v4
	v_fma_f32 v11, v39, v3, -v5
	v_fma_f32 v2, v38, v2, v4
	v_fma_f32 v3, v39, v3, v5
	v_sub_f32_e32 v4, v176, v170
	v_sub_f32_e32 v5, v177, v171
	v_mov_b32_e32 v11, v3
	v_add_f32_e32 v2, v176, v170
	v_add_f32_e32 v3, v177, v171
	v_sub_f32_e32 v170, v174, v172
	v_sub_f32_e32 v171, v175, v173
	v_add_f32_e32 v172, v2, v144
	v_add_f32_e32 v173, v3, v145
	v_sub_f32_e32 v2, v2, v144
	v_sub_f32_e32 v3, v3, v145
	v_add_f32_e32 v144, v4, v171
	v_add_f32_e32 v145, v5, v170
	v_sub_f32_e32 v174, v4, v171
	v_sub_f32_e32 v175, v5, v170
	v_mov_b32_e32 v176, v144
	v_mov_b32_e32 v177, v175
	v_pk_mov_b32 v[174:175], v[174:175], v[144:145] op_sel:[1,0]
	s_nop 0
	v_mul_f32_e32 v174, v18, v174
	v_mul_f32_e32 v175, v19, v175
	s_nop 0
	v_fma_f32 v144, v20, v144, v174
	v_fma_f32 v145, v21, v145, v175
	v_fma_f32 v174, v20, v176, -v174
	v_fma_f32 v175, v21, v177, -v175
	s_nop 0
	v_mov_b32_e32 v145, v175
	v_mul_f32_e32 v174, v28, v3
	v_mul_f32_e32 v175, v29, v3
	s_nop 0
	v_fma_f32 v176, v26, v2, -v174
	v_fma_f32 v177, v27, v3, -v175
	v_fma_f32 v3, v27, v2, v175
	v_fma_f32 v2, v26, v2, v174
	s_nop 0
	v_mov_b32_e32 v177, v3
	v_sub_f32_e32 v2, v4, v171
	v_sub_f32_e32 v3, v4, v171
	v_add_f32_e32 v4, v5, v170
	v_add_f32_e32 v5, v5, v170
	s_nop 0
	v_mul_f32_e32 v4, v118, v4
	v_mul_f32_e32 v5, v119, v5
	s_nop 0
	v_fma_f32 v170, v38, v2, -v4
	v_fma_f32 v171, v39, v3, -v5
	v_fma_f32 v2, v38, v2, v4
	v_fma_f32 v3, v39, v3, v5
	v_sub_f32_e32 v4, v6, v142
	v_sub_f32_e32 v5, v7, v143
	v_mov_b32_e32 v171, v3
	v_add_f32_e32 v2, v6, v142
	v_add_f32_e32 v3, v7, v143
	v_add_f32_e32 v6, v8, v148
	v_add_f32_e32 v7, v9, v149
	v_sub_f32_e32 v8, v8, v148
	v_sub_f32_e32 v9, v9, v149
	v_add_f32_e32 v142, v2, v6
	v_add_f32_e32 v143, v3, v7
	v_sub_f32_e32 v2, v2, v6
	v_sub_f32_e32 v3, v3, v7
	v_add_f32_e32 v6, v4, v9
	v_add_f32_e32 v7, v5, v8
	v_sub_f32_e32 v148, v4, v9
	v_sub_f32_e32 v149, v5, v8
	v_mov_b32_e32 v174, v6
	v_mov_b32_e32 v175, v149
	v_pk_mov_b32 v[148:149], v[148:149], v[6:7] op_sel:[1,0]
	s_nop 0
	v_mul_f32_e32 v148, v18, v148
	v_mul_f32_e32 v149, v19, v149
	s_nop 0
	v_fma_f32 v6, v20, v6, v148
	v_fma_f32 v7, v21, v7, v149
	v_fma_f32 v148, v20, v174, -v148
	v_fma_f32 v149, v21, v175, -v149
	s_nop 0
	v_mov_b32_e32 v7, v149
	v_mul_f32_e32 v148, v28, v3
	v_mul_f32_e32 v149, v29, v3
	s_nop 0
	v_fma_f32 v174, v26, v2, -v148
	v_fma_f32 v175, v27, v3, -v149
	v_fma_f32 v3, v27, v2, v149
	v_fma_f32 v2, v26, v2, v148
	s_nop 0
	v_mov_b32_e32 v175, v3
	v_sub_f32_e32 v2, v4, v9
	v_sub_f32_e32 v3, v4, v9
	v_add_f32_e32 v4, v5, v8
	v_add_f32_e32 v5, v5, v8
	s_nop 0
	v_mul_f32_e32 v4, v118, v4
	v_mul_f32_e32 v5, v119, v5
	s_nop 0
	v_fma_f32 v8, v38, v2, -v4
	v_fma_f32 v9, v39, v3, -v5
	v_fma_f32 v2, v38, v2, v4
	v_fma_f32 v3, v39, v3, v5
	s_nop 0
	v_mov_b32_e32 v9, v3
	ds_write2_b64 v1, v[146:147], v[138:139] offset1:65
	ds_write2_b64 v127, v[140:141], v[14:15] offset0:4 offset1:69
	ds_write2_b64 v131, v[172:173], v[144:145] offset0:8 offset1:73
	ds_write2_b64 v132, v[142:143], v[6:7] offset0:12 offset1:77
	ds_write2_b64 v1, v[152:153], v[12:13] offset0:130 offset1:195
	ds_write2_b64 v127, v[150:151], v[10:11] offset0:134 offset1:199
	ds_write2_b64 v131, v[176:177], v[170:171] offset0:138 offset1:203
	ds_write2_b64 v132, v[174:175], v[8:9] offset0:142 offset1:207
	s_cbranch_vccnz .LBB0_523
	s_mov_b32 s6, 0
	s_mov_b64 s[4:5], -1
	s_waitcnt lgkmcnt(0)
	s_barrier
; __device__ __forceinline__ cf cmul(cf a, cf b) { return mk2(a.x * b.x - a.y * b.y, a.x * b.y + a.y * b.x); }
; __device__ __forceinline__ cf twid(float frac) { return mk2(__builtin_amdgcn_cosf(frac), -__builtin_amdgcn_sinf(frac)); }
; template <int LG, bool INV> __device__ __forceinline__ void fft_pass2(LAS cf* X, int tid) {
;     ...
;     for (int i = 0; i < 2; ++i) {
;         const int it = tid + 512 * i; int g, j;
;         if (LG == 14) { g = 0; j = it; } else if (LG == 10) { j = it & 63; g = it >> 6; } else { g = it & 255; j = it >> 8; }
;         const int base = g * L + j;
;         const int pb = PX(base);
;     ...
;         cf e[4][4];
; #pragma unroll
;         for (int r = 0; r < 4; ++r)
; #pragma unroll
;             for (int m = 0; m < 4; ++m) e[r][m] = X[pb + POFF(r, m)];
;         const cf v1 = twid((float)(4 * j) * fL), v2 = cmul(v1, v1), v3 = cmul(v2, v1);
;         if (!INV) {
; #pragma unroll
;             for (int r = 0; r < 4; ++r) { bfly4_fwd(e[r][0], e[r][1], e[r][2], e[r][3]);
;                 const cf w1 = twid((float)(j + r * L16) * fL), w2 = cmul(w1, w1), w3 = cmul(w2, w1);
;                 e[r][1] = cmul(e[r][1], w1); e[r][2] = cmul(e[r][2], w2); e[r][3] = cmul(e[r][3], w3); }
; #pragma unroll
;             for (int p = 0; p < 4; ++p) { bfly4_fwd(e[0][p], e[1][p], e[2][p], e[3][p]); e[1][p] = cmul(e[1][p], v1); e[2][p] = cmul(e[2][p], v2); e[3][p] = cmul(e[3][p], v3); }
.LBB0_525:
	v_add_u32_e32 v1, s6, v16
	v_ashrrev_i32_e32 v1, 8, v1
	v_add_u32_e32 v2, v1, v156
	v_cvt_f32_i32_e32 v131, v1
	v_ashrrev_i32_e32 v3, 6, v2
	v_lshlrev_b32_e32 v3, 3, v3
	v_lshlrev_b32_e32 v2, 3, v2
	v_add3_u32 v127, 0, v3, v2
	ds_read2_b64 v[4:7], v127 offset0:16 offset1:20
	ds_read2_b64 v[8:11], v127 offset0:32 offset1:36
	ds_read2_b64 v[12:15], v127 offset0:48 offset1:52
	ds_read2_b64 v[138:141], v127 offset1:4
	ds_read2_b64 v[142:145], v127 offset0:8 offset1:12
	ds_read2_b64 v[146:149], v127 offset0:24 offset1:28
	ds_read2_b64 v[150:153], v127 offset0:40 offset1:44
	ds_read2_b64 v[170:173], v127 offset0:56 offset1:60
	v_mul_f32_e32 v131, 0x3c800000, v131
	s_waitcnt lgkmcnt(4)
	v_add_f32_e32 v176, v138, v8
	v_add_f32_e32 v177, v139, v9
	v_sub_f32_e32 v8, v138, v8
	v_sub_f32_e32 v9, v139, v9
	v_add_f32_e32 v138, v4, v12
	v_add_f32_e32 v139, v5, v13
	v_sin_f32_e32 v178, v131
	v_sub_f32_e32 v4, v4, v12
	v_sub_f32_e32 v5, v5, v13
	v_add_f32_e32 v12, v176, v138
	v_add_f32_e32 v13, v177, v139
	v_sub_f32_e32 v138, v176, v138
	v_sub_f32_e32 v139, v177, v139
	v_cos_f32_e32 v176, v131
	v_add_f32_e32 v180, v8, v5
	v_add_f32_e32 v181, v9, v4
	v_sub_f32_e32 v182, v8, v5
	v_sub_f32_e32 v183, v9, v4
	v_xor_b32_e32 v177, 0x80000000, v178
	v_mov_b32_e32 v185, v183
	v_pk_mov_b32 v[182:183], v[182:183], v[180:181] op_sel:[1,0]
	v_mov_b32_e32 v184, v180
	v_mul_f32_e32 v182, v178, v182
	v_mul_f32_e32 v183, v178, v183
	v_fma_f32 v180, v176, v180, v182
	v_fma_f32 v181, v177, v181, v183
	v_fma_f32 v182, v176, v184, -v182
	v_fma_f32 v183, v176, v185, -v183
	v_mov_b32_e32 v181, v183
	v_mov_b32_e32 v179, v176
	v_mov_b32_e32 v182, v178
	v_mov_b32_e32 v183, v177
	v_mul_f32_e32 v182, v178, v182
	v_mul_f32_e32 v183, v179, v183
	v_add_u32_e32 v131, 4, v1
	v_fma_f32 v184, v176, v176, -v182
	v_fma_f32 v185, v176, v177, -v183
	v_fma_f32 v182, v176, v176, v182
	v_fma_f32 v183, v176, v177, v183
	v_mov_b32_e32 v187, v183
	v_pk_mov_b32 v[182:183], v[182:183], v[184:185] op_sel:[1,0]
	v_mov_b32_e32 v186, v184
	v_mul_f32_e32 v179, v178, v183
	v_mul_f32_e32 v178, v178, v182
	v_mul_f32_e32 v182, v182, v139
	v_mul_f32_e32 v183, v183, v139
	v_fma_f32 v188, v176, v186, v178
	v_fma_f32 v189, v176, v187, v179
	v_fma_f32 v177, v176, v187, -v179
	v_fma_f32 v176, v176, v186, -v178
	v_fma_f32 v184, v184, v138, -v182
	v_fma_f32 v185, v185, v139, -v183
	v_fma_f32 v139, v187, v138, v183
	v_fma_f32 v138, v186, v138, v182
	v_cvt_f32_i32_e32 v131, v131
	v_mov_b32_e32 v185, v139
	v_sub_f32_e32 v138, v8, v5
	v_sub_f32_e32 v139, v8, v5
	v_add_f32_e32 v5, v9, v4
	v_add_f32_e32 v4, v9, v4
	v_pk_mov_b32 v[8:9], v[176:177], v[188:189] op_sel:[1,0]
	v_mov_b32_e32 v178, v188
	v_mov_b32_e32 v179, v177
	v_mul_f32_e32 v4, v4, v8
	v_mul_f32_e32 v5, v5, v9
	v_mul_f32_e32 v131, 0x3c800000, v131
	v_fma_f32 v8, v138, v188, -v4
	v_fma_f32 v9, v139, v189, -v5
	v_fma_f32 v4, v138, v178, v4
	v_fma_f32 v5, v139, v179, v5
	v_add_f32_e32 v138, v6, v14
	v_add_f32_e32 v139, v7, v15
	v_mov_b32_e32 v9, v5
	v_add_f32_e32 v4, v140, v10
	v_add_f32_e32 v5, v141, v11
	v_sub_f32_e32 v6, v6, v14
	v_sub_f32_e32 v7, v7, v15
	v_add_f32_e32 v14, v4, v138
	v_add_f32_e32 v15, v5, v139
	v_sub_f32_e32 v4, v4, v138
	v_sub_f32_e32 v5, v5, v139
	v_sin_f32_e32 v139, v131
	v_cos_f32_e32 v138, v131
	v_sub_f32_e32 v10, v140, v10
	v_sub_f32_e32 v11, v141, v11
	v_add_u32_e32 v131, 8, v1
	v_xor_b32_e32 v140, 0x80000000, v139
	v_mov_b32_e32 v176, v140
	v_mov_b32_e32 v177, v139
	v_add_f32_e32 v186, v10, v7
	v_add_f32_e32 v187, v11, v6
	v_pk_add_f32 v[6:7], v[10:11], v[6:7] op_sel:[0,1] op_sel_hi:[1,0] neg_lo:[0,1] neg_hi:[0,1]
	v_mov_b32_e32 v141, v138
	v_mul_f32_e32 v176, v138, v176
	v_mul_f32_e32 v177, v139, v177
	v_mov_b32_e32 v132, v139
	v_pk_mov_b32 v[188:189], v[6:7], v[186:187] op_sel:[1,0]
	v_fma_f32 v178, v138, v140, v176
	v_fma_f32 v179, v138, v141, v177
	v_fma_f32 v140, v138, v140, -v176
	v_fma_f32 v141, v138, v141, -v177
	v_mov_b32_e32 v10, v186
	v_mov_b32_e32 v11, v7
	v_mul_f32_e32 v188, v132, v188
	v_mul_f32_e32 v189, v132, v189
	v_mov_b32_e32 v176, v178
	v_mov_b32_e32 v177, v141
	v_mov_b32_e32 v182, v139
	v_mov_b32_e32 v183, v138
	v_fma_f32 v190, v138, v186, v188
	v_fma_f32 v191, v139, v187, v189
	v_fma_f32 v10, v138, v10, -v188
	v_fma_f32 v11, v138, v11, -v189
	v_mul_f32_e32 v182, v182, v176
	v_mul_f32_e32 v183, v183, v177
	v_mul_f32_e32 v176, v138, v176
	v_mul_f32_e32 v177, v139, v177
	v_mov_b32_e32 v191, v11
	v_mul_f32_e32 v10, v178, v5
	v_mul_f32_e32 v11, v178, v4
	v_cvt_f32_i32_e32 v131, v131
	v_fma_f32 v138, v141, v4, -v10
	v_fma_f32 v139, v141, v5, -v11
	v_fma_f32 v4, v141, v4, v10
	v_fma_f32 v5, v141, v5, v11
	v_sub_f32_e32 v10, v176, v177
	v_sub_f32_e32 v11, v176, v177
	v_pk_mov_b32 v[140:141], v[186:187], v[6:7] op_sel:[1,0]
	v_mov_b32_e32 v139, v5
	v_mov_b32_e32 v4, v6
	v_mov_b32_e32 v5, v187
	v_mul_f32_e32 v10, v10, v140
	v_mul_f32_e32 v11, v11, v141
	v_add_f32_e32 v140, v183, v182
	v_add_f32_e32 v141, v183, v182
	v_mul_f32_e32 v131, 0x3c800000, v131
	v_fma_f32 v6, v140, v6, -v10
	v_fma_f32 v7, v141, v7, -v11
	v_fma_f32 v4, v140, v4, v10
	v_fma_f32 v5, v141, v5, v11
	s_waitcnt lgkmcnt(0)
; __device__ __forceinline__ cf cmul(cf a, cf b) { return mk2(a.x * b.x - a.y * b.y, a.x * b.y + a.y * b.x); }
; __device__ __forceinline__ cf twid(float frac) { return mk2(__builtin_amdgcn_cosf(frac), -__builtin_amdgcn_sinf(frac)); }
; template <int LG, bool INV> __device__ __forceinline__ void fft_pass2(LAS cf* X, int tid) {
;     ...
;         const cf v1 = twid((float)(4 * j) * fL), v2 = cmul(v1, v1), v3 = cmul(v2, v1);
;         if (!INV) {
; #pragma unroll
;             for (int r = 0; r < 4; ++r) { bfly4_fwd(e[r][0], e[r][1], e[r][2], e[r][3]);
;                 const cf w1 = twid((float)(j + r * L16) * fL), w2 = cmul(w1, w1), w3 = cmul(w2, w1);
;                 e[r][1] = cmul(e[r][1], w1); e[r][2] = cmul(e[r][2], w2); e[r][3] = cmul(e[r][3], w3); }
; #pragma unroll
;             for (int p = 0; p < 4; ++p) { bfly4_fwd(e[0][p], e[1][p], e[2][p], e[3][p]); e[1][p] = cmul(e[1][p], v1); e[2][p] = cmul(e[2][p], v2); e[3][p] = cmul(e[3][p], v3); }
	v_add_f32_e32 v140, v146, v170
	v_add_f32_e32 v141, v147, v171
	v_mov_b32_e32 v7, v5
	v_add_f32_e32 v4, v142, v150
	v_add_f32_e32 v5, v143, v151
	v_sub_f32_e32 v10, v142, v150
	v_sub_f32_e32 v11, v143, v151
	v_sub_f32_e32 v142, v146, v170
	v_sub_f32_e32 v143, v147, v171
	v_add_f32_e32 v146, v4, v140
	v_add_f32_e32 v147, v5, v141
	v_sub_f32_e32 v4, v4, v140
	v_sub_f32_e32 v5, v5, v141
	v_sin_f32_e32 v141, v131
	v_cos_f32_e32 v140, v131
	v_add_f32_e32 v182, v10, v143
	v_add_f32_e32 v183, v11, v142
	v_sub_f32_e32 v10, v10, v143
	v_sub_f32_e32 v11, v11, v142
	v_xor_b32_e32 v150, 0x80000000, v141
	v_mov_b32_e32 v170, v150
	v_mov_b32_e32 v171, v141
	v_mov_b32_e32 v151, v140
	v_mul_f32_e32 v170, v140, v170
	v_mul_f32_e32 v171, v141, v171
	v_mov_b32_e32 v132, v141
	v_fma_f32 v176, v140, v150, v170
	v_fma_f32 v177, v140, v151, v171
	v_fma_f32 v150, v140, v150, -v170
	v_fma_f32 v151, v140, v151, -v171
	v_pk_mov_b32 v[186:187], v[10:11], v[182:183] op_sel:[1,0]
	v_mov_b32_e32 v170, v176
	v_mov_b32_e32 v171, v151
	v_mov_b32_e32 v178, v141
	v_mov_b32_e32 v179, v140
	v_mov_b32_e32 v142, v182
	v_mov_b32_e32 v143, v11
	v_mul_f32_e32 v186, v132, v186
	v_mul_f32_e32 v187, v132, v187
	v_lshlrev_b32_e32 v2, 2, v1
	v_mul_f32_e32 v178, v178, v170
	v_mul_f32_e32 v179, v179, v171
	v_mul_f32_e32 v170, v140, v170
	v_mul_f32_e32 v171, v141, v171
	v_fma_f32 v188, v140, v182, v186
	v_fma_f32 v189, v141, v183, v187
	v_fma_f32 v141, v140, v143, -v187
	v_fma_f32 v140, v140, v142, -v186
	v_add_u32_e32 v1, 12, v1
	v_mov_b32_e32 v189, v141
	v_mul_f32_e32 v140, v176, v5
	v_mul_f32_e32 v141, v176, v4
	v_cvt_f32_i32_e32 v1, v1
	v_fma_f32 v142, v151, v4, -v140
	v_fma_f32 v143, v151, v5, -v141
	v_fma_f32 v4, v151, v4, v140
	v_fma_f32 v5, v151, v5, v141
	v_sub_f32_e32 v140, v170, v171
	v_sub_f32_e32 v141, v170, v171
	v_pk_mov_b32 v[150:151], v[182:183], v[10:11] op_sel:[1,0]
	v_mov_b32_e32 v143, v5
	v_mov_b32_e32 v4, v10
	v_mov_b32_e32 v5, v183
	v_mul_f32_e32 v140, v140, v150
	v_mul_f32_e32 v141, v141, v151
	v_add_f32_e32 v150, v179, v178
	v_add_f32_e32 v151, v179, v178
	v_mul_f32_e32 v1, 0x3c800000, v1
	v_fma_f32 v10, v150, v10, -v140
	v_fma_f32 v11, v151, v11, -v141
	v_fma_f32 v4, v150, v4, v140
	v_fma_f32 v5, v151, v5, v141
	v_sub_f32_e32 v140, v144, v152
	v_sub_f32_e32 v141, v145, v153
	v_mov_b32_e32 v11, v5
	v_add_f32_e32 v4, v144, v152
	v_add_f32_e32 v5, v145, v153
	v_add_f32_e32 v144, v148, v172
	v_add_f32_e32 v145, v149, v173
	v_cvt_f32_i32_e32 v2, v2
	v_add_f32_e32 v150, v4, v144
	v_add_f32_e32 v151, v5, v145
	v_sub_f32_e32 v4, v4, v144
	v_sub_f32_e32 v5, v5, v145
	v_sin_f32_e32 v145, v1
	v_cos_f32_e32 v144, v1
	v_sub_f32_e32 v148, v148, v172
	v_sub_f32_e32 v149, v149, v173
	v_mul_f32_e32 v3, 0x3c800000, v2
	v_xor_b32_e32 v152, 0x80000000, v145
	v_mov_b32_e32 v170, v152
	v_mov_b32_e32 v171, v145
	v_mov_b32_e32 v153, v144
	v_mul_f32_e32 v170, v144, v170
	v_mul_f32_e32 v171, v145, v171
	v_add_f32_e32 v178, v140, v149
	v_add_f32_e32 v179, v141, v148
	v_sub_f32_e32 v140, v140, v149
	v_sub_f32_e32 v141, v141, v148
	v_fma_f32 v172, v144, v152, v170
	v_fma_f32 v173, v144, v153, v171
	v_fma_f32 v152, v144, v152, -v170
	v_fma_f32 v153, v144, v153, -v171
	v_mov_b32_e32 v132, v145
	v_pk_mov_b32 v[182:183], v[140:141], v[178:179] op_sel:[1,0]
	v_mov_b32_e32 v170, v172
	v_mov_b32_e32 v171, v153
	v_mov_b32_e32 v176, v145
	v_mov_b32_e32 v177, v144
	v_mov_b32_e32 v148, v178
	v_mov_b32_e32 v149, v141
	v_mul_f32_e32 v182, v132, v182
	v_mul_f32_e32 v183, v132, v183
	v_cos_f32_e32 v2, v3
	v_sin_f32_e32 v3, v3
	v_mul_f32_e32 v176, v176, v170
	v_mul_f32_e32 v177, v177, v171
	v_mul_f32_e32 v170, v144, v170
	v_mul_f32_e32 v171, v145, v171
	v_fma_f32 v186, v144, v178, v182
	v_fma_f32 v187, v145, v179, v183
	v_fma_f32 v145, v144, v149, -v183
	v_fma_f32 v144, v144, v148, -v182
	v_mov_b32_e32 v187, v145
	v_mul_f32_e32 v144, v172, v5
	v_mul_f32_e32 v145, v172, v4
	v_fma_f32 v148, v153, v4, -v144
	v_fma_f32 v149, v153, v5, -v145
	v_fma_f32 v4, v153, v4, v144
	v_fma_f32 v5, v153, v5, v145
	v_sub_f32_e32 v144, v170, v171
	v_sub_f32_e32 v145, v170, v171
	v_pk_mov_b32 v[152:153], v[178:179], v[140:141] op_sel:[1,0]
	v_mov_b32_e32 v149, v5
	v_mov_b32_e32 v4, v140
	v_mov_b32_e32 v5, v179
	v_mul_f32_e32 v144, v144, v152
	v_mul_f32_e32 v145, v145, v153
	v_add_f32_e32 v152, v177, v176
	v_add_f32_e32 v153, v177, v176
	v_xor_b32_e32 v174, 0x80000000, v3
	v_fma_f32 v140, v152, v140, -v144
	v_fma_f32 v141, v153, v141, -v145
	v_fma_f32 v4, v152, v4, v144
	v_fma_f32 v5, v153, v5, v145
	v_add_f32_e32 v172, v12, v146
	v_add_f32_e32 v173, v13, v147
	v_mov_b32_e32 v141, v5
	v_mov_b32_e32 v4, v174
	v_mov_b32_e32 v5, v3
	v_sub_f32_e32 v12, v12, v146
	v_sub_f32_e32 v13, v13, v147
	v_add_f32_e32 v146, v14, v150
	v_add_f32_e32 v147, v15, v151
	v_sub_f32_e32 v14, v14, v150
	v_sub_f32_e32 v15, v15, v151
	v_mov_b32_e32 v175, v2
	v_mul_f32_e32 v4, v2, v4
	v_mul_f32_e32 v5, v3, v5
	v_add_f32_e32 v150, v172, v146
	v_add_f32_e32 v151, v173, v147
	v_sub_f32_e32 v146, v172, v146
	v_sub_f32_e32 v147, v173, v147
	v_add_f32_e32 v172, v12, v15
	v_add_f32_e32 v173, v13, v14
	v_sub_f32_e32 v12, v12, v15
	v_sub_f32_e32 v13, v13, v14
	v_fma_f32 v144, v2, v174, v4
	v_fma_f32 v145, v2, v175, v5
	v_fma_f32 v4, v2, v174, -v4
	v_fma_f32 v5, v2, v175, -v5
	v_mov_b32_e32 v132, v3
	v_pk_mov_b32 v[174:175], v[12:13], v[172:173] op_sel:[1,0]
	v_mov_b32_e32 v14, v172
	v_mov_b32_e32 v15, v13
	v_mul_f32_e32 v174, v132, v174
	v_mul_f32_e32 v175, v132, v175
	v_mov_b32_e32 v152, v144
	v_mov_b32_e32 v153, v5
	v_mov_b32_e32 v170, v3
	v_mov_b32_e32 v171, v2
	v_fma_f32 v176, v2, v172, v174
	v_fma_f32 v177, v3, v173, v175
	v_fma_f32 v14, v2, v14, -v174
; __device__ __forceinline__ cf cmul(cf a, cf b) { return mk2(a.x * b.x - a.y * b.y, a.x * b.y + a.y * b.x); }
; __device__ __forceinline__ cf cmulc(cf a, cf b) { return mk2(a.x * b.x + a.y * b.y, a.y * b.x - a.x * b.y); }
; __device__ __forceinline__ cf twid(float frac) { return mk2(__builtin_amdgcn_cosf(frac), -__builtin_amdgcn_sinf(frac)); }
; template <int LG, bool INV> __device__ __forceinline__ void fft_pass2(LAS cf* X, int tid) {
;     ...
;             for (int r = 0; r < 4; ++r) { bfly4_fwd(e[r][0], e[r][1], e[r][2], e[r][3]);
;                 const cf w1 = twid((float)(j + r * L16) * fL), w2 = cmul(w1, w1), w3 = cmul(w2, w1);
;                 e[r][1] = cmul(e[r][1], w1); e[r][2] = cmul(e[r][2], w2); e[r][3] = cmul(e[r][3], w3); }
; #pragma unroll
;             for (int p = 0; p < 4; ++p) { bfly4_fwd(e[0][p], e[1][p], e[2][p], e[3][p]); e[1][p] = cmul(e[1][p], v1); e[2][p] = cmul(e[2][p], v2); e[3][p] = cmul(e[3][p], v3); }
;         } else {
; #pragma unroll
;             for (int p = 0; p < 4; ++p) { e[1][p] = cmulc(e[1][p], v1); e[2][p] = cmulc(e[2][p], v2); e[3][p] = cmulc(e[3][p], v3); bfly4_inv(e[0][p], e[1][p], e[2][p], e[3][p]); }
; #pragma unroll
;             for (int r = 0; r < 4; ++r) { const cf w1 = twid((float)(j + r * L16) * fL), w2 = cmul(w1, w1), w3 = cmul(w2, w1);
;                 e[r][1] = cmulc(e[r][1], w1); e[r][2] = cmulc(e[r][2], w2); e[r][3] = cmulc(e[r][3], w3); bfly4_inv(e[r][0], e[r][1], e[r][2], e[r][3]); }
;         }
; #pragma unroll
;         for (int r = 0; r < 4; ++r)
; #pragma unroll
;             for (int m = 0; m < 4; ++m) X[pb + POFF(r, m)] = e[r][m];
;     }
;     ...
;     __syncthreads();
	v_fma_f32 v15, v2, v15, -v175
	v_mul_f32_e32 v170, v170, v152
	v_mul_f32_e32 v171, v171, v153
	v_mul_f32_e32 v152, v2, v152
	v_mul_f32_e32 v153, v3, v153
	v_mov_b32_e32 v177, v15
	v_mul_f32_e32 v14, v144, v146
	v_mul_f32_e32 v15, v144, v147
	v_fma_f32 v174, v5, v146, -v15
	v_fma_f32 v175, v5, v147, -v14
	v_pk_fma_f32 v[14:15], v[4:5], v[146:147], v[14:15] op_sel:[1,0,1] op_sel_hi:[1,1,0]
	v_sub_f32_e32 v146, v152, v153
	v_sub_f32_e32 v147, v152, v153
	v_pk_mov_b32 v[152:153], v[172:173], v[12:13] op_sel:[1,0]
	v_mov_b32_e32 v175, v15
	v_mov_b32_e32 v14, v12
	v_mov_b32_e32 v15, v173
	v_mul_f32_e32 v152, v146, v152
	v_mul_f32_e32 v153, v147, v153
	v_pk_add_f32 v[170:171], v[170:171], v[170:171] op_sel:[1,0] op_sel_hi:[1,0]
	v_add_f32_e32 v172, v190, v186
	v_add_f32_e32 v173, v191, v187
	v_fma_f32 v12, v170, v12, -v152
	v_fma_f32 v13, v171, v13, -v153
	v_fma_f32 v14, v170, v14, v152
	v_fma_f32 v15, v171, v15, v153
	v_sub_f32_e32 v152, v180, v188
	v_sub_f32_e32 v153, v181, v189
	v_mov_b32_e32 v13, v15
	v_add_f32_e32 v14, v180, v188
	v_add_f32_e32 v15, v181, v189
	v_sub_f32_e32 v178, v190, v186
	v_sub_f32_e32 v179, v191, v187
	v_add_f32_e32 v180, v14, v172
	v_add_f32_e32 v181, v15, v173
	v_sub_f32_e32 v14, v14, v172
	v_sub_f32_e32 v15, v15, v173
	v_add_f32_e32 v172, v152, v179
	v_add_f32_e32 v173, v153, v178
	v_sub_f32_e32 v152, v152, v179
	v_sub_f32_e32 v153, v153, v178
	v_mov_b32_e32 v178, v172
	v_pk_mov_b32 v[182:183], v[152:153], v[172:173] op_sel:[1,0]
	v_mov_b32_e32 v179, v153
	v_mul_f32_e32 v182, v132, v182
	v_mul_f32_e32 v183, v132, v183
	v_fma_f32 v186, v2, v172, v182
	v_fma_f32 v187, v3, v173, v183
	v_fma_f32 v178, v2, v178, -v182
	v_fma_f32 v179, v2, v179, -v183
	v_mov_b32_e32 v187, v179
	v_mul_f32_e32 v178, v144, v14
	v_mul_f32_e32 v179, v144, v15
	v_fma_f32 v182, v5, v14, -v179
	v_fma_f32 v183, v5, v15, -v178
	v_fma_f32 v14, v5, v14, v179
	v_fma_f32 v15, v5, v15, v178
	s_movk_i32 s6, 0x200
	v_mov_b32_e32 v183, v15
	v_mov_b32_e32 v15, v173
	v_pk_mov_b32 v[172:173], v[172:173], v[152:153] op_sel:[1,0]
	v_mov_b32_e32 v14, v152
	v_mul_f32_e32 v172, v146, v172
	v_mul_f32_e32 v173, v147, v173
	s_and_b64 vcc, exec, s[4:5]
	v_fma_f32 v152, v170, v152, -v172
	v_fma_f32 v153, v171, v153, -v173
	v_fma_f32 v14, v170, v14, v172
	v_fma_f32 v15, v171, v15, v173
	v_add_f32_e32 v172, v138, v148
	v_add_f32_e32 v173, v139, v149
	v_mov_b32_e32 v153, v15
	v_add_f32_e32 v14, v184, v142
	v_add_f32_e32 v15, v185, v143
	v_sub_f32_e32 v142, v184, v142
	v_sub_f32_e32 v143, v185, v143
	v_sub_f32_e32 v138, v138, v148
	v_sub_f32_e32 v139, v139, v149
	v_add_f32_e32 v148, v14, v172
	v_add_f32_e32 v149, v15, v173
	v_sub_f32_e32 v14, v14, v172
	v_sub_f32_e32 v15, v15, v173
	v_add_f32_e32 v172, v142, v139
	v_add_f32_e32 v173, v143, v138
	v_pk_add_f32 v[138:139], v[142:143], v[138:139] op_sel:[0,1] op_sel_hi:[1,0] neg_lo:[0,1] neg_hi:[0,1]
	v_mov_b32_e32 v142, v172
	v_pk_mov_b32 v[178:179], v[138:139], v[172:173] op_sel:[1,0]
	v_mov_b32_e32 v143, v139
	v_mul_f32_e32 v178, v132, v178
	v_mul_f32_e32 v179, v132, v179
	v_fma_f32 v184, v2, v172, v178
	v_fma_f32 v185, v3, v173, v179
	v_fma_f32 v142, v2, v142, -v178
	v_fma_f32 v143, v2, v143, -v179
	v_mov_b32_e32 v185, v143
	v_mul_f32_e32 v142, v144, v14
	v_mul_f32_e32 v143, v144, v15
	v_fma_f32 v178, v5, v14, -v143
	v_fma_f32 v179, v5, v15, -v142
	v_fma_f32 v14, v5, v14, v143
	v_fma_f32 v15, v5, v15, v142
	v_pk_mov_b32 v[142:143], v[172:173], v[138:139] op_sel:[1,0]
	v_mov_b32_e32 v179, v15
	v_mov_b32_e32 v14, v138
	v_mov_b32_e32 v15, v173
	v_mul_f32_e32 v142, v146, v142
	v_mul_f32_e32 v143, v147, v143
	s_mov_b64 s[4:5], 0
	v_fma_f32 v138, v170, v138, -v142
	v_fma_f32 v139, v171, v139, -v143
	v_fma_f32 v14, v170, v14, v142
	v_fma_f32 v15, v171, v15, v143
	s_nop 0
	v_mov_b32_e32 v139, v15
	v_add_f32_e32 v14, v8, v10
	v_add_f32_e32 v15, v9, v11
	v_sub_f32_e32 v8, v8, v10
	v_sub_f32_e32 v9, v9, v11
	v_add_f32_e32 v10, v6, v140
	v_add_f32_e32 v11, v7, v141
	v_sub_f32_e32 v6, v6, v140
	v_sub_f32_e32 v7, v7, v141
	v_add_f32_e32 v140, v14, v10
	v_add_f32_e32 v141, v15, v11
	v_sub_f32_e32 v10, v14, v10
	v_sub_f32_e32 v11, v15, v11
	v_add_f32_e32 v14, v8, v7
	v_add_f32_e32 v15, v9, v6
	v_pk_add_f32 v[6:7], v[8:9], v[6:7] op_sel:[0,1] op_sel_hi:[1,0] neg_lo:[0,1] neg_hi:[0,1]
	v_mov_b32_e32 v8, v14
	v_pk_mov_b32 v[142:143], v[6:7], v[14:15] op_sel:[1,0]
	v_mov_b32_e32 v9, v7
	v_mul_f32_e32 v142, v132, v142
	v_mul_f32_e32 v143, v132, v143
	v_fma_f32 v172, v2, v14, v142
	v_fma_f32 v173, v3, v15, v143
	v_fma_f32 v3, v2, v9, -v143
	v_fma_f32 v2, v2, v8, -v142
	v_mov_b32_e32 v173, v3
	v_mul_f32_e32 v2, v144, v10
	v_mul_f32_e32 v3, v144, v11
	v_fma_f32 v8, v5, v10, -v3
	v_fma_f32 v9, v5, v11, -v2
	v_pk_fma_f32 v[2:3], v[4:5], v[10:11], v[2:3] op_sel:[1,0,1] op_sel_hi:[1,1,0]
	v_pk_mov_b32 v[4:5], v[14:15], v[6:7] op_sel:[1,0]
	v_mov_b32_e32 v9, v3
	v_mov_b32_e32 v2, v6
	v_mov_b32_e32 v3, v15
	v_mul_f32_e32 v4, v146, v4
	v_mul_f32_e32 v5, v147, v5
	s_nop 0
	v_fma_f32 v6, v170, v6, -v4
	v_fma_f32 v7, v171, v7, -v5
	v_fma_f32 v2, v170, v2, v4
	v_fma_f32 v3, v171, v3, v5
	s_nop 0
	v_mov_b32_e32 v7, v3
	ds_write2_b64 v127, v[150:151], v[176:177] offset1:4
	ds_write2_b64 v127, v[180:181], v[186:187] offset0:16 offset1:20
	ds_write2_b64 v127, v[148:149], v[184:185] offset0:32 offset1:36
	ds_write2_b64 v127, v[140:141], v[172:173] offset0:48 offset1:52
	ds_write2_b64 v127, v[174:175], v[12:13] offset0:8 offset1:12
	ds_write2_b64 v127, v[182:183], v[152:153] offset0:24 offset1:28
	ds_write2_b64 v127, v[178:179], v[138:139] offset0:40 offset1:44
	ds_write2_b64 v127, v[8:9], v[6:7] offset0:56 offset1:60
	s_cbranch_vccnz .LBB0_525
	s_lshl_b32 s4, s48, 14
	s_mov_b32 s5, s64
	s_waitcnt vmcnt(0)
	v_cndmask_b32_e64 v2, v164, v165, s[46:47]
	v_lshl_add_u64 v[4:5], s[4:5], 3, v[136:137]
	s_mov_b32 s4, 0
	s_waitcnt lgkmcnt(0)
	s_barrier
; __device__ __forceinline__ void fft_last_fwd(LAS cf* X, int tid, cf* KFW, float bias, float scale) {
;     ...
;     for (int i = 0; i < 8; ++i) { const int it = tid + 512 * i, g = it & 255, k = it >> 8, base = g * 64 + 4 * k;
;         cf e0 = X[PX(base)], e1 = X[PX(base + 1)], e2 = X[PX(base + 2)], e3 = X[PX(base + 3)];
;         bfly4_fwd(e0, e1, e2, e3);
;         if (KFW) { cf* o = KFW + (4 * k) * 256 + g; o[0] = mk2((e0.x + bias) * scale, e0.y * scale); o[256] = mk2((e1.x + bias) * scale, e1.y * scale); o[512] = mk2((e2.x + bias) * scale, e2.y * scale); o[768] = mk2((e3.x + bias) * scale, e3.y * scale); }
;         else { X[PX(base)] = e0; X[PX(base + 1)] = e1; X[PX(base + 2)] = e2; X[PX(base + 3)] = e3; } }
;     __syncthreads();
; __global__ void __launch_bounds__(NTHR, 2) fwd_mega(Args a) {
;     ...
;                     fft_last_fwd(X, tid, KF + o * FFTN, o == 0 ? bias1 : bias2, 1.0f / FFTN);
;                 }
;                 __threadfence(); __syncthreads();
;                 for (int bp = 0; bp < 2; ++bp) {
;                     const int b0 = 2 * bp, b1 = b0 + 1;
;                     const bf16_t* pv0 = HYR + ((size_t)b0 * 768 + c) * 8192; const bf16_t* pv1 = HYR + ((size_t)b1 * 768 + c) * 8192;
.LBB0_527:
	v_add_u32_e32 v1, s4, v16
	v_ashrrev_i32_e32 v3, 6, v1
	v_and_b32_e32 v3, -4, v3
	v_add_u32_e32 v6, v3, v157
	v_ashrrev_i32_e32 v7, 6, v6
	v_lshlrev_b32_e32 v7, 3, v7
	v_lshlrev_b32_e32 v6, 3, v6
	v_add3_u32 v10, 0, v7, v6
	ds_read2_b64 v[6:9], v10 offset1:1
	ds_read2_b64 v[10:13], v10 offset0:2 offset1:3
	v_lshlrev_b32_e32 v140, 8, v3
	v_ashrrev_i32_e32 v141, 31, v140
	v_lshl_add_u64 v[140:141], v[140:141], 3, v[4:5]
	v_add_u32_e32 v1, 0x200, v1
	s_waitcnt lgkmcnt(0)
	v_add_f32_e32 v14, v6, v10
	v_add_f32_e32 v15, v7, v11
	v_sub_f32_e32 v6, v6, v10
	v_sub_f32_e32 v7, v7, v11
	v_add_f32_e32 v10, v8, v12
	v_add_f32_e32 v11, v9, v13
	v_sub_f32_e32 v8, v8, v12
	v_sub_f32_e32 v9, v9, v13
	v_add_f32_e32 v12, v14, v10
	v_add_f32_e32 v13, v15, v11
	v_sub_f32_e32 v10, v14, v10
	v_sub_f32_e32 v11, v15, v11
	v_add_f32_e32 v12, v2, v12
	v_add_f32_e32 v14, v6, v9
	v_add_f32_e32 v15, v7, v8
	v_mul_f32_e64 v12, v12, s22
	v_mul_f32_e64 v13, v13, s22
	v_mov_b32_e32 v3, v7
	v_sub_f32_e32 v138, v6, v9
	v_sub_f32_e32 v139, v7, v8
	global_store_dwordx2 v[140:141], v[12:13], off
	v_add_f32_e32 v12, v2, v14
	v_add_f32_e32 v13, v3, v15
	v_sub_f32_e32 v6, v6, v8
	v_sub_f32_e32 v7, v7, v8
	v_add_f32_e32 v10, v2, v10
	v_mov_b32_e32 v13, v7
	v_mul_f32_e64 v6, v12, s22
	v_mul_f32_e64 v7, v13, s22
	global_store_dwordx2 v[140:141], v[6:7], off offset:2048
	v_mul_f32_e64 v6, v10, s22
	v_mul_f32_e64 v7, v11, s22
	v_add_co_u32_e32 v10, vcc, s96, v140
	v_mov_b32_e32 v139, v8
	s_nop 0
	v_addc_co_u32_e32 v11, vcc, 0, v141, vcc
	v_ashrrev_i32_e32 v1, 6, v1
	global_store_dwordx2 v[10:11], v[6:7], off
	v_add_f32_e32 v6, v2, v138
	v_add_f32_e32 v7, v3, v139
	v_and_b32_e32 v1, -4, v1
	v_mul_f32_e64 v6, v6, s22
	v_mul_f32_e64 v7, v7, s22
	v_add_u32_e32 v3, v1, v157
	global_store_dwordx2 v[10:11], v[6:7], off offset:2048
	v_ashrrev_i32_e32 v6, 6, v3
	v_lshlrev_b32_e32 v6, 3, v6
	v_lshlrev_b32_e32 v3, 3, v3
	v_add3_u32 v3, 0, v6, v3
	ds_read2_b64 v[6:9], v3 offset1:1
	ds_read2_b64 v[10:13], v3 offset0:2 offset1:3
	v_lshlrev_b32_e32 v140, 8, v1
	v_ashrrev_i32_e32 v141, 31, v140
	v_lshl_add_u64 v[140:141], v[140:141], 3, v[4:5]
	s_addk_i32 s4, 0x400
	s_waitcnt lgkmcnt(0)
	v_add_f32_e32 v14, v6, v10
	v_add_f32_e32 v15, v7, v11
	v_sub_f32_e32 v6, v6, v10
	v_sub_f32_e32 v7, v7, v11
	v_add_f32_e32 v10, v8, v12
	v_add_f32_e32 v11, v9, v13
	v_sub_f32_e32 v8, v8, v12
	v_sub_f32_e32 v9, v9, v13
	v_add_f32_e32 v12, v14, v10
	v_add_f32_e32 v13, v15, v11
	v_sub_f32_e32 v10, v14, v10
	v_sub_f32_e32 v11, v15, v11
	v_add_f32_e32 v12, v2, v12
	v_add_f32_e32 v14, v6, v9
	v_add_f32_e32 v15, v7, v8
	v_mul_f32_e64 v12, v12, s22
	v_mul_f32_e64 v13, v13, s22
	v_mov_b32_e32 v3, v7
	v_sub_f32_e32 v138, v6, v9
	v_sub_f32_e32 v139, v7, v8
	global_store_dwordx2 v[140:141], v[12:13], off
	v_add_f32_e32 v12, v2, v14
	v_add_f32_e32 v13, v3, v15
	v_sub_f32_e32 v6, v6, v8
	v_sub_f32_e32 v7, v7, v8
	v_add_f32_e32 v10, v2, v10
	v_mov_b32_e32 v13, v7
	v_mul_f32_e64 v6, v12, s22
	v_mul_f32_e64 v7, v13, s22
	global_store_dwordx2 v[140:141], v[6:7], off offset:2048
	v_mul_f32_e64 v6, v10, s22
	v_mul_f32_e64 v7, v11, s22
	v_add_co_u32_e32 v10, vcc, 0x1000, v140
	v_mov_b32_e32 v139, v8
	s_nop 0
	v_addc_co_u32_e32 v11, vcc, 0, v141, vcc
	global_store_dwordx2 v[10:11], v[6:7], off
	v_add_f32_e32 v6, v2, v138
	v_add_f32_e32 v7, v3, v139
	s_cmpk_lg_i32 s4, 0x1000
	v_mul_f32_e64 v6, v6, s22
	v_mul_f32_e64 v7, v7, s22
	global_store_dwordx2 v[10:11], v[6:7], off offset:2048
	s_cbranch_scc1 .LBB0_527
	s_mov_b32 s48, 1
	s_mov_b64 s[46:47], 0
	s_and_b64 vcc, exec, s[36:37]
	s_waitcnt lgkmcnt(0)
	s_barrier
	s_cbranch_vccz .LBB0_509
	v_mov_b32_e32 v1, v209
	v_lshl_add_u64 v[0:1], s[12:13], 0, v[0:1]
	s_mov_b32 s78, s81
	v_lshl_add_u64 v[142:143], v[0:1], 0, s[66:67]
	s_lshl_b64 s[48:49], s[14:15], 15
	v_mov_b32_e32 v132, v124
	v_mov_b32_e32 v138, v133
	v_mov_b32_e32 v139, v124
	v_mov_b32_e32 v140, v135
	v_mov_b32_e32 v141, v134
	v_mov_b32_e32 v131, v130
	v_mov_b32_e32 v144, v129
	v_mov_b32_e32 v145, v129
	v_mov_b32_e32 v127, v126
	v_mov_b32_e32 v146, v128
	v_mov_b32_e32 v147, v128
	v_mov_b32_e32 v148, v128
	v_mov_b32_e32 v149, v126
	s_mov_b32 s12, 0
	s_mov_b64 s[4:5], -1
	buffer_wbl2 sc1
	s_waitcnt vmcnt(0)
	buffer_inv sc1
	s_barrier
	s_branch .LBB0_531

; __device__ __forceinline__ float bf2f(bf16_t u) { return __uint_as_float((unsigned)u << 16); }
; __device__ __forceinline__ float bflo(unsigned w) { return __uint_as_float(w << 16); }
; __device__ __forceinline__ float bfhi(unsigned w) { return __uint_as_float(w & 0xffff0000u); }
; __device__ __forceinline__ void conv8(const bf16_t* p, int c, int n, float w0, float w1, float w2, float b, float (&o)[8]) {
;     const v4u v = *(const v4u*)(p + 8 * c);
;     const float um = c > 0 ? bf2f(p[8 * c - 1]) : 0.f, up = 8 * c + 8 < n ? bf2f(p[8 * c + 8]) : 0.f;
;     const float u0 = bflo(v.x), u1 = bfhi(v.x), u2 = bflo(v.y), u3 = bfhi(v.y), u4 = bflo(v.z), u5 = bfhi(v.z), u6 = bflo(v.w), u7 = bfhi(v.w);
;     o[0] = w0 * um + w1 * u0 + w2 * u1 + b; o[1] = w0 * u0 + w1 * u1 + w2 * u2 + b; o[2] = w0 * u1 + w1 * u2 + w2 * u3 + b; o[3] = w0 * u2 + w1 * u3 + w2 * u4 + b;
;     o[4] = w0 * u3 + w1 * u4 + w2 * u5 + b; o[5] = w0 * u4 + w1 * u5 + w2 * u6 + b; o[6] = w0 * u5 + w1 * u6 + w2 * u7 + b; o[7] = w0 * u6 + w1 * u7 + w2 * up + b;
; }
; __global__ void __launch_bounds__(NTHR, 2) fwd_mega(Args a) {
;     ...
;                     for (int k = 0; k < 2; ++k) { const int ch = 64 * (wave + 8 * k) + cw; float u0[8], u1[8];
;                         conv8(pv0, ch, 8192, wv0, wv1, wv2, bv, u0); conv8(pv1, ch, 8192, wv0, wv1, wv2, bv, u1);
; #pragma unroll
;                         for (int e = 0; e < 8; ++e) { X[PX(8 * ch + e)] = mk2(u0[e], u1[e]); X[PX(8192 + 8 * ch + e)] = mk2(0.f, 0.f); } }
.LBB0_532:
	s_or_b64 exec, exec, s[4:5]
	s_waitcnt vmcnt(0) lgkmcnt(0)
	v_and_b32_e32 v13, 0xffff0000, v4
	v_lshlrev_b32_e32 v12, 16, v4
	v_lshlrev_b32_e32 v150, 16, v5
	v_lshlrev_b32_e32 v151, 16, v6
	v_and_b32_e32 v153, 0xffff0000, v6
	v_mul_f32_e32 v4, v133, v15
	v_mul_f32_e32 v6, v125, v13
	v_and_b32_e32 v5, 0xffff0000, v5
	v_fmac_f32_e32 v4, v125, v12
	v_fmac_f32_e32 v6, v133, v12
	v_mul_f32_e32 v12, v125, v150
	v_fmac_f32_e32 v4, v124, v13
	v_fmac_f32_e32 v12, v133, v13
	v_mul_f32_e32 v13, v125, v5
	v_fmac_f32_e32 v13, v133, v150
	v_fmac_f32_e32 v13, v124, v151
	v_fmac_f32_e32 v6, v124, v150
	v_add_f32_e32 v150, v166, v13
	v_mul_f32_e32 v13, v125, v151
	v_fmac_f32_e32 v12, v124, v5
	v_fmac_f32_e32 v13, v133, v5
	v_mul_f32_e32 v5, v125, v153
	v_lshlrev_b32_e32 v171, 16, v7
	v_fmac_f32_e32 v5, v133, v151
	v_fmac_f32_e32 v5, v124, v171
	v_add_f32_e32 v170, v166, v5
	v_mul_f32_e32 v5, v125, v171
	v_and_b32_e32 v7, 0xffff0000, v7
	v_fmac_f32_e32 v5, v133, v153
	v_fmac_f32_e32 v5, v124, v7
	v_and_b32_e32 v176, 0xffff0000, v0
	v_lshlrev_b32_e32 v177, 16, v0
	v_add_f32_e32 v172, v166, v5
	v_mul_f32_e32 v5, v125, v7
	v_mul_f32_e32 v178, v124, v176
	v_mul_f32_e32 v179, v125, v177
	v_fmac_f32_e32 v5, v133, v171
	v_fma_f32 v0, v133, v9, v179
	v_fmac_f32_e32 v5, v124, v10
	v_add_f32_e32 v0, v178, v0
	v_add_f32_e32 v174, v166, v5
	v_add_f32_e32 v5, v166, v0
	v_and_b32_e32 v0, 0xffff0000, v1
	v_lshlrev_b32_e32 v1, 16, v1
	v_mov_b32_e32 v178, v1
	v_mov_b32_e32 v179, v177
	v_mul_f32_e32 v178, v132, v178
	v_mul_f32_e32 v179, v133, v179
	v_lshlrev_b32_e32 v177, 16, v2
	v_fma_f32 v7, v125, v176, v179
	v_add_f32_e32 v7, v178, v7
	v_mul_f32_e32 v178, v124, v0
	v_mul_f32_e32 v179, v125, v1
	v_fmac_f32_e32 v13, v124, v153
	v_fma_f32 v9, v133, v176, v179
	v_add_f32_e32 v9, v178, v9
	v_mov_b32_e32 v178, v177
	v_mov_b32_e32 v179, v1
	v_mul_f32_e32 v178, v132, v178
	v_mul_f32_e32 v179, v133, v179
	v_and_b32_e32 v176, 0xffff0000, v2
	v_fma_f32 v1, v125, v0, v179
	v_add_f32_e32 v1, v178, v1
	v_mul_f32_e32 v178, v124, v176
	v_mul_f32_e32 v179, v125, v177
	v_add_f32_e32 v151, v166, v1
	v_fma_f32 v0, v133, v0, v179
	v_add_f32_e32 v0, v178, v0
	v_lshlrev_b32_e32 v1, 16, v3
	v_add_f32_e32 v153, v166, v0
	v_and_b32_e32 v0, 0xffff0000, v3
	v_mov_b32_e32 v2, v1
	v_mov_b32_e32 v3, v177
	v_mul_f32_e32 v2, v132, v2
	v_mul_f32_e32 v3, v133, v3
	v_mov_b32_e32 v10, v1
	v_fma_f32 v3, v125, v176, v3
	v_add_f32_e32 v2, v2, v3
	v_add_f32_e32 v171, v166, v2
	v_mul_f32_e32 v2, v124, v0
	v_mul_f32_e32 v3, v125, v1
	v_lshlrev_b32_e32 v1, 3, v8
	v_fma_f32 v3, v133, v176, v3
	v_add_f32_e32 v2, v2, v3
	v_add_f32_e32 v173, v166, v2
	v_mul_f32_e32 v2, v138, v10
	v_mul_f32_e32 v3, v139, v11
	s_xor_b64 s[4:5], s[6:7], -1
	v_fma_f32 v0, v125, v0, v2
	v_add_f32_e32 v0, v0, v3
	v_add_f32_e32 v175, v166, v0
	v_and_b32_e32 v0, -8, v14
	v_add3_u32 v0, 0, v0, v1
	v_add_u32_e32 v1, 0x2000, v8
	v_ashrrev_i32_e32 v2, 6, v1
	v_lshlrev_b32_e32 v2, 3, v2
	v_lshlrev_b32_e32 v1, 3, v1
	s_mov_b32 s65, s64
	v_add_f32_e32 v4, v166, v4
	v_add3_u32 v1, 0, v2, v1
	v_mov_b64_e32 v[2:3], s[64:65]
	s_movk_i32 s10, 0x200
	s_mov_b64 s[6:7], 0
	s_and_b64 vcc, exec, s[4:5]
	v_add_f32_e32 v6, v166, v6
	v_add_f32_e32 v12, v166, v12
	v_add_f32_e32 v152, v166, v13
	v_add_f32_e32 v7, v166, v7
	v_add_f32_e32 v13, v166, v9
	ds_write_b64 v0, v[4:5]
	ds_write_b64 v1, v[2:3]
	ds_write_b64 v0, v[6:7] offset:8
	ds_write_b64 v1, v[2:3] offset:8
	ds_write_b64 v0, v[12:13] offset:16
	ds_write_b64 v1, v[2:3] offset:16
	ds_write_b64 v0, v[150:151] offset:24
	ds_write_b64 v1, v[2:3] offset:24
	ds_write_b64 v0, v[152:153] offset:32
	ds_write_b64 v1, v[2:3] offset:32
	ds_write_b64 v0, v[170:171] offset:40
	ds_write_b64 v1, v[2:3] offset:40
	ds_write_b64 v0, v[172:173] offset:48
	ds_write_b64 v1, v[2:3] offset:48
	ds_write_b64 v0, v[174:175] offset:56
	ds_write_b64 v1, v[2:3] offset:56
	s_cbranch_vccnz .LBB0_541

; __device__ __forceinline__ cf cmul(cf a, cf b) { return mk2(a.x * b.x - a.y * b.y, a.x * b.y + a.y * b.x); }
; __device__ __forceinline__ cf twid(float frac) { return mk2(__builtin_amdgcn_cosf(frac), -__builtin_amdgcn_sinf(frac)); }
; template <int LG, bool INV> __device__ __forceinline__ void fft_pass2(LAS cf* X, int tid) {
;     ...
;         const int it = tid + 512 * i; int g, j;
;         if (LG == 14) { g = 0; j = it; } else if (LG == 10) { j = it & 63; g = it >> 6; } else { g = it & 255; j = it >> 8; }
;         const int base = g * L + j;
;         const int pb = PX(base);
;     ...
;         cf e[4][4];
; #pragma unroll
;         for (int r = 0; r < 4; ++r)
; #pragma unroll
;             for (int m = 0; m < 4; ++m) e[r][m] = X[pb + POFF(r, m)];
;         const cf v1 = twid((float)(4 * j) * fL), v2 = cmul(v1, v1), v3 = cmul(v2, v1);
;         if (!INV) {
; #pragma unroll
;             for (int r = 0; r < 4; ++r) { bfly4_fwd(e[r][0], e[r][1], e[r][2], e[r][3]);
;                 const cf w1 = twid((float)(j + r * L16) * fL), w2 = cmul(w1, w1), w3 = cmul(w2, w1);
;                 e[r][1] = cmul(e[r][1], w1); e[r][2] = cmul(e[r][2], w2); e[r][3] = cmul(e[r][3], w3); }
; #pragma unroll
;             for (int p = 0; p < 4; ++p) { bfly4_fwd(e[0][p], e[1][p], e[2][p], e[3][p]); e[1][p] = cmul(e[1][p], v1); e[2][p] = cmul(e[2][p], v2); e[3][p] = cmul(e[3][p], v3); }
.LBB0_542:
	v_add_u32_e32 v185, s6, v16
	v_ashrrev_i32_e32 v0, 6, v185
	v_lshlrev_b32_e32 v0, 3, v0
	v_lshlrev_b32_e32 v1, 3, v185
	v_add3_u32 v202, 0, v0, v1
	v_add_u32_e32 v203, 0x10400, v202
	ds_read_b64 v[2:3], v202
	ds_read_b64 v[4:5], v202 offset:33280
	ds_read_b64 v[6:7], v203
	v_add_u32_e32 v204, 0x18600, v202
	ds_read_b64 v[8:9], v204
	ds_read_b64 v[10:11], v202 offset:8320
	ds_read_b64 v[12:13], v202 offset:41600
	v_add_u32_e32 v205, 0x12480, v202
	ds_read_b64 v[14:15], v205
	s_waitcnt lgkmcnt(4)
	v_add_f32_e32 v186, v2, v6
	v_add_f32_e32 v187, v3, v7
	v_sub_f32_e32 v2, v2, v6
	v_sub_f32_e32 v3, v3, v7
	s_waitcnt lgkmcnt(3)
	v_add_f32_e32 v6, v4, v8
	v_add_f32_e32 v7, v5, v9
	v_sub_f32_e32 v4, v4, v8
	v_sub_f32_e32 v5, v5, v9
	v_add_f32_e32 v8, v186, v6
	v_add_f32_e32 v9, v187, v7
	v_sub_f32_e32 v6, v186, v6
	v_sub_f32_e32 v7, v187, v7
	v_cvt_f32_i32_e32 v186, v185
	v_add_f32_e32 v190, v2, v5
	v_add_f32_e32 v191, v3, v4
	v_sub_f32_e32 v192, v2, v5
	v_sub_f32_e32 v193, v3, v4
	v_mov_b32_e32 v194, v190
	v_mul_f32_e32 v187, 0x38800000, v186
	v_sin_f32_e32 v188, v187
	v_cos_f32_e32 v186, v187
	v_mov_b32_e32 v195, v193
	v_pk_mov_b32 v[192:193], v[192:193], v[190:191] op_sel:[1,0]
	v_xor_b32_e32 v187, 0x80000000, v188
	v_mul_f32_e32 v192, v188, v192
	v_mul_f32_e32 v193, v188, v193
	v_fma_f32 v190, v186, v190, v192
	v_fma_f32 v191, v187, v191, v193
	v_fma_f32 v192, v186, v194, -v192
	v_fma_f32 v193, v186, v195, -v193
	v_mov_b32_e32 v191, v193
	v_mov_b32_e32 v189, v186
	v_mov_b32_e32 v192, v188
	v_mov_b32_e32 v193, v187
	v_mul_f32_e32 v192, v188, v192
	v_mul_f32_e32 v193, v189, v193
	v_add_u32_e32 v206, 0x1a680, v202
	v_fma_f32 v194, v186, v186, -v192
	v_fma_f32 v195, v186, v187, -v193
	v_fma_f32 v192, v186, v186, v192
	v_fma_f32 v193, v186, v187, v193
	v_mov_b32_e32 v197, v193
	v_pk_mov_b32 v[192:193], v[192:193], v[194:195] op_sel:[1,0]
	v_mov_b32_e32 v196, v194
	v_mul_f32_e32 v189, v188, v193
	v_mul_f32_e32 v188, v188, v192
	v_mul_f32_e32 v192, v192, v7
	v_mul_f32_e32 v193, v193, v7
	v_fma_f32 v198, v186, v196, v188
	v_fma_f32 v199, v186, v197, v189
	v_fma_f32 v187, v186, v197, -v189
	v_fma_f32 v186, v186, v196, -v188
	v_fma_f32 v194, v194, v6, -v192
	v_fma_f32 v195, v195, v7, -v193
	v_fma_f32 v7, v197, v6, v193
	v_fma_f32 v6, v196, v6, v192
	ds_read_b64 v[150:151], v206
	ds_read_b64 v[152:153], v202 offset:16640
	ds_read_b64 v[170:171], v202 offset:49920
	v_mov_b32_e32 v195, v7
	v_sub_f32_e32 v6, v2, v5
	v_sub_f32_e32 v7, v2, v5
	v_add_f32_e32 v2, v3, v4
	v_add_f32_e32 v3, v3, v4
	v_pk_mov_b32 v[4:5], v[186:187], v[198:199] op_sel:[1,0]
	v_mov_b32_e32 v188, v198
	v_mov_b32_e32 v189, v187
	v_mul_f32_e32 v2, v2, v4
	v_mul_f32_e32 v3, v3, v5
	v_add_u32_e32 v207, 0x14500, v202
	v_fma_f32 v4, v6, v198, -v2
	v_fma_f32 v5, v7, v199, -v3
	v_fma_f32 v2, v6, v188, v2
	v_fma_f32 v3, v7, v189, v3
	s_waitcnt lgkmcnt(3)
	v_sub_f32_e32 v6, v10, v14
	v_sub_f32_e32 v7, v11, v15
	v_mov_b32_e32 v5, v3
	v_add_f32_e32 v2, v10, v14
	v_add_f32_e32 v3, v11, v15
	s_waitcnt lgkmcnt(2)
	v_add_f32_e32 v10, v12, v150
	v_add_f32_e32 v11, v13, v151
	v_sub_f32_e32 v12, v12, v150
	v_sub_f32_e32 v13, v13, v151
	v_add_f32_e32 v14, v2, v10
	v_add_f32_e32 v15, v3, v11
	v_sub_f32_e32 v2, v2, v10
	v_sub_f32_e32 v3, v3, v11
	v_add_u32_e32 v10, 0x400, v185
	v_cvt_f32_i32_e32 v10, v10
	v_add_f32_e32 v196, v6, v13
	v_add_f32_e32 v197, v7, v12
	v_sub_f32_e32 v6, v6, v13
	v_sub_f32_e32 v7, v7, v12
	v_mov_b32_e32 v12, v196
	v_mul_f32_e32 v11, 0x38800000, v10
	v_cos_f32_e32 v10, v11
	v_sin_f32_e32 v11, v11
	v_pk_mov_b32 v[200:201], v[6:7], v[196:197] op_sel:[1,0]
	v_mov_b32_e32 v13, v7
	v_mov_b32_e32 v151, v10
	v_xor_b32_e32 v150, 0x80000000, v11
	v_mov_b32_e32 v186, v150
	v_mov_b32_e32 v187, v11
	v_mul_f32_e32 v186, v10, v186
	v_mul_f32_e32 v187, v11, v187
	v_mov_b32_e32 v198, v11
	v_fma_f32 v188, v10, v150, v186
	v_fma_f32 v189, v10, v151, v187
	v_fma_f32 v150, v10, v150, -v186
	v_fma_f32 v151, v10, v151, -v187
	v_mov_b32_e32 v186, v188
	v_mov_b32_e32 v187, v151
	v_mov_b32_e32 v192, v11
	v_mov_b32_e32 v193, v10
	v_mul_f32_e32 v199, v198, v201
	v_mul_f32_e32 v198, v198, v200
	ds_read_b64 v[172:173], v207
	v_mul_f32_e32 v192, v192, v186
	v_mul_f32_e32 v193, v193, v187
	v_mul_f32_e32 v186, v10, v186
	v_mul_f32_e32 v187, v11, v187
	v_fma_f32 v200, v10, v196, v198
	v_fma_f32 v201, v11, v197, v199
	v_fma_f32 v11, v10, v13, -v199
	v_fma_f32 v10, v10, v12, -v198
	v_add_u32_e32 v208, 0x1c700, v202
	v_mov_b32_e32 v201, v11
	v_mul_f32_e32 v10, v188, v3
	v_mul_f32_e32 v11, v188, v2
	ds_read_b64 v[174:175], v208
	ds_read_b64 v[176:177], v202 offset:24960
	ds_read_b64 v[178:179], v202 offset:58240
	v_fma_f32 v12, v151, v2, -v10
	v_fma_f32 v13, v151, v3, -v11
	v_fma_f32 v2, v151, v2, v10
	v_fma_f32 v3, v151, v3, v11
	v_sub_f32_e32 v10, v186, v187
	v_sub_f32_e32 v11, v186, v187
	v_pk_mov_b32 v[150:151], v[196:197], v[6:7] op_sel:[1,0]
	v_mov_b32_e32 v13, v3
	v_mov_b32_e32 v2, v6
	v_mov_b32_e32 v3, v197
	v_mul_f32_e32 v10, v10, v150
	v_mul_f32_e32 v11, v11, v151
	v_add_f32_e32 v150, v193, v192
	v_add_f32_e32 v151, v193, v192
	v_add_u32_e32 v210, 0x16580, v202
	v_fma_f32 v6, v150, v6, -v10
	v_fma_f32 v7, v151, v7, -v11
	v_fma_f32 v2, v150, v2, v10
	v_fma_f32 v3, v151, v3, v11
	s_waitcnt lgkmcnt(2)
; __device__ __forceinline__ cf cmul(cf a, cf b) { return mk2(a.x * b.x - a.y * b.y, a.x * b.y + a.y * b.x); }
; __device__ __forceinline__ cf twid(float frac) { return mk2(__builtin_amdgcn_cosf(frac), -__builtin_amdgcn_sinf(frac)); }
; template <int LG, bool INV> __device__ __forceinline__ void fft_pass2(LAS cf* X, int tid) {
;     ...
;         const cf v1 = twid((float)(4 * j) * fL), v2 = cmul(v1, v1), v3 = cmul(v2, v1);
;         if (!INV) {
; #pragma unroll
;             for (int r = 0; r < 4; ++r) { bfly4_fwd(e[r][0], e[r][1], e[r][2], e[r][3]);
;                 const cf w1 = twid((float)(j + r * L16) * fL), w2 = cmul(w1, w1), w3 = cmul(w2, w1);
;                 e[r][1] = cmul(e[r][1], w1); e[r][2] = cmul(e[r][2], w2); e[r][3] = cmul(e[r][3], w3); }
; #pragma unroll
;             for (int p = 0; p < 4; ++p) { bfly4_fwd(e[0][p], e[1][p], e[2][p], e[3][p]); e[1][p] = cmul(e[1][p], v1); e[2][p] = cmul(e[2][p], v2); e[3][p] = cmul(e[3][p], v3); }
	v_add_f32_e32 v150, v170, v174
	v_add_f32_e32 v151, v171, v175
	v_mov_b32_e32 v7, v3
	v_add_f32_e32 v2, v152, v172
	v_add_f32_e32 v3, v153, v173
	v_sub_f32_e32 v10, v152, v172
	v_sub_f32_e32 v11, v153, v173
	v_sub_f32_e32 v152, v170, v174
	v_sub_f32_e32 v153, v171, v175
	v_add_f32_e32 v170, v2, v150
	v_add_f32_e32 v171, v3, v151
	v_sub_f32_e32 v2, v2, v150
	v_sub_f32_e32 v3, v3, v151
	v_add_u32_e32 v150, 0x800, v185
	v_cvt_f32_i32_e32 v150, v150
	v_add_f32_e32 v192, v10, v153
	v_add_f32_e32 v193, v11, v152
	v_sub_f32_e32 v10, v10, v153
	v_sub_f32_e32 v11, v11, v152
	v_add_u32_e32 v211, 0x1e780, v202
	v_mul_f32_e32 v151, 0x38800000, v150
	v_cos_f32_e32 v150, v151
	v_sin_f32_e32 v151, v151
	v_pk_mov_b32 v[198:199], v[10:11], v[192:193] op_sel:[1,0]
	v_mov_b32_e32 v152, v192
	v_mov_b32_e32 v173, v150
	v_xor_b32_e32 v172, 0x80000000, v151
	v_mov_b32_e32 v174, v172
	v_mov_b32_e32 v175, v151
	v_mul_f32_e32 v174, v150, v174
	v_mul_f32_e32 v175, v151, v175
	v_mov_b32_e32 v196, v151
	v_fma_f32 v186, v150, v172, v174
	v_fma_f32 v187, v150, v173, v175
	v_fma_f32 v172, v150, v172, -v174
	v_fma_f32 v173, v150, v173, -v175
	v_mov_b32_e32 v174, v186
	v_mov_b32_e32 v175, v173
	v_mov_b32_e32 v188, v151
	v_mov_b32_e32 v189, v150
	v_mov_b32_e32 v153, v11
	v_mul_f32_e32 v197, v196, v199
	v_mul_f32_e32 v196, v196, v198
	ds_read_b64 v[180:181], v210
	ds_read_b64 v[182:183], v211
	v_mul_f32_e32 v188, v188, v174
	v_mul_f32_e32 v189, v189, v175
	v_mul_f32_e32 v174, v150, v174
	v_mul_f32_e32 v175, v151, v175
	v_fma_f32 v198, v150, v192, v196
	v_fma_f32 v199, v151, v193, v197
	v_fma_f32 v151, v150, v153, -v197
	v_fma_f32 v150, v150, v152, -v196
	v_mov_b32_e32 v199, v151
	v_mul_f32_e32 v150, v186, v3
	v_mul_f32_e32 v151, v186, v2
	v_fma_f32 v152, v173, v2, -v150
	v_fma_f32 v153, v173, v3, -v151
	v_fma_f32 v2, v173, v2, v150
	v_fma_f32 v3, v173, v3, v151
	v_sub_f32_e32 v150, v174, v175
	v_sub_f32_e32 v151, v174, v175
	v_pk_mov_b32 v[172:173], v[192:193], v[10:11] op_sel:[1,0]
	v_mov_b32_e32 v153, v3
	v_mov_b32_e32 v2, v10
	v_mov_b32_e32 v3, v193
	v_mul_f32_e32 v150, v150, v172
	v_mul_f32_e32 v151, v151, v173
	v_add_f32_e32 v172, v189, v188
	v_add_f32_e32 v173, v189, v188
	v_lshlrev_b32_e32 v0, 2, v185
	v_fma_f32 v10, v172, v10, -v150
	v_fma_f32 v11, v173, v11, -v151
	v_fma_f32 v2, v172, v2, v150
	v_fma_f32 v3, v173, v3, v151
	s_waitcnt lgkmcnt(0)
	v_add_f32_e32 v172, v178, v182
	v_add_f32_e32 v173, v179, v183
	v_mov_b32_e32 v11, v3
	v_add_f32_e32 v2, v176, v180
	v_add_f32_e32 v3, v177, v181
	v_sub_f32_e32 v150, v176, v180
	v_sub_f32_e32 v151, v177, v181
	v_add_f32_e32 v176, v2, v172
	v_add_f32_e32 v177, v3, v173
	v_sub_f32_e32 v2, v2, v172
	v_sub_f32_e32 v3, v3, v173
	v_add_u32_e32 v172, 0xc00, v185
	v_cvt_f32_i32_e32 v172, v172
	v_cvt_f32_i32_e32 v0, v0
	v_sub_f32_e32 v174, v178, v182
	v_sub_f32_e32 v175, v179, v183
	s_movk_i32 s6, 0x200
	v_mul_f32_e32 v173, 0x38800000, v172
	v_cos_f32_e32 v172, v173
	v_sin_f32_e32 v173, v173
	v_add_f32_e32 v188, v150, v175
	v_add_f32_e32 v189, v151, v174
	v_sub_f32_e32 v150, v150, v175
	v_sub_f32_e32 v151, v151, v174
	v_mov_b32_e32 v179, v172
	v_xor_b32_e32 v178, 0x80000000, v173
	v_mov_b32_e32 v180, v178
	v_mov_b32_e32 v181, v173
	v_mul_f32_e32 v180, v172, v180
	v_mul_f32_e32 v181, v173, v181
	v_mov_b32_e32 v192, v173
	v_fma_f32 v182, v172, v178, v180
	v_fma_f32 v183, v172, v179, v181
	v_fma_f32 v178, v172, v178, -v180
	v_fma_f32 v179, v172, v179, -v181
	v_pk_mov_b32 v[196:197], v[150:151], v[188:189] op_sel:[1,0]
	v_mul_f32_e32 v1, 0x38800000, v0
	v_mov_b32_e32 v180, v182
	v_mov_b32_e32 v181, v179
	v_mov_b32_e32 v186, v173
	v_mov_b32_e32 v187, v172
	v_mov_b32_e32 v174, v188
	v_mov_b32_e32 v175, v151
	v_mul_f32_e32 v193, v192, v197
	v_mul_f32_e32 v192, v192, v196
	v_cos_f32_e32 v0, v1
	v_sin_f32_e32 v1, v1
	v_mul_f32_e32 v186, v186, v180
	v_mul_f32_e32 v187, v187, v181
	v_mul_f32_e32 v180, v172, v180
	v_mul_f32_e32 v181, v173, v181
	v_fma_f32 v196, v172, v188, v192
	v_fma_f32 v197, v173, v189, v193
	v_fma_f32 v173, v172, v175, -v193
	v_fma_f32 v172, v172, v174, -v192
	v_mov_b32_e32 v197, v173
	v_mul_f32_e32 v172, v182, v3
	v_mul_f32_e32 v173, v182, v2
	v_fma_f32 v174, v179, v2, -v172
	v_fma_f32 v175, v179, v3, -v173
	v_fma_f32 v2, v179, v2, v172
	v_fma_f32 v3, v179, v3, v173
	v_sub_f32_e32 v172, v180, v181
	v_sub_f32_e32 v173, v180, v181
	v_pk_mov_b32 v[178:179], v[188:189], v[150:151] op_sel:[1,0]
	v_mov_b32_e32 v175, v3
	v_mov_b32_e32 v2, v150
	v_mov_b32_e32 v3, v189
	v_mul_f32_e32 v172, v172, v178
	v_mul_f32_e32 v173, v173, v179
	v_add_f32_e32 v178, v187, v186
	v_add_f32_e32 v179, v187, v186
	v_xor_b32_e32 v184, 0x80000000, v1
	v_fma_f32 v150, v178, v150, -v172
	v_fma_f32 v151, v179, v151, -v173
	v_fma_f32 v2, v178, v2, v172
	v_fma_f32 v3, v179, v3, v173
	v_add_f32_e32 v182, v8, v170
	v_add_f32_e32 v183, v9, v171
	v_mov_b32_e32 v151, v3
	v_mov_b32_e32 v2, v184
	v_mov_b32_e32 v3, v1
	v_sub_f32_e32 v8, v8, v170
	v_sub_f32_e32 v9, v9, v171
	v_add_f32_e32 v170, v14, v176
	v_add_f32_e32 v171, v15, v177
	v_sub_f32_e32 v14, v14, v176
	v_sub_f32_e32 v15, v15, v177
	v_mov_b32_e32 v185, v0
	v_mul_f32_e32 v2, v0, v2
	v_mul_f32_e32 v3, v1, v3
	v_add_f32_e32 v176, v182, v170
	v_add_f32_e32 v177, v183, v171
	v_sub_f32_e32 v170, v182, v170
	v_sub_f32_e32 v171, v183, v171
	v_add_f32_e32 v182, v8, v15
	v_add_f32_e32 v183, v9, v14
	v_sub_f32_e32 v8, v8, v15
	v_sub_f32_e32 v9, v9, v14
	v_fma_f32 v172, v0, v184, v2
	v_fma_f32 v173, v0, v185, v3
	v_fma_f32 v2, v0, v184, -v2
	v_fma_f32 v3, v0, v185, -v3
	v_mov_b32_e32 v184, v1
	v_pk_mov_b32 v[186:187], v[8:9], v[182:183] op_sel:[1,0]
	v_mov_b32_e32 v14, v182
	v_mov_b32_e32 v15, v9
; __device__ __forceinline__ cf cmul(cf a, cf b) { return mk2(a.x * b.x - a.y * b.y, a.x * b.y + a.y * b.x); }
; __device__ __forceinline__ cf cmulc(cf a, cf b) { return mk2(a.x * b.x + a.y * b.y, a.y * b.x - a.x * b.y); }
; __device__ __forceinline__ cf twid(float frac) { return mk2(__builtin_amdgcn_cosf(frac), -__builtin_amdgcn_sinf(frac)); }
; template <int LG, bool INV> __device__ __forceinline__ void fft_pass2(LAS cf* X, int tid) {
;     ...
;                 const cf w1 = twid((float)(j + r * L16) * fL), w2 = cmul(w1, w1), w3 = cmul(w2, w1);
;                 e[r][1] = cmul(e[r][1], w1); e[r][2] = cmul(e[r][2], w2); e[r][3] = cmul(e[r][3], w3); }
; #pragma unroll
;             for (int p = 0; p < 4; ++p) { bfly4_fwd(e[0][p], e[1][p], e[2][p], e[3][p]); e[1][p] = cmul(e[1][p], v1); e[2][p] = cmul(e[2][p], v2); e[3][p] = cmul(e[3][p], v3); }
;         } else {
; #pragma unroll
;             for (int p = 0; p < 4; ++p) { e[1][p] = cmulc(e[1][p], v1); e[2][p] = cmulc(e[2][p], v2); e[3][p] = cmulc(e[3][p], v3); bfly4_inv(e[0][p], e[1][p], e[2][p], e[3][p]); }
; #pragma unroll
;             for (int r = 0; r < 4; ++r) { const cf w1 = twid((float)(j + r * L16) * fL), w2 = cmul(w1, w1), w3 = cmul(w2, w1);
;                 e[r][1] = cmulc(e[r][1], w1); e[r][2] = cmulc(e[r][2], w2); e[r][3] = cmulc(e[r][3], w3); bfly4_inv(e[r][0], e[r][1], e[r][2], e[r][3]); }
;         }
; #pragma unroll
;         for (int r = 0; r < 4; ++r)
; #pragma unroll
;             for (int m = 0; m < 4; ++m) X[pb + POFF(r, m)] = e[r][m];
	v_mul_f32_e32 v186, v184, v186
	v_mul_f32_e32 v187, v184, v187
	v_mov_b32_e32 v178, v172
	v_mov_b32_e32 v179, v3
	v_mov_b32_e32 v180, v1
	v_mov_b32_e32 v181, v0
	v_fma_f32 v188, v0, v182, v186
	v_fma_f32 v189, v1, v183, v187
	v_fma_f32 v14, v0, v14, -v186
	v_fma_f32 v15, v0, v15, -v187
	v_mul_f32_e32 v180, v180, v178
	v_mul_f32_e32 v181, v181, v179
	v_mul_f32_e32 v178, v0, v178
	v_mul_f32_e32 v179, v1, v179
	v_mov_b32_e32 v189, v15
	v_mul_f32_e32 v14, v172, v170
	v_mul_f32_e32 v15, v172, v171
	v_fma_f32 v186, v3, v170, -v15
	v_fma_f32 v187, v3, v171, -v14
	v_pk_fma_f32 v[14:15], v[2:3], v[170:171], v[14:15] op_sel:[1,0,1] op_sel_hi:[1,1,0]
	v_sub_f32_e32 v170, v178, v179
	v_sub_f32_e32 v171, v178, v179
	v_pk_mov_b32 v[178:179], v[182:183], v[8:9] op_sel:[1,0]
	v_mov_b32_e32 v187, v15
	v_mov_b32_e32 v14, v8
	v_mov_b32_e32 v15, v183
	v_mul_f32_e32 v178, v170, v178
	v_mul_f32_e32 v179, v171, v179
	v_pk_add_f32 v[180:181], v[180:181], v[180:181] op_sel:[1,0] op_sel_hi:[1,0]
	v_add_f32_e32 v182, v200, v196
	v_add_f32_e32 v183, v201, v197
	v_fma_f32 v8, v180, v8, -v178
	v_fma_f32 v9, v181, v9, -v179
	v_fma_f32 v14, v180, v14, v178
	v_fma_f32 v15, v181, v15, v179
	v_sub_f32_e32 v178, v190, v198
	v_sub_f32_e32 v179, v191, v199
	v_mov_b32_e32 v9, v15
	v_add_f32_e32 v14, v190, v198
	v_add_f32_e32 v15, v191, v199
	v_sub_f32_e32 v190, v200, v196
	v_sub_f32_e32 v191, v201, v197
	v_add_f32_e32 v192, v14, v182
	v_add_f32_e32 v193, v15, v183
	v_sub_f32_e32 v14, v14, v182
	v_sub_f32_e32 v15, v15, v183
	v_add_f32_e32 v182, v178, v191
	v_add_f32_e32 v183, v179, v190
	v_sub_f32_e32 v178, v178, v191
	v_sub_f32_e32 v179, v179, v190
	v_mov_b32_e32 v190, v182
	v_pk_mov_b32 v[196:197], v[178:179], v[182:183] op_sel:[1,0]
	v_mov_b32_e32 v191, v179
	v_mul_f32_e32 v196, v184, v196
	v_mul_f32_e32 v197, v184, v197
	v_fma_f32 v198, v0, v182, v196
	v_fma_f32 v199, v1, v183, v197
	v_fma_f32 v190, v0, v190, -v196
	v_fma_f32 v191, v0, v191, -v197
	v_mov_b32_e32 v199, v191
	v_mul_f32_e32 v190, v172, v14
	v_mul_f32_e32 v191, v172, v15
	v_fma_f32 v196, v3, v14, -v191
	v_fma_f32 v197, v3, v15, -v190
	v_fma_f32 v14, v3, v14, v191
	v_fma_f32 v15, v3, v15, v190
	s_and_b64 vcc, exec, s[4:5]
	v_mov_b32_e32 v197, v15
	v_mov_b32_e32 v15, v183
	v_pk_mov_b32 v[182:183], v[182:183], v[178:179] op_sel:[1,0]
	v_mov_b32_e32 v14, v178
	v_mul_f32_e32 v182, v170, v182
	v_mul_f32_e32 v183, v171, v183
	s_mov_b64 s[4:5], 0
	v_fma_f32 v178, v180, v178, -v182
	v_fma_f32 v179, v181, v179, -v183
	v_fma_f32 v14, v180, v14, v182
	v_fma_f32 v15, v181, v15, v183
	v_add_f32_e32 v182, v12, v174
	v_add_f32_e32 v183, v13, v175
	v_mov_b32_e32 v179, v15
	v_add_f32_e32 v14, v194, v152
	v_add_f32_e32 v15, v195, v153
	v_sub_f32_e32 v152, v194, v152
	v_sub_f32_e32 v153, v195, v153
	v_sub_f32_e32 v12, v12, v174
	v_sub_f32_e32 v13, v13, v175
	v_add_f32_e32 v174, v14, v182
	v_add_f32_e32 v175, v15, v183
	v_sub_f32_e32 v14, v14, v182
	v_sub_f32_e32 v15, v15, v183
	v_add_f32_e32 v182, v152, v13
	v_add_f32_e32 v183, v153, v12
	v_pk_add_f32 v[12:13], v[152:153], v[12:13] op_sel:[0,1] op_sel_hi:[1,0] neg_lo:[0,1] neg_hi:[0,1]
	v_mov_b32_e32 v152, v182
	v_pk_mov_b32 v[190:191], v[12:13], v[182:183] op_sel:[1,0]
	v_mov_b32_e32 v153, v13
	v_mul_f32_e32 v190, v184, v190
	v_mul_f32_e32 v191, v184, v191
	v_fma_f32 v194, v0, v182, v190
	v_fma_f32 v195, v1, v183, v191
	v_fma_f32 v152, v0, v152, -v190
	v_fma_f32 v153, v0, v153, -v191
	v_mov_b32_e32 v195, v153
	v_mul_f32_e32 v152, v172, v14
	v_mul_f32_e32 v153, v172, v15
	v_fma_f32 v190, v3, v14, -v153
	v_fma_f32 v191, v3, v15, -v152
	v_fma_f32 v14, v3, v14, v153
	v_fma_f32 v15, v3, v15, v152
	v_pk_mov_b32 v[152:153], v[182:183], v[12:13] op_sel:[1,0]
	v_mov_b32_e32 v191, v15
	v_mov_b32_e32 v14, v12
	v_mov_b32_e32 v15, v183
	v_mul_f32_e32 v152, v170, v152
	v_mul_f32_e32 v153, v171, v153
	s_nop 0
	v_fma_f32 v12, v180, v12, -v152
	v_fma_f32 v13, v181, v13, -v153
	v_fma_f32 v14, v180, v14, v152
	v_fma_f32 v15, v181, v15, v153
	s_nop 0
	v_mov_b32_e32 v13, v15
	v_add_f32_e32 v14, v4, v10
	v_add_f32_e32 v15, v5, v11
	v_sub_f32_e32 v4, v4, v10
	v_sub_f32_e32 v5, v5, v11
	v_add_f32_e32 v10, v6, v150
	v_add_f32_e32 v11, v7, v151
	v_sub_f32_e32 v6, v6, v150
	v_sub_f32_e32 v7, v7, v151
	v_add_f32_e32 v150, v14, v10
	v_add_f32_e32 v151, v15, v11
	v_sub_f32_e32 v10, v14, v10
	v_sub_f32_e32 v11, v15, v11
	v_add_f32_e32 v14, v4, v7
	v_add_f32_e32 v15, v5, v6
	v_sub_f32_e32 v4, v4, v7
	v_sub_f32_e32 v5, v5, v6
	v_mov_b32_e32 v6, v14
	v_pk_mov_b32 v[152:153], v[4:5], v[14:15] op_sel:[1,0]
	v_mov_b32_e32 v7, v5
	v_mul_f32_e32 v152, v184, v152
	v_mul_f32_e32 v153, v184, v153
	v_fma_f32 v182, v0, v14, v152
	v_fma_f32 v183, v1, v15, v153
	v_fma_f32 v1, v0, v7, -v153
	v_fma_f32 v0, v0, v6, -v152
	v_mov_b32_e32 v183, v1
	v_mul_f32_e32 v0, v172, v10
	v_mul_f32_e32 v1, v172, v11
	v_fma_f32 v6, v3, v10, -v1
	v_fma_f32 v7, v3, v11, -v0
	v_pk_fma_f32 v[0:1], v[2:3], v[10:11], v[0:1] op_sel:[1,0,1] op_sel_hi:[1,1,0]
	v_pk_mov_b32 v[2:3], v[14:15], v[4:5] op_sel:[1,0]
	v_mov_b32_e32 v7, v1
	v_mov_b32_e32 v0, v4
	v_mov_b32_e32 v1, v15
	v_mul_f32_e32 v2, v170, v2
	v_mul_f32_e32 v3, v171, v3
	s_nop 0
	v_fma_f32 v4, v180, v4, -v2
	v_fma_f32 v5, v181, v5, -v3
	v_fma_f32 v0, v180, v0, v2
	v_fma_f32 v1, v181, v1, v3
	s_nop 0
	v_mov_b32_e32 v5, v1
	ds_write_b64 v202, v[176:177]
	ds_write_b64 v202, v[192:193] offset:33280
	ds_write_b64 v203, v[174:175]
	ds_write_b64 v204, v[150:151]
	ds_write_b64 v202, v[188:189] offset:8320
	ds_write_b64 v202, v[198:199] offset:41600
	ds_write_b64 v205, v[194:195]
	ds_write_b64 v206, v[182:183]
	ds_write_b64 v202, v[186:187] offset:16640
	ds_write_b64 v202, v[196:197] offset:49920
	ds_write_b64 v207, v[190:191]
	ds_write_b64 v208, v[6:7]
	ds_write_b64 v202, v[8:9] offset:24960
	ds_write_b64 v202, v[178:179] offset:58240
	ds_write_b64 v210, v[12:13]
	ds_write_b64 v211, v[4:5]
	s_cbranch_vccnz .LBB0_542
	s_mov_b32 s6, 0
	s_mov_b64 s[4:5], -1
	s_waitcnt lgkmcnt(0)
	s_barrier
; __device__ __forceinline__ cf cmul(cf a, cf b) { return mk2(a.x * b.x - a.y * b.y, a.x * b.y + a.y * b.x); }
; __device__ __forceinline__ cf twid(float frac) { return mk2(__builtin_amdgcn_cosf(frac), -__builtin_amdgcn_sinf(frac)); }
; template <int LG, bool INV> __device__ __forceinline__ void fft_pass2(LAS cf* X, int tid) {
;     ...
;         const int it = tid + 512 * i; int g, j;
;         if (LG == 14) { g = 0; j = it; } else if (LG == 10) { j = it & 63; g = it >> 6; } else { g = it & 255; j = it >> 8; }
;         const int base = g * L + j;
;         const int pb = PX(base);
;     ...
;         cf e[4][4];
; #pragma unroll
;         for (int r = 0; r < 4; ++r)
; #pragma unroll
;             for (int m = 0; m < 4; ++m) e[r][m] = X[pb + POFF(r, m)];
;         const cf v1 = twid((float)(4 * j) * fL), v2 = cmul(v1, v1), v3 = cmul(v2, v1);
;         if (!INV) {
; #pragma unroll
;             for (int r = 0; r < 4; ++r) { bfly4_fwd(e[r][0], e[r][1], e[r][2], e[r][3]);
;                 const cf w1 = twid((float)(j + r * L16) * fL), w2 = cmul(w1, w1), w3 = cmul(w2, w1);
;                 e[r][1] = cmul(e[r][1], w1); e[r][2] = cmul(e[r][2], w2); e[r][3] = cmul(e[r][3], w3); }
; #pragma unroll
;             for (int p = 0; p < 4; ++p) { bfly4_fwd(e[0][p], e[1][p], e[2][p], e[3][p]); e[1][p] = cmul(e[1][p], v1); e[2][p] = cmul(e[2][p], v2); e[3][p] = cmul(e[3][p], v3); }
.LBB0_544:
	v_add_u32_e32 v0, s6, v155
	v_and_b32_e32 v0, 0xfffffc00, v0
	v_ashrrev_i32_e32 v1, 3, v0
	v_add_u32_e32 v1, 0, v1
	v_lshlrev_b32_e32 v0, 3, v0
	v_add3_u32 v188, v1, v0, v169
	v_add_u32_e32 v189, 0x800, v188
	v_add_u32_e32 v190, 0x1000, v188
	ds_read2_b64 v[0:3], v188 offset1:65
	ds_read2_b64 v[4:7], v189 offset0:4 offset1:69
	ds_read2_b64 v[8:11], v190 offset0:8 offset1:73
	v_add_u32_e32 v191, 0x1800, v188
	ds_read2_b64 v[12:15], v191 offset0:12 offset1:77
	ds_read2_b64 v[150:153], v188 offset0:130 offset1:195
	ds_read2_b64 v[170:173], v189 offset0:134 offset1:199
	ds_read2_b64 v[174:177], v190 offset0:138 offset1:203
	ds_read2_b64 v[178:181], v191 offset0:142 offset1:207
	s_movk_i32 s6, 0x2000
	s_and_b64 vcc, exec, s[4:5]
	s_waitcnt lgkmcnt(5)
	v_add_f32_e32 v182, v0, v8
	v_add_f32_e32 v183, v1, v9
	v_sub_f32_e32 v0, v0, v8
	v_sub_f32_e32 v1, v1, v9
	s_waitcnt lgkmcnt(4)
	v_add_f32_e32 v8, v4, v12
	v_add_f32_e32 v9, v5, v13
	v_sub_f32_e32 v4, v4, v12
	v_sub_f32_e32 v5, v5, v13
	v_add_f32_e32 v12, v182, v8
	v_add_f32_e32 v13, v183, v9
	v_sub_f32_e32 v8, v182, v8
	v_sub_f32_e32 v9, v183, v9
	v_add_f32_e32 v182, v0, v5
	v_add_f32_e32 v183, v1, v4
	v_sub_f32_e32 v184, v0, v5
	v_sub_f32_e32 v185, v1, v4
	v_mov_b32_e32 v186, v182
	v_mov_b32_e32 v187, v185
	v_pk_mov_b32 v[184:185], v[184:185], v[182:183] op_sel:[1,0]
	s_mov_b64 s[4:5], 0
	v_mul_f32_e32 v184, v34, v184
	v_mul_f32_e32 v185, v35, v185
	s_nop 0
	v_fma_f32 v182, v36, v182, v184
	v_fma_f32 v183, v37, v183, v185
	v_fma_f32 v184, v36, v186, -v184
	v_fma_f32 v185, v37, v187, -v185
	s_nop 0
	v_mov_b32_e32 v183, v185
	v_mul_f32_e32 v184, v46, v9
	v_mul_f32_e32 v185, v47, v9
	s_nop 0
	v_fma_f32 v186, v44, v8, -v184
	v_fma_f32 v187, v45, v9, -v185
	v_fma_f32 v9, v45, v8, v185
	v_fma_f32 v8, v44, v8, v184
	s_nop 0
	v_mov_b32_e32 v187, v9
	v_sub_f32_e32 v8, v0, v5
	v_sub_f32_e32 v9, v0, v5
	v_add_f32_e32 v0, v1, v4
	v_add_f32_e32 v1, v1, v4
	s_nop 0
	v_mul_f32_e32 v0, v110, v0
	v_mul_f32_e32 v1, v111, v1
	s_nop 0
	v_fma_f32 v4, v56, v8, -v0
	v_fma_f32 v5, v57, v9, -v1
	v_fma_f32 v0, v56, v8, v0
	v_fma_f32 v1, v57, v9, v1
	v_add_f32_e32 v8, v6, v14
	v_add_f32_e32 v9, v7, v15
	v_mov_b32_e32 v5, v1
	v_add_f32_e32 v0, v2, v10
	v_add_f32_e32 v1, v3, v11
	v_sub_f32_e32 v2, v2, v10
	v_sub_f32_e32 v3, v3, v11
	v_sub_f32_e32 v6, v6, v14
	v_sub_f32_e32 v7, v7, v15
	v_add_f32_e32 v10, v0, v8
	v_add_f32_e32 v11, v1, v9
	v_sub_f32_e32 v0, v0, v8
	v_sub_f32_e32 v1, v1, v9
	v_add_f32_e32 v8, v2, v7
	v_add_f32_e32 v9, v3, v6
	v_sub_f32_e32 v14, v2, v7
	v_sub_f32_e32 v15, v3, v6
	v_mov_b32_e32 v184, v8
	v_mov_b32_e32 v185, v15
	v_pk_mov_b32 v[14:15], v[14:15], v[8:9] op_sel:[1,0]
	s_nop 0
	v_mul_f32_e32 v14, v52, v14
	v_mul_f32_e32 v15, v53, v15
	s_nop 0
	v_fma_f32 v8, v54, v8, v14
	v_fma_f32 v9, v55, v9, v15
	v_fma_f32 v14, v54, v184, -v14
	v_fma_f32 v15, v55, v185, -v15
	s_nop 0
	v_mov_b32_e32 v9, v15
	v_mul_f32_e32 v14, v64, v1
	v_mul_f32_e32 v15, v65, v1
	s_nop 0
	v_fma_f32 v184, v62, v0, -v14
	v_fma_f32 v185, v63, v1, -v15
	v_fma_f32 v1, v63, v0, v15
	v_fma_f32 v0, v62, v0, v14
	s_waitcnt lgkmcnt(0)
	v_add_f32_e32 v14, v170, v178
	v_add_f32_e32 v15, v171, v179
	v_mov_b32_e32 v185, v1
	v_sub_f32_e32 v0, v2, v7
	v_sub_f32_e32 v1, v2, v7
	v_add_f32_e32 v2, v3, v6
	v_add_f32_e32 v3, v3, v6
	s_nop 0
	v_mul_f32_e32 v2, v112, v2
	v_mul_f32_e32 v3, v113, v3
	s_nop 0
	v_fma_f32 v6, v74, v0, -v2
	v_fma_f32 v7, v75, v1, -v3
	v_fma_f32 v0, v74, v0, v2
	v_fma_f32 v1, v75, v1, v3
	v_sub_f32_e32 v2, v150, v174
	v_sub_f32_e32 v3, v151, v175
	v_mov_b32_e32 v7, v1
	v_add_f32_e32 v0, v150, v174
	v_add_f32_e32 v1, v151, v175
	v_sub_f32_e32 v150, v170, v178
	v_sub_f32_e32 v151, v171, v179
	v_add_f32_e32 v170, v0, v14
	v_add_f32_e32 v171, v1, v15
	v_sub_f32_e32 v0, v0, v14
	v_sub_f32_e32 v1, v1, v15
	v_add_f32_e32 v14, v2, v151
	v_add_f32_e32 v15, v3, v150
	v_sub_f32_e32 v174, v2, v151
	v_sub_f32_e32 v175, v3, v150
	v_mov_b32_e32 v178, v14
	v_mov_b32_e32 v179, v175
	v_pk_mov_b32 v[174:175], v[174:175], v[14:15] op_sel:[1,0]
	s_nop 0
	v_mul_f32_e32 v174, v70, v174
	v_mul_f32_e32 v175, v71, v175
	s_nop 0
	v_fma_f32 v14, v72, v14, v174
	v_fma_f32 v15, v73, v15, v175
	v_fma_f32 v174, v72, v178, -v174
	v_fma_f32 v175, v73, v179, -v175
	s_nop 0
	v_mov_b32_e32 v15, v175
	v_mul_f32_e32 v174, v82, v1
	v_mul_f32_e32 v175, v83, v1
	s_nop 0
	v_fma_f32 v178, v80, v0, -v174
	v_fma_f32 v179, v81, v1, -v175
	v_fma_f32 v1, v81, v0, v175
	v_fma_f32 v0, v80, v0, v174
	s_nop 0
	v_mov_b32_e32 v179, v1
	v_sub_f32_e32 v0, v2, v151
	v_sub_f32_e32 v1, v2, v151
	v_add_f32_e32 v2, v3, v150
	v_add_f32_e32 v3, v3, v150
	s_nop 0
	v_mul_f32_e32 v2, v114, v2
	v_mul_f32_e32 v3, v115, v3
	s_nop 0
	v_fma_f32 v150, v92, v0, -v2
	v_fma_f32 v151, v93, v1, -v3
	v_fma_f32 v0, v92, v0, v2
	v_fma_f32 v1, v93, v1, v3
	v_sub_f32_e32 v2, v152, v176
	v_sub_f32_e32 v3, v153, v177
	v_mov_b32_e32 v151, v1
	v_add_f32_e32 v0, v152, v176
	v_add_f32_e32 v1, v153, v177
	v_add_f32_e32 v152, v172, v180
	v_add_f32_e32 v153, v173, v181
	v_sub_f32_e32 v172, v172, v180
	v_sub_f32_e32 v173, v173, v181
	v_add_f32_e32 v174, v0, v152
	v_add_f32_e32 v175, v1, v153
	v_sub_f32_e32 v0, v0, v152
	v_sub_f32_e32 v1, v1, v153
	v_add_f32_e32 v152, v2, v173
	v_add_f32_e32 v153, v3, v172
	v_sub_f32_e32 v176, v2, v173
	v_sub_f32_e32 v177, v3, v172
	v_mov_b32_e32 v180, v152
	v_mov_b32_e32 v181, v177
	v_pk_mov_b32 v[176:177], v[176:177], v[152:153] op_sel:[1,0]
	s_nop 0
	v_mul_f32_e32 v176, v88, v176
	v_mul_f32_e32 v177, v89, v177
	s_nop 0
	v_fma_f32 v152, v90, v152, v176
	v_fma_f32 v153, v91, v153, v177
	v_fma_f32 v176, v90, v180, -v176
	v_fma_f32 v177, v91, v181, -v177
	s_nop 0
; __device__ __forceinline__ cf cmul(cf a, cf b) { return mk2(a.x * b.x - a.y * b.y, a.x * b.y + a.y * b.x); }
; __device__ __forceinline__ cf cmulc(cf a, cf b) { return mk2(a.x * b.x + a.y * b.y, a.y * b.x - a.x * b.y); }
; __device__ __forceinline__ cf twid(float frac) { return mk2(__builtin_amdgcn_cosf(frac), -__builtin_amdgcn_sinf(frac)); }
; template <int LG, bool INV> __device__ __forceinline__ void fft_pass2(LAS cf* X, int tid) {
;     ...
;                 e[r][1] = cmul(e[r][1], w1); e[r][2] = cmul(e[r][2], w2); e[r][3] = cmul(e[r][3], w3); }
; #pragma unroll
;             for (int p = 0; p < 4; ++p) { bfly4_fwd(e[0][p], e[1][p], e[2][p], e[3][p]); e[1][p] = cmul(e[1][p], v1); e[2][p] = cmul(e[2][p], v2); e[3][p] = cmul(e[3][p], v3); }
;         } else {
; #pragma unroll
;             for (int p = 0; p < 4; ++p) { e[1][p] = cmulc(e[1][p], v1); e[2][p] = cmulc(e[2][p], v2); e[3][p] = cmulc(e[3][p], v3); bfly4_inv(e[0][p], e[1][p], e[2][p], e[3][p]); }
; #pragma unroll
;             for (int r = 0; r < 4; ++r) { const cf w1 = twid((float)(j + r * L16) * fL), w2 = cmul(w1, w1), w3 = cmul(w2, w1);
;                 e[r][1] = cmulc(e[r][1], w1); e[r][2] = cmulc(e[r][2], w2); e[r][3] = cmulc(e[r][3], w3); bfly4_inv(e[r][0], e[r][1], e[r][2], e[r][3]); }
;         }
; #pragma unroll
;         for (int r = 0; r < 4; ++r)
; #pragma unroll
;             for (int m = 0; m < 4; ++m) X[pb + POFF(r, m)] = e[r][m];
	v_mov_b32_e32 v153, v177
	v_mul_f32_e32 v176, v100, v1
	v_mul_f32_e32 v177, v101, v1
	s_nop 0
	v_fma_f32 v180, v98, v0, -v176
	v_fma_f32 v181, v99, v1, -v177
	v_fma_f32 v1, v99, v0, v177
	v_fma_f32 v0, v98, v0, v176
	s_nop 0
	v_mov_b32_e32 v181, v1
	v_sub_f32_e32 v0, v2, v173
	v_sub_f32_e32 v1, v2, v173
	v_add_f32_e32 v2, v3, v172
	v_add_f32_e32 v3, v3, v172
	s_nop 0
	v_mul_f32_e32 v2, v116, v2
	v_mul_f32_e32 v3, v117, v3
	s_nop 0
	v_fma_f32 v172, v106, v0, -v2
	v_fma_f32 v173, v107, v1, -v3
	v_fma_f32 v0, v106, v0, v2
	v_fma_f32 v1, v107, v1, v3
	v_sub_f32_e32 v2, v12, v170
	v_sub_f32_e32 v3, v13, v171
	v_mov_b32_e32 v173, v1
	v_add_f32_e32 v0, v12, v170
	v_add_f32_e32 v1, v13, v171
	v_add_f32_e32 v12, v10, v174
	v_add_f32_e32 v13, v11, v175
	v_sub_f32_e32 v10, v10, v174
	v_sub_f32_e32 v11, v11, v175
	v_add_f32_e32 v170, v0, v12
	v_add_f32_e32 v171, v1, v13
	v_sub_f32_e32 v0, v0, v12
	v_sub_f32_e32 v1, v1, v13
	v_add_f32_e32 v12, v2, v11
	v_add_f32_e32 v13, v3, v10
	v_sub_f32_e32 v174, v2, v11
	v_sub_f32_e32 v175, v3, v10
	v_mov_b32_e32 v176, v12
	v_mov_b32_e32 v177, v175
	v_pk_mov_b32 v[174:175], v[174:175], v[12:13] op_sel:[1,0]
	s_nop 0
	v_mul_f32_e32 v174, v18, v174
	v_mul_f32_e32 v175, v19, v175
	s_nop 0
	v_fma_f32 v12, v20, v12, v174
	v_fma_f32 v13, v21, v13, v175
	v_fma_f32 v174, v20, v176, -v174
	v_fma_f32 v175, v21, v177, -v175
	s_nop 0
	v_mov_b32_e32 v13, v175
	v_mul_f32_e32 v174, v28, v1
	v_mul_f32_e32 v175, v29, v1
	s_nop 0
	v_fma_f32 v176, v26, v0, -v174
	v_fma_f32 v177, v27, v1, -v175
	v_fma_f32 v1, v27, v0, v175
	v_fma_f32 v0, v26, v0, v174
	s_nop 0
	v_mov_b32_e32 v177, v1
	v_sub_f32_e32 v0, v2, v11
	v_sub_f32_e32 v1, v2, v11
	v_add_f32_e32 v2, v3, v10
	v_add_f32_e32 v3, v3, v10
	s_nop 0
	v_mul_f32_e32 v2, v118, v2
	v_mul_f32_e32 v3, v119, v3
	s_nop 0
	v_fma_f32 v10, v38, v0, -v2
	v_fma_f32 v11, v39, v1, -v3
	v_fma_f32 v0, v38, v0, v2
	v_fma_f32 v1, v39, v1, v3
	v_sub_f32_e32 v2, v182, v14
	v_sub_f32_e32 v3, v183, v15
	v_mov_b32_e32 v11, v1
	v_add_f32_e32 v0, v182, v14
	v_add_f32_e32 v1, v183, v15
	v_add_f32_e32 v14, v8, v152
	v_add_f32_e32 v15, v9, v153
	v_sub_f32_e32 v8, v8, v152
	v_sub_f32_e32 v9, v9, v153
	v_add_f32_e32 v152, v0, v14
	v_add_f32_e32 v153, v1, v15
	v_sub_f32_e32 v0, v0, v14
	v_sub_f32_e32 v1, v1, v15
	v_add_f32_e32 v14, v2, v9
	v_add_f32_e32 v15, v3, v8
	v_sub_f32_e32 v174, v2, v9
	v_sub_f32_e32 v175, v3, v8
	v_mov_b32_e32 v182, v14
	v_mov_b32_e32 v183, v175
	v_pk_mov_b32 v[174:175], v[174:175], v[14:15] op_sel:[1,0]
	s_nop 0
	v_mul_f32_e32 v174, v18, v174
	v_mul_f32_e32 v175, v19, v175
	s_nop 0
	v_fma_f32 v14, v20, v14, v174
	v_fma_f32 v15, v21, v15, v175
	v_fma_f32 v174, v20, v182, -v174
	v_fma_f32 v175, v21, v183, -v175
	s_nop 0
	v_mov_b32_e32 v15, v175
	v_mul_f32_e32 v174, v28, v1
	v_mul_f32_e32 v175, v29, v1
	s_nop 0
	v_fma_f32 v182, v26, v0, -v174
	v_fma_f32 v183, v27, v1, -v175
	v_fma_f32 v1, v27, v0, v175
	v_fma_f32 v0, v26, v0, v174
	v_add_f32_e32 v174, v184, v180
	v_add_f32_e32 v175, v185, v181
	v_mov_b32_e32 v183, v1
	v_sub_f32_e32 v0, v2, v9
	v_sub_f32_e32 v1, v2, v9
	v_add_f32_e32 v2, v3, v8
	v_add_f32_e32 v3, v3, v8
	s_nop 0
	v_mul_f32_e32 v2, v118, v2
	v_mul_f32_e32 v3, v119, v3
	s_nop 0
	v_fma_f32 v8, v38, v0, -v2
	v_fma_f32 v9, v39, v1, -v3
	v_fma_f32 v0, v38, v0, v2
	v_fma_f32 v1, v39, v1, v3
	v_sub_f32_e32 v2, v186, v178
	v_sub_f32_e32 v3, v187, v179
	v_mov_b32_e32 v9, v1
	v_add_f32_e32 v0, v186, v178
	v_add_f32_e32 v1, v187, v179
	v_sub_f32_e32 v178, v184, v180
	v_sub_f32_e32 v179, v185, v181
	v_add_f32_e32 v180, v0, v174
	v_add_f32_e32 v181, v1, v175
	v_sub_f32_e32 v0, v0, v174
	v_sub_f32_e32 v1, v1, v175
	v_add_f32_e32 v174, v2, v179
	v_add_f32_e32 v175, v3, v178
	v_sub_f32_e32 v184, v2, v179
	v_sub_f32_e32 v185, v3, v178
	v_mov_b32_e32 v186, v174
	v_mov_b32_e32 v187, v185
	v_pk_mov_b32 v[184:185], v[184:185], v[174:175] op_sel:[1,0]
	s_nop 0
	v_mul_f32_e32 v184, v18, v184
	v_mul_f32_e32 v185, v19, v185
	s_nop 0
	v_fma_f32 v174, v20, v174, v184
	v_fma_f32 v175, v21, v175, v185
	v_fma_f32 v184, v20, v186, -v184
	v_fma_f32 v185, v21, v187, -v185
	s_nop 0
	v_mov_b32_e32 v175, v185
	v_mul_f32_e32 v184, v28, v1
	v_mul_f32_e32 v185, v29, v1
	s_nop 0
	v_fma_f32 v186, v26, v0, -v184
	v_fma_f32 v187, v27, v1, -v185
	v_fma_f32 v1, v27, v0, v185
	v_fma_f32 v0, v26, v0, v184
	s_nop 0
	v_mov_b32_e32 v187, v1
	v_sub_f32_e32 v0, v2, v179
	v_sub_f32_e32 v1, v2, v179
	v_add_f32_e32 v2, v3, v178
	v_add_f32_e32 v3, v3, v178
	s_nop 0
	v_mul_f32_e32 v2, v118, v2
	v_mul_f32_e32 v3, v119, v3
	s_nop 0
	v_fma_f32 v178, v38, v0, -v2
	v_fma_f32 v179, v39, v1, -v3
	v_fma_f32 v0, v38, v0, v2
	v_fma_f32 v1, v39, v1, v3
	v_sub_f32_e32 v2, v4, v150
	v_sub_f32_e32 v3, v5, v151
	v_mov_b32_e32 v179, v1
	v_add_f32_e32 v0, v4, v150
	v_add_f32_e32 v1, v5, v151
	v_add_f32_e32 v4, v6, v172
	v_add_f32_e32 v5, v7, v173
	v_sub_f32_e32 v6, v6, v172
	v_sub_f32_e32 v7, v7, v173
	v_add_f32_e32 v150, v0, v4
	v_add_f32_e32 v151, v1, v5
	v_sub_f32_e32 v0, v0, v4
	v_sub_f32_e32 v1, v1, v5
	v_add_f32_e32 v4, v2, v7
	v_add_f32_e32 v5, v3, v6
	v_sub_f32_e32 v172, v2, v7
	v_sub_f32_e32 v173, v3, v6
	v_mov_b32_e32 v184, v4
	v_mov_b32_e32 v185, v173
	v_pk_mov_b32 v[172:173], v[172:173], v[4:5] op_sel:[1,0]
	s_nop 0
	v_mul_f32_e32 v172, v18, v172
	v_mul_f32_e32 v173, v19, v173
	s_nop 0
	v_fma_f32 v4, v20, v4, v172
	v_fma_f32 v5, v21, v5, v173
	v_fma_f32 v172, v20, v184, -v172
	v_fma_f32 v173, v21, v185, -v173
	s_nop 0
	v_mov_b32_e32 v5, v173
	v_mul_f32_e32 v172, v28, v1
	v_mul_f32_e32 v173, v29, v1
	s_nop 0
	v_fma_f32 v184, v26, v0, -v172
	v_fma_f32 v185, v27, v1, -v173
	v_fma_f32 v1, v27, v0, v173
	v_fma_f32 v0, v26, v0, v172
	s_nop 0
	v_mov_b32_e32 v185, v1
	v_sub_f32_e32 v0, v2, v7
	v_sub_f32_e32 v1, v2, v7
	v_add_f32_e32 v2, v3, v6
	v_add_f32_e32 v3, v3, v6
	s_nop 0
	v_mul_f32_e32 v2, v118, v2
	v_mul_f32_e32 v3, v119, v3
	s_nop 0
	v_fma_f32 v6, v38, v0, -v2
	v_fma_f32 v7, v39, v1, -v3
	v_fma_f32 v0, v38, v0, v2
	v_fma_f32 v1, v39, v1, v3
	s_nop 0
	v_mov_b32_e32 v7, v1
	ds_write2_b64 v188, v[170:171], v[12:13] offset1:65
	ds_write2_b64 v189, v[152:153], v[14:15] offset0:4 offset1:69
	ds_write2_b64 v190, v[180:181], v[174:175] offset0:8 offset1:73
	ds_write2_b64 v191, v[150:151], v[4:5] offset0:12 offset1:77
	ds_write2_b64 v188, v[176:177], v[10:11] offset0:130 offset1:195
	ds_write2_b64 v189, v[182:183], v[8:9] offset0:134 offset1:199
	ds_write2_b64 v190, v[186:187], v[178:179] offset0:138 offset1:203
	ds_write2_b64 v191, v[184:185], v[6:7] offset0:142 offset1:207
	s_cbranch_vccnz .LBB0_544
	s_mov_b32 s6, 0
	s_mov_b64 s[4:5], -1
	s_waitcnt lgkmcnt(0)
	s_barrier
; __device__ __forceinline__ cf cmul(cf a, cf b) { return mk2(a.x * b.x - a.y * b.y, a.x * b.y + a.y * b.x); }
; __device__ __forceinline__ cf twid(float frac) { return mk2(__builtin_amdgcn_cosf(frac), -__builtin_amdgcn_sinf(frac)); }
; template <int LG, bool INV> __device__ __forceinline__ void fft_pass2(LAS cf* X, int tid) {
;     ...
;         const int it = tid + 512 * i; int g, j;
;         if (LG == 14) { g = 0; j = it; } else if (LG == 10) { j = it & 63; g = it >> 6; } else { g = it & 255; j = it >> 8; }
;         const int base = g * L + j;
;         const int pb = PX(base);
;     ...
;         cf e[4][4];
; #pragma unroll
;         for (int r = 0; r < 4; ++r)
; #pragma unroll
;             for (int m = 0; m < 4; ++m) e[r][m] = X[pb + POFF(r, m)];
;         const cf v1 = twid((float)(4 * j) * fL), v2 = cmul(v1, v1), v3 = cmul(v2, v1);
;         if (!INV) {
; #pragma unroll
;             for (int r = 0; r < 4; ++r) { bfly4_fwd(e[r][0], e[r][1], e[r][2], e[r][3]);
;                 const cf w1 = twid((float)(j + r * L16) * fL), w2 = cmul(w1, w1), w3 = cmul(w2, w1);
;                 e[r][1] = cmul(e[r][1], w1); e[r][2] = cmul(e[r][2], w2); e[r][3] = cmul(e[r][3], w3); }
; #pragma unroll
;             for (int p = 0; p < 4; ++p) { bfly4_fwd(e[0][p], e[1][p], e[2][p], e[3][p]); e[1][p] = cmul(e[1][p], v1); e[2][p] = cmul(e[2][p], v2); e[3][p] = cmul(e[3][p], v3); }
.LBB0_546:
	v_add_u32_e32 v0, s6, v16
	v_ashrrev_i32_e32 v15, 8, v0
	v_add_u32_e32 v0, v15, v156
	v_ashrrev_i32_e32 v1, 6, v0
	v_lshlrev_b32_e32 v1, 3, v1
	v_lshlrev_b32_e32 v0, 3, v0
	v_add3_u32 v202, 0, v1, v0
	ds_read2_b64 v[2:5], v202 offset0:16 offset1:20
	ds_read2_b64 v[6:9], v202 offset0:32 offset1:36
	ds_read2_b64 v[10:13], v202 offset0:48 offset1:52
	ds_read2_b64 v[150:153], v202 offset1:4
	ds_read2_b64 v[170:173], v202 offset0:8 offset1:12
	ds_read2_b64 v[174:177], v202 offset0:24 offset1:28
	ds_read2_b64 v[178:181], v202 offset0:40 offset1:44
	ds_read2_b64 v[182:185], v202 offset0:56 offset1:60
	s_waitcnt lgkmcnt(4)
	v_add_f32_e32 v186, v150, v6
	v_add_f32_e32 v187, v151, v7
	v_sub_f32_e32 v6, v150, v6
	v_sub_f32_e32 v7, v151, v7
	v_add_f32_e32 v150, v2, v10
	v_add_f32_e32 v151, v3, v11
	v_sub_f32_e32 v2, v2, v10
	v_sub_f32_e32 v3, v3, v11
	v_add_f32_e32 v10, v186, v150
	v_add_f32_e32 v11, v187, v151
	v_sub_f32_e32 v150, v186, v150
	v_sub_f32_e32 v151, v187, v151
	v_cvt_f32_i32_e32 v186, v15
	v_add_f32_e32 v190, v6, v3
	v_add_f32_e32 v191, v7, v2
	v_sub_f32_e32 v192, v6, v3
	v_sub_f32_e32 v193, v7, v2
	v_mov_b32_e32 v194, v190
	v_mul_f32_e32 v187, 0x3c800000, v186
	v_sin_f32_e32 v188, v187
	v_cos_f32_e32 v186, v187
	v_mov_b32_e32 v195, v193
	v_pk_mov_b32 v[192:193], v[192:193], v[190:191] op_sel:[1,0]
	v_xor_b32_e32 v187, 0x80000000, v188
	v_mul_f32_e32 v192, v188, v192
	v_mul_f32_e32 v193, v188, v193
	v_fma_f32 v190, v186, v190, v192
	v_fma_f32 v191, v187, v191, v193
	v_fma_f32 v192, v186, v194, -v192
	v_fma_f32 v193, v186, v195, -v193
	v_mov_b32_e32 v191, v193
	v_mov_b32_e32 v189, v186
	v_mov_b32_e32 v192, v188
	v_mov_b32_e32 v193, v187
	v_mul_f32_e32 v192, v188, v192
	v_mul_f32_e32 v193, v189, v193
	v_lshlrev_b32_e32 v0, 2, v15
	v_fma_f32 v194, v186, v186, -v192
	v_fma_f32 v195, v186, v187, -v193
	v_fma_f32 v192, v186, v186, v192
	v_fma_f32 v193, v186, v187, v193
	v_mov_b32_e32 v197, v193
	v_pk_mov_b32 v[192:193], v[192:193], v[194:195] op_sel:[1,0]
	v_mov_b32_e32 v196, v194
	v_mul_f32_e32 v189, v188, v193
	v_mul_f32_e32 v188, v188, v192
	v_mul_f32_e32 v192, v192, v151
	v_mul_f32_e32 v193, v193, v151
	v_fma_f32 v198, v186, v196, v188
	v_fma_f32 v199, v186, v197, v189
	v_fma_f32 v187, v186, v197, -v189
	v_fma_f32 v186, v186, v196, -v188
	v_fma_f32 v194, v194, v150, -v192
	v_fma_f32 v195, v195, v151, -v193
	v_fma_f32 v151, v197, v150, v193
	v_fma_f32 v150, v196, v150, v192
	v_mov_b32_e32 v188, v198
	v_mov_b32_e32 v195, v151
	v_sub_f32_e32 v150, v6, v3
	v_sub_f32_e32 v151, v6, v3
	v_add_f32_e32 v3, v7, v2
	v_add_f32_e32 v2, v7, v2
	v_pk_mov_b32 v[6:7], v[186:187], v[198:199] op_sel:[1,0]
	v_mov_b32_e32 v189, v187
	v_mul_f32_e32 v2, v2, v6
	v_mul_f32_e32 v3, v3, v7
	v_cvt_f32_i32_e32 v0, v0
	v_fma_f32 v6, v150, v198, -v2
	v_fma_f32 v7, v151, v199, -v3
	v_fma_f32 v2, v150, v188, v2
	v_fma_f32 v3, v151, v189, v3
	v_add_f32_e32 v150, v4, v12
	v_add_f32_e32 v151, v5, v13
	v_mov_b32_e32 v7, v3
	v_add_f32_e32 v2, v152, v8
	v_add_f32_e32 v3, v153, v9
	v_sub_f32_e32 v4, v4, v12
	v_sub_f32_e32 v5, v5, v13
	v_add_f32_e32 v12, v2, v150
	v_add_f32_e32 v13, v3, v151
	v_sub_f32_e32 v2, v2, v150
	v_sub_f32_e32 v3, v3, v151
	v_add_u32_e32 v150, 4, v15
	v_cvt_f32_i32_e32 v150, v150
	v_sub_f32_e32 v8, v152, v8
	v_sub_f32_e32 v9, v153, v9
	v_mul_f32_e32 v1, 0x3c800000, v0
	v_add_f32_e32 v196, v8, v5
	v_add_f32_e32 v197, v9, v4
	v_mul_f32_e32 v151, 0x3c800000, v150
	v_cos_f32_e32 v150, v151
	v_sin_f32_e32 v151, v151
	v_pk_add_f32 v[4:5], v[8:9], v[4:5] op_sel:[0,1] op_sel_hi:[1,0] neg_lo:[0,1] neg_hi:[0,1]
	v_mov_b32_e32 v8, v196
	v_mov_b32_e32 v153, v150
	v_xor_b32_e32 v152, 0x80000000, v151
	v_mov_b32_e32 v186, v152
	v_mov_b32_e32 v187, v151
	v_mul_f32_e32 v186, v150, v186
	v_mul_f32_e32 v187, v151, v187
	v_mov_b32_e32 v198, v151
	v_pk_mov_b32 v[200:201], v[4:5], v[196:197] op_sel:[1,0]
	v_fma_f32 v188, v150, v152, v186
	v_fma_f32 v189, v150, v153, v187
	v_fma_f32 v152, v150, v152, -v186
	v_fma_f32 v153, v150, v153, -v187
	v_mov_b32_e32 v9, v5
	v_mul_f32_e32 v199, v198, v201
	v_mul_f32_e32 v198, v198, v200
	v_mov_b32_e32 v186, v188
	v_mov_b32_e32 v187, v153
	v_mov_b32_e32 v192, v151
	v_mov_b32_e32 v193, v150
	v_fma_f32 v200, v150, v196, v198
	v_fma_f32 v201, v151, v197, v199
	v_fma_f32 v8, v150, v8, -v198
	v_fma_f32 v9, v150, v9, -v199
	v_mul_f32_e32 v192, v192, v186
	v_mul_f32_e32 v193, v193, v187
	v_mul_f32_e32 v186, v150, v186
	v_mul_f32_e32 v187, v151, v187
	v_mov_b32_e32 v201, v9
	v_mul_f32_e32 v8, v188, v3
	v_mul_f32_e32 v9, v188, v2
	v_fma_f32 v150, v153, v2, -v8
	v_fma_f32 v151, v153, v3, -v9
	v_fma_f32 v2, v153, v2, v8
	v_fma_f32 v3, v153, v3, v9
	v_sub_f32_e32 v8, v186, v187
	v_sub_f32_e32 v9, v186, v187
	v_pk_mov_b32 v[152:153], v[196:197], v[4:5] op_sel:[1,0]
	v_mov_b32_e32 v151, v3
	v_mov_b32_e32 v2, v4
	v_mov_b32_e32 v3, v197
	v_mul_f32_e32 v8, v8, v152
	v_mul_f32_e32 v9, v9, v153
	v_add_f32_e32 v152, v193, v192
	v_add_f32_e32 v153, v193, v192
	v_cos_f32_e32 v0, v1
	v_fma_f32 v4, v152, v4, -v8
	v_fma_f32 v5, v153, v5, -v9
	v_fma_f32 v2, v152, v2, v8
	v_fma_f32 v3, v153, v3, v9
	s_waitcnt lgkmcnt(0)
; __device__ __forceinline__ cf cmul(cf a, cf b) { return mk2(a.x * b.x - a.y * b.y, a.x * b.y + a.y * b.x); }
; __device__ __forceinline__ cf twid(float frac) { return mk2(__builtin_amdgcn_cosf(frac), -__builtin_amdgcn_sinf(frac)); }
; template <int LG, bool INV> __device__ __forceinline__ void fft_pass2(LAS cf* X, int tid) {
;     ...
;         const cf v1 = twid((float)(4 * j) * fL), v2 = cmul(v1, v1), v3 = cmul(v2, v1);
;         if (!INV) {
; #pragma unroll
;             for (int r = 0; r < 4; ++r) { bfly4_fwd(e[r][0], e[r][1], e[r][2], e[r][3]);
;                 const cf w1 = twid((float)(j + r * L16) * fL), w2 = cmul(w1, w1), w3 = cmul(w2, w1);
;                 e[r][1] = cmul(e[r][1], w1); e[r][2] = cmul(e[r][2], w2); e[r][3] = cmul(e[r][3], w3); }
; #pragma unroll
;             for (int p = 0; p < 4; ++p) { bfly4_fwd(e[0][p], e[1][p], e[2][p], e[3][p]); e[1][p] = cmul(e[1][p], v1); e[2][p] = cmul(e[2][p], v2); e[3][p] = cmul(e[3][p], v3); }
	v_add_f32_e32 v152, v174, v182
	v_add_f32_e32 v153, v175, v183
	v_mov_b32_e32 v5, v3
	v_add_f32_e32 v2, v170, v178
	v_add_f32_e32 v3, v171, v179
	v_sub_f32_e32 v8, v170, v178
	v_sub_f32_e32 v9, v171, v179
	v_sub_f32_e32 v170, v174, v182
	v_sub_f32_e32 v171, v175, v183
	v_add_f32_e32 v174, v2, v152
	v_add_f32_e32 v175, v3, v153
	v_sub_f32_e32 v2, v2, v152
	v_sub_f32_e32 v3, v3, v153
	v_add_u32_e32 v152, 8, v15
	v_cvt_f32_i32_e32 v152, v152
	v_add_f32_e32 v192, v8, v171
	v_add_f32_e32 v193, v9, v170
	v_sub_f32_e32 v8, v8, v171
	v_sub_f32_e32 v9, v9, v170
	v_mov_b32_e32 v170, v192
	v_mul_f32_e32 v153, 0x3c800000, v152
	v_cos_f32_e32 v152, v153
	v_sin_f32_e32 v153, v153
	v_pk_mov_b32 v[198:199], v[8:9], v[192:193] op_sel:[1,0]
	v_mov_b32_e32 v171, v9
	v_mov_b32_e32 v179, v152
	v_xor_b32_e32 v178, 0x80000000, v153
	v_mov_b32_e32 v182, v178
	v_mov_b32_e32 v183, v153
	v_mul_f32_e32 v182, v152, v182
	v_mul_f32_e32 v183, v153, v183
	v_mov_b32_e32 v196, v153
	v_fma_f32 v186, v152, v178, v182
	v_fma_f32 v187, v152, v179, v183
	v_fma_f32 v178, v152, v178, -v182
	v_fma_f32 v179, v152, v179, -v183
	v_mov_b32_e32 v182, v186
	v_mov_b32_e32 v183, v179
	v_mov_b32_e32 v188, v153
	v_mov_b32_e32 v189, v152
	v_mul_f32_e32 v197, v196, v199
	v_mul_f32_e32 v196, v196, v198
	v_mul_f32_e32 v188, v188, v182
	v_mul_f32_e32 v189, v189, v183
	v_mul_f32_e32 v182, v152, v182
	v_mul_f32_e32 v183, v153, v183
	v_fma_f32 v198, v152, v192, v196
	v_fma_f32 v199, v153, v193, v197
	v_fma_f32 v153, v152, v171, -v197
	v_fma_f32 v152, v152, v170, -v196
	v_add_u32_e32 v15, 12, v15
	v_mov_b32_e32 v199, v153
	v_mul_f32_e32 v152, v186, v3
	v_mul_f32_e32 v153, v186, v2
	v_cvt_f32_i32_e32 v15, v15
	v_fma_f32 v170, v179, v2, -v152
	v_fma_f32 v171, v179, v3, -v153
	v_fma_f32 v2, v179, v2, v152
	v_fma_f32 v3, v179, v3, v153
	v_sub_f32_e32 v152, v182, v183
	v_sub_f32_e32 v153, v182, v183
	v_pk_mov_b32 v[178:179], v[192:193], v[8:9] op_sel:[1,0]
	v_mov_b32_e32 v171, v3
	v_mov_b32_e32 v2, v8
	v_mov_b32_e32 v3, v193
	v_mul_f32_e32 v152, v152, v178
	v_mul_f32_e32 v153, v153, v179
	v_add_f32_e32 v178, v189, v188
	v_add_f32_e32 v179, v189, v188
	v_mul_f32_e32 v15, 0x3c800000, v15
	v_fma_f32 v8, v178, v8, -v152
	v_fma_f32 v9, v179, v9, -v153
	v_fma_f32 v2, v178, v2, v152
	v_fma_f32 v3, v179, v3, v153
	v_sub_f32_e32 v152, v172, v180
	v_sub_f32_e32 v153, v173, v181
	v_mov_b32_e32 v9, v3
	v_add_f32_e32 v2, v172, v180
	v_add_f32_e32 v3, v173, v181
	v_add_f32_e32 v172, v176, v184
	v_add_f32_e32 v173, v177, v185
	v_sub_f32_e32 v176, v176, v184
	v_sub_f32_e32 v177, v177, v185
	v_add_f32_e32 v178, v2, v172
	v_add_f32_e32 v179, v3, v173
	v_sub_f32_e32 v2, v2, v172
	v_sub_f32_e32 v3, v3, v173
	v_sin_f32_e32 v173, v15
	v_cos_f32_e32 v172, v15
	v_add_f32_e32 v188, v152, v177
	v_add_f32_e32 v189, v153, v176
	v_sub_f32_e32 v152, v152, v177
	v_sub_f32_e32 v153, v153, v176
	v_xor_b32_e32 v180, 0x80000000, v173
	v_mov_b32_e32 v182, v180
	v_mov_b32_e32 v183, v173
	v_mov_b32_e32 v181, v172
	v_mul_f32_e32 v182, v172, v182
	v_mul_f32_e32 v183, v173, v183
	v_mov_b32_e32 v192, v173
	v_fma_f32 v184, v172, v180, v182
	v_fma_f32 v185, v172, v181, v183
	v_fma_f32 v180, v172, v180, -v182
	v_fma_f32 v181, v172, v181, -v183
	v_pk_mov_b32 v[196:197], v[152:153], v[188:189] op_sel:[1,0]
	v_mov_b32_e32 v182, v184
	v_mov_b32_e32 v183, v181
	v_mov_b32_e32 v186, v173
	v_mov_b32_e32 v187, v172
	v_mov_b32_e32 v176, v188
	v_mov_b32_e32 v177, v153
	v_mul_f32_e32 v193, v192, v197
	v_mul_f32_e32 v192, v192, v196
	v_sin_f32_e32 v1, v1
	v_mul_f32_e32 v186, v186, v182
	v_mul_f32_e32 v187, v187, v183
	v_mul_f32_e32 v182, v172, v182
	v_mul_f32_e32 v183, v173, v183
	v_fma_f32 v196, v172, v188, v192
	v_fma_f32 v197, v173, v189, v193
	v_fma_f32 v173, v172, v177, -v193
	v_fma_f32 v172, v172, v176, -v192
	v_mov_b32_e32 v197, v173
	v_mul_f32_e32 v172, v184, v3
	v_mul_f32_e32 v173, v184, v2
	v_fma_f32 v176, v181, v2, -v172
	v_fma_f32 v177, v181, v3, -v173
	v_fma_f32 v2, v181, v2, v172
	v_fma_f32 v3, v181, v3, v173
	v_sub_f32_e32 v172, v182, v183
	v_sub_f32_e32 v173, v182, v183
	v_pk_mov_b32 v[180:181], v[188:189], v[152:153] op_sel:[1,0]
	v_mov_b32_e32 v177, v3
	v_mov_b32_e32 v2, v152
	v_mov_b32_e32 v3, v189
	v_mul_f32_e32 v172, v172, v180
	v_mul_f32_e32 v173, v173, v181
	v_add_f32_e32 v180, v187, v186
	v_add_f32_e32 v181, v187, v186
	v_xor_b32_e32 v14, 0x80000000, v1
	v_fma_f32 v152, v180, v152, -v172
	v_fma_f32 v153, v181, v153, -v173
	v_fma_f32 v2, v180, v2, v172
	v_fma_f32 v3, v181, v3, v173
	v_add_f32_e32 v182, v10, v174
	v_add_f32_e32 v183, v11, v175
	v_sub_f32_e32 v10, v10, v174
	v_sub_f32_e32 v11, v11, v175
	v_add_f32_e32 v174, v12, v178
	v_add_f32_e32 v175, v13, v179
	v_sub_f32_e32 v12, v12, v178
	v_sub_f32_e32 v13, v13, v179
	v_mov_b32_e32 v153, v3
	v_mov_b32_e32 v2, v14
	v_mov_b32_e32 v3, v1
	v_add_f32_e32 v178, v182, v174
	v_add_f32_e32 v179, v183, v175
	v_sub_f32_e32 v174, v182, v174
	v_sub_f32_e32 v175, v183, v175
	v_add_f32_e32 v182, v10, v13
	v_add_f32_e32 v183, v11, v12
	v_sub_f32_e32 v10, v10, v13
	v_sub_f32_e32 v11, v11, v12
	v_mov_b32_e32 v15, v0
	v_mul_f32_e32 v2, v0, v2
	v_mul_f32_e32 v3, v1, v3
	v_mov_b32_e32 v184, v1
	v_pk_mov_b32 v[186:187], v[10:11], v[182:183] op_sel:[1,0]
	v_fma_f32 v172, v0, v14, v2
	v_fma_f32 v173, v0, v15, v3
	v_fma_f32 v2, v0, v14, -v2
	v_fma_f32 v3, v0, v15, -v3
	v_mov_b32_e32 v12, v182
	v_mov_b32_e32 v13, v11
	v_mul_f32_e32 v186, v184, v186
	v_mul_f32_e32 v187, v184, v187
	v_mov_b32_e32 v14, v172
	v_mov_b32_e32 v15, v3
	v_mov_b32_e32 v180, v1
	v_mov_b32_e32 v181, v0
	v_fma_f32 v188, v0, v182, v186
	v_fma_f32 v189, v1, v183, v187
	v_fma_f32 v12, v0, v12, -v186
	v_fma_f32 v13, v0, v13, -v187
; __device__ __forceinline__ cf cmul(cf a, cf b) { return mk2(a.x * b.x - a.y * b.y, a.x * b.y + a.y * b.x); }
; __device__ __forceinline__ cf cmulc(cf a, cf b) { return mk2(a.x * b.x + a.y * b.y, a.y * b.x - a.x * b.y); }
; __device__ __forceinline__ cf twid(float frac) { return mk2(__builtin_amdgcn_cosf(frac), -__builtin_amdgcn_sinf(frac)); }
; template <int LG, bool INV> __device__ __forceinline__ void fft_pass2(LAS cf* X, int tid) {
;     ...
;                 const cf w1 = twid((float)(j + r * L16) * fL), w2 = cmul(w1, w1), w3 = cmul(w2, w1);
;                 e[r][1] = cmul(e[r][1], w1); e[r][2] = cmul(e[r][2], w2); e[r][3] = cmul(e[r][3], w3); }
; #pragma unroll
;             for (int p = 0; p < 4; ++p) { bfly4_fwd(e[0][p], e[1][p], e[2][p], e[3][p]); e[1][p] = cmul(e[1][p], v1); e[2][p] = cmul(e[2][p], v2); e[3][p] = cmul(e[3][p], v3); }
;         } else {
; #pragma unroll
;             for (int p = 0; p < 4; ++p) { e[1][p] = cmulc(e[1][p], v1); e[2][p] = cmulc(e[2][p], v2); e[3][p] = cmulc(e[3][p], v3); bfly4_inv(e[0][p], e[1][p], e[2][p], e[3][p]); }
; #pragma unroll
;             for (int r = 0; r < 4; ++r) { const cf w1 = twid((float)(j + r * L16) * fL), w2 = cmul(w1, w1), w3 = cmul(w2, w1);
;                 e[r][1] = cmulc(e[r][1], w1); e[r][2] = cmulc(e[r][2], w2); e[r][3] = cmulc(e[r][3], w3); bfly4_inv(e[r][0], e[r][1], e[r][2], e[r][3]); }
;         }
; #pragma unroll
;         for (int r = 0; r < 4; ++r)
; #pragma unroll
;             for (int m = 0; m < 4; ++m) X[pb + POFF(r, m)] = e[r][m];
	v_mul_f32_e32 v180, v180, v14
	v_mul_f32_e32 v181, v181, v15
	v_mul_f32_e32 v14, v0, v14
	v_mul_f32_e32 v15, v1, v15
	v_mov_b32_e32 v189, v13
	v_mul_f32_e32 v12, v172, v174
	v_mul_f32_e32 v13, v172, v175
	v_fma_f32 v186, v3, v174, -v13
	v_fma_f32 v187, v3, v175, -v12
	v_pk_fma_f32 v[12:13], v[2:3], v[174:175], v[12:13] op_sel:[1,0,1] op_sel_hi:[1,1,0]
	v_pk_add_f32 v[14:15], v[14:15], v[14:15] op_sel:[0,1] op_sel_hi:[0,1] neg_lo:[0,1] neg_hi:[0,1]
	v_pk_mov_b32 v[174:175], v[182:183], v[10:11] op_sel:[1,0]
	v_mov_b32_e32 v187, v13
	v_mov_b32_e32 v12, v10
	v_mov_b32_e32 v13, v183
	v_mul_f32_e32 v174, v14, v174
	v_mul_f32_e32 v175, v15, v175
	v_pk_add_f32 v[180:181], v[180:181], v[180:181] op_sel:[1,0] op_sel_hi:[1,0]
	v_add_f32_e32 v182, v200, v196
	v_add_f32_e32 v183, v201, v197
	v_fma_f32 v10, v180, v10, -v174
	v_fma_f32 v11, v181, v11, -v175
	v_fma_f32 v12, v180, v12, v174
	v_fma_f32 v13, v181, v13, v175
	v_sub_f32_e32 v174, v190, v198
	v_sub_f32_e32 v175, v191, v199
	v_mov_b32_e32 v11, v13
	v_add_f32_e32 v12, v190, v198
	v_add_f32_e32 v13, v191, v199
	v_sub_f32_e32 v190, v200, v196
	v_sub_f32_e32 v191, v201, v197
	v_add_f32_e32 v192, v12, v182
	v_add_f32_e32 v193, v13, v183
	v_sub_f32_e32 v12, v12, v182
	v_sub_f32_e32 v13, v13, v183
	v_add_f32_e32 v182, v174, v191
	v_add_f32_e32 v183, v175, v190
	v_sub_f32_e32 v174, v174, v191
	v_sub_f32_e32 v175, v175, v190
	v_mov_b32_e32 v190, v182
	v_pk_mov_b32 v[196:197], v[174:175], v[182:183] op_sel:[1,0]
	v_mov_b32_e32 v191, v175
	v_mul_f32_e32 v196, v184, v196
	v_mul_f32_e32 v197, v184, v197
	v_fma_f32 v198, v0, v182, v196
	v_fma_f32 v199, v1, v183, v197
	v_fma_f32 v190, v0, v190, -v196
	v_fma_f32 v191, v0, v191, -v197
	v_mov_b32_e32 v199, v191
	v_mul_f32_e32 v190, v172, v12
	v_mul_f32_e32 v191, v172, v13
	v_fma_f32 v196, v3, v12, -v191
	v_fma_f32 v197, v3, v13, -v190
	v_fma_f32 v12, v3, v12, v191
	v_fma_f32 v13, v3, v13, v190
	s_movk_i32 s6, 0x200
	v_mov_b32_e32 v197, v13
	v_mov_b32_e32 v13, v183
	v_pk_mov_b32 v[182:183], v[182:183], v[174:175] op_sel:[1,0]
	v_mov_b32_e32 v12, v174
	v_mul_f32_e32 v182, v14, v182
	v_mul_f32_e32 v183, v15, v183
	s_and_b64 vcc, exec, s[4:5]
	v_fma_f32 v174, v180, v174, -v182
	v_fma_f32 v175, v181, v175, -v183
	v_fma_f32 v12, v180, v12, v182
	v_fma_f32 v13, v181, v13, v183
	v_add_f32_e32 v182, v150, v176
	v_add_f32_e32 v183, v151, v177
	v_mov_b32_e32 v175, v13
	v_add_f32_e32 v12, v194, v170
	v_add_f32_e32 v13, v195, v171
	v_sub_f32_e32 v170, v194, v170
	v_sub_f32_e32 v171, v195, v171
	v_sub_f32_e32 v150, v150, v176
	v_sub_f32_e32 v151, v151, v177
	v_add_f32_e32 v176, v12, v182
	v_add_f32_e32 v177, v13, v183
	v_sub_f32_e32 v12, v12, v182
	v_sub_f32_e32 v13, v13, v183
	v_add_f32_e32 v182, v170, v151
	v_add_f32_e32 v183, v171, v150
	v_pk_add_f32 v[150:151], v[170:171], v[150:151] op_sel:[0,1] op_sel_hi:[1,0] neg_lo:[0,1] neg_hi:[0,1]
	v_mov_b32_e32 v170, v182
	v_pk_mov_b32 v[190:191], v[150:151], v[182:183] op_sel:[1,0]
	v_mov_b32_e32 v171, v151
	v_mul_f32_e32 v190, v184, v190
	v_mul_f32_e32 v191, v184, v191
	v_fma_f32 v194, v0, v182, v190
	v_fma_f32 v195, v1, v183, v191
	v_fma_f32 v170, v0, v170, -v190
	v_fma_f32 v171, v0, v171, -v191
	v_mov_b32_e32 v195, v171
	v_mul_f32_e32 v170, v172, v12
	v_mul_f32_e32 v171, v172, v13
	v_fma_f32 v190, v3, v12, -v171
	v_fma_f32 v191, v3, v13, -v170
	v_fma_f32 v12, v3, v12, v171
	v_fma_f32 v13, v3, v13, v170
	v_pk_mov_b32 v[170:171], v[182:183], v[150:151] op_sel:[1,0]
	v_mov_b32_e32 v191, v13
	v_mov_b32_e32 v12, v150
	v_mov_b32_e32 v13, v183
	v_mul_f32_e32 v170, v14, v170
	v_mul_f32_e32 v171, v15, v171
	s_mov_b64 s[4:5], 0
	v_fma_f32 v150, v180, v150, -v170
	v_fma_f32 v151, v181, v151, -v171
	v_fma_f32 v12, v180, v12, v170
	v_fma_f32 v13, v181, v13, v171
	s_nop 0
	v_mov_b32_e32 v151, v13
	v_add_f32_e32 v12, v6, v8
	v_add_f32_e32 v13, v7, v9
	v_sub_f32_e32 v6, v6, v8
	v_sub_f32_e32 v7, v7, v9
	v_add_f32_e32 v8, v4, v152
	v_add_f32_e32 v9, v5, v153
	v_sub_f32_e32 v4, v4, v152
	v_sub_f32_e32 v5, v5, v153
	v_add_f32_e32 v152, v12, v8
	v_add_f32_e32 v153, v13, v9
	v_sub_f32_e32 v8, v12, v8
	v_sub_f32_e32 v9, v13, v9
	v_add_f32_e32 v12, v6, v5
	v_add_f32_e32 v13, v7, v4
	v_pk_add_f32 v[4:5], v[6:7], v[4:5] op_sel:[0,1] op_sel_hi:[1,0] neg_lo:[0,1] neg_hi:[0,1]
	v_mov_b32_e32 v6, v12
	v_pk_mov_b32 v[170:171], v[4:5], v[12:13] op_sel:[1,0]
	v_mov_b32_e32 v7, v5
	v_mul_f32_e32 v170, v184, v170
	v_mul_f32_e32 v171, v184, v171
	v_fma_f32 v182, v0, v12, v170
	v_fma_f32 v183, v1, v13, v171
	v_fma_f32 v1, v0, v7, -v171
	v_fma_f32 v0, v0, v6, -v170
	v_mov_b32_e32 v183, v1
	v_mul_f32_e32 v0, v172, v8
	v_mul_f32_e32 v1, v172, v9
	v_fma_f32 v6, v3, v8, -v1
	v_fma_f32 v7, v3, v9, -v0
	v_pk_fma_f32 v[0:1], v[2:3], v[8:9], v[0:1] op_sel:[1,0,1] op_sel_hi:[1,1,0]
	v_pk_mov_b32 v[2:3], v[12:13], v[4:5] op_sel:[1,0]
	v_mov_b32_e32 v7, v1
	v_mov_b32_e32 v0, v4
	v_mov_b32_e32 v1, v13
	v_mul_f32_e32 v2, v14, v2
	v_mul_f32_e32 v3, v15, v3
	s_nop 0
	v_fma_f32 v4, v180, v4, -v2
	v_fma_f32 v5, v181, v5, -v3
	v_fma_f32 v0, v180, v0, v2
	v_fma_f32 v1, v181, v1, v3
	s_nop 0
	v_mov_b32_e32 v5, v1
	ds_write2_b64 v202, v[178:179], v[188:189] offset1:4
	ds_write2_b64 v202, v[192:193], v[198:199] offset0:16 offset1:20
	ds_write2_b64 v202, v[176:177], v[194:195] offset0:32 offset1:36
	ds_write2_b64 v202, v[152:153], v[182:183] offset0:48 offset1:52
	ds_write2_b64 v202, v[186:187], v[10:11] offset0:8 offset1:12
	ds_write2_b64 v202, v[196:197], v[174:175] offset0:24 offset1:28
	ds_write2_b64 v202, v[190:191], v[150:151] offset0:40 offset1:44
	ds_write2_b64 v202, v[6:7], v[4:5] offset0:56 offset1:60
	s_cbranch_vccnz .LBB0_546
	s_mov_b32 s4, 0
	s_waitcnt lgkmcnt(0)
	s_barrier
; #define LAS __attribute__((address_space(3)))
; __device__ __forceinline__ cf cmul(cf a, cf b) { return mk2(a.x * b.x - a.y * b.y, a.x * b.y + a.y * b.x); }
; __device__ __forceinline__ void fft_mid_mul(LAS cf* X, int tid, const cf* KFR) {
; #pragma unroll 2
;     for (int i = 0; i < 8; ++i) { const int it = tid + 512 * i, g = it & 255, k = it >> 8, base = g * 64 + 4 * k; const cf* q = KFR + (4 * k) * 256 + g;
;         cf e0 = X[PX(base)], e1 = X[PX(base + 1)], e2 = X[PX(base + 2)], e3 = X[PX(base + 3)];
;         const cf k0 = ld_f2_l2(q), k1 = ld_f2_l2(q + 256), k2 = ld_f2_l2(q + 512), k3 = ld_f2_l2(q + 768);
;         bfly4_fwd(e0, e1, e2, e3);
;         e0 = cmul(e0, k0); e1 = cmul(e1, k1); e2 = cmul(e2, k2); e3 = cmul(e3, k3);
;         bfly4_inv(e0, e1, e2, e3);
;         X[PX(base)] = e0; X[PX(base + 1)] = e1; X[PX(base + 2)] = e2; X[PX(base + 3)] = e3; }
;     __syncthreads();
; }
.LBB0_548:
	v_add_u32_e32 v170, s4, v16
	v_ashrrev_i32_e32 v0, 6, v170
	v_and_b32_e32 v0, -4, v0
	v_add_u32_e32 v2, v0, v157
	v_lshlrev_b32_e32 v0, 8, v0
	v_ashrrev_i32_e32 v1, 31, v0
	v_lshl_add_u64 v[8:9], v[0:1], 3, v[136:137]
	v_ashrrev_i32_e32 v0, 6, v2
	v_lshlrev_b32_e32 v0, 3, v0
	v_lshlrev_b32_e32 v1, 3, v2
	v_add3_u32 v171, 0, v0, v1
	ds_read2_b64 v[0:3], v171 offset1:1
	ds_read2_b64 v[4:7], v171 offset0:2 offset1:3
	global_load_dwordx2 v[10:11], v[8:9], off sc1
	global_load_dwordx2 v[12:13], v[8:9], off offset:2048 sc1
	v_add_co_u32_e32 v8, vcc, s96, v8
	s_addk_i32 s4, 0x400
	s_nop 0
	v_addc_co_u32_e32 v9, vcc, 0, v9, vcc
	global_load_dwordx2 v[14:15], v[8:9], off sc1
	s_nop 0
	global_load_dwordx2 v[8:9], v[8:9], off offset:2048 sc1
	s_waitcnt lgkmcnt(0)
	v_add_f32_e32 v150, v0, v4
	v_add_f32_e32 v151, v1, v5
	v_sub_f32_e32 v0, v0, v4
	v_sub_f32_e32 v1, v1, v5
	v_add_f32_e32 v4, v2, v6
	v_add_f32_e32 v5, v3, v7
	v_sub_f32_e32 v2, v2, v6
	v_sub_f32_e32 v3, v3, v7
	v_add_f32_e32 v6, v150, v4
	v_add_f32_e32 v7, v151, v5
	v_sub_f32_e32 v4, v150, v4
	v_sub_f32_e32 v5, v151, v5
	s_cmpk_lg_i32 s4, 0x1000
	s_waitcnt vmcnt(0)
	v_mul_f32_e32 v150, v7, v11
	v_mul_f32_e32 v151, v7, v10
	s_nop 0
	v_fma_f32 v152, v6, v10, -v150
	v_fma_f32 v153, v7, v11, -v151
	v_fma_f32 v7, v6, v11, v151
	v_fma_f32 v6, v6, v10, v150
	v_sub_f32_e32 v10, v1, v2
	v_sub_f32_e32 v11, v1, v2
	v_mov_b32_e32 v153, v7
	v_add_f32_e32 v6, v0, v3
	v_add_f32_e32 v7, v0, v3
	v_mul_f32_e32 v10, v10, v13
	v_mul_f32_e32 v11, v11, v12
	s_nop 0
	v_fma_f32 v150, v6, v12, -v10
	v_fma_f32 v151, v7, v13, -v11
	v_fma_f32 v6, v6, v12, v10
	v_fma_f32 v7, v7, v13, v11
	s_nop 0
	v_mov_b32_e32 v151, v7
	v_mul_f32_e32 v6, v5, v15
	v_mul_f32_e32 v7, v5, v14
	s_nop 0
	v_fma_f32 v10, v4, v14, -v6
	v_fma_f32 v11, v5, v15, -v7
	v_fma_f32 v5, v4, v15, v7
	v_fma_f32 v4, v4, v14, v6
	v_mov_b32_e32 v11, v5
	v_sub_f32_e32 v4, v0, v3
	v_sub_f32_e32 v5, v0, v3
	v_add_f32_e32 v0, v1, v2
	v_add_f32_e32 v1, v1, v2
	s_nop 0
	v_mul_f32_e32 v0, v0, v9
	v_mul_f32_e32 v1, v1, v8
	s_nop 0
	v_fma_f32 v2, v4, v8, -v0
	v_fma_f32 v3, v5, v9, -v1
	v_fma_f32 v0, v4, v8, v0
	v_fma_f32 v1, v5, v9, v1
	v_sub_f32_e32 v4, v152, v10
	v_sub_f32_e32 v5, v153, v11
	v_mov_b32_e32 v3, v1
	v_add_f32_e32 v0, v152, v10
	v_add_f32_e32 v1, v153, v11
	v_add_f32_e32 v6, v150, v2
	v_add_f32_e32 v7, v151, v3
	v_sub_f32_e32 v2, v150, v2
	v_sub_f32_e32 v3, v151, v3
	v_add_f32_e32 v8, v0, v6
	v_add_f32_e32 v9, v1, v7
	v_sub_f32_e32 v0, v0, v6
	v_sub_f32_e32 v1, v1, v7
	v_sub_f32_e32 v6, v4, v3
	v_sub_f32_e32 v7, v5, v2
	v_add_f32_e32 v10, v4, v2
	v_add_f32_e32 v11, v5, v2
	v_add_f32_e32 v12, v4, v3
	v_add_f32_e32 v13, v5, v2
	v_sub_f32_e32 v3, v5, v2
	v_sub_f32_e32 v2, v4, v2
	v_mov_b32_e32 v7, v11
	v_mov_b32_e32 v13, v3
	ds_write2_b64 v171, v[0:1], v[12:13] offset0:2 offset1:3
	v_add_u32_e32 v0, 0x200, v170
	v_ashrrev_i32_e32 v0, 6, v0
	v_and_b32_e32 v0, -4, v0
	v_add_u32_e32 v2, v0, v157
	v_lshlrev_b32_e32 v0, 8, v0
	v_ashrrev_i32_e32 v1, 31, v0
	ds_write2_b64 v171, v[8:9], v[6:7] offset1:1
	v_lshl_add_u64 v[8:9], v[0:1], 3, v[136:137]
	v_ashrrev_i32_e32 v0, 6, v2
	v_lshlrev_b32_e32 v0, 3, v0
	v_lshlrev_b32_e32 v1, 3, v2
	v_add3_u32 v170, 0, v0, v1
	ds_read2_b64 v[0:3], v170 offset1:1
	ds_read2_b64 v[4:7], v170 offset0:2 offset1:3
	global_load_dwordx2 v[10:11], v[8:9], off sc1
	global_load_dwordx2 v[12:13], v[8:9], off offset:2048 sc1
	v_add_co_u32_e32 v8, vcc, s96, v8
	s_waitcnt lgkmcnt(0)
	v_add_f32_e32 v150, v0, v4
	v_add_f32_e32 v151, v1, v5
	v_addc_co_u32_e32 v9, vcc, 0, v9, vcc
	global_load_dwordx2 v[14:15], v[8:9], off sc1
	s_nop 0
	global_load_dwordx2 v[8:9], v[8:9], off offset:2048 sc1
	v_sub_f32_e32 v0, v0, v4
	v_sub_f32_e32 v1, v1, v5
	v_add_f32_e32 v4, v2, v6
	v_add_f32_e32 v5, v3, v7
	v_sub_f32_e32 v2, v2, v6
	v_sub_f32_e32 v3, v3, v7
	v_add_f32_e32 v6, v150, v4
	v_add_f32_e32 v7, v151, v5
	v_sub_f32_e32 v4, v150, v4
	v_sub_f32_e32 v5, v151, v5
	s_waitcnt vmcnt(0)
	v_mul_f32_e32 v150, v7, v11
	v_mul_f32_e32 v151, v7, v10
	s_nop 0
	v_fma_f32 v152, v6, v10, -v150
	v_fma_f32 v153, v7, v11, -v151
	v_fma_f32 v7, v6, v11, v151
	v_fma_f32 v6, v6, v10, v150
	v_sub_f32_e32 v10, v1, v2
	v_sub_f32_e32 v11, v1, v2
	v_mov_b32_e32 v153, v7
	v_add_f32_e32 v6, v0, v3
	v_add_f32_e32 v7, v0, v3
	v_mul_f32_e32 v10, v10, v13
	v_mul_f32_e32 v11, v11, v12
	s_nop 0
	v_fma_f32 v150, v6, v12, -v10
	v_fma_f32 v151, v7, v13, -v11
	v_fma_f32 v6, v6, v12, v10
	v_fma_f32 v7, v7, v13, v11
	s_nop 0
	v_mov_b32_e32 v151, v7
	s_waitcnt lgkmcnt(0)
	v_mul_f32_e32 v6, v5, v15
	v_mul_f32_e32 v7, v5, v14
	s_nop 0
	v_fma_f32 v10, v4, v14, -v6
	v_fma_f32 v11, v5, v15, -v7
	v_fma_f32 v5, v4, v15, v7
	v_fma_f32 v4, v4, v14, v6
	v_mov_b32_e32 v11, v5
	v_sub_f32_e32 v4, v0, v3
	v_sub_f32_e32 v5, v0, v3
	v_add_f32_e32 v0, v1, v2
	v_add_f32_e32 v1, v1, v2
	s_nop 0
	v_mul_f32_e32 v0, v0, v9
	v_mul_f32_e32 v1, v1, v8
	s_nop 0
	v_fma_f32 v2, v4, v8, -v0
	v_fma_f32 v3, v5, v9, -v1
	v_fma_f32 v0, v4, v8, v0
	v_fma_f32 v1, v5, v9, v1
	v_sub_f32_e32 v4, v152, v10
	v_sub_f32_e32 v5, v153, v11
	v_mov_b32_e32 v3, v1
	v_add_f32_e32 v0, v152, v10
	v_add_f32_e32 v1, v153, v11
	v_add_f32_e32 v6, v150, v2
	v_add_f32_e32 v7, v151, v3
	v_sub_f32_e32 v2, v150, v2
	v_sub_f32_e32 v3, v151, v3
	v_add_f32_e32 v8, v0, v6
	v_add_f32_e32 v9, v1, v7
	v_sub_f32_e32 v0, v0, v6
	v_sub_f32_e32 v1, v1, v7
	v_sub_f32_e32 v6, v4, v3
	v_sub_f32_e32 v7, v5, v2
	v_add_f32_e32 v10, v4, v2
	v_add_f32_e32 v11, v5, v2
	v_add_f32_e32 v12, v4, v3
	v_add_f32_e32 v13, v5, v2
	v_sub_f32_e32 v3, v5, v2
	v_sub_f32_e32 v2, v4, v2
	v_mov_b32_e32 v7, v11
	v_mov_b32_e32 v13, v3
	ds_write2_b64 v170, v[8:9], v[6:7] offset1:1
	ds_write2_b64 v170, v[0:1], v[12:13] offset0:2 offset1:3
	s_cbranch_scc1 .LBB0_548
	s_mov_b32 s6, 0
	s_mov_b64 s[4:5], -1
	s_waitcnt lgkmcnt(0)
	s_barrier
; __device__ __forceinline__ cf cmul(cf a, cf b) { return mk2(a.x * b.x - a.y * b.y, a.x * b.y + a.y * b.x); }
; __device__ __forceinline__ cf cmulc(cf a, cf b) { return mk2(a.x * b.x + a.y * b.y, a.y * b.x - a.x * b.y); }
; __device__ __forceinline__ cf twid(float frac) { return mk2(__builtin_amdgcn_cosf(frac), -__builtin_amdgcn_sinf(frac)); }
; template <int LG, bool INV> __device__ __forceinline__ void fft_pass2(LAS cf* X, int tid) {
;     ...
;         const int it = tid + 512 * i; int g, j;
;         if (LG == 14) { g = 0; j = it; } else if (LG == 10) { j = it & 63; g = it >> 6; } else { g = it & 255; j = it >> 8; }
;         const int base = g * L + j;
;         const int pb = PX(base);
;     ...
;         cf e[4][4];
; #pragma unroll
;         for (int r = 0; r < 4; ++r)
; #pragma unroll
;             for (int m = 0; m < 4; ++m) e[r][m] = X[pb + POFF(r, m)];
;         const cf v1 = twid((float)(4 * j) * fL), v2 = cmul(v1, v1), v3 = cmul(v2, v1);
;         if (!INV) {
; #pragma unroll
;             for (int r = 0; r < 4; ++r) { bfly4_fwd(e[r][0], e[r][1], e[r][2], e[r][3]);
;                 const cf w1 = twid((float)(j + r * L16) * fL), w2 = cmul(w1, w1), w3 = cmul(w2, w1);
;                 e[r][1] = cmul(e[r][1], w1); e[r][2] = cmul(e[r][2], w2); e[r][3] = cmul(e[r][3], w3); }
; #pragma unroll
;             for (int p = 0; p < 4; ++p) { bfly4_fwd(e[0][p], e[1][p], e[2][p], e[3][p]); e[1][p] = cmul(e[1][p], v1); e[2][p] = cmul(e[2][p], v2); e[3][p] = cmul(e[3][p], v3); }
;         } else {
; #pragma unroll
;             for (int p = 0; p < 4; ++p) { e[1][p] = cmulc(e[1][p], v1); e[2][p] = cmulc(e[2][p], v2); e[3][p] = cmulc(e[3][p], v3); bfly4_inv(e[0][p], e[1][p], e[2][p], e[3][p]); }
; #pragma unroll
;             for (int r = 0; r < 4; ++r) { const cf w1 = twid((float)(j + r * L16) * fL), w2 = cmul(w1, w1), w3 = cmul(w2, w1);
;                 e[r][1] = cmulc(e[r][1], w1); e[r][2] = cmulc(e[r][2], w2); e[r][3] = cmulc(e[r][3], w3); bfly4_inv(e[r][0], e[r][1], e[r][2], e[r][3]); }
.LBB0_550:
	v_add_u32_e32 v0, s6, v16
	v_ashrrev_i32_e32 v202, 8, v0
	v_lshlrev_b32_e32 v182, 2, v202
	v_cvt_f32_i32_e32 v182, v182
	v_add_u32_e32 v0, v202, v156
	v_ashrrev_i32_e32 v1, 6, v0
	v_lshlrev_b32_e32 v1, 3, v1
	v_mul_f32_e32 v183, 0x3c800000, v182
	v_cos_f32_e32 v182, v183
	v_sin_f32_e32 v183, v183
	v_lshlrev_b32_e32 v0, 3, v0
	v_add3_u32 v203, 0, v1, v0
	ds_read2_b64 v[0:3], v203 offset0:16 offset1:20
	ds_read2_b64 v[4:7], v203 offset0:32 offset1:36
	ds_read2_b64 v[8:11], v203 offset0:48 offset1:52
	ds_read2_b64 v[12:15], v203 offset1:4
	ds_read2_b64 v[150:153], v203 offset0:8 offset1:12
	ds_read2_b64 v[170:173], v203 offset0:24 offset1:28
	ds_read2_b64 v[174:177], v203 offset0:40 offset1:44
	ds_read2_b64 v[178:181], v203 offset0:56 offset1:60
	v_xor_b32_e32 v184, 0x80000000, v183
	v_mov_b32_e32 v186, v184
	v_mov_b32_e32 v187, v183
	v_mov_b32_e32 v185, v182
	v_mul_f32_e32 v186, v182, v186
	v_mul_f32_e32 v187, v183, v187
	v_mov_b32_e32 v192, v183
	v_fma_f32 v188, v182, v184, -v186
	v_fma_f32 v189, v182, v185, -v187
	v_fma_f32 v184, v182, v184, v186
	v_fma_f32 v185, v182, v185, v187
	s_waitcnt lgkmcnt(4)
	v_mul_f32_e32 v194, v192, v14
	v_mul_f32_e32 v195, v192, v15
	v_mov_b32_e32 v186, v184
	v_mov_b32_e32 v187, v189
	v_fma_f32 v196, v182, v14, -v195
	v_fma_f32 v197, v183, v15, -v194
	v_fma_f32 v14, v182, v14, v195
	v_fma_f32 v15, v182, v15, v194
	v_mul_f32_e32 v190, v183, v186
	v_mul_f32_e32 v191, v182, v187
	v_mul_f32_e32 v186, v182, v186
	v_mul_f32_e32 v187, v183, v187
	v_mov_b32_e32 v197, v15
	s_waitcnt lgkmcnt(3)
	v_mul_f32_e32 v14, v184, v150
	v_mul_f32_e32 v15, v184, v151
	v_fma_f32 v194, v189, v150, v15
	v_fma_f32 v195, v189, v151, v14
	v_pk_fma_f32 v[14:15], v[188:189], v[150:151], v[14:15] op_sel:[1,0,1] op_sel_hi:[1,1,0] neg_lo:[0,0,1] neg_hi:[0,0,1]
	v_sub_f32_e32 v150, v186, v187
	v_sub_f32_e32 v151, v186, v187
	v_mov_b32_e32 v195, v15
	v_add_f32_e32 v14, v191, v190
	v_add_f32_e32 v15, v191, v190
	v_mul_f32_e32 v186, v150, v152
	v_mul_f32_e32 v187, v151, v153
	s_movk_i32 s6, 0x200
	v_fma_f32 v190, v14, v152, v187
	v_fma_f32 v191, v15, v153, v186
	v_fma_f32 v152, v14, v152, -v187
	v_fma_f32 v153, v15, v153, -v186
	s_and_b64 vcc, exec, s[4:5]
	v_mov_b32_e32 v191, v153
	v_add_f32_e32 v152, v12, v194
	v_add_f32_e32 v153, v13, v195
	v_sub_f32_e32 v12, v12, v194
	v_sub_f32_e32 v13, v13, v195
	v_add_f32_e32 v186, v196, v190
	v_add_f32_e32 v187, v197, v191
	v_sub_f32_e32 v190, v196, v190
	v_sub_f32_e32 v191, v197, v191
	v_add_f32_e32 v194, v152, v186
	v_add_f32_e32 v195, v153, v187
	v_sub_f32_e32 v152, v152, v186
	v_sub_f32_e32 v153, v153, v187
	v_sub_f32_e32 v186, v12, v191
	v_sub_f32_e32 v187, v13, v190
	v_add_f32_e32 v196, v12, v190
	v_add_f32_e32 v197, v13, v190
	s_mov_b64 s[4:5], 0
	v_mov_b32_e32 v187, v197
	v_add_f32_e32 v196, v12, v191
	v_add_f32_e32 v197, v13, v190
	v_sub_f32_e32 v12, v12, v190
	v_sub_f32_e32 v13, v13, v190
	s_nop 0
	v_mov_b32_e32 v197, v13
	v_mul_f32_e32 v12, v192, v2
	v_mul_f32_e32 v13, v192, v3
	v_fma_f32 v190, v182, v2, -v13
	v_fma_f32 v191, v183, v3, -v12
	v_fma_f32 v2, v182, v2, v13
	v_fma_f32 v3, v182, v3, v12
	v_mov_b32_e32 v191, v3
	s_waitcnt lgkmcnt(2)
	v_mul_f32_e32 v2, v184, v170
	v_mul_f32_e32 v3, v184, v171
	v_fma_f32 v12, v189, v170, v3
	v_fma_f32 v13, v189, v171, v2
	v_pk_fma_f32 v[2:3], v[188:189], v[170:171], v[2:3] op_sel:[1,0,1] op_sel_hi:[1,1,0] neg_lo:[0,0,1] neg_hi:[0,0,1]
	s_nop 0
	v_mov_b32_e32 v13, v3
	v_mul_f32_e32 v2, v150, v172
	v_mul_f32_e32 v3, v151, v173
	s_nop 0
	v_fma_f32 v170, v14, v172, v3
	v_fma_f32 v171, v15, v173, v2
	v_pk_fma_f32 v[2:3], v[14:15], v[172:173], v[2:3] op_sel:[0,0,1] op_sel_hi:[1,1,0] neg_lo:[0,0,1] neg_hi:[0,0,1]
	s_nop 0
	v_mov_b32_e32 v171, v3
	v_add_f32_e32 v2, v0, v12
	v_add_f32_e32 v3, v1, v13
	v_sub_f32_e32 v0, v0, v12
	v_sub_f32_e32 v1, v1, v13
	v_add_f32_e32 v12, v190, v170
	v_add_f32_e32 v13, v191, v171
	v_sub_f32_e32 v170, v190, v170
	v_sub_f32_e32 v171, v191, v171
	v_add_f32_e32 v172, v2, v12
	v_add_f32_e32 v173, v3, v13
	v_sub_f32_e32 v2, v2, v12
	v_sub_f32_e32 v3, v3, v13
	v_mul_f32_e32 v12, v192, v6
	v_mul_f32_e32 v13, v192, v7
	v_fma_f32 v190, v182, v6, -v13
	v_fma_f32 v191, v183, v7, -v12
	v_fma_f32 v6, v182, v6, v13
	v_fma_f32 v7, v182, v7, v12
	v_mov_b32_e32 v191, v7
	s_waitcnt lgkmcnt(1)
	v_mul_f32_e32 v6, v184, v174
	v_mul_f32_e32 v7, v184, v175
	v_fma_f32 v12, v189, v174, v7
	v_fma_f32 v13, v189, v175, v6
	v_pk_fma_f32 v[6:7], v[188:189], v[174:175], v[6:7] op_sel:[1,0,1] op_sel_hi:[1,1,0] neg_lo:[0,0,1] neg_hi:[0,0,1]
	s_nop 0
	v_mov_b32_e32 v13, v7
	v_mul_f32_e32 v6, v150, v176
	v_mul_f32_e32 v7, v151, v177
	s_nop 0
	v_fma_f32 v174, v14, v176, v7
	v_fma_f32 v175, v15, v177, v6
	v_pk_fma_f32 v[6:7], v[14:15], v[176:177], v[6:7] op_sel:[0,0,1] op_sel_hi:[1,1,0] neg_lo:[0,0,1] neg_hi:[0,0,1]
	s_nop 0
	v_mov_b32_e32 v175, v7
	v_add_f32_e32 v6, v4, v12
	v_add_f32_e32 v7, v5, v13
	v_sub_f32_e32 v4, v4, v12
	v_sub_f32_e32 v5, v5, v13
	v_add_f32_e32 v12, v190, v174
	v_add_f32_e32 v13, v191, v175
	v_sub_f32_e32 v174, v190, v174
	v_sub_f32_e32 v175, v191, v175
	v_add_f32_e32 v176, v6, v12
	v_add_f32_e32 v177, v7, v13
	v_sub_f32_e32 v6, v6, v12
	v_sub_f32_e32 v7, v7, v13
	v_mul_f32_e32 v12, v192, v10
	v_mul_f32_e32 v13, v192, v11
	v_fma_f32 v190, v182, v10, -v13
	v_fma_f32 v191, v183, v11, -v12
	v_fma_f32 v10, v182, v10, v13
	v_fma_f32 v11, v182, v11, v12
	v_mov_b32_e32 v191, v11
	s_waitcnt lgkmcnt(0)
; __device__ __forceinline__ cf cmul(cf a, cf b) { return mk2(a.x * b.x - a.y * b.y, a.x * b.y + a.y * b.x); }
; __device__ __forceinline__ cf cmulc(cf a, cf b) { return mk2(a.x * b.x + a.y * b.y, a.y * b.x - a.x * b.y); }
; __device__ __forceinline__ cf twid(float frac) { return mk2(__builtin_amdgcn_cosf(frac), -__builtin_amdgcn_sinf(frac)); }
; template <int LG, bool INV> __device__ __forceinline__ void fft_pass2(LAS cf* X, int tid) {
;     ...
;         const cf v1 = twid((float)(4 * j) * fL), v2 = cmul(v1, v1), v3 = cmul(v2, v1);
;         if (!INV) {
; #pragma unroll
;             for (int r = 0; r < 4; ++r) { bfly4_fwd(e[r][0], e[r][1], e[r][2], e[r][3]);
;                 const cf w1 = twid((float)(j + r * L16) * fL), w2 = cmul(w1, w1), w3 = cmul(w2, w1);
;                 e[r][1] = cmul(e[r][1], w1); e[r][2] = cmul(e[r][2], w2); e[r][3] = cmul(e[r][3], w3); }
; #pragma unroll
;             for (int p = 0; p < 4; ++p) { bfly4_fwd(e[0][p], e[1][p], e[2][p], e[3][p]); e[1][p] = cmul(e[1][p], v1); e[2][p] = cmul(e[2][p], v2); e[3][p] = cmul(e[3][p], v3); }
;         } else {
; #pragma unroll
;             for (int p = 0; p < 4; ++p) { e[1][p] = cmulc(e[1][p], v1); e[2][p] = cmulc(e[2][p], v2); e[3][p] = cmulc(e[3][p], v3); bfly4_inv(e[0][p], e[1][p], e[2][p], e[3][p]); }
; #pragma unroll
;             for (int r = 0; r < 4; ++r) { const cf w1 = twid((float)(j + r * L16) * fL), w2 = cmul(w1, w1), w3 = cmul(w2, w1);
;                 e[r][1] = cmulc(e[r][1], w1); e[r][2] = cmulc(e[r][2], w2); e[r][3] = cmulc(e[r][3], w3); bfly4_inv(e[r][0], e[r][1], e[r][2], e[r][3]); }
	v_mul_f32_e32 v10, v184, v178
	v_mul_f32_e32 v11, v184, v179
	v_fma_f32 v12, v189, v178, v11
	v_fma_f32 v13, v189, v179, v10
	v_pk_fma_f32 v[10:11], v[188:189], v[178:179], v[10:11] op_sel:[1,0,1] op_sel_hi:[1,1,0] neg_lo:[0,0,1] neg_hi:[0,0,1]
	v_add_f32_e32 v192, v5, v174
	v_add_f32_e32 v193, v5, v174
	v_mov_b32_e32 v13, v11
	v_mul_f32_e32 v10, v150, v180
	v_mul_f32_e32 v11, v151, v181
	s_nop 0
	v_fma_f32 v150, v14, v180, v11
	v_fma_f32 v151, v15, v181, v10
	v_pk_fma_f32 v[10:11], v[14:15], v[180:181], v[10:11] op_sel:[0,0,1] op_sel_hi:[1,1,0] neg_lo:[0,0,1] neg_hi:[0,0,1]
	s_nop 0
	v_mov_b32_e32 v151, v11
	v_add_f32_e32 v10, v8, v12
	v_add_f32_e32 v11, v9, v13
	v_sub_f32_e32 v8, v8, v12
	v_sub_f32_e32 v9, v9, v13
	v_add_f32_e32 v12, v190, v150
	v_add_f32_e32 v13, v191, v151
	v_sub_f32_e32 v14, v190, v150
	v_sub_f32_e32 v15, v191, v151
	v_add_f32_e32 v150, v10, v12
	v_add_f32_e32 v151, v11, v13
	v_sub_f32_e32 v10, v10, v12
	v_sub_f32_e32 v11, v11, v13
	v_cvt_f32_i32_e32 v12, v202
	v_mul_f32_e32 v13, 0x3c800000, v12
	v_cos_f32_e32 v12, v13
	v_sin_f32_e32 v13, v13
	v_mov_b32_e32 v179, v12
	v_xor_b32_e32 v178, 0x80000000, v13
	v_mov_b32_e32 v180, v178
	v_mov_b32_e32 v181, v13
	v_mul_f32_e32 v180, v12, v180
	v_mul_f32_e32 v181, v13, v181
	v_mov_b32_e32 v188, v13
	v_fma_f32 v182, v12, v178, -v180
	v_fma_f32 v183, v12, v179, -v181
	v_fma_f32 v178, v12, v178, v180
	v_fma_f32 v179, v12, v179, v181
	v_mov_b32_e32 v180, v178
	v_mov_b32_e32 v181, v183
	v_mul_f32_e32 v189, v188, v172
	v_mul_f32_e32 v188, v188, v173
	v_mul_f32_e32 v184, v13, v180
	v_mul_f32_e32 v185, v12, v181
	v_mul_f32_e32 v180, v12, v180
	v_mul_f32_e32 v181, v13, v181
	v_fma_f32 v190, v12, v172, -v188
	v_fma_f32 v191, v13, v173, -v189
	v_fma_f32 v13, v12, v173, v189
	v_fma_f32 v12, v12, v172, v188
	v_mov_b32_e32 v191, v13
	v_mul_f32_e32 v12, v178, v177
	v_mul_f32_e32 v13, v178, v176
	v_fma_f32 v172, v183, v176, v12
	v_fma_f32 v173, v183, v177, v13
	v_fma_f32 v12, v183, v176, -v12
	v_fma_f32 v13, v183, v177, -v13
	v_sub_f32_e32 v176, v180, v181
	v_sub_f32_e32 v177, v180, v181
	v_mov_b32_e32 v173, v13
	v_add_f32_e32 v12, v185, v184
	v_add_f32_e32 v13, v185, v184
	v_mul_f32_e32 v176, v176, v151
	v_mul_f32_e32 v177, v177, v150
	v_sub_f32_e32 v184, v0, v171
	v_sub_f32_e32 v185, v1, v170
	v_fma_f32 v178, v12, v150, v176
	v_fma_f32 v179, v13, v151, v177
	v_fma_f32 v12, v12, v150, -v176
	v_fma_f32 v13, v13, v151, -v177
	v_sub_f32_e32 v150, v194, v172
	v_sub_f32_e32 v151, v195, v173
	v_mov_b32_e32 v179, v13
	v_add_f32_e32 v12, v194, v172
	v_add_f32_e32 v13, v195, v173
	v_add_f32_e32 v172, v190, v178
	v_add_f32_e32 v173, v191, v179
	v_sub_f32_e32 v176, v190, v178
	v_sub_f32_e32 v177, v191, v179
	v_add_f32_e32 v178, v12, v172
	v_add_f32_e32 v179, v13, v173
	v_sub_f32_e32 v12, v12, v172
	v_sub_f32_e32 v13, v13, v173
	v_sub_f32_e32 v172, v150, v177
	v_sub_f32_e32 v173, v151, v176
	v_add_f32_e32 v180, v150, v176
	v_add_f32_e32 v181, v151, v176
	v_add_f32_e32 v0, v0, v171
	v_add_f32_e32 v1, v1, v170
	v_mov_b32_e32 v173, v181
	v_add_f32_e32 v180, v150, v177
	v_add_f32_e32 v181, v151, v176
	v_sub_f32_e32 v150, v150, v176
	v_sub_f32_e32 v151, v151, v176
	v_pk_mov_b32 v[188:189], v[0:1], v[184:185] op_sel:[1,0]
	v_add_u32_e32 v150, 4, v202
	v_cvt_f32_i32_e32 v150, v150
	v_mov_b32_e32 v181, v151
	v_mov_b32_e32 v170, v184
	v_mov_b32_e32 v171, v1
	v_mul_f32_e32 v151, 0x3c800000, v150
	v_sin_f32_e32 v176, v151
	v_cos_f32_e32 v150, v151
	v_sub_f32_e32 v194, v4, v175
	v_sub_f32_e32 v195, v4, v175
	v_mul_f32_e32 v188, v176, v188
	v_mul_f32_e32 v189, v176, v189
	v_xor_b32_e32 v182, 0x80000000, v176
	v_fma_f32 v190, v150, v184, -v188
	v_fma_f32 v191, v151, v185, -v189
	v_fma_f32 v170, v150, v170, v188
	v_fma_f32 v171, v150, v171, v189
	v_mov_b32_e32 v191, v171
	v_mov_b32_e32 v151, v176
	v_mov_b32_e32 v170, v182
	v_mov_b32_e32 v171, v176
	v_mov_b32_e32 v183, v150
	v_mul_f32_e32 v170, v150, v170
	v_mul_f32_e32 v171, v151, v171
	v_mov_b32_e32 v177, v150
	v_fma_f32 v188, v150, v182, v170
	v_fma_f32 v189, v150, v183, v171
	v_fma_f32 v170, v150, v182, -v170
	v_fma_f32 v171, v150, v183, -v171
	v_mov_b32_e32 v183, v171
	v_pk_mov_b32 v[170:171], v[170:171], v[188:189] op_sel:[1,0]
	v_mov_b32_e32 v182, v188
	v_mul_f32_e32 v170, v170, v194
	v_mul_f32_e32 v171, v171, v195
	v_mul_f32_e32 v176, v176, v182
	v_mul_f32_e32 v177, v177, v183
	v_fma_f32 v188, v188, v192, v170
	v_fma_f32 v189, v189, v193, v171
	v_fma_f32 v170, v182, v192, -v170
	v_fma_f32 v171, v183, v193, -v171
	v_mul_f32_e32 v150, v150, v182
	v_mul_f32_e32 v151, v151, v183
	v_mov_b32_e32 v189, v171
	v_sub_f32_e32 v170, v8, v15
	v_sub_f32_e32 v171, v9, v14
	v_add_f32_e32 v182, v8, v15
	v_add_f32_e32 v183, v9, v14
	v_pk_add_f32 v[150:151], v[150:151], v[150:151] op_sel:[0,1] op_sel_hi:[0,1] neg_lo:[0,1] neg_hi:[0,1]
	v_mov_b32_e32 v193, v183
	v_pk_mov_b32 v[182:183], v[182:183], v[170:171] op_sel:[1,0]
	v_mov_b32_e32 v192, v170
	v_pk_add_f32 v[176:177], v[176:177], v[176:177] op_sel:[1,0] op_sel_hi:[1,0]
	v_mul_f32_e32 v150, v150, v182
	v_mul_f32_e32 v151, v151, v183
	s_nop 0
	v_fma_f32 v170, v176, v170, v150
	v_fma_f32 v171, v177, v171, v151
	v_fma_f32 v150, v176, v192, -v150
	v_fma_f32 v151, v177, v193, -v151
	v_sub_f32_e32 v176, v186, v188
	v_sub_f32_e32 v177, v187, v189
	v_mov_b32_e32 v171, v151
	v_add_f32_e32 v150, v186, v188
	v_add_f32_e32 v151, v187, v189
	v_add_f32_e32 v182, v190, v170
	v_add_f32_e32 v183, v191, v171
	v_sub_f32_e32 v170, v190, v170
	v_sub_f32_e32 v171, v191, v171
	v_add_f32_e32 v186, v150, v182
	v_add_f32_e32 v187, v151, v183
	v_sub_f32_e32 v150, v150, v182
	v_sub_f32_e32 v151, v151, v183
	v_sub_f32_e32 v182, v176, v171
; __device__ __forceinline__ cf cmul(cf a, cf b) { return mk2(a.x * b.x - a.y * b.y, a.x * b.y + a.y * b.x); }
; __device__ __forceinline__ cf cmulc(cf a, cf b) { return mk2(a.x * b.x + a.y * b.y, a.y * b.x - a.x * b.y); }
; __device__ __forceinline__ cf twid(float frac) { return mk2(__builtin_amdgcn_cosf(frac), -__builtin_amdgcn_sinf(frac)); }
; template <int LG, bool INV> __device__ __forceinline__ void fft_pass2(LAS cf* X, int tid) {
;     ...
;         const cf v1 = twid((float)(4 * j) * fL), v2 = cmul(v1, v1), v3 = cmul(v2, v1);
;         if (!INV) {
; #pragma unroll
;             for (int r = 0; r < 4; ++r) { bfly4_fwd(e[r][0], e[r][1], e[r][2], e[r][3]);
;                 const cf w1 = twid((float)(j + r * L16) * fL), w2 = cmul(w1, w1), w3 = cmul(w2, w1);
;                 e[r][1] = cmul(e[r][1], w1); e[r][2] = cmul(e[r][2], w2); e[r][3] = cmul(e[r][3], w3); }
; #pragma unroll
;             for (int p = 0; p < 4; ++p) { bfly4_fwd(e[0][p], e[1][p], e[2][p], e[3][p]); e[1][p] = cmul(e[1][p], v1); e[2][p] = cmul(e[2][p], v2); e[3][p] = cmul(e[3][p], v3); }
;         } else {
; #pragma unroll
;             for (int p = 0; p < 4; ++p) { e[1][p] = cmulc(e[1][p], v1); e[2][p] = cmulc(e[2][p], v2); e[3][p] = cmulc(e[3][p], v3); bfly4_inv(e[0][p], e[1][p], e[2][p], e[3][p]); }
; #pragma unroll
;             for (int r = 0; r < 4; ++r) { const cf w1 = twid((float)(j + r * L16) * fL), w2 = cmul(w1, w1), w3 = cmul(w2, w1);
;                 e[r][1] = cmulc(e[r][1], w1); e[r][2] = cmulc(e[r][2], w2); e[r][3] = cmulc(e[r][3], w3); bfly4_inv(e[r][0], e[r][1], e[r][2], e[r][3]); }
;         }
; #pragma unroll
;         for (int r = 0; r < 4; ++r)
; #pragma unroll
;             for (int m = 0; m < 4; ++m) X[pb + POFF(r, m)] = e[r][m];
;     }
;     ...
;     __syncthreads();
	v_sub_f32_e32 v183, v177, v170
	v_add_f32_e32 v188, v176, v170
	v_add_f32_e32 v189, v177, v170
	s_nop 0
	v_mov_b32_e32 v183, v189
	v_add_f32_e32 v188, v176, v171
	v_add_f32_e32 v189, v177, v170
	v_sub_f32_e32 v171, v177, v170
	v_sub_f32_e32 v170, v176, v170
	s_nop 0
	v_add_u32_e32 v170, 8, v202
	v_cvt_f32_i32_e32 v170, v170
	v_mov_b32_e32 v189, v171
	v_mul_f32_e32 v171, 0x3c800000, v170
	v_cos_f32_e32 v170, v171
	v_sin_f32_e32 v171, v171
	v_mov_b32_e32 v177, v170
	v_xor_b32_e32 v176, 0x80000000, v171
	v_mov_b32_e32 v190, v176
	v_mov_b32_e32 v191, v171
	v_mul_f32_e32 v190, v170, v190
	v_mul_f32_e32 v191, v171, v191
	v_mov_b32_e32 v198, v171
	v_fma_f32 v192, v170, v176, -v190
	v_fma_f32 v193, v170, v177, -v191
	v_fma_f32 v176, v170, v176, v190
	v_fma_f32 v177, v170, v177, v191
	v_mul_f32_e32 v199, v198, v2
	v_mul_f32_e32 v198, v198, v3
	v_mov_b32_e32 v190, v176
	v_mov_b32_e32 v191, v193
	v_fma_f32 v200, v170, v2, -v198
	v_fma_f32 v201, v171, v3, -v199
	v_fma_f32 v2, v170, v2, v198
	v_fma_f32 v3, v170, v3, v199
	v_mul_f32_e32 v194, v171, v190
	v_mul_f32_e32 v195, v170, v191
	v_mul_f32_e32 v190, v170, v190
	v_mul_f32_e32 v191, v171, v191
	v_mov_b32_e32 v201, v3
	v_mul_f32_e32 v2, v176, v7
	v_mul_f32_e32 v3, v176, v6
	v_fma_f32 v170, v193, v6, v2
	v_fma_f32 v171, v193, v7, v3
	v_fma_f32 v2, v193, v6, -v2
	v_fma_f32 v3, v193, v7, -v3
	v_sub_f32_e32 v6, v190, v191
	v_sub_f32_e32 v7, v190, v191
	v_mov_b32_e32 v171, v3
	v_add_f32_e32 v2, v195, v194
	v_add_f32_e32 v3, v195, v194
	v_mul_f32_e32 v6, v6, v11
	v_mul_f32_e32 v7, v7, v10
	v_mov_b32_e32 v193, v185
	v_fma_f32 v176, v2, v10, v6
	v_fma_f32 v177, v3, v11, v7
	v_fma_f32 v2, v2, v10, -v6
	v_fma_f32 v3, v3, v11, -v7
	v_sub_f32_e32 v6, v152, v170
	v_sub_f32_e32 v7, v153, v171
	v_mov_b32_e32 v177, v3
	v_add_f32_e32 v2, v152, v170
	v_add_f32_e32 v3, v153, v171
	v_add_f32_e32 v10, v200, v176
	v_add_f32_e32 v11, v201, v177
	v_sub_f32_e32 v152, v200, v176
	v_sub_f32_e32 v153, v201, v177
	v_add_f32_e32 v170, v2, v10
	v_add_f32_e32 v171, v3, v11
	v_sub_f32_e32 v2, v2, v10
	v_sub_f32_e32 v3, v3, v11
	v_sub_f32_e32 v10, v6, v153
	v_sub_f32_e32 v11, v7, v152
	v_add_f32_e32 v176, v6, v152
	v_add_f32_e32 v177, v7, v152
	v_pk_mov_b32 v[184:185], v[184:185], v[0:1] op_sel:[1,0]
	v_mov_b32_e32 v11, v177
	v_add_f32_e32 v176, v6, v153
	v_add_f32_e32 v177, v7, v152
	v_sub_f32_e32 v6, v6, v152
	v_sub_f32_e32 v7, v7, v152
	v_mov_b32_e32 v192, v0
	v_add_u32_e32 v6, 12, v202
	v_cvt_f32_i32_e32 v6, v6
	v_mov_b32_e32 v177, v7
	v_sub_f32_e32 v198, v5, v174
	v_sub_f32_e32 v199, v5, v174
	v_add_f32_e32 v5, v4, v175
	v_add_f32_e32 v4, v4, v175
	v_mul_f32_e32 v7, 0x3c800000, v6
	v_sin_f32_e32 v152, v7
	v_cos_f32_e32 v6, v7
	v_mul_f32_e32 v184, v152, v184
	v_mul_f32_e32 v185, v152, v185
	v_xor_b32_e32 v190, 0x80000000, v152
	v_fma_f32 v0, v6, v0, -v184
	v_fma_f32 v1, v7, v1, -v185
	v_fma_f32 v184, v6, v192, v184
	v_fma_f32 v185, v6, v193, v185
	v_mov_b32_e32 v1, v185
	v_mov_b32_e32 v7, v152
	v_mov_b32_e32 v184, v190
	v_mov_b32_e32 v185, v152
	v_mov_b32_e32 v191, v6
	v_mul_f32_e32 v152, v6, v184
	v_mul_f32_e32 v153, v7, v185
	s_nop 0
	v_fma_f32 v184, v6, v190, v152
	v_fma_f32 v185, v6, v191, v153
	v_fma_f32 v152, v6, v190, -v152
	v_fma_f32 v153, v6, v191, -v153
	v_mov_b32_e32 v191, v153
	v_pk_mov_b32 v[152:153], v[152:153], v[184:185] op_sel:[1,0]
	v_mov_b32_e32 v190, v184
	v_mul_f32_e32 v192, v7, v152
	v_mul_f32_e32 v193, v7, v153
	v_mul_f32_e32 v4, v152, v4
	v_mul_f32_e32 v5, v153, v5
	v_fma_f32 v194, v6, v190, -v192
	v_fma_f32 v195, v6, v191, -v193
	v_fma_f32 v7, v6, v191, v193
	v_fma_f32 v6, v6, v190, v192
	v_fma_f32 v152, v184, v198, v4
	v_fma_f32 v153, v185, v199, v5
	v_fma_f32 v4, v190, v198, -v4
	v_fma_f32 v5, v191, v199, -v5
	v_mov_b32_e32 v193, v7
	v_mov_b32_e32 v153, v5
	v_sub_f32_e32 v4, v9, v14
	v_sub_f32_e32 v5, v9, v14
	v_pk_mov_b32 v[6:7], v[6:7], v[194:195] op_sel:[1,0]
	v_add_f32_e32 v9, v8, v15
	v_add_f32_e32 v8, v8, v15
	v_mov_b32_e32 v192, v194
	v_mul_f32_e32 v6, v6, v8
	v_mul_f32_e32 v7, v7, v9
	s_nop 0
	v_fma_f32 v8, v194, v4, v6
	v_fma_f32 v9, v195, v5, v7
	v_fma_f32 v4, v192, v4, -v6
	v_fma_f32 v5, v193, v5, -v7
	v_sub_f32_e32 v6, v196, v152
	v_sub_f32_e32 v7, v197, v153
	v_mov_b32_e32 v9, v5
	v_add_f32_e32 v4, v196, v152
	v_add_f32_e32 v5, v197, v153
	v_add_f32_e32 v14, v0, v8
	v_add_f32_e32 v15, v1, v9
	v_sub_f32_e32 v0, v0, v8
	v_sub_f32_e32 v1, v1, v9
	v_add_f32_e32 v8, v4, v14
	v_add_f32_e32 v9, v5, v15
	v_sub_f32_e32 v4, v4, v14
	v_sub_f32_e32 v5, v5, v15
	v_sub_f32_e32 v14, v6, v1
	v_sub_f32_e32 v15, v7, v0
	v_add_f32_e32 v152, v6, v0
	v_add_f32_e32 v153, v7, v0
	s_nop 0
	v_mov_b32_e32 v15, v153
	v_add_f32_e32 v152, v6, v1
	v_add_f32_e32 v153, v7, v0
	v_sub_f32_e32 v1, v7, v0
	v_sub_f32_e32 v0, v6, v0
	s_nop 0
	v_mov_b32_e32 v153, v1
	ds_write2_b64 v203, v[178:179], v[186:187] offset1:4
	ds_write2_b64 v203, v[172:173], v[182:183] offset0:16 offset1:20
	ds_write2_b64 v203, v[12:13], v[150:151] offset0:32 offset1:36
	ds_write2_b64 v203, v[180:181], v[188:189] offset0:48 offset1:52
	ds_write2_b64 v203, v[170:171], v[8:9] offset0:8 offset1:12
	ds_write2_b64 v203, v[10:11], v[14:15] offset0:24 offset1:28
	ds_write2_b64 v203, v[2:3], v[4:5] offset0:40 offset1:44
	ds_write2_b64 v203, v[176:177], v[152:153] offset0:56 offset1:60
	s_cbranch_vccnz .LBB0_550
	s_mov_b32 s6, 0
	s_mov_b64 s[4:5], -1
	s_waitcnt lgkmcnt(0)
	s_barrier
; __device__ __forceinline__ cf cmul(cf a, cf b) { return mk2(a.x * b.x - a.y * b.y, a.x * b.y + a.y * b.x); }
; __device__ __forceinline__ cf cmulc(cf a, cf b) { return mk2(a.x * b.x + a.y * b.y, a.y * b.x - a.x * b.y); }
; __device__ __forceinline__ cf twid(float frac) { return mk2(__builtin_amdgcn_cosf(frac), -__builtin_amdgcn_sinf(frac)); }
; template <int LG, bool INV> __device__ __forceinline__ void fft_pass2(LAS cf* X, int tid) {
;     ...
;         const int it = tid + 512 * i; int g, j;
;         if (LG == 14) { g = 0; j = it; } else if (LG == 10) { j = it & 63; g = it >> 6; } else { g = it & 255; j = it >> 8; }
;         const int base = g * L + j;
;         const int pb = PX(base);
;     ...
;         cf e[4][4];
; #pragma unroll
;         for (int r = 0; r < 4; ++r)
; #pragma unroll
;             for (int m = 0; m < 4; ++m) e[r][m] = X[pb + POFF(r, m)];
;         const cf v1 = twid((float)(4 * j) * fL), v2 = cmul(v1, v1), v3 = cmul(v2, v1);
;         if (!INV) {
; #pragma unroll
;             for (int r = 0; r < 4; ++r) { bfly4_fwd(e[r][0], e[r][1], e[r][2], e[r][3]);
;                 const cf w1 = twid((float)(j + r * L16) * fL), w2 = cmul(w1, w1), w3 = cmul(w2, w1);
;                 e[r][1] = cmul(e[r][1], w1); e[r][2] = cmul(e[r][2], w2); e[r][3] = cmul(e[r][3], w3); }
; #pragma unroll
;             for (int p = 0; p < 4; ++p) { bfly4_fwd(e[0][p], e[1][p], e[2][p], e[3][p]); e[1][p] = cmul(e[1][p], v1); e[2][p] = cmul(e[2][p], v2); e[3][p] = cmul(e[3][p], v3); }
;         } else {
; #pragma unroll
;             for (int p = 0; p < 4; ++p) { e[1][p] = cmulc(e[1][p], v1); e[2][p] = cmulc(e[2][p], v2); e[3][p] = cmulc(e[3][p], v3); bfly4_inv(e[0][p], e[1][p], e[2][p], e[3][p]); }
; #pragma unroll
;             for (int r = 0; r < 4; ++r) { const cf w1 = twid((float)(j + r * L16) * fL), w2 = cmul(w1, w1), w3 = cmul(w2, w1);
;                 e[r][1] = cmulc(e[r][1], w1); e[r][2] = cmulc(e[r][2], w2); e[r][3] = cmulc(e[r][3], w3); bfly4_inv(e[r][0], e[r][1], e[r][2], e[r][3]); }
.LBB0_552:
	v_add_u32_e32 v0, s6, v155
	v_and_b32_e32 v0, 0xfffffc00, v0
	v_ashrrev_i32_e32 v1, 3, v0
	v_add_u32_e32 v1, 0, v1
	v_lshlrev_b32_e32 v0, 3, v0
	v_add3_u32 v192, v1, v0, v169
	ds_read2_b64 v[0:3], v192 offset1:65
	v_add_u32_e32 v193, 0x800, v192
	v_add_u32_e32 v194, 0x1000, v192
	v_add_u32_e32 v195, 0x1800, v192
	ds_read2_b64 v[4:7], v193 offset0:4 offset1:69
	ds_read2_b64 v[8:11], v194 offset0:8 offset1:73
	ds_read2_b64 v[12:15], v195 offset0:12 offset1:77
	ds_read2_b64 v[150:153], v192 offset0:130 offset1:195
	ds_read2_b64 v[170:173], v193 offset0:134 offset1:199
	ds_read2_b64 v[174:177], v194 offset0:138 offset1:203
	ds_read2_b64 v[178:181], v195 offset0:142 offset1:207
	s_waitcnt lgkmcnt(7)
	v_mul_f32_e32 v182, v18, v2
	v_mul_f32_e32 v183, v19, v3
	s_movk_i32 s6, 0x2000
	v_fma_f32 v184, v20, v2, -v183
	v_fma_f32 v185, v21, v3, -v182
	v_fma_f32 v2, v20, v2, v183
	v_fma_f32 v3, v21, v3, v182
	s_and_b64 vcc, exec, s[4:5]
	v_mov_b32_e32 v185, v3
	s_waitcnt lgkmcnt(3)
	v_mul_f32_e32 v2, v24, v150
	v_mul_f32_e32 v3, v25, v151
	s_mov_b64 s[4:5], 0
	v_fma_f32 v182, v22, v150, v3
	v_fma_f32 v183, v23, v151, v2
	v_pk_fma_f32 v[2:3], v[22:23], v[150:151], v[2:3] op_sel:[0,0,1] op_sel_hi:[1,1,0] neg_lo:[0,0,1] neg_hi:[0,0,1]
	s_nop 0
	v_mov_b32_e32 v183, v3
	v_mul_f32_e32 v2, v32, v152
	v_mul_f32_e32 v3, v33, v153
	s_nop 0
	v_fma_f32 v150, v30, v152, v3
	v_fma_f32 v151, v31, v153, v2
	v_pk_fma_f32 v[2:3], v[30:31], v[152:153], v[2:3] op_sel:[0,0,1] op_sel_hi:[1,1,0] neg_lo:[0,0,1] neg_hi:[0,0,1]
	s_nop 0
	v_mov_b32_e32 v151, v3
	v_add_f32_e32 v2, v0, v182
	v_add_f32_e32 v3, v1, v183
	v_sub_f32_e32 v0, v0, v182
	v_sub_f32_e32 v1, v1, v183
	v_add_f32_e32 v152, v184, v150
	v_add_f32_e32 v153, v185, v151
	v_sub_f32_e32 v150, v184, v150
	v_sub_f32_e32 v151, v185, v151
	v_add_f32_e32 v182, v2, v152
	v_add_f32_e32 v183, v3, v153
	v_sub_f32_e32 v2, v2, v152
	v_sub_f32_e32 v3, v3, v153
	v_sub_f32_e32 v152, v0, v151
	v_sub_f32_e32 v153, v1, v150
	v_add_f32_e32 v184, v0, v150
	v_add_f32_e32 v185, v1, v150
	s_nop 0
	v_mov_b32_e32 v153, v185
	v_add_f32_e32 v184, v0, v151
	v_add_f32_e32 v185, v1, v150
	v_sub_f32_e32 v0, v0, v150
	v_sub_f32_e32 v1, v1, v150
	s_nop 0
	v_mov_b32_e32 v185, v1
	v_mul_f32_e32 v0, v18, v6
	v_mul_f32_e32 v1, v19, v7
	s_nop 0
	v_fma_f32 v150, v20, v6, -v1
	v_fma_f32 v151, v21, v7, -v0
	v_pk_fma_f32 v[0:1], v[20:21], v[6:7], v[0:1] op_sel:[0,0,1] op_sel_hi:[1,1,0]
	s_nop 0
	v_mov_b32_e32 v151, v1
	s_waitcnt lgkmcnt(2)
	v_mul_f32_e32 v0, v24, v170
	v_mul_f32_e32 v1, v25, v171
	s_nop 0
	v_fma_f32 v6, v22, v170, v1
	v_fma_f32 v7, v23, v171, v0
	v_pk_fma_f32 v[0:1], v[22:23], v[170:171], v[0:1] op_sel:[0,0,1] op_sel_hi:[1,1,0] neg_lo:[0,0,1] neg_hi:[0,0,1]
	s_nop 0
	v_mov_b32_e32 v7, v1
	v_mul_f32_e32 v0, v32, v172
	v_mul_f32_e32 v1, v33, v173
	s_nop 0
	v_fma_f32 v170, v30, v172, v1
	v_fma_f32 v171, v31, v173, v0
	v_pk_fma_f32 v[0:1], v[30:31], v[172:173], v[0:1] op_sel:[0,0,1] op_sel_hi:[1,1,0] neg_lo:[0,0,1] neg_hi:[0,0,1]
	s_nop 0
	v_mov_b32_e32 v171, v1
	v_add_f32_e32 v0, v4, v6
	v_add_f32_e32 v1, v5, v7
	v_sub_f32_e32 v4, v4, v6
	v_sub_f32_e32 v5, v5, v7
	v_add_f32_e32 v6, v150, v170
	v_add_f32_e32 v7, v151, v171
	v_sub_f32_e32 v150, v150, v170
	v_sub_f32_e32 v151, v151, v171
	v_add_f32_e32 v170, v0, v6
	v_add_f32_e32 v171, v1, v7
	v_sub_f32_e32 v0, v0, v6
	v_sub_f32_e32 v1, v1, v7
	v_mul_f32_e32 v6, v18, v10
	v_mul_f32_e32 v7, v19, v11
	s_nop 0
	v_fma_f32 v172, v20, v10, -v7
	v_fma_f32 v173, v21, v11, -v6
	v_pk_fma_f32 v[6:7], v[20:21], v[10:11], v[6:7] op_sel:[0,0,1] op_sel_hi:[1,1,0]
	s_nop 0
	v_mov_b32_e32 v173, v7
	s_waitcnt lgkmcnt(1)
	v_mul_f32_e32 v6, v24, v174
	v_mul_f32_e32 v7, v25, v175
	s_nop 0
	v_fma_f32 v10, v22, v174, v7
	v_fma_f32 v11, v23, v175, v6
	v_pk_fma_f32 v[6:7], v[22:23], v[174:175], v[6:7] op_sel:[0,0,1] op_sel_hi:[1,1,0] neg_lo:[0,0,1] neg_hi:[0,0,1]
	s_nop 0
	v_mov_b32_e32 v11, v7
	v_mul_f32_e32 v6, v32, v176
	v_mul_f32_e32 v7, v33, v177
	s_nop 0
	v_fma_f32 v174, v30, v176, v7
	v_fma_f32 v175, v31, v177, v6
	v_pk_fma_f32 v[6:7], v[30:31], v[176:177], v[6:7] op_sel:[0,0,1] op_sel_hi:[1,1,0] neg_lo:[0,0,1] neg_hi:[0,0,1]
	s_nop 0
	v_mov_b32_e32 v175, v7
	v_add_f32_e32 v6, v8, v10
	v_add_f32_e32 v7, v9, v11
	v_sub_f32_e32 v8, v8, v10
	v_sub_f32_e32 v9, v9, v11
	v_add_f32_e32 v10, v172, v174
	v_add_f32_e32 v11, v173, v175
	v_sub_f32_e32 v172, v172, v174
	v_sub_f32_e32 v173, v173, v175
	v_add_f32_e32 v174, v6, v10
	v_add_f32_e32 v175, v7, v11
	v_sub_f32_e32 v6, v6, v10
	v_sub_f32_e32 v7, v7, v11
	v_mul_f32_e32 v10, v18, v14
	v_mul_f32_e32 v11, v19, v15
	s_nop 0
	v_fma_f32 v176, v20, v14, -v11
	v_fma_f32 v177, v21, v15, -v10
	v_pk_fma_f32 v[10:11], v[20:21], v[14:15], v[10:11] op_sel:[0,0,1] op_sel_hi:[1,1,0]
	s_nop 0
	v_mov_b32_e32 v177, v11
	s_waitcnt lgkmcnt(0)
; __device__ __forceinline__ cf cmul(cf a, cf b) { return mk2(a.x * b.x - a.y * b.y, a.x * b.y + a.y * b.x); }
; __device__ __forceinline__ cf cmulc(cf a, cf b) { return mk2(a.x * b.x + a.y * b.y, a.y * b.x - a.x * b.y); }
; __device__ __forceinline__ cf twid(float frac) { return mk2(__builtin_amdgcn_cosf(frac), -__builtin_amdgcn_sinf(frac)); }
; template <int LG, bool INV> __device__ __forceinline__ void fft_pass2(LAS cf* X, int tid) {
;     ...
;         const cf v1 = twid((float)(4 * j) * fL), v2 = cmul(v1, v1), v3 = cmul(v2, v1);
;         if (!INV) {
; #pragma unroll
;             for (int r = 0; r < 4; ++r) { bfly4_fwd(e[r][0], e[r][1], e[r][2], e[r][3]);
;                 const cf w1 = twid((float)(j + r * L16) * fL), w2 = cmul(w1, w1), w3 = cmul(w2, w1);
;                 e[r][1] = cmul(e[r][1], w1); e[r][2] = cmul(e[r][2], w2); e[r][3] = cmul(e[r][3], w3); }
; #pragma unroll
;             for (int p = 0; p < 4; ++p) { bfly4_fwd(e[0][p], e[1][p], e[2][p], e[3][p]); e[1][p] = cmul(e[1][p], v1); e[2][p] = cmul(e[2][p], v2); e[3][p] = cmul(e[3][p], v3); }
;         } else {
; #pragma unroll
;             for (int p = 0; p < 4; ++p) { e[1][p] = cmulc(e[1][p], v1); e[2][p] = cmulc(e[2][p], v2); e[3][p] = cmulc(e[3][p], v3); bfly4_inv(e[0][p], e[1][p], e[2][p], e[3][p]); }
; #pragma unroll
;             for (int r = 0; r < 4; ++r) { const cf w1 = twid((float)(j + r * L16) * fL), w2 = cmul(w1, w1), w3 = cmul(w2, w1);
;                 e[r][1] = cmulc(e[r][1], w1); e[r][2] = cmulc(e[r][2], w2); e[r][3] = cmulc(e[r][3], w3); bfly4_inv(e[r][0], e[r][1], e[r][2], e[r][3]); }
	v_mul_f32_e32 v10, v24, v178
	v_mul_f32_e32 v11, v25, v179
	s_nop 0
	v_fma_f32 v14, v22, v178, v11
	v_fma_f32 v15, v23, v179, v10
	v_pk_fma_f32 v[10:11], v[22:23], v[178:179], v[10:11] op_sel:[0,0,1] op_sel_hi:[1,1,0] neg_lo:[0,0,1] neg_hi:[0,0,1]
	s_nop 0
	v_mov_b32_e32 v15, v11
	v_mul_f32_e32 v10, v32, v180
	v_mul_f32_e32 v11, v33, v181
	s_nop 0
	v_fma_f32 v178, v30, v180, v11
	v_fma_f32 v179, v31, v181, v10
	v_pk_fma_f32 v[10:11], v[30:31], v[180:181], v[10:11] op_sel:[0,0,1] op_sel_hi:[1,1,0] neg_lo:[0,0,1] neg_hi:[0,0,1]
	s_nop 0
	v_mov_b32_e32 v179, v11
	v_add_f32_e32 v10, v12, v14
	v_add_f32_e32 v11, v13, v15
	v_sub_f32_e32 v12, v12, v14
	v_sub_f32_e32 v13, v13, v15
	v_add_f32_e32 v14, v176, v178
	v_add_f32_e32 v15, v177, v179
	v_sub_f32_e32 v176, v176, v178
	v_sub_f32_e32 v177, v177, v179
	v_add_f32_e32 v178, v10, v14
	v_add_f32_e32 v179, v11, v15
	v_sub_f32_e32 v10, v10, v14
	v_sub_f32_e32 v11, v11, v15
	v_mul_f32_e32 v14, v34, v170
	v_mul_f32_e32 v15, v35, v171
	s_nop 0
	v_fma_f32 v180, v36, v170, -v15
	v_fma_f32 v181, v37, v171, -v14
	v_pk_fma_f32 v[14:15], v[36:37], v[170:171], v[14:15] op_sel:[0,0,1] op_sel_hi:[1,1,0]
	s_nop 0
	v_mov_b32_e32 v181, v15
	v_mul_f32_e32 v14, v42, v175
	v_mul_f32_e32 v15, v43, v174
	s_nop 0
	v_fma_f32 v170, v40, v174, v14
	v_fma_f32 v171, v41, v175, v15
	v_fma_f32 v14, v40, v174, -v14
	v_fma_f32 v15, v41, v175, -v15
	s_nop 0
	v_mov_b32_e32 v171, v15
	v_mul_f32_e32 v14, v50, v179
	v_mul_f32_e32 v15, v51, v178
	s_nop 0
	v_fma_f32 v174, v48, v178, v14
	v_fma_f32 v175, v49, v179, v15
	v_fma_f32 v14, v48, v178, -v14
	v_fma_f32 v15, v49, v179, -v15
	s_nop 0
	v_mov_b32_e32 v175, v15
	v_add_f32_e32 v14, v182, v170
	v_add_f32_e32 v15, v183, v171
	v_sub_f32_e32 v170, v182, v170
	v_sub_f32_e32 v171, v183, v171
	v_add_f32_e32 v178, v180, v174
	v_add_f32_e32 v179, v181, v175
	v_sub_f32_e32 v174, v180, v174
	v_sub_f32_e32 v175, v181, v175
	v_add_f32_e32 v180, v14, v178
	v_add_f32_e32 v181, v15, v179
	v_sub_f32_e32 v14, v14, v178
	v_sub_f32_e32 v15, v15, v179
	v_sub_f32_e32 v178, v170, v175
	v_sub_f32_e32 v179, v171, v174
	v_add_f32_e32 v182, v170, v174
	v_add_f32_e32 v183, v171, v174
	s_nop 0
	v_mov_b32_e32 v179, v183
	v_add_f32_e32 v182, v170, v175
	v_add_f32_e32 v183, v171, v174
	v_sub_f32_e32 v170, v170, v174
	v_sub_f32_e32 v171, v171, v174
	s_nop 0
	v_mov_b32_e32 v183, v171
	v_sub_f32_e32 v170, v4, v151
	v_sub_f32_e32 v171, v5, v150
	v_add_f32_e32 v4, v4, v151
	v_add_f32_e32 v5, v5, v150
	v_mov_b32_e32 v150, v170
	v_pk_mov_b32 v[174:175], v[4:5], v[170:171] op_sel:[1,0]
	v_mov_b32_e32 v151, v5
	v_mul_f32_e32 v174, v52, v174
	v_mul_f32_e32 v175, v53, v175
	s_nop 0
	v_fma_f32 v186, v54, v170, -v174
	v_fma_f32 v187, v55, v171, -v175
	v_fma_f32 v150, v54, v150, v174
	v_fma_f32 v151, v55, v151, v175
	v_sub_f32_e32 v174, v8, v173
	v_sub_f32_e32 v175, v8, v173
	v_mov_b32_e32 v187, v151
	v_add_f32_e32 v150, v9, v172
	v_add_f32_e32 v151, v9, v172
	v_mul_f32_e32 v174, v62, v174
	v_mul_f32_e32 v175, v63, v175
	s_nop 0
	v_fma_f32 v188, v64, v150, v174
	v_fma_f32 v189, v65, v151, v175
	v_fma_f32 v150, v64, v150, -v174
	v_fma_f32 v151, v65, v151, -v175
	v_sub_f32_e32 v174, v12, v177
	v_sub_f32_e32 v175, v12, v177
	v_mov_b32_e32 v189, v151
	v_add_f32_e32 v150, v13, v176
	v_add_f32_e32 v151, v13, v176
	v_mul_f32_e32 v174, v74, v174
	v_mul_f32_e32 v175, v75, v175
	s_nop 0
	v_fma_f32 v190, v112, v150, v174
	v_fma_f32 v191, v113, v151, v175
	v_fma_f32 v150, v112, v150, -v174
	v_fma_f32 v151, v113, v151, -v175
	s_nop 0
	v_mov_b32_e32 v191, v151
	v_add_f32_e32 v150, v152, v188
	v_add_f32_e32 v151, v153, v189
	v_sub_f32_e32 v152, v152, v188
	v_sub_f32_e32 v153, v153, v189
	v_add_f32_e32 v174, v186, v190
	v_add_f32_e32 v175, v187, v191
	v_sub_f32_e32 v186, v186, v190
	v_sub_f32_e32 v187, v187, v191
	v_add_f32_e32 v188, v150, v174
	v_add_f32_e32 v189, v151, v175
	v_sub_f32_e32 v150, v150, v174
	v_sub_f32_e32 v151, v151, v175
	v_sub_f32_e32 v174, v152, v187
	v_sub_f32_e32 v175, v153, v186
	v_add_f32_e32 v190, v152, v186
	v_add_f32_e32 v191, v153, v186
	s_nop 0
	v_mov_b32_e32 v175, v191
	v_add_f32_e32 v190, v152, v187
	v_add_f32_e32 v191, v153, v186
	v_sub_f32_e32 v152, v152, v186
	v_sub_f32_e32 v153, v153, v186
	s_nop 0
	v_mov_b32_e32 v191, v153
	v_mul_f32_e32 v152, v70, v0
	v_mul_f32_e32 v153, v71, v1
	s_nop 0
	v_fma_f32 v186, v72, v0, -v153
	v_fma_f32 v187, v73, v1, -v152
	v_fma_f32 v0, v72, v0, v153
	v_fma_f32 v1, v73, v1, v152
	s_nop 0
	v_mov_b32_e32 v187, v1
	v_mul_f32_e32 v0, v78, v7
	v_mul_f32_e32 v1, v79, v6
	s_nop 0
	v_fma_f32 v152, v76, v6, v0
	v_fma_f32 v153, v77, v7, v1
	v_fma_f32 v0, v76, v6, -v0
	v_fma_f32 v1, v77, v7, -v1
	s_nop 0
	v_mov_b32_e32 v153, v1
	v_mul_f32_e32 v0, v86, v11
	v_mul_f32_e32 v1, v87, v10
	s_nop 0
	v_fma_f32 v6, v84, v10, v0
	v_fma_f32 v7, v85, v11, v1
	v_fma_f32 v0, v84, v10, -v0
	v_fma_f32 v1, v85, v11, -v1
	s_nop 0
	v_mov_b32_e32 v7, v1
	v_add_f32_e32 v0, v2, v152
	v_add_f32_e32 v1, v3, v153
	v_sub_f32_e32 v2, v2, v152
	v_sub_f32_e32 v3, v3, v153
	v_add_f32_e32 v10, v186, v6
	v_add_f32_e32 v11, v187, v7
	v_sub_f32_e32 v6, v186, v6
	v_sub_f32_e32 v7, v187, v7
	v_add_f32_e32 v152, v0, v10
	v_add_f32_e32 v153, v1, v11
	v_sub_f32_e32 v0, v0, v10
	v_sub_f32_e32 v1, v1, v11
	v_sub_f32_e32 v10, v2, v7
	v_sub_f32_e32 v11, v3, v6
	v_add_f32_e32 v186, v2, v6
	v_add_f32_e32 v187, v3, v6
	s_nop 0
	v_mov_b32_e32 v11, v187
	v_add_f32_e32 v186, v2, v7
	v_add_f32_e32 v187, v3, v6
	v_sub_f32_e32 v2, v2, v6
	v_sub_f32_e32 v3, v3, v6
	v_pk_mov_b32 v[6:7], v[170:171], v[4:5] op_sel:[1,0]
	v_mov_b32_e32 v187, v3
	v_mov_b32_e32 v2, v4
	v_mov_b32_e32 v3, v171
	v_mul_f32_e32 v6, v88, v6
	v_mul_f32_e32 v7, v89, v7
; __device__ __forceinline__ cf cmul(cf a, cf b) { return mk2(a.x * b.x - a.y * b.y, a.x * b.y + a.y * b.x); }
; __device__ __forceinline__ cf cmulc(cf a, cf b) { return mk2(a.x * b.x + a.y * b.y, a.y * b.x - a.x * b.y); }
; __device__ __forceinline__ cf twid(float frac) { return mk2(__builtin_amdgcn_cosf(frac), -__builtin_amdgcn_sinf(frac)); }
; template <int LG, bool INV> __device__ __forceinline__ void fft_pass2(LAS cf* X, int tid) {
;     ...
;         const int it = tid + 512 * i; int g, j;
;         if (LG == 14) { g = 0; j = it; } else if (LG == 10) { j = it & 63; g = it >> 6; } else { g = it & 255; j = it >> 8; }
;         const int base = g * L + j;
;         const int pb = PX(base);
;     ...
;         cf e[4][4];
; #pragma unroll
;         for (int r = 0; r < 4; ++r)
; #pragma unroll
;             for (int m = 0; m < 4; ++m) e[r][m] = X[pb + POFF(r, m)];
;         const cf v1 = twid((float)(4 * j) * fL), v2 = cmul(v1, v1), v3 = cmul(v2, v1);
;         if (!INV) {
; #pragma unroll
;             for (int r = 0; r < 4; ++r) { bfly4_fwd(e[r][0], e[r][1], e[r][2], e[r][3]);
;                 const cf w1 = twid((float)(j + r * L16) * fL), w2 = cmul(w1, w1), w3 = cmul(w2, w1);
;                 e[r][1] = cmul(e[r][1], w1); e[r][2] = cmul(e[r][2], w2); e[r][3] = cmul(e[r][3], w3); }
; #pragma unroll
;             for (int p = 0; p < 4; ++p) { bfly4_fwd(e[0][p], e[1][p], e[2][p], e[3][p]); e[1][p] = cmul(e[1][p], v1); e[2][p] = cmul(e[2][p], v2); e[3][p] = cmul(e[3][p], v3); }
;         } else {
; #pragma unroll
;             for (int p = 0; p < 4; ++p) { e[1][p] = cmulc(e[1][p], v1); e[2][p] = cmulc(e[2][p], v2); e[3][p] = cmulc(e[3][p], v3); bfly4_inv(e[0][p], e[1][p], e[2][p], e[3][p]); }
; #pragma unroll
;             for (int r = 0; r < 4; ++r) { const cf w1 = twid((float)(j + r * L16) * fL), w2 = cmul(w1, w1), w3 = cmul(w2, w1);
;                 e[r][1] = cmulc(e[r][1], w1); e[r][2] = cmulc(e[r][2], w2); e[r][3] = cmulc(e[r][3], w3); bfly4_inv(e[r][0], e[r][1], e[r][2], e[r][3]); }
;         }
; #pragma unroll
;         for (int r = 0; r < 4; ++r)
; #pragma unroll
;             for (int m = 0; m < 4; ++m) X[pb + POFF(r, m)] = e[r][m];
	s_nop 0
	v_fma_f32 v4, v90, v4, -v6
	v_fma_f32 v5, v91, v5, -v7
	v_fma_f32 v2, v90, v2, v6
	v_fma_f32 v3, v91, v3, v7
	v_add_f32_e32 v6, v8, v173
	v_add_f32_e32 v7, v8, v173
	v_mov_b32_e32 v5, v3
	v_sub_f32_e32 v2, v9, v172
	v_sub_f32_e32 v3, v9, v172
	v_mul_f32_e32 v6, v98, v6
	v_mul_f32_e32 v7, v99, v7
	s_nop 0
	v_fma_f32 v8, v100, v2, v6
	v_fma_f32 v9, v101, v3, v7
	v_fma_f32 v2, v100, v2, -v6
	v_fma_f32 v3, v101, v3, -v7
	v_add_f32_e32 v6, v12, v177
	v_add_f32_e32 v7, v12, v177
	v_mov_b32_e32 v9, v3
	v_sub_f32_e32 v2, v13, v176
	v_sub_f32_e32 v3, v13, v176
	v_mul_f32_e32 v6, v106, v6
	v_mul_f32_e32 v7, v107, v7
	s_nop 0
	v_fma_f32 v12, v116, v2, v6
	v_fma_f32 v13, v117, v3, v7
	v_fma_f32 v2, v116, v2, -v6
	v_fma_f32 v3, v117, v3, -v7
	v_sub_f32_e32 v6, v184, v8
	v_sub_f32_e32 v7, v185, v9
	v_mov_b32_e32 v13, v3
	v_add_f32_e32 v2, v184, v8
	v_add_f32_e32 v3, v185, v9
	v_add_f32_e32 v8, v4, v12
	v_add_f32_e32 v9, v5, v13
	v_sub_f32_e32 v4, v4, v12
	v_sub_f32_e32 v5, v5, v13
	v_add_f32_e32 v12, v2, v8
	v_add_f32_e32 v13, v3, v9
	v_sub_f32_e32 v2, v2, v8
	v_sub_f32_e32 v3, v3, v9
	v_sub_f32_e32 v8, v6, v5
	v_sub_f32_e32 v9, v7, v4
	v_add_f32_e32 v170, v6, v4
	v_add_f32_e32 v171, v7, v4
	s_nop 0
	v_mov_b32_e32 v9, v171
	v_add_f32_e32 v170, v6, v5
	v_add_f32_e32 v171, v7, v4
	v_sub_f32_e32 v5, v7, v4
	v_sub_f32_e32 v4, v6, v4
	s_nop 0
	v_mov_b32_e32 v171, v5
	ds_write2_b64 v192, v[180:181], v[188:189] offset1:65
	ds_write2_b64 v193, v[178:179], v[174:175] offset0:4 offset1:69
	ds_write2_b64 v194, v[14:15], v[150:151] offset0:8 offset1:73
	ds_write2_b64 v195, v[182:183], v[190:191] offset0:12 offset1:77
	ds_write2_b64 v192, v[152:153], v[12:13] offset0:130 offset1:195
	ds_write2_b64 v193, v[10:11], v[8:9] offset0:134 offset1:199
	ds_write2_b64 v194, v[0:1], v[2:3] offset0:138 offset1:203
	ds_write2_b64 v195, v[186:187], v[170:171] offset0:142 offset1:207
	s_cbranch_vccnz .LBB0_552
	s_mov_b32 s6, 0
	s_mov_b64 s[4:5], -1
	s_waitcnt lgkmcnt(0)
	s_barrier
.LBB0_554:
	v_add_u32_e32 v202, s6, v16
	v_lshlrev_b32_e32 v182, 2, v202
	v_cvt_f32_i32_e32 v182, v182
	v_ashrrev_i32_e32 v0, 6, v202
	v_lshlrev_b32_e32 v0, 3, v0
	v_lshlrev_b32_e32 v1, 3, v202
	v_mul_f32_e32 v183, 0x38800000, v182
	v_cos_f32_e32 v182, v183
	v_sin_f32_e32 v183, v183
	v_add3_u32 v203, 0, v0, v1
	v_add_u32_e32 v204, 0x10400, v203
	v_add_u32_e32 v205, 0x18600, v203
	ds_read_b64 v[0:1], v203
	ds_read_b64 v[2:3], v203 offset:33280
	ds_read_b64 v[4:5], v204
	ds_read_b64 v[6:7], v205
	ds_read_b64 v[8:9], v203 offset:8320
	ds_read_b64 v[10:11], v203 offset:41600
	v_add_u32_e32 v206, 0x12480, v203
	v_add_u32_e32 v207, 0x1a680, v203
	v_xor_b32_e32 v184, 0x80000000, v183
	ds_read_b64 v[12:13], v206
	ds_read_b64 v[14:15], v207
	ds_read_b64 v[150:151], v203 offset:16640
	ds_read_b64 v[152:153], v203 offset:49920
	v_mov_b32_e32 v186, v184
	v_mov_b32_e32 v187, v183
	v_add_u32_e32 v208, 0x14500, v203
	v_add_u32_e32 v210, 0x1c700, v203
	v_mov_b32_e32 v185, v182
	v_mul_f32_e32 v186, v182, v186
	v_mul_f32_e32 v187, v183, v187
	v_mov_b32_e32 v192, v183
	ds_read_b64 v[170:171], v208
	ds_read_b64 v[172:173], v210
	ds_read_b64 v[174:175], v203 offset:24960
	ds_read_b64 v[176:177], v203 offset:58240
	v_fma_f32 v188, v182, v184, -v186
	v_fma_f32 v189, v182, v185, -v187
	v_fma_f32 v184, v182, v184, v186
	v_fma_f32 v185, v182, v185, v187
	s_waitcnt lgkmcnt(9)
	v_mul_f32_e32 v194, v192, v8
	v_mul_f32_e32 v195, v192, v9
	v_mov_b32_e32 v186, v184
	v_mov_b32_e32 v187, v189
	v_fma_f32 v196, v182, v8, -v195
	v_fma_f32 v197, v183, v9, -v194
	v_fma_f32 v8, v182, v8, v195
	v_fma_f32 v9, v182, v9, v194
	v_mul_f32_e32 v190, v183, v186
	v_mul_f32_e32 v191, v182, v187
	v_mul_f32_e32 v186, v182, v186
	v_mul_f32_e32 v187, v183, v187
	v_mov_b32_e32 v197, v9
	s_waitcnt lgkmcnt(5)
	v_mul_f32_e32 v8, v184, v150
	v_mul_f32_e32 v9, v184, v151
	v_fma_f32 v194, v189, v150, v9
	v_fma_f32 v195, v189, v151, v8
	v_pk_fma_f32 v[8:9], v[188:189], v[150:151], v[8:9] op_sel:[1,0,1] op_sel_hi:[1,1,0] neg_lo:[0,0,1] neg_hi:[0,0,1]
	v_sub_f32_e32 v150, v186, v187
	v_sub_f32_e32 v151, v186, v187
	v_mov_b32_e32 v195, v9
	v_add_f32_e32 v8, v191, v190
	v_add_f32_e32 v9, v191, v190
	s_waitcnt lgkmcnt(1)
	v_mul_f32_e32 v186, v150, v174
	v_mul_f32_e32 v187, v151, v175
	v_add_u32_e32 v211, 0x16580, v203
	v_fma_f32 v190, v8, v174, v187
	v_fma_f32 v191, v9, v175, v186
	v_fma_f32 v174, v8, v174, -v187
	v_fma_f32 v175, v9, v175, -v186
	ds_read_b64 v[178:179], v211
	v_mov_b32_e32 v191, v175
	v_add_f32_e32 v174, v0, v194
	v_add_f32_e32 v175, v1, v195
	v_sub_f32_e32 v0, v0, v194
	v_sub_f32_e32 v1, v1, v195
	v_add_f32_e32 v186, v196, v190
	v_add_f32_e32 v187, v197, v191
	v_sub_f32_e32 v190, v196, v190
	v_sub_f32_e32 v191, v197, v191
	v_add_f32_e32 v194, v174, v186
	v_add_f32_e32 v195, v175, v187
	v_sub_f32_e32 v174, v174, v186
	v_sub_f32_e32 v175, v175, v187
	v_sub_f32_e32 v186, v0, v191
	v_sub_f32_e32 v187, v1, v190
	v_add_f32_e32 v196, v0, v190
	v_add_f32_e32 v197, v1, v190
	v_add_u32_e32 v212, 0x1e780, v203
	v_mov_b32_e32 v187, v197
	v_add_f32_e32 v196, v0, v191
	v_add_f32_e32 v197, v1, v190
	v_sub_f32_e32 v0, v0, v190
	v_sub_f32_e32 v1, v1, v190
	ds_read_b64 v[180:181], v212
	v_mov_b32_e32 v197, v1
	v_mul_f32_e32 v0, v192, v10
	v_mul_f32_e32 v1, v192, v11
	v_fma_f32 v190, v182, v10, -v1
	v_fma_f32 v191, v183, v11, -v0
	v_pk_fma_f32 v[0:1], v[182:183], v[10:11], v[0:1] op_sel:[0,0,1] op_sel_hi:[0,1,0]
	v_mov_b32_e32 v191, v1
	v_mul_f32_e32 v0, v184, v152
	v_mul_f32_e32 v1, v184, v153
	v_fma_f32 v10, v189, v152, v1
	v_fma_f32 v11, v189, v153, v0
	v_pk_fma_f32 v[0:1], v[188:189], v[152:153], v[0:1] op_sel:[1,0,1] op_sel_hi:[1,1,0] neg_lo:[0,0,1] neg_hi:[0,0,1]
	s_movk_i32 s6, 0x200
	v_mov_b32_e32 v11, v1
	s_waitcnt lgkmcnt(2)
; __device__ __forceinline__ cf cmul(cf a, cf b) { return mk2(a.x * b.x - a.y * b.y, a.x * b.y + a.y * b.x); }
; __device__ __forceinline__ cf cmulc(cf a, cf b) { return mk2(a.x * b.x + a.y * b.y, a.y * b.x - a.x * b.y); }
; __device__ __forceinline__ cf twid(float frac) { return mk2(__builtin_amdgcn_cosf(frac), -__builtin_amdgcn_sinf(frac)); }
; template <int LG, bool INV> __device__ __forceinline__ void fft_pass2(LAS cf* X, int tid) {
;     ...
;         const cf v1 = twid((float)(4 * j) * fL), v2 = cmul(v1, v1), v3 = cmul(v2, v1);
;         if (!INV) {
; #pragma unroll
;             for (int r = 0; r < 4; ++r) { bfly4_fwd(e[r][0], e[r][1], e[r][2], e[r][3]);
;                 const cf w1 = twid((float)(j + r * L16) * fL), w2 = cmul(w1, w1), w3 = cmul(w2, w1);
;                 e[r][1] = cmul(e[r][1], w1); e[r][2] = cmul(e[r][2], w2); e[r][3] = cmul(e[r][3], w3); }
; #pragma unroll
;             for (int p = 0; p < 4; ++p) { bfly4_fwd(e[0][p], e[1][p], e[2][p], e[3][p]); e[1][p] = cmul(e[1][p], v1); e[2][p] = cmul(e[2][p], v2); e[3][p] = cmul(e[3][p], v3); }
;         } else {
; #pragma unroll
;             for (int p = 0; p < 4; ++p) { e[1][p] = cmulc(e[1][p], v1); e[2][p] = cmulc(e[2][p], v2); e[3][p] = cmulc(e[3][p], v3); bfly4_inv(e[0][p], e[1][p], e[2][p], e[3][p]); }
; #pragma unroll
;             for (int r = 0; r < 4; ++r) { const cf w1 = twid((float)(j + r * L16) * fL), w2 = cmul(w1, w1), w3 = cmul(w2, w1);
;                 e[r][1] = cmulc(e[r][1], w1); e[r][2] = cmulc(e[r][2], w2); e[r][3] = cmulc(e[r][3], w3); bfly4_inv(e[r][0], e[r][1], e[r][2], e[r][3]); }
	v_mul_f32_e32 v0, v150, v176
	v_mul_f32_e32 v1, v151, v177
	s_and_b64 vcc, exec, s[4:5]
	v_fma_f32 v152, v8, v176, v1
	v_fma_f32 v153, v9, v177, v0
	v_pk_fma_f32 v[0:1], v[8:9], v[176:177], v[0:1] op_sel:[0,0,1] op_sel_hi:[1,1,0] neg_lo:[0,0,1] neg_hi:[0,0,1]
	s_mov_b64 s[4:5], 0
	v_mov_b32_e32 v153, v1
	v_add_f32_e32 v0, v2, v10
	v_add_f32_e32 v1, v3, v11
	v_sub_f32_e32 v2, v2, v10
	v_sub_f32_e32 v3, v3, v11
	v_add_f32_e32 v10, v190, v152
	v_add_f32_e32 v11, v191, v153
	v_sub_f32_e32 v152, v190, v152
	v_sub_f32_e32 v153, v191, v153
	v_add_f32_e32 v176, v0, v10
	v_add_f32_e32 v177, v1, v11
	v_sub_f32_e32 v0, v0, v10
	v_sub_f32_e32 v1, v1, v11
	v_mul_f32_e32 v10, v192, v12
	v_mul_f32_e32 v11, v192, v13
	v_fma_f32 v190, v182, v12, -v11
	v_fma_f32 v191, v183, v13, -v10
	v_pk_fma_f32 v[10:11], v[182:183], v[12:13], v[10:11] op_sel:[0,0,1] op_sel_hi:[0,1,0]
	v_mov_b32_e32 v191, v11
	v_mul_f32_e32 v10, v184, v170
	v_mul_f32_e32 v11, v184, v171
	v_fma_f32 v12, v189, v170, v11
	v_fma_f32 v13, v189, v171, v10
	v_pk_fma_f32 v[10:11], v[188:189], v[170:171], v[10:11] op_sel:[1,0,1] op_sel_hi:[1,1,0] neg_lo:[0,0,1] neg_hi:[0,0,1]
	s_nop 0
	v_mov_b32_e32 v13, v11
	s_waitcnt lgkmcnt(1)
	v_mul_f32_e32 v10, v150, v178
	v_mul_f32_e32 v11, v151, v179
	s_nop 0
	v_fma_f32 v170, v8, v178, v11
	v_fma_f32 v171, v9, v179, v10
	v_pk_fma_f32 v[10:11], v[8:9], v[178:179], v[10:11] op_sel:[0,0,1] op_sel_hi:[1,1,0] neg_lo:[0,0,1] neg_hi:[0,0,1]
	s_nop 0
	v_mov_b32_e32 v171, v11
	v_add_f32_e32 v10, v4, v12
	v_add_f32_e32 v11, v5, v13
	v_sub_f32_e32 v4, v4, v12
	v_sub_f32_e32 v5, v5, v13
	v_add_f32_e32 v12, v190, v170
	v_add_f32_e32 v13, v191, v171
	v_sub_f32_e32 v170, v190, v170
	v_sub_f32_e32 v171, v191, v171
	v_add_f32_e32 v178, v10, v12
	v_add_f32_e32 v179, v11, v13
	v_sub_f32_e32 v10, v10, v12
	v_sub_f32_e32 v11, v11, v13
	v_mul_f32_e32 v12, v192, v14
	v_mul_f32_e32 v13, v192, v15
	v_fma_f32 v190, v182, v14, -v13
	v_fma_f32 v191, v183, v15, -v12
	v_pk_fma_f32 v[12:13], v[182:183], v[14:15], v[12:13] op_sel:[0,0,1] op_sel_hi:[0,1,0]
	v_mov_b32_e32 v191, v13
	v_mul_f32_e32 v12, v184, v172
	v_mul_f32_e32 v13, v184, v173
	v_fma_f32 v14, v189, v172, v13
	v_fma_f32 v15, v189, v173, v12
	v_pk_fma_f32 v[12:13], v[188:189], v[172:173], v[12:13] op_sel:[1,0,1] op_sel_hi:[1,1,0] neg_lo:[0,0,1] neg_hi:[0,0,1]
	v_add_f32_e32 v192, v5, v170
	v_add_f32_e32 v193, v5, v170
	v_mov_b32_e32 v15, v13
	s_waitcnt lgkmcnt(0)
	v_mul_f32_e32 v12, v150, v180
	v_mul_f32_e32 v13, v151, v181
	s_nop 0
	v_fma_f32 v150, v8, v180, v13
	v_fma_f32 v151, v9, v181, v12
	v_fma_f32 v8, v8, v180, -v13
	v_fma_f32 v9, v9, v181, -v12
	s_nop 0
	v_mov_b32_e32 v151, v9
	v_add_f32_e32 v8, v6, v14
	v_add_f32_e32 v9, v7, v15
	v_add_f32_e32 v12, v190, v150
	v_add_f32_e32 v13, v191, v151
	v_sub_f32_e32 v6, v6, v14
	v_sub_f32_e32 v7, v7, v15
	v_sub_f32_e32 v14, v190, v150
	v_sub_f32_e32 v15, v191, v151
	v_add_f32_e32 v150, v8, v12
	v_add_f32_e32 v151, v9, v13
	v_sub_f32_e32 v8, v8, v12
	v_sub_f32_e32 v9, v9, v13
	v_cvt_f32_i32_e32 v12, v202
	v_mul_f32_e32 v13, 0x38800000, v12
	v_cos_f32_e32 v12, v13
	v_sin_f32_e32 v13, v13
	v_mov_b32_e32 v173, v12
	v_xor_b32_e32 v172, 0x80000000, v13
	v_mov_b32_e32 v180, v172
	v_mov_b32_e32 v181, v13
	v_mul_f32_e32 v180, v12, v180
	v_mul_f32_e32 v181, v13, v181
	v_mov_b32_e32 v188, v13
	v_fma_f32 v182, v12, v172, -v180
	v_fma_f32 v183, v12, v173, -v181
	v_fma_f32 v172, v12, v172, v180
	v_fma_f32 v173, v12, v173, v181
	v_mov_b32_e32 v180, v172
	v_mov_b32_e32 v181, v183
	v_mul_f32_e32 v189, v188, v176
	v_mul_f32_e32 v188, v188, v177
	v_mul_f32_e32 v184, v13, v180
	v_mul_f32_e32 v185, v12, v181
	v_mul_f32_e32 v180, v12, v180
	v_mul_f32_e32 v181, v13, v181
	v_fma_f32 v190, v12, v176, -v188
	v_fma_f32 v191, v13, v177, -v189
	v_fma_f32 v13, v12, v177, v189
	v_fma_f32 v12, v12, v176, v188
	v_mov_b32_e32 v191, v13
	v_mul_f32_e32 v12, v172, v179
	v_mul_f32_e32 v13, v172, v178
	v_fma_f32 v172, v183, v178, v12
	v_fma_f32 v173, v183, v179, v13
	v_fma_f32 v12, v183, v178, -v12
	v_fma_f32 v13, v183, v179, -v13
	v_sub_f32_e32 v176, v180, v181
	v_sub_f32_e32 v177, v180, v181
	v_mov_b32_e32 v173, v13
	v_add_f32_e32 v12, v185, v184
	v_add_f32_e32 v13, v185, v184
	v_mul_f32_e32 v176, v176, v151
	v_mul_f32_e32 v177, v177, v150
	v_sub_f32_e32 v184, v2, v153
	v_sub_f32_e32 v185, v3, v152
	v_fma_f32 v178, v12, v150, v176
	v_fma_f32 v179, v13, v151, v177
	v_fma_f32 v12, v12, v150, -v176
	v_fma_f32 v13, v13, v151, -v177
	v_sub_f32_e32 v150, v194, v172
	v_sub_f32_e32 v151, v195, v173
	v_mov_b32_e32 v179, v13
	v_add_f32_e32 v12, v194, v172
	v_add_f32_e32 v13, v195, v173
	v_add_f32_e32 v172, v190, v178
	v_add_f32_e32 v173, v191, v179
	v_sub_f32_e32 v176, v190, v178
	v_sub_f32_e32 v177, v191, v179
	v_add_f32_e32 v178, v12, v172
	v_add_f32_e32 v179, v13, v173
	v_sub_f32_e32 v12, v12, v172
	v_sub_f32_e32 v13, v13, v173
	v_sub_f32_e32 v172, v150, v177
	v_sub_f32_e32 v173, v151, v176
	v_add_f32_e32 v180, v150, v176
	v_add_f32_e32 v181, v151, v176
	v_add_f32_e32 v2, v2, v153
	v_add_f32_e32 v3, v3, v152
	v_mov_b32_e32 v173, v181
	v_add_f32_e32 v180, v150, v177
	v_add_f32_e32 v181, v151, v176
	v_sub_f32_e32 v150, v150, v176
	v_sub_f32_e32 v151, v151, v176
	v_pk_mov_b32 v[188:189], v[2:3], v[184:185] op_sel:[1,0]
	v_add_u32_e32 v150, 0x400, v202
	v_cvt_f32_i32_e32 v150, v150
	v_mov_b32_e32 v181, v151
	v_mov_b32_e32 v152, v184
	v_mov_b32_e32 v153, v3
	v_mul_f32_e32 v151, 0x38800000, v150
	v_sin_f32_e32 v176, v151
	v_cos_f32_e32 v150, v151
	v_sub_f32_e32 v194, v4, v171
	v_sub_f32_e32 v195, v4, v171
	v_mul_f32_e32 v188, v176, v188
	v_mul_f32_e32 v189, v176, v189
	v_xor_b32_e32 v182, 0x80000000, v176
; __device__ __forceinline__ cf cmul(cf a, cf b) { return mk2(a.x * b.x - a.y * b.y, a.x * b.y + a.y * b.x); }
; __device__ __forceinline__ cf cmulc(cf a, cf b) { return mk2(a.x * b.x + a.y * b.y, a.y * b.x - a.x * b.y); }
; __device__ __forceinline__ cf twid(float frac) { return mk2(__builtin_amdgcn_cosf(frac), -__builtin_amdgcn_sinf(frac)); }
; template <int LG, bool INV> __device__ __forceinline__ void fft_pass2(LAS cf* X, int tid) {
;     ...
;         const cf v1 = twid((float)(4 * j) * fL), v2 = cmul(v1, v1), v3 = cmul(v2, v1);
;         if (!INV) {
; #pragma unroll
;             for (int r = 0; r < 4; ++r) { bfly4_fwd(e[r][0], e[r][1], e[r][2], e[r][3]);
;                 const cf w1 = twid((float)(j + r * L16) * fL), w2 = cmul(w1, w1), w3 = cmul(w2, w1);
;                 e[r][1] = cmul(e[r][1], w1); e[r][2] = cmul(e[r][2], w2); e[r][3] = cmul(e[r][3], w3); }
; #pragma unroll
;             for (int p = 0; p < 4; ++p) { bfly4_fwd(e[0][p], e[1][p], e[2][p], e[3][p]); e[1][p] = cmul(e[1][p], v1); e[2][p] = cmul(e[2][p], v2); e[3][p] = cmul(e[3][p], v3); }
;         } else {
; #pragma unroll
;             for (int p = 0; p < 4; ++p) { e[1][p] = cmulc(e[1][p], v1); e[2][p] = cmulc(e[2][p], v2); e[3][p] = cmulc(e[3][p], v3); bfly4_inv(e[0][p], e[1][p], e[2][p], e[3][p]); }
; #pragma unroll
;             for (int r = 0; r < 4; ++r) { const cf w1 = twid((float)(j + r * L16) * fL), w2 = cmul(w1, w1), w3 = cmul(w2, w1);
;                 e[r][1] = cmulc(e[r][1], w1); e[r][2] = cmulc(e[r][2], w2); e[r][3] = cmulc(e[r][3], w3); bfly4_inv(e[r][0], e[r][1], e[r][2], e[r][3]); }
	v_fma_f32 v190, v150, v184, -v188
	v_fma_f32 v191, v151, v185, -v189
	v_fma_f32 v152, v150, v152, v188
	v_fma_f32 v153, v150, v153, v189
	v_mov_b32_e32 v191, v153
	v_mov_b32_e32 v151, v176
	v_mov_b32_e32 v152, v182
	v_mov_b32_e32 v153, v176
	v_mov_b32_e32 v183, v150
	v_mul_f32_e32 v152, v150, v152
	v_mul_f32_e32 v153, v151, v153
	v_mov_b32_e32 v177, v150
	v_fma_f32 v188, v150, v182, v152
	v_fma_f32 v189, v150, v183, v153
	v_fma_f32 v152, v150, v182, -v152
	v_fma_f32 v153, v150, v183, -v153
	v_mov_b32_e32 v183, v153
	v_pk_mov_b32 v[152:153], v[152:153], v[188:189] op_sel:[1,0]
	v_mov_b32_e32 v182, v188
	v_mul_f32_e32 v152, v152, v194
	v_mul_f32_e32 v153, v153, v195
	v_mul_f32_e32 v176, v176, v182
	v_mul_f32_e32 v177, v177, v183
	v_fma_f32 v188, v188, v192, v152
	v_fma_f32 v189, v189, v193, v153
	v_fma_f32 v152, v182, v192, -v152
	v_fma_f32 v153, v183, v193, -v153
	v_mul_f32_e32 v150, v150, v182
	v_mul_f32_e32 v151, v151, v183
	v_mov_b32_e32 v189, v153
	v_sub_f32_e32 v152, v6, v15
	v_sub_f32_e32 v153, v7, v14
	v_add_f32_e32 v182, v6, v15
	v_add_f32_e32 v183, v7, v14
	v_pk_add_f32 v[150:151], v[150:151], v[150:151] op_sel:[0,1] op_sel_hi:[0,1] neg_lo:[0,1] neg_hi:[0,1]
	v_mov_b32_e32 v193, v183
	v_pk_mov_b32 v[182:183], v[182:183], v[152:153] op_sel:[1,0]
	v_mov_b32_e32 v192, v152
	v_pk_add_f32 v[176:177], v[176:177], v[176:177] op_sel:[1,0] op_sel_hi:[1,0]
	v_mul_f32_e32 v150, v150, v182
	v_mul_f32_e32 v151, v151, v183
	s_nop 0
	v_fma_f32 v152, v176, v152, v150
	v_fma_f32 v153, v177, v153, v151
	v_fma_f32 v150, v176, v192, -v150
	v_fma_f32 v151, v177, v193, -v151
	v_sub_f32_e32 v176, v186, v188
	v_sub_f32_e32 v177, v187, v189
	v_mov_b32_e32 v153, v151
	v_add_f32_e32 v150, v186, v188
	v_add_f32_e32 v151, v187, v189
	v_add_f32_e32 v182, v190, v152
	v_add_f32_e32 v183, v191, v153
	v_sub_f32_e32 v152, v190, v152
	v_sub_f32_e32 v153, v191, v153
	v_add_f32_e32 v186, v150, v182
	v_add_f32_e32 v187, v151, v183
	v_sub_f32_e32 v150, v150, v182
	v_sub_f32_e32 v151, v151, v183
	v_sub_f32_e32 v182, v176, v153
	v_sub_f32_e32 v183, v177, v152
	v_add_f32_e32 v188, v176, v152
	v_add_f32_e32 v189, v177, v152
	s_nop 0
	v_mov_b32_e32 v183, v189
	v_add_f32_e32 v188, v176, v153
	v_add_f32_e32 v189, v177, v152
	v_sub_f32_e32 v153, v177, v152
	v_sub_f32_e32 v152, v176, v152
	s_nop 0
	v_add_u32_e32 v152, 0x800, v202
	v_cvt_f32_i32_e32 v152, v152
	v_mov_b32_e32 v189, v153
	v_mul_f32_e32 v153, 0x38800000, v152
	v_cos_f32_e32 v152, v153
	v_sin_f32_e32 v153, v153
	v_mov_b32_e32 v177, v152
	v_xor_b32_e32 v176, 0x80000000, v153
	v_mov_b32_e32 v190, v176
	v_mov_b32_e32 v191, v153
	v_mul_f32_e32 v190, v152, v190
	v_mul_f32_e32 v191, v153, v191
	v_mov_b32_e32 v198, v153
	v_fma_f32 v192, v152, v176, -v190
	v_fma_f32 v193, v152, v177, -v191
	v_fma_f32 v176, v152, v176, v190
	v_fma_f32 v177, v152, v177, v191
	v_mul_f32_e32 v199, v198, v0
	v_mul_f32_e32 v198, v198, v1
	v_mov_b32_e32 v190, v176
	v_mov_b32_e32 v191, v193
	v_fma_f32 v200, v152, v0, -v198
	v_fma_f32 v201, v153, v1, -v199
	v_fma_f32 v0, v152, v0, v198
	v_fma_f32 v1, v152, v1, v199
	v_mul_f32_e32 v194, v153, v190
	v_mul_f32_e32 v195, v152, v191
	v_mul_f32_e32 v190, v152, v190
	v_mul_f32_e32 v191, v153, v191
	v_mov_b32_e32 v201, v1
	v_mul_f32_e32 v0, v176, v11
	v_mul_f32_e32 v1, v176, v10
	v_fma_f32 v152, v193, v10, v0
	v_fma_f32 v153, v193, v11, v1
	v_fma_f32 v0, v193, v10, -v0
	v_fma_f32 v1, v193, v11, -v1
	v_sub_f32_e32 v10, v190, v191
	v_sub_f32_e32 v11, v190, v191
	v_mov_b32_e32 v153, v1
	v_add_f32_e32 v0, v195, v194
	v_add_f32_e32 v1, v195, v194
	v_mul_f32_e32 v10, v10, v9
	v_mul_f32_e32 v11, v11, v8
	v_mov_b32_e32 v193, v185
	v_fma_f32 v176, v0, v8, v10
	v_fma_f32 v177, v1, v9, v11
	v_fma_f32 v0, v0, v8, -v10
	v_fma_f32 v1, v1, v9, -v11
	v_sub_f32_e32 v8, v174, v152
	v_sub_f32_e32 v9, v175, v153
	v_mov_b32_e32 v177, v1
	v_add_f32_e32 v0, v174, v152
	v_add_f32_e32 v1, v175, v153
	v_add_f32_e32 v10, v200, v176
	v_add_f32_e32 v11, v201, v177
	v_sub_f32_e32 v152, v200, v176
	v_sub_f32_e32 v153, v201, v177
	v_add_f32_e32 v174, v0, v10
	v_add_f32_e32 v175, v1, v11
	v_sub_f32_e32 v0, v0, v10
	v_sub_f32_e32 v1, v1, v11
	v_sub_f32_e32 v10, v8, v153
	v_sub_f32_e32 v11, v9, v152
	v_add_f32_e32 v176, v8, v152
	v_add_f32_e32 v177, v9, v152
	v_pk_mov_b32 v[184:185], v[184:185], v[2:3] op_sel:[1,0]
	v_mov_b32_e32 v11, v177
	v_add_f32_e32 v176, v8, v153
	v_add_f32_e32 v177, v9, v152
	v_sub_f32_e32 v8, v8, v152
	v_sub_f32_e32 v9, v9, v152
	v_mov_b32_e32 v192, v2
	v_add_u32_e32 v8, 0xc00, v202
	v_cvt_f32_i32_e32 v8, v8
	v_mov_b32_e32 v177, v9
	v_sub_f32_e32 v198, v5, v170
	v_sub_f32_e32 v199, v5, v170
	v_add_f32_e32 v5, v4, v171
	v_add_f32_e32 v4, v4, v171
	v_mul_f32_e32 v9, 0x38800000, v8
	v_sin_f32_e32 v152, v9
	v_cos_f32_e32 v8, v9
	v_mul_f32_e32 v184, v152, v184
	v_mul_f32_e32 v185, v152, v185
	v_xor_b32_e32 v190, 0x80000000, v152
	v_fma_f32 v2, v8, v2, -v184
	v_fma_f32 v3, v9, v3, -v185
	v_fma_f32 v184, v8, v192, v184
	v_fma_f32 v185, v8, v193, v185
	v_mov_b32_e32 v3, v185
	v_mov_b32_e32 v9, v152
	v_mov_b32_e32 v184, v190
	v_mov_b32_e32 v185, v152
	v_mov_b32_e32 v191, v8
	v_mul_f32_e32 v152, v8, v184
	v_mul_f32_e32 v153, v9, v185
	s_nop 0
	v_fma_f32 v184, v8, v190, v152
	v_fma_f32 v185, v8, v191, v153
	v_fma_f32 v152, v8, v190, -v152
	v_fma_f32 v153, v8, v191, -v153
	v_mov_b32_e32 v191, v153
	v_pk_mov_b32 v[152:153], v[152:153], v[184:185] op_sel:[1,0]
	v_mov_b32_e32 v190, v184
	v_mul_f32_e32 v192, v9, v152
	v_mul_f32_e32 v193, v9, v153
	v_mul_f32_e32 v4, v152, v4
	v_mul_f32_e32 v5, v153, v5
	v_fma_f32 v194, v8, v190, -v192
	v_fma_f32 v195, v8, v191, -v193
	v_fma_f32 v9, v8, v191, v193
	v_fma_f32 v8, v8, v190, v192
; __device__ __forceinline__ cf cmul(cf a, cf b) { return mk2(a.x * b.x - a.y * b.y, a.x * b.y + a.y * b.x); }
; __device__ __forceinline__ cf cmulc(cf a, cf b) { return mk2(a.x * b.x + a.y * b.y, a.y * b.x - a.x * b.y); }
; __device__ __forceinline__ cf twid(float frac) { return mk2(__builtin_amdgcn_cosf(frac), -__builtin_amdgcn_sinf(frac)); }
; template <int LG, bool INV> __device__ __forceinline__ void fft_pass2(LAS cf* X, int tid) {
;     ...
;             for (int r = 0; r < 4; ++r) { const cf w1 = twid((float)(j + r * L16) * fL), w2 = cmul(w1, w1), w3 = cmul(w2, w1);
;                 e[r][1] = cmulc(e[r][1], w1); e[r][2] = cmulc(e[r][2], w2); e[r][3] = cmulc(e[r][3], w3); bfly4_inv(e[r][0], e[r][1], e[r][2], e[r][3]); }
;         }
; #pragma unroll
;         for (int r = 0; r < 4; ++r)
; #pragma unroll
;             for (int m = 0; m < 4; ++m) X[pb + POFF(r, m)] = e[r][m];
;     }
;     ...
;     __syncthreads();
; __global__ void __launch_bounds__(NTHR, 2) fwd_mega(Args a) {
;     ...
; #pragma unroll 1
;                     for (int k = 0; k < 2; ++k) { const int ch = 64 * (wave + 8 * k) + cw; float a0_[8], a1_[8];
;                         conv8(pv0 + 256 * 8192, ch, 8192, wa0, wa1, wa2, ba, a0_); conv8(pv1 + 256 * 8192, ch, 8192, wa0, wa1, wa2, ba, a1_);
; #pragma unroll
;                         for (int e = 0; e < 8; ++e) { const cf cv = X[PX(8 * ch + e)]; X[PX(8 * ch + e)] = mk2(a0_[e] * cv.x, a1_[e] * cv.y); X[PX(8192 + 8 * ch + e)] = mk2(0.f, 0.f); } }
;                     __syncthreads();
	v_fma_f32 v152, v184, v198, v4
	v_fma_f32 v153, v185, v199, v5
	v_fma_f32 v4, v190, v198, -v4
	v_fma_f32 v5, v191, v199, -v5
	v_mov_b32_e32 v193, v9
	v_mov_b32_e32 v153, v5
	v_sub_f32_e32 v4, v7, v14
	v_sub_f32_e32 v5, v7, v14
	v_pk_mov_b32 v[8:9], v[8:9], v[194:195] op_sel:[1,0]
	v_add_f32_e32 v7, v6, v15
	v_add_f32_e32 v6, v6, v15
	v_mov_b32_e32 v192, v194
	v_mul_f32_e32 v6, v8, v6
	v_mul_f32_e32 v7, v9, v7
	s_nop 0
	v_fma_f32 v8, v194, v4, v6
	v_fma_f32 v9, v195, v5, v7
	v_fma_f32 v4, v192, v4, -v6
	v_fma_f32 v5, v193, v5, -v7
	v_sub_f32_e32 v6, v196, v152
	v_sub_f32_e32 v7, v197, v153
	v_mov_b32_e32 v9, v5
	v_add_f32_e32 v4, v196, v152
	v_add_f32_e32 v5, v197, v153
	v_add_f32_e32 v14, v2, v8
	v_add_f32_e32 v15, v3, v9
	v_sub_f32_e32 v2, v2, v8
	v_sub_f32_e32 v3, v3, v9
	v_add_f32_e32 v8, v4, v14
	v_add_f32_e32 v9, v5, v15
	v_sub_f32_e32 v4, v4, v14
	v_sub_f32_e32 v5, v5, v15
	v_sub_f32_e32 v14, v6, v3
	v_sub_f32_e32 v15, v7, v2
	v_add_f32_e32 v152, v6, v2
	v_add_f32_e32 v153, v7, v2
	s_nop 0
	v_mov_b32_e32 v15, v153
	v_add_f32_e32 v152, v6, v3
	v_add_f32_e32 v153, v7, v2
	v_sub_f32_e32 v3, v7, v2
	v_sub_f32_e32 v2, v6, v2
	s_nop 0
	v_mov_b32_e32 v153, v3
	ds_write_b64 v203, v[178:179]
	ds_write_b64 v203, v[172:173] offset:33280
	ds_write_b64 v204, v[12:13]
	ds_write_b64 v205, v[180:181]
	ds_write_b64 v203, v[186:187] offset:8320
	ds_write_b64 v203, v[182:183] offset:41600
	ds_write_b64 v206, v[150:151]
	ds_write_b64 v207, v[188:189]
	ds_write_b64 v203, v[174:175] offset:16640
	ds_write_b64 v203, v[10:11] offset:49920
	ds_write_b64 v208, v[0:1]
	ds_write_b64 v210, v[176:177]
	ds_write_b64 v203, v[8:9] offset:24960
	ds_write_b64 v203, v[14:15] offset:58240
	ds_write_b64 v211, v[4:5]
	ds_write_b64 v212, v[152:153]
	s_cbranch_vccnz .LBB0_554
	s_add_u32 s4, s36, 0x400000
	s_addc_u32 s5, s37, 0
	s_add_u32 s6, s80, 0x400000
	s_addc_u32 s7, s81, 0
	s_mov_b32 s13, 0
	s_mov_b64 s[68:69], -1
	s_waitcnt lgkmcnt(0)
	s_barrier
	s_branch .LBB0_557
.LBB0_556:
	s_or_b64 exec, exec, s[10:11]
	s_waitcnt vmcnt(0) lgkmcnt(0)
	v_and_b32_e32 v11, 0xffff0000, v4
	v_lshlrev_b32_e32 v10, 16, v4
	v_lshlrev_b32_e32 v150, 16, v5
	v_lshlrev_b32_e32 v151, 16, v6
	v_and_b32_e32 v153, 0xffff0000, v6
	v_mul_f32_e32 v4, v167, v15
	v_mul_f32_e32 v6, v135, v11
	v_and_b32_e32 v5, 0xffff0000, v5
	v_fmac_f32_e32 v4, v135, v10
	v_fmac_f32_e32 v6, v167, v10
	v_mul_f32_e32 v10, v135, v150
	v_fmac_f32_e32 v4, v134, v11
	v_fmac_f32_e32 v10, v167, v11
	v_mul_f32_e32 v11, v135, v5
	v_fmac_f32_e32 v11, v167, v150
	v_fmac_f32_e32 v11, v134, v151
	v_fmac_f32_e32 v6, v134, v150
	v_add_f32_e32 v150, v168, v11
	v_mul_f32_e32 v11, v135, v151
	v_fmac_f32_e32 v10, v134, v5
	v_fmac_f32_e32 v11, v167, v5
	v_mul_f32_e32 v5, v135, v153
	v_lshlrev_b32_e32 v171, 16, v7
	v_fmac_f32_e32 v5, v167, v151
	v_fmac_f32_e32 v5, v134, v171
	v_add_f32_e32 v170, v168, v5
	v_mul_f32_e32 v5, v135, v171
	v_and_b32_e32 v7, 0xffff0000, v7
	v_fmac_f32_e32 v5, v167, v153
	v_and_b32_e32 v176, 0xffff0000, v0
	v_fmac_f32_e32 v5, v134, v7
	v_lshlrev_b32_e32 v179, 16, v0
	v_mov_b32_e32 v178, v176
	v_add_f32_e32 v172, v168, v5
	v_mul_f32_e32 v5, v135, v7
	v_mul_f32_e32 v180, v134, v178
	v_mul_f32_e32 v181, v135, v179
	v_fmac_f32_e32 v5, v167, v171
	v_and_b32_e32 v177, 16, v0
	v_fma_f32 v0, v167, v14, v181
	v_fmac_f32_e32 v5, v134, v13
	v_add_f32_e32 v0, v180, v0
	v_and_b32_e32 v14, 0xffff0000, v1
	v_add_f32_e32 v174, v168, v5
	v_add_f32_e32 v5, v168, v0
	v_and_b32_e32 v15, 16, v1
	v_lshlrev_b32_e32 v1, 16, v1
	v_mov_b32_e32 v0, v14
	v_pk_mov_b32 v[180:181], v[0:1], v[176:177] op_sel:[1,0]
	v_fmac_f32_e32 v11, v134, v153
	v_mul_f32_e32 v180, v134, v180
	v_mul_f32_e32 v181, v135, v181
	v_add_f32_e32 v152, v168, v11
	v_fma_f32 v7, v167, v179, v181
	v_mul_f32_e32 v178, v134, v0
	v_mul_f32_e32 v179, v135, v1
	v_add_f32_e32 v7, v180, v7
	v_fma_f32 v0, v167, v176, v179
	v_add_f32_e32 v0, v178, v0
	v_add_f32_e32 v11, v168, v0
	v_and_b32_e32 v0, -8, v12
	v_lshlrev_b32_e32 v12, 3, v8
	v_add3_u32 v180, 0, v0, v12
	ds_read_b64 v[176:177], v180
	v_add_u32_e32 v0, 0x2000, v8
	v_ashrrev_i32_e32 v8, 6, v0
	v_add_f32_e32 v4, v168, v4
	v_lshlrev_b32_e32 v8, 3, v8
	v_lshlrev_b32_e32 v0, 3, v0
	s_mov_b32 s65, s64
	v_add3_u32 v181, 0, v8, v0
	s_waitcnt lgkmcnt(0)
	v_mul_f32_e32 v4, v4, v176
	v_mul_f32_e32 v5, v5, v177
	v_mov_b64_e32 v[182:183], s[64:65]
	ds_write_b64 v180, v[4:5]
	ds_write_b64 v181, v[182:183]
	ds_read_b64 v[4:5], v180 offset:8
	v_add_f32_e32 v6, v168, v6
	v_add_f32_e32 v7, v168, v7
	v_and_b32_e32 v12, 0xffff0000, v2
	v_lshlrev_b32_e32 v177, 16, v2
	s_waitcnt lgkmcnt(0)
	v_mul_f32_e32 v4, v6, v4
	v_mul_f32_e32 v5, v7, v5
	ds_write_b64 v180, v[4:5] offset:8
	ds_write_b64 v181, v[182:183] offset:8
	v_mov_b32_e32 v176, v12
	ds_read_b64 v[4:5], v180 offset:16
	v_pk_mov_b32 v[178:179], v[176:177], v[14:15] op_sel:[1,0]
	v_add_f32_e32 v10, v168, v10
	v_mul_f32_e32 v6, v134, v178
	v_mul_f32_e32 v7, v135, v179
	v_and_b32_e32 v13, 16, v2
	v_fma_f32 v0, v167, v1, v7
	v_add_f32_e32 v0, v6, v0
	v_add_f32_e32 v151, v168, v0
	s_waitcnt lgkmcnt(0)
	v_mul_f32_e32 v0, v10, v4
	v_mul_f32_e32 v1, v11, v5
	ds_write_b64 v180, v[0:1] offset:16
	ds_write_b64 v181, v[182:183] offset:16
	ds_read_b64 v[0:1], v180 offset:24
	v_mul_f32_e32 v4, v134, v176
	v_mul_f32_e32 v5, v135, v177
	s_xor_b64 s[10:11], s[68:69], -1
	v_fma_f32 v2, v167, v14, v5
	v_add_f32_e32 v2, v4, v2
	s_waitcnt lgkmcnt(0)
	v_mul_f32_e32 v0, v150, v0
	v_mul_f32_e32 v1, v151, v1
	ds_write_b64 v180, v[0:1] offset:24
	ds_write_b64 v181, v[182:183] offset:24
	ds_read_b64 v[0:1], v180 offset:32
	v_add_f32_e32 v153, v168, v2
	v_and_b32_e32 v2, 0xffff0000, v3
	v_lshlrev_b32_e32 v3, 16, v3
	v_pk_mov_b32 v[4:5], v[2:3], v[12:13] op_sel:[1,0]
	s_waitcnt lgkmcnt(0)
	v_mul_f32_e32 v0, v152, v0
	v_mul_f32_e32 v1, v153, v1
	ds_write_b64 v180, v[0:1] offset:32
	ds_write_b64 v181, v[182:183] offset:32
	ds_read_b64 v[0:1], v180 offset:40
	v_mul_f32_e32 v4, v134, v4
	v_mul_f32_e32 v5, v135, v5
	v_mov_b32_e32 v8, v2
	v_fma_f32 v5, v167, v177, v5
	v_add_f32_e32 v4, v4, v5
	v_add_f32_e32 v171, v168, v4
	s_waitcnt lgkmcnt(0)
	v_mul_f32_e32 v0, v170, v0
	v_mul_f32_e32 v1, v171, v1
	ds_write_b64 v180, v[0:1] offset:40
	ds_write_b64 v181, v[182:183] offset:40
	ds_read_b64 v[0:1], v180 offset:48
	v_mul_f32_e32 v4, v134, v2
	v_mul_f32_e32 v5, v135, v3
	s_movk_i32 s13, 0x200
	v_fma_f32 v5, v167, v12, v5
	v_add_f32_e32 v4, v4, v5
	v_add_f32_e32 v173, v168, v4
	s_waitcnt lgkmcnt(0)
	v_mul_f32_e32 v0, v172, v0
	v_mul_f32_e32 v1, v173, v1
	ds_write_b64 v180, v[0:1] offset:48
	ds_write_b64 v181, v[182:183] offset:48
	ds_read_b64 v[0:1], v180 offset:56
	v_mul_f32_e32 v4, v140, v8
	v_mul_f32_e32 v5, v141, v9
	s_mov_b64 s[68:69], 0
	v_fma_f32 v2, v167, v3, v4
	v_add_f32_e32 v2, v2, v5
	v_add_f32_e32 v175, v168, v2
	s_waitcnt lgkmcnt(0)
	v_mul_f32_e32 v0, v174, v0
	v_mul_f32_e32 v1, v175, v1
	s_and_b64 vcc, exec, s[10:11]
	ds_write_b64 v180, v[0:1] offset:56
	ds_write_b64 v181, v[182:183] offset:56
	s_cbranch_vccnz .LBB0_565

; #define LAS __attribute__((address_space(3)))
; __device__ __forceinline__ cf cmul(cf a, cf b) { return mk2(a.x * b.x - a.y * b.y, a.x * b.y + a.y * b.x); }
; __device__ __forceinline__ void fft_mid_mul(LAS cf* X, int tid, const cf* KFR) {
; #pragma unroll 2
;     for (int i = 0; i < 8; ++i) { const int it = tid + 512 * i, g = it & 255, k = it >> 8, base = g * 64 + 4 * k; const cf* q = KFR + (4 * k) * 256 + g;
;         cf e0 = X[PX(base)], e1 = X[PX(base + 1)], e2 = X[PX(base + 2)], e3 = X[PX(base + 3)];
;         const cf k0 = ld_f2_l2(q), k1 = ld_f2_l2(q + 256), k2 = ld_f2_l2(q + 512), k3 = ld_f2_l2(q + 768);
;         bfly4_fwd(e0, e1, e2, e3);
;         e0 = cmul(e0, k0); e1 = cmul(e1, k1); e2 = cmul(e2, k2); e3 = cmul(e3, k3);
;         bfly4_inv(e0, e1, e2, e3);
;         X[PX(base)] = e0; X[PX(base + 1)] = e1; X[PX(base + 2)] = e2; X[PX(base + 3)] = e3; }
;     __syncthreads();
; }
.LBB0_572:
	v_add_u32_e32 v170, s4, v16
	v_ashrrev_i32_e32 v0, 6, v170
	v_and_b32_e32 v0, -4, v0
	v_add_u32_e32 v2, v0, v157
	v_lshlrev_b32_e32 v0, 8, v0
	v_ashrrev_i32_e32 v1, 31, v0
	v_lshl_add_u64 v[8:9], v[0:1], 3, v[142:143]
	v_ashrrev_i32_e32 v0, 6, v2
	v_lshlrev_b32_e32 v0, 3, v0
	v_lshlrev_b32_e32 v1, 3, v2
	v_add3_u32 v171, 0, v0, v1
	ds_read2_b64 v[0:3], v171 offset1:1
	ds_read2_b64 v[4:7], v171 offset0:2 offset1:3
	global_load_dwordx2 v[10:11], v[8:9], off sc1
	global_load_dwordx2 v[12:13], v[8:9], off offset:2048 sc1
	v_add_co_u32_e32 v8, vcc, s96, v8
	s_addk_i32 s4, 0x400
	s_nop 0
	v_addc_co_u32_e32 v9, vcc, 0, v9, vcc
	global_load_dwordx2 v[14:15], v[8:9], off sc1
	s_nop 0
	global_load_dwordx2 v[8:9], v[8:9], off offset:2048 sc1
	s_waitcnt lgkmcnt(0)
	v_add_f32_e32 v150, v0, v4
	v_add_f32_e32 v151, v1, v5
	v_sub_f32_e32 v0, v0, v4
	v_sub_f32_e32 v1, v1, v5
	v_add_f32_e32 v4, v2, v6
	v_add_f32_e32 v5, v3, v7
	v_sub_f32_e32 v2, v2, v6
	v_sub_f32_e32 v3, v3, v7
	v_add_f32_e32 v6, v150, v4
	v_add_f32_e32 v7, v151, v5
	v_sub_f32_e32 v4, v150, v4
	v_sub_f32_e32 v5, v151, v5
	s_cmpk_lg_i32 s4, 0x1000
	s_waitcnt vmcnt(0)
	v_mul_f32_e32 v150, v7, v11
	v_mul_f32_e32 v151, v7, v10
	s_nop 0
	v_fma_f32 v152, v6, v10, -v150
	v_fma_f32 v153, v7, v11, -v151
	v_fma_f32 v7, v6, v11, v151
	v_fma_f32 v6, v6, v10, v150
	v_sub_f32_e32 v10, v1, v2
	v_sub_f32_e32 v11, v1, v2
	v_mov_b32_e32 v153, v7
	v_add_f32_e32 v6, v0, v3
	v_add_f32_e32 v7, v0, v3
	v_mul_f32_e32 v10, v10, v13
	v_mul_f32_e32 v11, v11, v12
	s_nop 0
	v_fma_f32 v150, v6, v12, -v10
	v_fma_f32 v151, v7, v13, -v11
	v_fma_f32 v6, v6, v12, v10
	v_fma_f32 v7, v7, v13, v11
	s_nop 0
	v_mov_b32_e32 v151, v7
	v_mul_f32_e32 v6, v5, v15
	v_mul_f32_e32 v7, v5, v14
	s_nop 0
	v_fma_f32 v10, v4, v14, -v6
	v_fma_f32 v11, v5, v15, -v7
	v_fma_f32 v5, v4, v15, v7
	v_fma_f32 v4, v4, v14, v6
	v_mov_b32_e32 v11, v5
	v_sub_f32_e32 v4, v0, v3
	v_sub_f32_e32 v5, v0, v3
	v_add_f32_e32 v0, v1, v2
	v_add_f32_e32 v1, v1, v2
	s_nop 0
	v_mul_f32_e32 v0, v0, v9
	v_mul_f32_e32 v1, v1, v8
	s_nop 0
	v_fma_f32 v2, v4, v8, -v0
	v_fma_f32 v3, v5, v9, -v1
	v_fma_f32 v0, v4, v8, v0
	v_fma_f32 v1, v5, v9, v1
	v_sub_f32_e32 v4, v152, v10
	v_sub_f32_e32 v5, v153, v11
	v_mov_b32_e32 v3, v1
	v_add_f32_e32 v0, v152, v10
	v_add_f32_e32 v1, v153, v11
	v_add_f32_e32 v6, v150, v2
	v_add_f32_e32 v7, v151, v3
	v_sub_f32_e32 v2, v150, v2
	v_sub_f32_e32 v3, v151, v3
	v_add_f32_e32 v8, v0, v6
	v_add_f32_e32 v9, v1, v7
	v_sub_f32_e32 v0, v0, v6
	v_sub_f32_e32 v1, v1, v7
	v_sub_f32_e32 v6, v4, v3
	v_sub_f32_e32 v7, v5, v2
	v_add_f32_e32 v10, v4, v2
	v_add_f32_e32 v11, v5, v2
	v_add_f32_e32 v12, v4, v3
	v_add_f32_e32 v13, v5, v2
	v_sub_f32_e32 v3, v5, v2
	v_sub_f32_e32 v2, v4, v2
	v_mov_b32_e32 v7, v11
	v_mov_b32_e32 v13, v3
	ds_write2_b64 v171, v[0:1], v[12:13] offset0:2 offset1:3
	v_add_u32_e32 v0, 0x200, v170
	v_ashrrev_i32_e32 v0, 6, v0
	v_and_b32_e32 v0, -4, v0
	v_add_u32_e32 v2, v0, v157
	v_lshlrev_b32_e32 v0, 8, v0
	v_ashrrev_i32_e32 v1, 31, v0
	ds_write2_b64 v171, v[8:9], v[6:7] offset1:1
	v_lshl_add_u64 v[8:9], v[0:1], 3, v[142:143]
	v_ashrrev_i32_e32 v0, 6, v2
	v_lshlrev_b32_e32 v0, 3, v0
	v_lshlrev_b32_e32 v1, 3, v2
	v_add3_u32 v170, 0, v0, v1
	ds_read2_b64 v[0:3], v170 offset1:1
	ds_read2_b64 v[4:7], v170 offset0:2 offset1:3
	global_load_dwordx2 v[10:11], v[8:9], off sc1
	global_load_dwordx2 v[12:13], v[8:9], off offset:2048 sc1
	v_add_co_u32_e32 v8, vcc, s96, v8
	s_waitcnt lgkmcnt(0)
	v_add_f32_e32 v150, v0, v4
	v_add_f32_e32 v151, v1, v5
	v_addc_co_u32_e32 v9, vcc, 0, v9, vcc
	global_load_dwordx2 v[14:15], v[8:9], off sc1
	s_nop 0
	global_load_dwordx2 v[8:9], v[8:9], off offset:2048 sc1
	v_sub_f32_e32 v0, v0, v4
	v_sub_f32_e32 v1, v1, v5
	v_add_f32_e32 v4, v2, v6
	v_add_f32_e32 v5, v3, v7
	v_sub_f32_e32 v2, v2, v6
	v_sub_f32_e32 v3, v3, v7
	v_add_f32_e32 v6, v150, v4
	v_add_f32_e32 v7, v151, v5
	v_sub_f32_e32 v4, v150, v4
	v_sub_f32_e32 v5, v151, v5
	s_waitcnt vmcnt(0)
	v_mul_f32_e32 v150, v7, v11
	v_mul_f32_e32 v151, v7, v10
	s_nop 0
	v_fma_f32 v152, v6, v10, -v150
	v_fma_f32 v153, v7, v11, -v151
	v_fma_f32 v7, v6, v11, v151
	v_fma_f32 v6, v6, v10, v150
	v_sub_f32_e32 v10, v1, v2
	v_sub_f32_e32 v11, v1, v2
	v_mov_b32_e32 v153, v7
	v_add_f32_e32 v6, v0, v3
	v_add_f32_e32 v7, v0, v3
	v_mul_f32_e32 v10, v10, v13
	v_mul_f32_e32 v11, v11, v12
	s_nop 0
	v_fma_f32 v150, v6, v12, -v10
	v_fma_f32 v151, v7, v13, -v11
	v_fma_f32 v6, v6, v12, v10
	v_fma_f32 v7, v7, v13, v11
	s_nop 0
	v_mov_b32_e32 v151, v7
	s_waitcnt lgkmcnt(0)
	v_mul_f32_e32 v6, v5, v15
	v_mul_f32_e32 v7, v5, v14
	s_nop 0
	v_fma_f32 v10, v4, v14, -v6
	v_fma_f32 v11, v5, v15, -v7
	v_fma_f32 v5, v4, v15, v7
	v_fma_f32 v4, v4, v14, v6
	v_mov_b32_e32 v11, v5
	v_sub_f32_e32 v4, v0, v3
	v_sub_f32_e32 v5, v0, v3
	v_add_f32_e32 v0, v1, v2
	v_add_f32_e32 v1, v1, v2
	s_nop 0
	v_mul_f32_e32 v0, v0, v9
	v_mul_f32_e32 v1, v1, v8
	s_nop 0
	v_fma_f32 v2, v4, v8, -v0
	v_fma_f32 v3, v5, v9, -v1
	v_fma_f32 v0, v4, v8, v0
	v_fma_f32 v1, v5, v9, v1
	v_sub_f32_e32 v4, v152, v10
	v_sub_f32_e32 v5, v153, v11
	v_mov_b32_e32 v3, v1
	v_add_f32_e32 v0, v152, v10
	v_add_f32_e32 v1, v153, v11
	v_add_f32_e32 v6, v150, v2
	v_add_f32_e32 v7, v151, v3
	v_sub_f32_e32 v2, v150, v2
	v_sub_f32_e32 v3, v151, v3
	v_add_f32_e32 v8, v0, v6
	v_add_f32_e32 v9, v1, v7
	v_sub_f32_e32 v0, v0, v6
	v_sub_f32_e32 v1, v1, v7
	v_sub_f32_e32 v6, v4, v3
	v_sub_f32_e32 v7, v5, v2
	v_add_f32_e32 v10, v4, v2
	v_add_f32_e32 v11, v5, v2
	v_add_f32_e32 v12, v4, v3
	v_add_f32_e32 v13, v5, v2
	v_sub_f32_e32 v3, v5, v2
	v_sub_f32_e32 v2, v4, v2
	v_mov_b32_e32 v7, v11
	v_mov_b32_e32 v13, v3
	ds_write2_b64 v170, v[8:9], v[6:7] offset1:1
	ds_write2_b64 v170, v[0:1], v[12:13] offset0:2 offset1:3
	s_cbranch_scc1 .LBB0_572
	s_mov_b32 s6, 0
	s_mov_b64 s[4:5], -1
	s_waitcnt lgkmcnt(0)
	s_barrier

; __device__ __forceinline__ cf cmul(cf a, cf b) { return mk2(a.x * b.x - a.y * b.y, a.x * b.y + a.y * b.x); }
; __device__ __forceinline__ cf cmulc(cf a, cf b) { return mk2(a.x * b.x + a.y * b.y, a.y * b.x - a.x * b.y); }
; __device__ __forceinline__ cf twid(float frac) { return mk2(__builtin_amdgcn_cosf(frac), -__builtin_amdgcn_sinf(frac)); }
; template <int LG, bool INV> __device__ __forceinline__ void fft_pass2(LAS cf* X, int tid) {
;     ...
;         const int it = tid + 512 * i; int g, j;
;         if (LG == 14) { g = 0; j = it; } else if (LG == 10) { j = it & 63; g = it >> 6; } else { g = it & 255; j = it >> 8; }
;         const int base = g * L + j;
;         const int pb = PX(base);
;     ...
;         cf e[4][4];
; #pragma unroll
;         for (int r = 0; r < 4; ++r)
; #pragma unroll
;             for (int m = 0; m < 4; ++m) e[r][m] = X[pb + POFF(r, m)];
;         const cf v1 = twid((float)(4 * j) * fL), v2 = cmul(v1, v1), v3 = cmul(v2, v1);
;         if (!INV) {
; #pragma unroll
;             for (int r = 0; r < 4; ++r) { bfly4_fwd(e[r][0], e[r][1], e[r][2], e[r][3]);
;                 const cf w1 = twid((float)(j + r * L16) * fL), w2 = cmul(w1, w1), w3 = cmul(w2, w1);
;                 e[r][1] = cmul(e[r][1], w1); e[r][2] = cmul(e[r][2], w2); e[r][3] = cmul(e[r][3], w3); }
; #pragma unroll
;             for (int p = 0; p < 4; ++p) { bfly4_fwd(e[0][p], e[1][p], e[2][p], e[3][p]); e[1][p] = cmul(e[1][p], v1); e[2][p] = cmul(e[2][p], v2); e[3][p] = cmul(e[3][p], v3); }
;         } else {
; #pragma unroll
;             for (int p = 0; p < 4; ++p) { e[1][p] = cmulc(e[1][p], v1); e[2][p] = cmulc(e[2][p], v2); e[3][p] = cmulc(e[3][p], v3); bfly4_inv(e[0][p], e[1][p], e[2][p], e[3][p]); }
; #pragma unroll
;             for (int r = 0; r < 4; ++r) { const cf w1 = twid((float)(j + r * L16) * fL), w2 = cmul(w1, w1), w3 = cmul(w2, w1);
;                 e[r][1] = cmulc(e[r][1], w1); e[r][2] = cmulc(e[r][2], w2); e[r][3] = cmulc(e[r][3], w3); bfly4_inv(e[r][0], e[r][1], e[r][2], e[r][3]); }
.LBB0_576:
	v_add_u32_e32 v0, s6, v155
	v_and_b32_e32 v0, 0xfffffc00, v0
	v_ashrrev_i32_e32 v1, 3, v0
	v_add_u32_e32 v1, 0, v1
	v_lshlrev_b32_e32 v0, 3, v0
	v_add3_u32 v192, v1, v0, v169
	ds_read2_b64 v[0:3], v192 offset1:65
	v_add_u32_e32 v193, 0x800, v192
	v_add_u32_e32 v194, 0x1000, v192
	v_add_u32_e32 v195, 0x1800, v192
	ds_read2_b64 v[4:7], v193 offset0:4 offset1:69
	ds_read2_b64 v[8:11], v194 offset0:8 offset1:73
	ds_read2_b64 v[12:15], v195 offset0:12 offset1:77
	ds_read2_b64 v[150:153], v192 offset0:130 offset1:195
	ds_read2_b64 v[170:173], v193 offset0:134 offset1:199
	ds_read2_b64 v[174:177], v194 offset0:138 offset1:203
	ds_read2_b64 v[178:181], v195 offset0:142 offset1:207
	s_waitcnt lgkmcnt(7)
	v_mul_f32_e32 v182, v18, v2
	v_mul_f32_e32 v183, v19, v3
	s_movk_i32 s6, 0x2000
	v_fma_f32 v184, v20, v2, -v183
	v_fma_f32 v185, v21, v3, -v182
	v_fma_f32 v2, v20, v2, v183
	v_fma_f32 v3, v21, v3, v182
	s_and_b64 vcc, exec, s[4:5]
	v_mov_b32_e32 v185, v3
	s_waitcnt lgkmcnt(3)
	v_mul_f32_e32 v2, v24, v150
	v_mul_f32_e32 v3, v25, v151
	s_mov_b64 s[4:5], 0
	v_fma_f32 v182, v22, v150, v3
	v_fma_f32 v183, v23, v151, v2
	v_pk_fma_f32 v[2:3], v[22:23], v[150:151], v[2:3] op_sel:[0,0,1] op_sel_hi:[1,1,0] neg_lo:[0,0,1] neg_hi:[0,0,1]
	s_nop 0
	v_mov_b32_e32 v183, v3
	v_mul_f32_e32 v2, v32, v152
	v_mul_f32_e32 v3, v33, v153
	s_nop 0
	v_fma_f32 v150, v30, v152, v3
	v_fma_f32 v151, v31, v153, v2
	v_pk_fma_f32 v[2:3], v[30:31], v[152:153], v[2:3] op_sel:[0,0,1] op_sel_hi:[1,1,0] neg_lo:[0,0,1] neg_hi:[0,0,1]
	s_nop 0
	v_mov_b32_e32 v151, v3
	v_add_f32_e32 v2, v0, v182
	v_add_f32_e32 v3, v1, v183
	v_sub_f32_e32 v0, v0, v182
	v_sub_f32_e32 v1, v1, v183
	v_add_f32_e32 v152, v184, v150
	v_add_f32_e32 v153, v185, v151
	v_sub_f32_e32 v150, v184, v150
	v_sub_f32_e32 v151, v185, v151
	v_add_f32_e32 v182, v2, v152
	v_add_f32_e32 v183, v3, v153
	v_sub_f32_e32 v2, v2, v152
	v_sub_f32_e32 v3, v3, v153
	v_sub_f32_e32 v152, v0, v151
	v_sub_f32_e32 v153, v1, v150
	v_add_f32_e32 v184, v0, v150
	v_add_f32_e32 v185, v1, v150
	s_nop 0
	v_mov_b32_e32 v153, v185
	v_add_f32_e32 v184, v0, v151
	v_add_f32_e32 v185, v1, v150
	v_sub_f32_e32 v0, v0, v150
	v_sub_f32_e32 v1, v1, v150
	s_nop 0
	v_mov_b32_e32 v185, v1
	v_mul_f32_e32 v0, v18, v6
	v_mul_f32_e32 v1, v19, v7
	s_nop 0
	v_fma_f32 v150, v20, v6, -v1
	v_fma_f32 v151, v21, v7, -v0
	v_pk_fma_f32 v[0:1], v[20:21], v[6:7], v[0:1] op_sel:[0,0,1] op_sel_hi:[1,1,0]
	s_nop 0
	v_mov_b32_e32 v151, v1
	s_waitcnt lgkmcnt(2)
	v_mul_f32_e32 v0, v24, v170
	v_mul_f32_e32 v1, v25, v171
	s_nop 0
	v_fma_f32 v6, v22, v170, v1
	v_fma_f32 v7, v23, v171, v0
	v_pk_fma_f32 v[0:1], v[22:23], v[170:171], v[0:1] op_sel:[0,0,1] op_sel_hi:[1,1,0] neg_lo:[0,0,1] neg_hi:[0,0,1]
	s_nop 0
	v_mov_b32_e32 v7, v1
	v_mul_f32_e32 v0, v32, v172
	v_mul_f32_e32 v1, v33, v173
	s_nop 0
	v_fma_f32 v170, v30, v172, v1
	v_fma_f32 v171, v31, v173, v0
	v_pk_fma_f32 v[0:1], v[30:31], v[172:173], v[0:1] op_sel:[0,0,1] op_sel_hi:[1,1,0] neg_lo:[0,0,1] neg_hi:[0,0,1]
	s_nop 0
	v_mov_b32_e32 v171, v1
	v_add_f32_e32 v0, v4, v6
	v_add_f32_e32 v1, v5, v7
	v_sub_f32_e32 v4, v4, v6
	v_sub_f32_e32 v5, v5, v7
	v_add_f32_e32 v6, v150, v170
	v_add_f32_e32 v7, v151, v171
	v_sub_f32_e32 v150, v150, v170
	v_sub_f32_e32 v151, v151, v171
	v_add_f32_e32 v170, v0, v6
	v_add_f32_e32 v171, v1, v7
	v_sub_f32_e32 v0, v0, v6
	v_sub_f32_e32 v1, v1, v7
	v_mul_f32_e32 v6, v18, v10
	v_mul_f32_e32 v7, v19, v11
	s_nop 0
	v_fma_f32 v172, v20, v10, -v7
	v_fma_f32 v173, v21, v11, -v6
	v_pk_fma_f32 v[6:7], v[20:21], v[10:11], v[6:7] op_sel:[0,0,1] op_sel_hi:[1,1,0]
	s_nop 0
	v_mov_b32_e32 v173, v7
	s_waitcnt lgkmcnt(1)
	v_mul_f32_e32 v6, v24, v174
	v_mul_f32_e32 v7, v25, v175
	s_nop 0
	v_fma_f32 v10, v22, v174, v7
	v_fma_f32 v11, v23, v175, v6
	v_pk_fma_f32 v[6:7], v[22:23], v[174:175], v[6:7] op_sel:[0,0,1] op_sel_hi:[1,1,0] neg_lo:[0,0,1] neg_hi:[0,0,1]
	s_nop 0
	v_mov_b32_e32 v11, v7
	v_mul_f32_e32 v6, v32, v176
	v_mul_f32_e32 v7, v33, v177
	s_nop 0
	v_fma_f32 v174, v30, v176, v7
	v_fma_f32 v175, v31, v177, v6
	v_pk_fma_f32 v[6:7], v[30:31], v[176:177], v[6:7] op_sel:[0,0,1] op_sel_hi:[1,1,0] neg_lo:[0,0,1] neg_hi:[0,0,1]
	s_nop 0
	v_mov_b32_e32 v175, v7
	v_add_f32_e32 v6, v8, v10
	v_add_f32_e32 v7, v9, v11
	v_sub_f32_e32 v8, v8, v10
	v_sub_f32_e32 v9, v9, v11
	v_add_f32_e32 v10, v172, v174
	v_add_f32_e32 v11, v173, v175
	v_sub_f32_e32 v172, v172, v174
	v_sub_f32_e32 v173, v173, v175
	v_add_f32_e32 v174, v6, v10
	v_add_f32_e32 v175, v7, v11
	v_sub_f32_e32 v6, v6, v10
	v_sub_f32_e32 v7, v7, v11
	v_mul_f32_e32 v10, v18, v14
	v_mul_f32_e32 v11, v19, v15
	s_nop 0
	v_fma_f32 v176, v20, v14, -v11
	v_fma_f32 v177, v21, v15, -v10
	v_pk_fma_f32 v[10:11], v[20:21], v[14:15], v[10:11] op_sel:[0,0,1] op_sel_hi:[1,1,0]
	s_nop 0
	v_mov_b32_e32 v177, v11
	s_waitcnt lgkmcnt(0)
; __device__ __forceinline__ cf cmul(cf a, cf b) { return mk2(a.x * b.x - a.y * b.y, a.x * b.y + a.y * b.x); }
; __device__ __forceinline__ cf cmulc(cf a, cf b) { return mk2(a.x * b.x + a.y * b.y, a.y * b.x - a.x * b.y); }
; __device__ __forceinline__ cf twid(float frac) { return mk2(__builtin_amdgcn_cosf(frac), -__builtin_amdgcn_sinf(frac)); }
; template <int LG, bool INV> __device__ __forceinline__ void fft_pass2(LAS cf* X, int tid) {
;     ...
;         } else {
; #pragma unroll
;             for (int p = 0; p < 4; ++p) { e[1][p] = cmulc(e[1][p], v1); e[2][p] = cmulc(e[2][p], v2); e[3][p] = cmulc(e[3][p], v3); bfly4_inv(e[0][p], e[1][p], e[2][p], e[3][p]); }
; #pragma unroll
;             for (int r = 0; r < 4; ++r) { const cf w1 = twid((float)(j + r * L16) * fL), w2 = cmul(w1, w1), w3 = cmul(w2, w1);
;                 e[r][1] = cmulc(e[r][1], w1); e[r][2] = cmulc(e[r][2], w2); e[r][3] = cmulc(e[r][3], w3); bfly4_inv(e[r][0], e[r][1], e[r][2], e[r][3]); }
;         }
; #pragma unroll
;         for (int r = 0; r < 4; ++r)
; #pragma unroll
;             for (int m = 0; m < 4; ++m) X[pb + POFF(r, m)] = e[r][m];
	v_mul_f32_e32 v10, v24, v178
	v_mul_f32_e32 v11, v25, v179
	s_nop 0
	v_fma_f32 v14, v22, v178, v11
	v_fma_f32 v15, v23, v179, v10
	v_pk_fma_f32 v[10:11], v[22:23], v[178:179], v[10:11] op_sel:[0,0,1] op_sel_hi:[1,1,0] neg_lo:[0,0,1] neg_hi:[0,0,1]
	s_nop 0
	v_mov_b32_e32 v15, v11
	v_mul_f32_e32 v10, v32, v180
	v_mul_f32_e32 v11, v33, v181
	s_nop 0
	v_fma_f32 v178, v30, v180, v11
	v_fma_f32 v179, v31, v181, v10
	v_pk_fma_f32 v[10:11], v[30:31], v[180:181], v[10:11] op_sel:[0,0,1] op_sel_hi:[1,1,0] neg_lo:[0,0,1] neg_hi:[0,0,1]
	s_nop 0
	v_mov_b32_e32 v179, v11
	v_add_f32_e32 v10, v12, v14
	v_add_f32_e32 v11, v13, v15
	v_sub_f32_e32 v12, v12, v14
	v_sub_f32_e32 v13, v13, v15
	v_add_f32_e32 v14, v176, v178
	v_add_f32_e32 v15, v177, v179
	v_sub_f32_e32 v176, v176, v178
	v_sub_f32_e32 v177, v177, v179
	v_add_f32_e32 v178, v10, v14
	v_add_f32_e32 v179, v11, v15
	v_sub_f32_e32 v10, v10, v14
	v_sub_f32_e32 v11, v11, v15
	v_mul_f32_e32 v14, v34, v170
	v_mul_f32_e32 v15, v35, v171
	s_nop 0
	v_fma_f32 v180, v36, v170, -v15
	v_fma_f32 v181, v37, v171, -v14
	v_pk_fma_f32 v[14:15], v[36:37], v[170:171], v[14:15] op_sel:[0,0,1] op_sel_hi:[1,1,0]
	s_nop 0
	v_mov_b32_e32 v181, v15
	v_mul_f32_e32 v14, v42, v175
	v_mul_f32_e32 v15, v43, v174
	s_nop 0
	v_fma_f32 v170, v40, v174, v14
	v_fma_f32 v171, v41, v175, v15
	v_fma_f32 v14, v40, v174, -v14
	v_fma_f32 v15, v41, v175, -v15
	s_nop 0
	v_mov_b32_e32 v171, v15
	v_mul_f32_e32 v14, v50, v179
	v_mul_f32_e32 v15, v51, v178
	s_nop 0
	v_fma_f32 v174, v48, v178, v14
	v_fma_f32 v175, v49, v179, v15
	v_fma_f32 v14, v48, v178, -v14
	v_fma_f32 v15, v49, v179, -v15
	s_nop 0
	v_mov_b32_e32 v175, v15
	v_add_f32_e32 v14, v182, v170
	v_add_f32_e32 v15, v183, v171
	v_sub_f32_e32 v170, v182, v170
	v_sub_f32_e32 v171, v183, v171
	v_add_f32_e32 v178, v180, v174
	v_add_f32_e32 v179, v181, v175
	v_sub_f32_e32 v174, v180, v174
	v_sub_f32_e32 v175, v181, v175
	v_add_f32_e32 v180, v14, v178
	v_add_f32_e32 v181, v15, v179
	v_sub_f32_e32 v14, v14, v178
	v_sub_f32_e32 v15, v15, v179
	v_sub_f32_e32 v178, v170, v175
	v_sub_f32_e32 v179, v171, v174
	v_add_f32_e32 v182, v170, v174
	v_add_f32_e32 v183, v171, v174
	s_nop 0
	v_mov_b32_e32 v179, v183
	v_add_f32_e32 v182, v170, v175
	v_add_f32_e32 v183, v171, v174
	v_sub_f32_e32 v170, v170, v174
	v_sub_f32_e32 v171, v171, v174
	s_nop 0
	v_mov_b32_e32 v183, v171
	v_sub_f32_e32 v170, v4, v151
	v_sub_f32_e32 v171, v5, v150
	v_add_f32_e32 v4, v4, v151
	v_add_f32_e32 v5, v5, v150
	v_mov_b32_e32 v150, v170
	v_pk_mov_b32 v[174:175], v[4:5], v[170:171] op_sel:[1,0]
	v_mov_b32_e32 v151, v5
	v_mul_f32_e32 v174, v52, v174
	v_mul_f32_e32 v175, v53, v175
	s_nop 0
	v_fma_f32 v186, v54, v170, -v174
	v_fma_f32 v187, v55, v171, -v175
	v_fma_f32 v150, v54, v150, v174
	v_fma_f32 v151, v55, v151, v175
	s_nop 0
	v_mov_b32_e32 v187, v151
	v_sub_f32_e32 v150, v8, v173
	v_sub_f32_e32 v151, v9, v172
	v_add_f32_e32 v8, v8, v173
	v_add_f32_e32 v9, v9, v172
	v_mov_b32_e32 v172, v150
	v_pk_mov_b32 v[174:175], v[8:9], v[150:151] op_sel:[1,0]
	v_mov_b32_e32 v173, v9
	v_mul_f32_e32 v174, v60, v174
	v_mul_f32_e32 v175, v61, v175
	s_nop 0
	v_fma_f32 v188, v58, v150, v174
	v_fma_f32 v189, v59, v151, v175
	v_fma_f32 v172, v58, v172, -v174
	v_fma_f32 v173, v59, v173, -v175
	s_nop 0
	v_mov_b32_e32 v189, v173
	v_sub_f32_e32 v172, v12, v177
	v_sub_f32_e32 v173, v13, v176
	v_add_f32_e32 v12, v12, v177
	v_add_f32_e32 v13, v13, v176
	v_mov_b32_e32 v174, v172
	v_pk_mov_b32 v[176:177], v[12:13], v[172:173] op_sel:[1,0]
	v_mov_b32_e32 v175, v13
	v_mul_f32_e32 v176, v68, v176
	v_mul_f32_e32 v177, v69, v177
	s_nop 0
	v_fma_f32 v190, v66, v172, v176
	v_fma_f32 v191, v67, v173, v177
	v_fma_f32 v174, v66, v174, -v176
	v_fma_f32 v175, v67, v175, -v177
	s_nop 0
	v_mov_b32_e32 v191, v175
	v_add_f32_e32 v174, v152, v188
	v_add_f32_e32 v175, v153, v189
	v_sub_f32_e32 v152, v152, v188
	v_sub_f32_e32 v153, v153, v189
	v_add_f32_e32 v176, v186, v190
	v_add_f32_e32 v177, v187, v191
	v_sub_f32_e32 v186, v186, v190
	v_sub_f32_e32 v187, v187, v191
	v_add_f32_e32 v188, v174, v176
	v_add_f32_e32 v189, v175, v177
	v_sub_f32_e32 v174, v174, v176
	v_sub_f32_e32 v175, v175, v177
	v_sub_f32_e32 v176, v152, v187
	v_sub_f32_e32 v177, v153, v186
	v_add_f32_e32 v190, v152, v186
	v_add_f32_e32 v191, v153, v186
	s_nop 0
	v_mov_b32_e32 v177, v191
	v_add_f32_e32 v190, v152, v187
	v_add_f32_e32 v191, v153, v186
	v_sub_f32_e32 v152, v152, v186
	v_sub_f32_e32 v153, v153, v186
	s_nop 0
	v_mov_b32_e32 v191, v153
	v_mul_f32_e32 v152, v70, v0
	v_mul_f32_e32 v153, v71, v1
	s_nop 0
	v_fma_f32 v186, v72, v0, -v153
	v_fma_f32 v187, v73, v1, -v152
	v_fma_f32 v0, v72, v0, v153
	v_fma_f32 v1, v73, v1, v152
	s_nop 0
	v_mov_b32_e32 v187, v1
	v_mul_f32_e32 v0, v78, v7
	v_mul_f32_e32 v1, v79, v6
	s_nop 0
	v_fma_f32 v152, v76, v6, v0
	v_fma_f32 v153, v77, v7, v1
	v_fma_f32 v0, v76, v6, -v0
	v_fma_f32 v1, v77, v7, -v1
	s_nop 0
	v_mov_b32_e32 v153, v1
	v_mul_f32_e32 v0, v86, v11
	v_mul_f32_e32 v1, v87, v10
	s_nop 0
	v_fma_f32 v6, v84, v10, v0
	v_fma_f32 v7, v85, v11, v1
	v_fma_f32 v0, v84, v10, -v0
	v_fma_f32 v1, v85, v11, -v1
	s_nop 0
	v_mov_b32_e32 v7, v1
	v_add_f32_e32 v0, v2, v152
	v_add_f32_e32 v1, v3, v153
	v_sub_f32_e32 v2, v2, v152
	v_sub_f32_e32 v3, v3, v153
	v_add_f32_e32 v10, v186, v6
	v_add_f32_e32 v11, v187, v7
	v_sub_f32_e32 v6, v186, v6
	v_sub_f32_e32 v7, v187, v7
	v_add_f32_e32 v152, v0, v10
	v_add_f32_e32 v153, v1, v11
	v_sub_f32_e32 v0, v0, v10
	v_sub_f32_e32 v1, v1, v11
	v_sub_f32_e32 v10, v2, v7
	v_sub_f32_e32 v11, v3, v6
	v_add_f32_e32 v186, v2, v6
	v_add_f32_e32 v187, v3, v6
	s_nop 0
	v_mov_b32_e32 v11, v187
	v_add_f32_e32 v186, v2, v7
	v_add_f32_e32 v187, v3, v6
; #define LAS __attribute__((address_space(3)))
; __device__ __forceinline__ cf cmul(cf a, cf b) { return mk2(a.x * b.x - a.y * b.y, a.x * b.y + a.y * b.x); }
; __device__ __forceinline__ cf cmulc(cf a, cf b) { return mk2(a.x * b.x + a.y * b.y, a.y * b.x - a.x * b.y); }
; __device__ __forceinline__ cf twid(float frac) { return mk2(__builtin_amdgcn_cosf(frac), -__builtin_amdgcn_sinf(frac)); }
; template <int LG, bool INV> __device__ __forceinline__ void fft_pass2(LAS cf* X, int tid) {
;     constexpr int L = 1 << LG, L16 = L >> 4, L4 = L >> 2; constexpr float fL = 1.0f / (float)L;
; #pragma unroll 1
;     for (int i = 0; i < 2; ++i) {
;         const int it = tid + 512 * i; int g, j;
;         if (LG == 14) { g = 0; j = it; } else if (LG == 10) { j = it & 63; g = it >> 6; } else { g = it & 255; j = it >> 8; }
;         const int base = g * L + j;
;         const int pb = PX(base);
;     ...
;         cf e[4][4];
; #pragma unroll
;         for (int r = 0; r < 4; ++r)
; #pragma unroll
;             for (int m = 0; m < 4; ++m) e[r][m] = X[pb + POFF(r, m)];
;         const cf v1 = twid((float)(4 * j) * fL), v2 = cmul(v1, v1), v3 = cmul(v2, v1);
;     ...
;             for (int p = 0; p < 4; ++p) { e[1][p] = cmulc(e[1][p], v1); e[2][p] = cmulc(e[2][p], v2); e[3][p] = cmulc(e[3][p], v3); bfly4_inv(e[0][p], e[1][p], e[2][p], e[3][p]); }
; #pragma unroll
;             for (int r = 0; r < 4; ++r) { const cf w1 = twid((float)(j + r * L16) * fL), w2 = cmul(w1, w1), w3 = cmul(w2, w1);
;                 e[r][1] = cmulc(e[r][1], w1); e[r][2] = cmulc(e[r][2], w2); e[r][3] = cmulc(e[r][3], w3); bfly4_inv(e[r][0], e[r][1], e[r][2], e[r][3]); }
;         }
; #pragma unroll
;         for (int r = 0; r < 4; ++r)
; #pragma unroll
;             for (int m = 0; m < 4; ++m) X[pb + POFF(r, m)] = e[r][m];
	v_sub_f32_e32 v2, v2, v6
	v_sub_f32_e32 v3, v3, v6
	v_pk_mov_b32 v[6:7], v[170:171], v[4:5] op_sel:[1,0]
	v_mov_b32_e32 v187, v3
	v_mov_b32_e32 v2, v4
	v_mov_b32_e32 v3, v171
	v_mul_f32_e32 v6, v88, v6
	v_mul_f32_e32 v7, v89, v7
	s_nop 0
	v_fma_f32 v4, v90, v4, -v6
	v_fma_f32 v5, v91, v5, -v7
	v_fma_f32 v2, v90, v2, v6
	v_fma_f32 v3, v91, v3, v7
	v_pk_mov_b32 v[6:7], v[150:151], v[8:9] op_sel:[1,0]
	v_mov_b32_e32 v5, v3
	v_mov_b32_e32 v2, v8
	v_mov_b32_e32 v3, v151
	v_mul_f32_e32 v6, v96, v6
	v_mul_f32_e32 v7, v97, v7
	s_nop 0
	v_fma_f32 v8, v94, v8, v6
	v_fma_f32 v9, v95, v9, v7
	v_fma_f32 v2, v94, v2, -v6
	v_fma_f32 v3, v95, v3, -v7
	v_pk_mov_b32 v[6:7], v[172:173], v[12:13] op_sel:[1,0]
	v_mov_b32_e32 v9, v3
	v_mov_b32_e32 v2, v12
	v_mov_b32_e32 v3, v173
	v_mul_f32_e32 v6, v104, v6
	v_mul_f32_e32 v7, v105, v7
	s_nop 0
	v_fma_f32 v12, v102, v12, v6
	v_fma_f32 v13, v103, v13, v7
	v_fma_f32 v2, v102, v2, -v6
	v_fma_f32 v3, v103, v3, -v7
	v_sub_f32_e32 v6, v184, v8
	v_sub_f32_e32 v7, v185, v9
	v_mov_b32_e32 v13, v3
	v_add_f32_e32 v2, v184, v8
	v_add_f32_e32 v3, v185, v9
	v_add_f32_e32 v8, v4, v12
	v_add_f32_e32 v9, v5, v13
	v_sub_f32_e32 v4, v4, v12
	v_sub_f32_e32 v5, v5, v13
	v_add_f32_e32 v12, v2, v8
	v_add_f32_e32 v13, v3, v9
	v_sub_f32_e32 v2, v2, v8
	v_sub_f32_e32 v3, v3, v9
	v_sub_f32_e32 v8, v6, v5
	v_sub_f32_e32 v9, v7, v4
	v_add_f32_e32 v150, v6, v4
	v_add_f32_e32 v151, v7, v4
	s_nop 0
	v_mov_b32_e32 v9, v151
	v_add_f32_e32 v150, v6, v5
	v_add_f32_e32 v151, v7, v4
	v_sub_f32_e32 v5, v7, v4
	v_sub_f32_e32 v4, v6, v4
	s_nop 0
	v_mov_b32_e32 v151, v5
	ds_write2_b64 v192, v[180:181], v[188:189] offset1:65
	ds_write2_b64 v193, v[178:179], v[176:177] offset0:4 offset1:69
	ds_write2_b64 v194, v[14:15], v[174:175] offset0:8 offset1:73
	ds_write2_b64 v195, v[182:183], v[190:191] offset0:12 offset1:77
	ds_write2_b64 v192, v[152:153], v[12:13] offset0:130 offset1:195
	ds_write2_b64 v193, v[10:11], v[8:9] offset0:134 offset1:199
	ds_write2_b64 v194, v[0:1], v[2:3] offset0:138 offset1:203
	ds_write2_b64 v195, v[186:187], v[150:151] offset0:142 offset1:207
	s_cbranch_vccnz .LBB0_576
	s_mov_b32 s6, 0
	s_mov_b64 s[4:5], -1
	s_waitcnt lgkmcnt(0)
	s_barrier
.LBB0_578:
	v_add_u32_e32 v202, s6, v16
	v_lshlrev_b32_e32 v182, 2, v202
	v_cvt_f32_i32_e32 v182, v182
	v_ashrrev_i32_e32 v0, 6, v202
	v_lshlrev_b32_e32 v0, 3, v0
	v_lshlrev_b32_e32 v1, 3, v202
	v_mul_f32_e32 v183, 0x38800000, v182
	v_cos_f32_e32 v182, v183
	v_sin_f32_e32 v183, v183
	v_add3_u32 v203, 0, v0, v1
	v_add_u32_e32 v204, 0x10400, v203
	v_add_u32_e32 v205, 0x18600, v203
	ds_read_b64 v[0:1], v203
	ds_read_b64 v[2:3], v203 offset:33280
	ds_read_b64 v[4:5], v204
	ds_read_b64 v[6:7], v205
	ds_read_b64 v[8:9], v203 offset:8320
	ds_read_b64 v[10:11], v203 offset:41600
	v_add_u32_e32 v206, 0x12480, v203
	v_add_u32_e32 v207, 0x1a680, v203
	v_xor_b32_e32 v184, 0x80000000, v183
	ds_read_b64 v[12:13], v206
	ds_read_b64 v[14:15], v207
	ds_read_b64 v[150:151], v203 offset:16640
	ds_read_b64 v[152:153], v203 offset:49920
	v_mov_b32_e32 v186, v184
	v_mov_b32_e32 v187, v183
	v_add_u32_e32 v208, 0x14500, v203
	v_add_u32_e32 v210, 0x1c700, v203
	v_mov_b32_e32 v185, v182
	v_mul_f32_e32 v186, v182, v186
	v_mul_f32_e32 v187, v183, v187
	v_mov_b32_e32 v192, v183
	ds_read_b64 v[170:171], v208
	ds_read_b64 v[172:173], v210
	ds_read_b64 v[174:175], v203 offset:24960
	ds_read_b64 v[176:177], v203 offset:58240
	v_fma_f32 v188, v182, v184, -v186
	v_fma_f32 v189, v182, v185, -v187
	v_fma_f32 v184, v182, v184, v186
	v_fma_f32 v185, v182, v185, v187
	s_waitcnt lgkmcnt(9)
	v_mul_f32_e32 v194, v192, v8
	v_mul_f32_e32 v195, v192, v9
	v_mov_b32_e32 v186, v184
	v_mov_b32_e32 v187, v189
	v_fma_f32 v196, v182, v8, -v195
	v_fma_f32 v197, v183, v9, -v194
	v_fma_f32 v8, v182, v8, v195
	v_fma_f32 v9, v182, v9, v194
	v_mul_f32_e32 v190, v183, v186
	v_mul_f32_e32 v191, v182, v187
	v_mul_f32_e32 v186, v182, v186
	v_mul_f32_e32 v187, v183, v187
	v_mov_b32_e32 v197, v9
	s_waitcnt lgkmcnt(5)
	v_mul_f32_e32 v8, v184, v150
	v_mul_f32_e32 v9, v184, v151
	v_fma_f32 v194, v189, v150, v9
	v_fma_f32 v195, v189, v151, v8
	v_pk_fma_f32 v[8:9], v[188:189], v[150:151], v[8:9] op_sel:[1,0,1] op_sel_hi:[1,1,0] neg_lo:[0,0,1] neg_hi:[0,0,1]
	v_sub_f32_e32 v150, v186, v187
	v_sub_f32_e32 v151, v186, v187
	v_mov_b32_e32 v195, v9
	v_add_f32_e32 v8, v191, v190
	v_add_f32_e32 v9, v191, v190
	s_waitcnt lgkmcnt(1)
	v_mul_f32_e32 v186, v150, v174
	v_mul_f32_e32 v187, v151, v175
	v_add_u32_e32 v211, 0x16580, v203
	v_fma_f32 v190, v8, v174, v187
	v_fma_f32 v191, v9, v175, v186
	v_fma_f32 v174, v8, v174, -v187
	v_fma_f32 v175, v9, v175, -v186
	ds_read_b64 v[178:179], v211
	v_mov_b32_e32 v191, v175
	v_add_f32_e32 v174, v0, v194
	v_add_f32_e32 v175, v1, v195
	v_sub_f32_e32 v0, v0, v194
	v_sub_f32_e32 v1, v1, v195
	v_add_f32_e32 v186, v196, v190
	v_add_f32_e32 v187, v197, v191
	v_sub_f32_e32 v190, v196, v190
	v_sub_f32_e32 v191, v197, v191
	v_add_f32_e32 v194, v174, v186
	v_add_f32_e32 v195, v175, v187
	v_sub_f32_e32 v174, v174, v186
	v_sub_f32_e32 v175, v175, v187
	v_sub_f32_e32 v186, v0, v191
	v_sub_f32_e32 v187, v1, v190
	v_add_f32_e32 v196, v0, v190
	v_add_f32_e32 v197, v1, v190
	v_add_u32_e32 v212, 0x1e780, v203
	v_mov_b32_e32 v187, v197
	v_add_f32_e32 v196, v0, v191
	v_add_f32_e32 v197, v1, v190
	v_sub_f32_e32 v0, v0, v190
	v_sub_f32_e32 v1, v1, v190
	ds_read_b64 v[180:181], v212
	v_mov_b32_e32 v197, v1
	v_mul_f32_e32 v0, v192, v10
	v_mul_f32_e32 v1, v192, v11
	v_fma_f32 v190, v182, v10, -v1
	v_fma_f32 v191, v183, v11, -v0
	v_pk_fma_f32 v[0:1], v[182:183], v[10:11], v[0:1] op_sel:[0,0,1] op_sel_hi:[0,1,0]
	v_mov_b32_e32 v191, v1
	v_mul_f32_e32 v0, v184, v152
	v_mul_f32_e32 v1, v184, v153
	v_fma_f32 v10, v189, v152, v1
	v_fma_f32 v11, v189, v153, v0
	v_pk_fma_f32 v[0:1], v[188:189], v[152:153], v[0:1] op_sel:[1,0,1] op_sel_hi:[1,1,0] neg_lo:[0,0,1] neg_hi:[0,0,1]
	s_movk_i32 s6, 0x200
	v_mov_b32_e32 v11, v1
	s_waitcnt lgkmcnt(2)
; __device__ __forceinline__ cf cmul(cf a, cf b) { return mk2(a.x * b.x - a.y * b.y, a.x * b.y + a.y * b.x); }
; __device__ __forceinline__ cf cmulc(cf a, cf b) { return mk2(a.x * b.x + a.y * b.y, a.y * b.x - a.x * b.y); }
; __device__ __forceinline__ cf twid(float frac) { return mk2(__builtin_amdgcn_cosf(frac), -__builtin_amdgcn_sinf(frac)); }
; template <int LG, bool INV> __device__ __forceinline__ void fft_pass2(LAS cf* X, int tid) {
;     ...
;         } else {
; #pragma unroll
;             for (int p = 0; p < 4; ++p) { e[1][p] = cmulc(e[1][p], v1); e[2][p] = cmulc(e[2][p], v2); e[3][p] = cmulc(e[3][p], v3); bfly4_inv(e[0][p], e[1][p], e[2][p], e[3][p]); }
; #pragma unroll
;             for (int r = 0; r < 4; ++r) { const cf w1 = twid((float)(j + r * L16) * fL), w2 = cmul(w1, w1), w3 = cmul(w2, w1);
;                 e[r][1] = cmulc(e[r][1], w1); e[r][2] = cmulc(e[r][2], w2); e[r][3] = cmulc(e[r][3], w3); bfly4_inv(e[r][0], e[r][1], e[r][2], e[r][3]); }
	v_mul_f32_e32 v0, v150, v176
	v_mul_f32_e32 v1, v151, v177
	s_and_b64 vcc, exec, s[4:5]
	v_fma_f32 v152, v8, v176, v1
	v_fma_f32 v153, v9, v177, v0
	v_pk_fma_f32 v[0:1], v[8:9], v[176:177], v[0:1] op_sel:[0,0,1] op_sel_hi:[1,1,0] neg_lo:[0,0,1] neg_hi:[0,0,1]
	s_mov_b64 s[4:5], 0
	v_mov_b32_e32 v153, v1
	v_add_f32_e32 v0, v2, v10
	v_add_f32_e32 v1, v3, v11
	v_sub_f32_e32 v2, v2, v10
	v_sub_f32_e32 v3, v3, v11
	v_add_f32_e32 v10, v190, v152
	v_add_f32_e32 v11, v191, v153
	v_sub_f32_e32 v152, v190, v152
	v_sub_f32_e32 v153, v191, v153
	v_add_f32_e32 v176, v0, v10
	v_add_f32_e32 v177, v1, v11
	v_sub_f32_e32 v0, v0, v10
	v_sub_f32_e32 v1, v1, v11
	v_mul_f32_e32 v10, v192, v12
	v_mul_f32_e32 v11, v192, v13
	v_fma_f32 v190, v182, v12, -v11
	v_fma_f32 v191, v183, v13, -v10
	v_pk_fma_f32 v[10:11], v[182:183], v[12:13], v[10:11] op_sel:[0,0,1] op_sel_hi:[0,1,0]
	v_mov_b32_e32 v191, v11
	v_mul_f32_e32 v10, v184, v170
	v_mul_f32_e32 v11, v184, v171
	v_fma_f32 v12, v189, v170, v11
	v_fma_f32 v13, v189, v171, v10
	v_pk_fma_f32 v[10:11], v[188:189], v[170:171], v[10:11] op_sel:[1,0,1] op_sel_hi:[1,1,0] neg_lo:[0,0,1] neg_hi:[0,0,1]
	s_nop 0
	v_mov_b32_e32 v13, v11
	s_waitcnt lgkmcnt(1)
	v_mul_f32_e32 v10, v150, v178
	v_mul_f32_e32 v11, v151, v179
	s_nop 0
	v_fma_f32 v170, v8, v178, v11
	v_fma_f32 v171, v9, v179, v10
	v_pk_fma_f32 v[10:11], v[8:9], v[178:179], v[10:11] op_sel:[0,0,1] op_sel_hi:[1,1,0] neg_lo:[0,0,1] neg_hi:[0,0,1]
	s_nop 0
	v_mov_b32_e32 v171, v11
	v_add_f32_e32 v10, v4, v12
	v_add_f32_e32 v11, v5, v13
	v_sub_f32_e32 v4, v4, v12
	v_sub_f32_e32 v5, v5, v13
	v_add_f32_e32 v12, v190, v170
	v_add_f32_e32 v13, v191, v171
	v_sub_f32_e32 v170, v190, v170
	v_sub_f32_e32 v171, v191, v171
	v_add_f32_e32 v178, v10, v12
	v_add_f32_e32 v179, v11, v13
	v_sub_f32_e32 v10, v10, v12
	v_sub_f32_e32 v11, v11, v13
	v_mul_f32_e32 v12, v192, v14
	v_mul_f32_e32 v13, v192, v15
	v_fma_f32 v190, v182, v14, -v13
	v_fma_f32 v191, v183, v15, -v12
	v_pk_fma_f32 v[12:13], v[182:183], v[14:15], v[12:13] op_sel:[0,0,1] op_sel_hi:[0,1,0]
	v_mov_b32_e32 v191, v13
	v_mul_f32_e32 v12, v184, v172
	v_mul_f32_e32 v13, v184, v173
	v_fma_f32 v14, v189, v172, v13
	v_fma_f32 v15, v189, v173, v12
	v_pk_fma_f32 v[12:13], v[188:189], v[172:173], v[12:13] op_sel:[1,0,1] op_sel_hi:[1,1,0] neg_lo:[0,0,1] neg_hi:[0,0,1]
	v_add_f32_e32 v192, v5, v170
	v_add_f32_e32 v193, v5, v170
	v_mov_b32_e32 v15, v13
	s_waitcnt lgkmcnt(0)
	v_mul_f32_e32 v12, v150, v180
	v_mul_f32_e32 v13, v151, v181
	s_nop 0
	v_fma_f32 v150, v8, v180, v13
	v_fma_f32 v151, v9, v181, v12
	v_fma_f32 v8, v8, v180, -v13
	v_fma_f32 v9, v9, v181, -v12
	s_nop 0
	v_mov_b32_e32 v151, v9
	v_add_f32_e32 v8, v6, v14
	v_add_f32_e32 v9, v7, v15
	v_add_f32_e32 v12, v190, v150
	v_add_f32_e32 v13, v191, v151
	v_sub_f32_e32 v6, v6, v14
	v_sub_f32_e32 v7, v7, v15
	v_sub_f32_e32 v14, v190, v150
	v_sub_f32_e32 v15, v191, v151
	v_add_f32_e32 v150, v8, v12
	v_add_f32_e32 v151, v9, v13
	v_sub_f32_e32 v8, v8, v12
	v_sub_f32_e32 v9, v9, v13
	v_cvt_f32_i32_e32 v12, v202
	v_mul_f32_e32 v13, 0x38800000, v12
	v_cos_f32_e32 v12, v13
	v_sin_f32_e32 v13, v13
	v_mov_b32_e32 v173, v12
	v_xor_b32_e32 v172, 0x80000000, v13
	v_mov_b32_e32 v180, v172
	v_mov_b32_e32 v181, v13
	v_mul_f32_e32 v180, v12, v180
	v_mul_f32_e32 v181, v13, v181
	v_mov_b32_e32 v188, v13
	v_fma_f32 v182, v12, v172, -v180
	v_fma_f32 v183, v12, v173, -v181
	v_fma_f32 v172, v12, v172, v180
	v_fma_f32 v173, v12, v173, v181
	v_mov_b32_e32 v180, v172
	v_mov_b32_e32 v181, v183
	v_mul_f32_e32 v189, v188, v176
	v_mul_f32_e32 v188, v188, v177
	v_mul_f32_e32 v184, v13, v180
	v_mul_f32_e32 v185, v12, v181
	v_mul_f32_e32 v180, v12, v180
	v_mul_f32_e32 v181, v13, v181
	v_fma_f32 v190, v12, v176, -v188
	v_fma_f32 v191, v13, v177, -v189
	v_fma_f32 v13, v12, v177, v189
	v_fma_f32 v12, v12, v176, v188
	v_mov_b32_e32 v191, v13
	v_mul_f32_e32 v12, v172, v179
	v_mul_f32_e32 v13, v172, v178
	v_fma_f32 v172, v183, v178, v12
	v_fma_f32 v173, v183, v179, v13
	v_fma_f32 v12, v183, v178, -v12
	v_fma_f32 v13, v183, v179, -v13
	v_sub_f32_e32 v176, v180, v181
	v_sub_f32_e32 v177, v180, v181
	v_mov_b32_e32 v173, v13
	v_add_f32_e32 v12, v185, v184
	v_add_f32_e32 v13, v185, v184
	v_mul_f32_e32 v176, v176, v151
	v_mul_f32_e32 v177, v177, v150
	v_sub_f32_e32 v184, v2, v153
	v_sub_f32_e32 v185, v3, v152
	v_fma_f32 v178, v12, v150, v176
	v_fma_f32 v179, v13, v151, v177
	v_fma_f32 v12, v12, v150, -v176
	v_fma_f32 v13, v13, v151, -v177
	v_sub_f32_e32 v150, v194, v172
	v_sub_f32_e32 v151, v195, v173
	v_mov_b32_e32 v179, v13
	v_add_f32_e32 v12, v194, v172
	v_add_f32_e32 v13, v195, v173
	v_add_f32_e32 v172, v190, v178
	v_add_f32_e32 v173, v191, v179
	v_sub_f32_e32 v176, v190, v178
	v_sub_f32_e32 v177, v191, v179
	v_add_f32_e32 v178, v12, v172
	v_add_f32_e32 v179, v13, v173
	v_sub_f32_e32 v12, v12, v172
	v_sub_f32_e32 v13, v13, v173
	v_sub_f32_e32 v172, v150, v177
	v_sub_f32_e32 v173, v151, v176
	v_add_f32_e32 v180, v150, v176
	v_add_f32_e32 v181, v151, v176
	v_add_f32_e32 v2, v2, v153
	v_add_f32_e32 v3, v3, v152
	v_mov_b32_e32 v173, v181
	v_add_f32_e32 v180, v150, v177
	v_add_f32_e32 v181, v151, v176
	v_sub_f32_e32 v150, v150, v176
	v_sub_f32_e32 v151, v151, v176
	v_pk_mov_b32 v[188:189], v[2:3], v[184:185] op_sel:[1,0]
	v_add_u32_e32 v150, 0x400, v202
	v_cvt_f32_i32_e32 v150, v150
	v_mov_b32_e32 v181, v151
	v_mov_b32_e32 v152, v184
	v_mov_b32_e32 v153, v3
	v_mul_f32_e32 v151, 0x38800000, v150
	v_sin_f32_e32 v176, v151
	v_cos_f32_e32 v150, v151
	v_sub_f32_e32 v194, v4, v171
	v_sub_f32_e32 v195, v4, v171
	v_mul_f32_e32 v188, v176, v188
	v_mul_f32_e32 v189, v176, v189
	v_xor_b32_e32 v182, 0x80000000, v176
; __device__ __forceinline__ cf cmul(cf a, cf b) { return mk2(a.x * b.x - a.y * b.y, a.x * b.y + a.y * b.x); }
; __device__ __forceinline__ cf cmulc(cf a, cf b) { return mk2(a.x * b.x + a.y * b.y, a.y * b.x - a.x * b.y); }
; __device__ __forceinline__ cf twid(float frac) { return mk2(__builtin_amdgcn_cosf(frac), -__builtin_amdgcn_sinf(frac)); }
; template <int LG, bool INV> __device__ __forceinline__ void fft_pass2(LAS cf* X, int tid) {
;     ...
;             for (int r = 0; r < 4; ++r) { const cf w1 = twid((float)(j + r * L16) * fL), w2 = cmul(w1, w1), w3 = cmul(w2, w1);
;                 e[r][1] = cmulc(e[r][1], w1); e[r][2] = cmulc(e[r][2], w2); e[r][3] = cmulc(e[r][3], w3); bfly4_inv(e[r][0], e[r][1], e[r][2], e[r][3]); }
	v_fma_f32 v190, v150, v184, -v188
	v_fma_f32 v191, v151, v185, -v189
	v_fma_f32 v152, v150, v152, v188
	v_fma_f32 v153, v150, v153, v189
	v_mov_b32_e32 v191, v153
	v_mov_b32_e32 v151, v176
	v_mov_b32_e32 v152, v182
	v_mov_b32_e32 v153, v176
	v_mov_b32_e32 v183, v150
	v_mul_f32_e32 v152, v150, v152
	v_mul_f32_e32 v153, v151, v153
	v_mov_b32_e32 v177, v150
	v_fma_f32 v188, v150, v182, v152
	v_fma_f32 v189, v150, v183, v153
	v_fma_f32 v152, v150, v182, -v152
	v_fma_f32 v153, v150, v183, -v153
	v_mov_b32_e32 v183, v153
	v_pk_mov_b32 v[152:153], v[152:153], v[188:189] op_sel:[1,0]
	v_mov_b32_e32 v182, v188
	v_mul_f32_e32 v152, v152, v194
	v_mul_f32_e32 v153, v153, v195
	v_mul_f32_e32 v176, v176, v182
	v_mul_f32_e32 v177, v177, v183
	v_fma_f32 v188, v188, v192, v152
	v_fma_f32 v189, v189, v193, v153
	v_fma_f32 v152, v182, v192, -v152
	v_fma_f32 v153, v183, v193, -v153
	v_mul_f32_e32 v150, v150, v182
	v_mul_f32_e32 v151, v151, v183
	v_mov_b32_e32 v189, v153
	v_sub_f32_e32 v152, v6, v15
	v_sub_f32_e32 v153, v7, v14
	v_add_f32_e32 v182, v6, v15
	v_add_f32_e32 v183, v7, v14
	v_pk_add_f32 v[150:151], v[150:151], v[150:151] op_sel:[0,1] op_sel_hi:[0,1] neg_lo:[0,1] neg_hi:[0,1]
	v_mov_b32_e32 v193, v183
	v_pk_mov_b32 v[182:183], v[182:183], v[152:153] op_sel:[1,0]
	v_mov_b32_e32 v192, v152
	v_pk_add_f32 v[176:177], v[176:177], v[176:177] op_sel:[1,0] op_sel_hi:[1,0]
	v_mul_f32_e32 v150, v150, v182
	v_mul_f32_e32 v151, v151, v183
	s_nop 0
	v_fma_f32 v152, v176, v152, v150
	v_fma_f32 v153, v177, v153, v151
	v_fma_f32 v150, v176, v192, -v150
	v_fma_f32 v151, v177, v193, -v151
	v_sub_f32_e32 v176, v186, v188
	v_sub_f32_e32 v177, v187, v189
	v_mov_b32_e32 v153, v151
	v_add_f32_e32 v150, v186, v188
	v_add_f32_e32 v151, v187, v189
	v_add_f32_e32 v182, v190, v152
	v_add_f32_e32 v183, v191, v153
	v_sub_f32_e32 v152, v190, v152
	v_sub_f32_e32 v153, v191, v153
	v_add_f32_e32 v186, v150, v182
	v_add_f32_e32 v187, v151, v183
	v_sub_f32_e32 v150, v150, v182
	v_sub_f32_e32 v151, v151, v183
	v_sub_f32_e32 v182, v176, v153
	v_sub_f32_e32 v183, v177, v152
	v_add_f32_e32 v188, v176, v152
	v_add_f32_e32 v189, v177, v152
	s_nop 0
	v_mov_b32_e32 v183, v189
	v_add_f32_e32 v188, v176, v153
	v_add_f32_e32 v189, v177, v152
	v_sub_f32_e32 v153, v177, v152
	v_sub_f32_e32 v152, v176, v152
	s_nop 0
	v_add_u32_e32 v152, 0x800, v202
	v_cvt_f32_i32_e32 v152, v152
	v_mov_b32_e32 v189, v153
	v_mul_f32_e32 v153, 0x38800000, v152
	v_cos_f32_e32 v152, v153
	v_sin_f32_e32 v153, v153
	v_mov_b32_e32 v177, v152
	v_xor_b32_e32 v176, 0x80000000, v153
	v_mov_b32_e32 v190, v176
	v_mov_b32_e32 v191, v153
	v_mul_f32_e32 v190, v152, v190
	v_mul_f32_e32 v191, v153, v191
	v_mov_b32_e32 v198, v153
	v_fma_f32 v192, v152, v176, -v190
	v_fma_f32 v193, v152, v177, -v191
	v_fma_f32 v176, v152, v176, v190
	v_fma_f32 v177, v152, v177, v191
	v_mul_f32_e32 v199, v198, v0
	v_mul_f32_e32 v198, v198, v1
	v_mov_b32_e32 v190, v176
	v_mov_b32_e32 v191, v193
	v_fma_f32 v200, v152, v0, -v198
	v_fma_f32 v201, v153, v1, -v199
	v_fma_f32 v0, v152, v0, v198
	v_fma_f32 v1, v152, v1, v199
	v_mul_f32_e32 v194, v153, v190
	v_mul_f32_e32 v195, v152, v191
	v_mul_f32_e32 v190, v152, v190
	v_mul_f32_e32 v191, v153, v191
	v_mov_b32_e32 v201, v1
	v_mul_f32_e32 v0, v176, v11
	v_mul_f32_e32 v1, v176, v10
	v_fma_f32 v152, v193, v10, v0
	v_fma_f32 v153, v193, v11, v1
	v_fma_f32 v0, v193, v10, -v0
	v_fma_f32 v1, v193, v11, -v1
	v_sub_f32_e32 v10, v190, v191
	v_sub_f32_e32 v11, v190, v191
	v_mov_b32_e32 v153, v1
	v_add_f32_e32 v0, v195, v194
	v_add_f32_e32 v1, v195, v194
	v_mul_f32_e32 v10, v10, v9
	v_mul_f32_e32 v11, v11, v8
	v_mov_b32_e32 v193, v185
	v_fma_f32 v176, v0, v8, v10
	v_fma_f32 v177, v1, v9, v11
	v_fma_f32 v0, v0, v8, -v10
	v_fma_f32 v1, v1, v9, -v11
	v_sub_f32_e32 v8, v174, v152
	v_sub_f32_e32 v9, v175, v153
	v_mov_b32_e32 v177, v1
	v_add_f32_e32 v0, v174, v152
	v_add_f32_e32 v1, v175, v153
	v_add_f32_e32 v10, v200, v176
	v_add_f32_e32 v11, v201, v177
	v_sub_f32_e32 v152, v200, v176
	v_sub_f32_e32 v153, v201, v177
	v_add_f32_e32 v174, v0, v10
	v_add_f32_e32 v175, v1, v11
	v_sub_f32_e32 v0, v0, v10
	v_sub_f32_e32 v1, v1, v11
	v_sub_f32_e32 v10, v8, v153
	v_sub_f32_e32 v11, v9, v152
	v_add_f32_e32 v176, v8, v152
	v_add_f32_e32 v177, v9, v152
	v_pk_mov_b32 v[184:185], v[184:185], v[2:3] op_sel:[1,0]
	v_mov_b32_e32 v11, v177
	v_add_f32_e32 v176, v8, v153
	v_add_f32_e32 v177, v9, v152
	v_sub_f32_e32 v8, v8, v152
	v_sub_f32_e32 v9, v9, v152
	v_mov_b32_e32 v192, v2
	v_add_u32_e32 v8, 0xc00, v202
	v_cvt_f32_i32_e32 v8, v8
	v_mov_b32_e32 v177, v9
	v_sub_f32_e32 v198, v5, v170
	v_sub_f32_e32 v199, v5, v170
	v_add_f32_e32 v5, v4, v171
	v_add_f32_e32 v4, v4, v171
	v_mul_f32_e32 v9, 0x38800000, v8
	v_sin_f32_e32 v152, v9
	v_cos_f32_e32 v8, v9
	v_mul_f32_e32 v184, v152, v184
	v_mul_f32_e32 v185, v152, v185
	v_xor_b32_e32 v190, 0x80000000, v152
	v_fma_f32 v2, v8, v2, -v184
	v_fma_f32 v3, v9, v3, -v185
	v_fma_f32 v184, v8, v192, v184
	v_fma_f32 v185, v8, v193, v185
	v_mov_b32_e32 v3, v185
	v_mov_b32_e32 v9, v152
	v_mov_b32_e32 v184, v190
	v_mov_b32_e32 v185, v152
	v_mov_b32_e32 v191, v8
	v_mul_f32_e32 v152, v8, v184
	v_mul_f32_e32 v153, v9, v185
	s_nop 0
	v_fma_f32 v184, v8, v190, v152
	v_fma_f32 v185, v8, v191, v153
	v_fma_f32 v152, v8, v190, -v152
	v_fma_f32 v153, v8, v191, -v153
	v_mov_b32_e32 v191, v153
	v_pk_mov_b32 v[152:153], v[152:153], v[184:185] op_sel:[1,0]
	v_mov_b32_e32 v190, v184
	v_mul_f32_e32 v192, v9, v152
	v_mul_f32_e32 v193, v9, v153
	v_mul_f32_e32 v4, v152, v4
	v_mul_f32_e32 v5, v153, v5
	v_fma_f32 v194, v8, v190, -v192
	v_fma_f32 v195, v8, v191, -v193
	v_fma_f32 v9, v8, v191, v193
	v_fma_f32 v8, v8, v190, v192
; __device__ __forceinline__ cf cmulc(cf a, cf b) { return mk2(a.x * b.x + a.y * b.y, a.y * b.x - a.x * b.y); }
; template <int LG, bool INV> __device__ __forceinline__ void fft_pass2(LAS cf* X, int tid) {
;     ...
;                 e[r][1] = cmulc(e[r][1], w1); e[r][2] = cmulc(e[r][2], w2); e[r][3] = cmulc(e[r][3], w3); bfly4_inv(e[r][0], e[r][1], e[r][2], e[r][3]); }
;         }
; #pragma unroll
;         for (int r = 0; r < 4; ++r)
; #pragma unroll
;             for (int m = 0; m < 4; ++m) X[pb + POFF(r, m)] = e[r][m];
	v_fma_f32 v152, v184, v198, v4
	v_fma_f32 v153, v185, v199, v5
	v_fma_f32 v4, v190, v198, -v4
	v_fma_f32 v5, v191, v199, -v5
	v_mov_b32_e32 v193, v9
	v_mov_b32_e32 v153, v5
	v_sub_f32_e32 v4, v7, v14
	v_sub_f32_e32 v5, v7, v14
	v_pk_mov_b32 v[8:9], v[8:9], v[194:195] op_sel:[1,0]
	v_add_f32_e32 v7, v6, v15
	v_add_f32_e32 v6, v6, v15
	v_mov_b32_e32 v192, v194
	v_mul_f32_e32 v6, v8, v6
	v_mul_f32_e32 v7, v9, v7
	s_nop 0
	v_fma_f32 v8, v194, v4, v6
	v_fma_f32 v9, v195, v5, v7
	v_fma_f32 v4, v192, v4, -v6
	v_fma_f32 v5, v193, v5, -v7
	v_sub_f32_e32 v6, v196, v152
	v_sub_f32_e32 v7, v197, v153
	v_mov_b32_e32 v9, v5
	v_add_f32_e32 v4, v196, v152
	v_add_f32_e32 v5, v197, v153
	v_add_f32_e32 v14, v2, v8
	v_add_f32_e32 v15, v3, v9
	v_sub_f32_e32 v2, v2, v8
	v_sub_f32_e32 v3, v3, v9
	v_add_f32_e32 v8, v4, v14
	v_add_f32_e32 v9, v5, v15
	v_sub_f32_e32 v4, v4, v14
	v_sub_f32_e32 v5, v5, v15
	v_sub_f32_e32 v14, v6, v3
	v_sub_f32_e32 v15, v7, v2
	v_add_f32_e32 v152, v6, v2
	v_add_f32_e32 v153, v7, v2
	s_nop 0
	v_mov_b32_e32 v15, v153
	v_add_f32_e32 v152, v6, v3
	v_add_f32_e32 v153, v7, v2
	v_sub_f32_e32 v3, v7, v2
	v_sub_f32_e32 v2, v6, v2
	s_nop 0
	v_mov_b32_e32 v153, v3
	ds_write_b64 v203, v[178:179]
	ds_write_b64 v203, v[172:173] offset:33280
	ds_write_b64 v204, v[12:13]
	ds_write_b64 v205, v[180:181]
	ds_write_b64 v203, v[186:187] offset:8320
	ds_write_b64 v203, v[182:183] offset:41600
	ds_write_b64 v206, v[150:151]
	ds_write_b64 v207, v[188:189]
	ds_write_b64 v203, v[174:175] offset:16640
	ds_write_b64 v203, v[10:11] offset:49920
	ds_write_b64 v208, v[0:1]
	ds_write_b64 v210, v[176:177]
	ds_write_b64 v203, v[8:9] offset:24960
	ds_write_b64 v203, v[14:15] offset:58240
	ds_write_b64 v211, v[4:5]
	ds_write_b64 v212, v[152:153]
	s_cbranch_vccnz .LBB0_578
	s_add_u32 s4, s36, 0x800000
	s_addc_u32 s5, s37, 0
	s_mov_b32 s13, s64
	s_mov_b32 s61, s64
	s_add_u32 s6, s80, 0x800000
	s_addc_u32 s7, s81, 0
	s_lshl_b64 s[10:11], s[12:13], 23
	s_lshl_b64 s[12:13], s[60:61], 23
	s_mov_b32 s23, 0
	s_mov_b64 s[60:61], -1
	s_waitcnt lgkmcnt(0)
	s_barrier
	s_branch .LBB0_581
; __device__ __forceinline__ float bf2f(bf16_t u) { return __uint_as_float((unsigned)u << 16); }
; __device__ __forceinline__ float bflo(unsigned w) { return __uint_as_float(w << 16); }
; __device__ __forceinline__ float bfhi(unsigned w) { return __uint_as_float(w & 0xffff0000u); }
; #define YH ((float*)(wsb(a.ws) + WS_YH))
; __device__ __forceinline__ void conv8(const bf16_t* p, int c, int n, float w0, float w1, float w2, float b, float (&o)[8]) {
;     const v4u v = *(const v4u*)(p + 8 * c);
;     const float um = c > 0 ? bf2f(p[8 * c - 1]) : 0.f, up = 8 * c + 8 < n ? bf2f(p[8 * c + 8]) : 0.f;
;     const float u0 = bflo(v.x), u1 = bfhi(v.x), u2 = bflo(v.y), u3 = bfhi(v.y), u4 = bflo(v.z), u5 = bfhi(v.z), u6 = bflo(v.w), u7 = bfhi(v.w);
;     o[0] = w0 * um + w1 * u0 + w2 * u1 + b; o[1] = w0 * u0 + w1 * u1 + w2 * u2 + b; o[2] = w0 * u1 + w1 * u2 + w2 * u3 + b; o[3] = w0 * u2 + w1 * u3 + w2 * u4 + b;
;     o[4] = w0 * u3 + w1 * u4 + w2 * u5 + b; o[5] = w0 * u4 + w1 * u5 + w2 * u6 + b; o[6] = w0 * u5 + w1 * u6 + w2 * u7 + b; o[7] = w0 * u6 + w1 * u7 + w2 * up + b;
; }
; __global__ void __launch_bounds__(NTHR, 2) fwd_mega(Args a) {
;     ...
;                     for (int k = 0; k < 2; ++k) { const int ch = 64 * (wave + 8 * k) + cw; float x0_[8], x1_[8];
;                         conv8(pv0 + 512 * 8192, ch, 8192, wb0, wb1, wb2, bb, x0_); conv8(pv1 + 512 * 8192, ch, 8192, wb0, wb1, wb2, bb, x1_);
;                         f32x4 o0a, o0b, o1a, o1b;
; #pragma unroll
;                         for (int e = 0; e < 4; ++e) { const cf ca = X[PX(8 * ch + e)], cb2 = X[PX(8 * ch + 4 + e)]; o0a[e] = x0_[e] * ca.x; o1a[e] = x1_[e] * ca.y; o0b[e] = x0_[4 + e] * cb2.x; o1b[e] = x1_[4 + e] * cb2.y; }
;                         float* y0p = YH + ((size_t)b0 * 256 + c) * 8192 + 8 * ch; float* y1p = YH + ((size_t)b1 * 256 + c) * 8192 + 8 * ch;
;                         *(f32x4*)y0p = o0a; *(f32x4*)(y0p + 4) = o0b; *(f32x4*)y1p = o1a; *(f32x4*)(y1p + 4) = o1b; }
.LBB0_580:
	s_or_b64 exec, exec, s[36:37]
	s_waitcnt vmcnt(0) lgkmcnt(0)
	v_and_b32_e32 v170, 0xffff0000, v0
	v_mov_b32_e32 v14, v170
	v_lshlrev_b32_e32 v4, 16, v0
	v_mul_f32_e32 v14, v148, v14
	v_mul_f32_e32 v15, v149, v15
	v_lshlrev_b32_e32 v171, 16, v1
	v_pk_fma_f32 v[14:15], v[148:149], v[4:5], v[14:15] op_sel:[0,0,1] op_sel_hi:[1,0,0]
	v_and_b32_e32 v153, 0xffff0000, v3
	v_fma_f32 v14, v144, v170, v14
	v_fma_f32 v15, v145, v171, v15
	v_and_b32_e32 v173, 16, v3
	v_add_f32_e32 v178, v130, v14
	v_add_f32_e32 v179, v131, v15
	v_and_b32_e32 v15, 16, v2
	v_and_b32_e32 v14, 0xffff0000, v1
	v_lshlrev_b32_e32 v1, 16, v2
	v_mov_b32_e32 v0, v14
	v_and_b32_e32 v172, 0xffff0000, v2
	v_lshlrev_b32_e32 v175, 16, v3
	v_pk_mov_b32 v[2:3], v[170:171], v[14:15] op_sel:[1,0]
	v_mov_b32_e32 v174, v172
	v_pk_mov_b32 v[172:173], v[0:1], v[172:173] op_sel:[1,0]
	v_mul_f32_e32 v2, v146, v2
	v_mul_f32_e32 v3, v147, v3
	v_mul_f32_e32 v14, v146, v172
	v_mul_f32_e32 v15, v147, v173
	v_fma_f32 v2, v126, v170, v2
	v_fma_f32 v3, v127, v171, v3
	v_mov_b32_e32 v152, v175
	v_fma_f32 v2, v144, v0, v2
	v_fma_f32 v3, v145, v1, v3
	v_fma_f32 v0, v126, v0, v14
	v_fma_f32 v1, v127, v1, v15
	v_mov_b32_e32 v4, v153
	v_fma_f32 v0, v144, v174, v0
	v_fma_f32 v1, v145, v175, v1
	v_lshlrev_b32_e32 v183, 16, v9
	v_add_f32_e32 v180, v130, v0
	v_add_f32_e32 v181, v131, v1
	v_mul_f32_e32 v0, v146, v152
	v_mul_f32_e32 v1, v147, v153
	v_and_b32_e32 v152, 0xffff0000, v6
	v_fma_f32 v0, v126, v174, v0
	v_fma_f32 v1, v127, v175, v1
	v_lshlrev_b32_e32 v153, 16, v7
	v_fma_f32 v0, v144, v4, v0
	v_fma_f32 v1, v145, v5, v1
	v_lshlrev_b32_e32 v4, 3, v150
	v_add_f32_e32 v14, v130, v0
	v_add_f32_e32 v15, v131, v1
	v_and_b32_e32 v1, -8, v12
	v_add3_u32 v184, 0, v1, v4
	ds_read2_b64 v[170:173], v184 offset1:1
	ds_read2_b64 v[174:177], v184 offset0:4 offset1:5
	v_mov_b32_e32 v12, v152
	v_lshlrev_b32_e32 v0, 16, v6
	v_mul_f32_e32 v12, v148, v12
	v_mul_f32_e32 v13, v149, v13
	s_waitcnt lgkmcnt(1)
	v_mov_b32_e32 v4, v170
	v_mov_b32_e32 v5, v172
	v_mul_f32_e32 v4, v4, v178
	v_mul_f32_e32 v5, v5, v179
	v_fma_f32 v1, v149, v0, v12
	v_fma_f32 v0, v148, v0, v13
	s_waitcnt lgkmcnt(0)
	v_mov_b32_e32 v12, v174
	v_mov_b32_e32 v13, v176
	v_and_b32_e32 v178, 0xffff0000, v7
	v_mul_f32_e32 v12, v12, v180
	v_mul_f32_e32 v13, v13, v181
	v_lshlrev_b32_e32 v181, 16, v8
	v_mov_b32_e32 v180, v178
	v_and_b32_e32 v7, 16, v9
	v_and_b32_e32 v6, 0xffff0000, v8
	v_mov_b32_e32 v182, v6
	v_pk_mov_b32 v[6:7], v[180:181], v[6:7] op_sel:[1,0]
	v_fma_f32 v0, v144, v152, v0
	v_fma_f32 v1, v145, v153, v1
	v_mul_f32_e32 v6, v146, v6
	v_mul_f32_e32 v7, v147, v7
	v_add_f32_e32 v0, v130, v0
	v_add_f32_e32 v1, v131, v1
	v_fma_f32 v6, v126, v180, v6
	v_fma_f32 v7, v127, v181, v7
	v_mov_b32_e32 v172, v171
	v_fma_f32 v6, v144, v182, v6
	v_fma_f32 v7, v145, v183, v7
	v_mov_b32_e32 v176, v175
	v_add_f32_e32 v6, v130, v6
	v_add_f32_e32 v7, v131, v7
	v_and_b32_e32 v10, 0xffff0000, v9
	v_mul_f32_e32 v0, v172, v0
	v_mul_f32_e32 v1, v173, v1
	v_and_b32_e32 v179, 16, v8
	v_mul_f32_e32 v8, v176, v6
	v_mul_f32_e32 v9, v177, v7
	ds_read2_b64 v[170:173], v184 offset0:2 offset1:3
	ds_read2_b64 v[174:177], v184 offset0:6 offset1:7
	v_add_f32_e32 v2, v130, v2
	v_add_f32_e32 v3, v131, v3
	s_xor_b64 s[36:37], s[60:61], -1
	s_mov_b64 s[34:35], s[58:59]
	s_waitcnt lgkmcnt(1)
	v_mov_b32_e32 v6, v170
	v_mov_b32_e32 v7, v172
	v_mul_f32_e32 v6, v6, v2
	v_mul_f32_e32 v7, v7, v3
	v_pk_mov_b32 v[2:3], v[152:153], v[178:179] op_sel:[1,0]
	s_add_u32 s23, s34, s10
	v_mul_f32_e32 v2, v146, v2
	v_mul_f32_e32 v3, v147, v3
	s_addc_u32 s35, s35, s11
	v_fma_f32 v2, v126, v152, v2
	v_fma_f32 v3, v127, v153, v3
	s_waitcnt lgkmcnt(0)
	v_mov_b32_e32 v152, v174
	v_mov_b32_e32 v153, v176
	v_mul_f32_e32 v14, v152, v14
	v_mul_f32_e32 v15, v153, v15
	v_mov_b32_e32 v152, v183
	v_mov_b32_e32 v153, v10
	v_mul_f32_e32 v152, v146, v152
	v_mul_f32_e32 v153, v147, v153
	s_add_u32 s34, s23, s48
	v_fma_f32 v152, v126, v182, v152
	v_fma_f32 v153, v127, v183, v153
	s_addc_u32 s35, s35, s49
	v_lshlrev_b64 v[150:151], 2, v[150:151]
	v_fma_f32 v10, v144, v10, v152
	v_fma_f32 v11, v145, v11, v153
	v_lshl_add_u64 v[152:153], s[34:35], 0, v[150:151]
	s_mov_b64 s[34:35], s[58:59]
	s_add_u32 s23, s34, s12
	s_addc_u32 s35, s35, s13
	s_add_u32 s34, s23, s48
	s_mov_b32 s23, 0xd500000
	v_mov_b32_e32 v172, v171
	v_lshl_add_u64 v[170:171], v[152:153], 0, s[26:27]
	s_addc_u32 s35, s35, s49
	v_add_co_u32_e32 v152, vcc, s23, v152
	v_lshl_add_u64 v[150:151], s[34:35], 0, v[150:151]
	s_nop 0
	v_addc_co_u32_e32 v153, vcc, 0, v153, vcc
	v_fma_f32 v2, v144, v180, v2
	v_fma_f32 v3, v145, v181, v3
	global_store_dwordx4 v[152:153], v[4:7], off
	global_store_dwordx4 v[170:171], v[12:15], off offset:16
	v_add_f32_e32 v2, v130, v2
	v_add_f32_e32 v3, v131, v3
	v_add_co_u32_e32 v4, vcc, 0xd500000, v150
	v_mul_f32_e32 v2, v172, v2
	v_mul_f32_e32 v3, v173, v3
	s_nop 0
	v_addc_co_u32_e32 v5, vcc, 0, v151, vcc
	v_add_f32_e32 v10, v130, v10
	v_add_f32_e32 v11, v131, v11
	v_mov_b32_e32 v176, v175
	s_movk_i32 s23, 0x200
	s_mov_b64 s[60:61], 0
	s_and_b64 vcc, exec, s[36:37]
	v_mul_f32_e32 v10, v176, v10
	v_mul_f32_e32 v11, v177, v11
	v_lshl_add_u64 v[172:173], v[150:151], 0, s[26:27]
	global_store_dwordx4 v[4:5], v[0:3], off
	global_store_dwordx4 v[172:173], v[8:11], off offset:16
	s_cbranch_vccnz .LBB0_530

; __device__ __forceinline__ float bf2f(bf16_t u) { return __uint_as_float((unsigned)u << 16); }
; __device__ __forceinline__ float hy_in(const bf16_t* p, int t, int n, float w0, float w1, float w2, float b) {
;     const float um = t > 0 ? bf2f(p[t - 1]) : 0.f, u0 = bf2f(p[t]), up = t < n - 1 ? bf2f(p[t + 1]) : 0.f;
;     return w0 * um + w1 * u0 + w2 * up + b;
; __global__ void __launch_bounds__(NTHR, 2) fwd_mega(Args a) {
;     ...
;                         U[i] = hy_in(p, t, 256, wv0, wv1, wv2, bv); XA[i] = hy_in(p + 256 * 256, t, 256, wa0, wa1, wa2, ba); XB[i] = hy_in(p + 512 * 256, t, 256, wb0, wb1, wb2, bb); }
.LBB0_609:
	s_or_b64 exec, exec, s[10:11]
	s_waitcnt vmcnt(0) lgkmcnt(0)
	v_lshlrev_b32_e32 v4, 16, v4
	v_mul_f32_e32 v2, v128, v4
	v_mul_f32_e32 v3, v129, v5
	s_xor_b64 s[12:13], s[6:7], -1
	v_fma_f32 v2, v126, v10, v2
	v_add_f32_e32 v2, v2, v3
	v_add_f32_e32 v2, v130, v2
	s_movk_i32 s10, 0x200
	s_mov_b64 s[6:7], 0
	s_and_b64 vcc, exec, s[12:13]
	ds_write_b32 v12, v2 offset:12288
	s_cbranch_vccnz .LBB0_622

; __device__ __forceinline__ float bf2f(bf16_t u) { return __uint_as_float((unsigned)u << 16); }
; __device__ __forceinline__ float hy_in(const bf16_t* p, int t, int n, float w0, float w1, float w2, float b) {
;     const float um = t > 0 ? bf2f(p[t - 1]) : 0.f, u0 = bf2f(p[t]), up = t < n - 1 ? bf2f(p[t + 1]) : 0.f;
;     return w0 * um + w1 * u0 + w2 * up + b;
; __global__ void __launch_bounds__(NTHR, 2) fwd_mega(Args a) {
;     ...
;                         U[i] = hy_in(p, t, 256, wv0, wv1, wv2, bv); XA[i] = hy_in(p + 256 * 256, t, 256, wa0, wa1, wa2, ba); XB[i] = hy_in(p + 512 * 256, t, 256, wb0, wb1, wb2, bb); }
.LBB0_614:
	s_or_b64 exec, exec, s[10:11]
	s_waitcnt vmcnt(0) lgkmcnt(0)
	v_lshlrev_b32_e32 v3, 16, v3
	v_mul_f32_e32 v6, v138, v6
	v_mul_f32_e32 v7, v139, v7
	v_lshl_add_u32 v12, v10, 2, 0
	v_fma_f32 v3, v125, v3, v6
	v_add_f32_e32 v3, v3, v7
	v_add_f32_e32 v3, v166, v3
	ds_write_b32 v12, v3 offset:4096
	v_lshl_add_u64 v[8:9], v[4:5], 0, s[66:67]
	v_mov_b32_e32 v7, 0
	v_mov_b64_e32 v[10:11], 0
	v_mov_b32_e32 v3, 0
	s_and_saveexec_b64 s[10:11], s[46:47]
	s_cbranch_execz .LBB0_616
	v_mov_b32_e32 v3, v209
	v_lshl_add_u64 v[10:11], v[8:9], 0, v[2:3]
	v_add_co_u32_e32 v10, vcc, -2, v10
	s_nop 1
	v_addc_co_u32_e32 v11, vcc, -1, v11, vcc
	global_load_ushort v3, v[10:11], off
	v_mov_b64_e32 v[10:11], v[0:1]
	s_waitcnt vmcnt(0) lgkmcnt(0)
	v_lshlrev_b32_e32 v3, 16, v3

; __device__ __forceinline__ float bf2f(bf16_t u) { return __uint_as_float((unsigned)u << 16); }
; __device__ __forceinline__ float hy_in(const bf16_t* p, int t, int n, float w0, float w1, float w2, float b) {
;     const float um = t > 0 ? bf2f(p[t - 1]) : 0.f, u0 = bf2f(p[t]), up = t < n - 1 ? bf2f(p[t + 1]) : 0.f;
;     return w0 * um + w1 * u0 + w2 * up + b;
; __global__ void __launch_bounds__(NTHR, 2) fwd_mega(Args a) {
;     ...
;                         U[i] = hy_in(p, t, 256, wv0, wv1, wv2, bv); XA[i] = hy_in(p + 256 * 256, t, 256, wa0, wa1, wa2, ba); XB[i] = hy_in(p + 512 * 256, t, 256, wb0, wb1, wb2, bb); }
.LBB0_618:
	s_or_b64 exec, exec, s[10:11]
	s_waitcnt vmcnt(0) lgkmcnt(0)
	v_lshlrev_b32_e32 v6, 16, v6
	v_mul_f32_e32 v6, v140, v6
	v_mul_f32_e32 v7, v141, v7
	s_mov_b64 s[10:11], 0x40000
	v_fma_f32 v3, v167, v3, v6
	v_add_f32_e32 v3, v3, v7
	v_add_f32_e32 v3, v168, v3
	v_lshl_add_u64 v[6:7], v[4:5], 0, s[10:11]
	v_mov_b32_e32 v5, 0
	v_mov_b64_e32 v[8:9], 0
	v_mov_b32_e32 v10, 0
	ds_write_b32 v12, v3 offset:8192
	s_and_saveexec_b64 s[10:11], s[46:47]
	s_cbranch_execz .LBB0_620
	v_mov_b32_e32 v3, v209
	v_lshl_add_u64 v[2:3], v[6:7], 0, v[2:3]
	v_add_co_u32_e32 v2, vcc, -2, v2
	v_mov_b64_e32 v[8:9], v[0:1]
	s_nop 0
	v_addc_co_u32_e32 v3, vcc, -1, v3, vcc
	global_load_ushort v2, v[2:3], off
	s_waitcnt vmcnt(0) lgkmcnt(0)
	v_lshlrev_b32_e32 v10, 16, v2
